# removed hipcc's alias-driven vmcnt(0) before ds_read in all 11 gemm256 instances (LDS-DMA stays in flight across barriers, template's counted vmcnt(6) governs)
# speedup vs baseline: 1.0456x; 1.0456x over previous
; #define STAGE(P, BASE, LD, br, kt) do { const long _g = (long)(br) * (LD) + (long)(kt) * 64; \
;     _Pragma("unroll") for (int _i = 0; _i < 2; ++_i) { const int _b = tid * 16 + _i * 8192; int _r, _c; stage_rc(_b, _r, _c); \
;       __builtin_amdgcn_global_load_lds((const G_AS1 unsigned*)((BASE) + _g + (long)_r * (LD) + _c), \
;         (LAS unsigned*)((char*)(P) + _b), 16, 0, 0); } } while (0)
; #define LDA(dst, b, h) _Pragma("unroll") for (int m = 0; m < 4; ++m) _Pragma("unroll") for (int k = 0; k < 2; ++k) \
;     dst[m][k] = *reinterpret_cast<const bf16x8*>((char*)SA(b, h) + lds_byte(wr * 64 + m * 16 + fr, k * 32 + fq * 8))
; #define LDB(dst, b, h) _Pragma("unroll") for (int n = 0; n < 2; ++n) _Pragma("unroll") for (int k = 0; k < 2; ++k) \
;     dst[n][k] = *reinterpret_cast<const bf16x8*>((char*)SB(b, h) + lds_byte(wc * 32 + n * 16 + fr, k * 32 + fq * 8))
; #define MMA(ai, bj, At_, Bt_) do { __builtin_amdgcn_s_setprio(1); \
;     _Pragma("unroll") for (int m = 0; m < 4; ++m) _Pragma("unroll") for (int n = 0; n < 2; ++n) _Pragma("unroll") for (int k = 0; k < 2; ++k) \
;       acc[ai][bj][m][n] = __builtin_amdgcn_mfma_f32_16x16x32_bf16(At_[m][k], Bt_[n][k], acc[ai][bj][m][n], 0, 0, 0); \
;     __builtin_amdgcn_s_setprio(0); } while (0)
; #define WAIT_L(n) asm volatile("s_waitcnt lgkmcnt(" #n ")" ::: "memory")
; #define BAR __builtin_amdgcn_s_barrier()
; #define SCHED __builtin_amdgcn_sched_barrier(0)
; __device__ __forceinline__ void gemm256(const bf16_t* __restrict__ A, long lda, const bf16_t* __restrict__ Bt, long ldb, int K,
;                                         int brow, int bcol, char* smem, f32x4 (&acc)[2][2][4][2]) {
;     ...
;         LDB(B0, 0, 0); SCHED; LDA(At, 0, 0); STAGE(SA(1, 1), A, lda, brow + 128, t + 1);
;         WAIT_L(8); BAR; WAIT_L(0); MMA(0, 0, At, B0); BAR; SCHED;
;         LDB(B1, 0, 1); STAGE(SB(0, 0), Bt, ldb, bcol, t + 2);
;         BAR; WAIT_L(0); MMA(0, 1, At, B1); BAR;
;         LDA(At, 0, 1); STAGE(SA(0, 0), A, lda, brow, t + 2);
;         BAR; WAIT_L(0); MMA(1, 0, At, B0); BAR; SCHED;
.LBB0_365:
	s_nop 0
	ds_read_b128 v[168:171], v164
	ds_read_b128 v[172:175], v164 offset:1024
	ds_read_b128 v[176:179], v164 offset:2048
	ds_read_b128 v[180:183], v164 offset:3072
	v_add_u32_e32 v165, 0xc000, v5
	v_lshl_add_u64 v[188:189], s[4:5], 0, v[140:141]
	v_readfirstlane_b32 s16, v165
	v_lshl_add_u64 v[166:167], v[188:189], 0, s[60:61]
	s_mov_b32 m0, s16
	ds_read_b128 v[184:187], v149
	ds_read_b128 v[192:195], v149 offset:1024
	ds_read_b128 v[196:199], v148
	ds_read_b128 v[200:203], v148 offset:1024
	ds_read_b128 v[204:207], v147
	ds_read_b128 v[208:211], v147 offset:1024
	ds_read_b128 v[212:215], v146
	ds_read_b128 v[216:219], v146 offset:1024
	global_load_lds_dwordx4 v[166:167], off
	v_add_u32_e32 v166, 0xe000, v5
	v_lshl_add_u64 v[190:191], s[4:5], 0, v[142:143]
	v_readfirstlane_b32 s16, v166
	v_lshl_add_u64 v[220:221], v[190:191], 0, s[60:61]
	s_mov_b32 m0, s16
	s_nop 0
	global_load_lds_dwordx4 v[220:221], off
	s_waitcnt lgkmcnt(8)
	s_barrier
	s_waitcnt lgkmcnt(0)
	s_setprio 1
	s_waitcnt lgkmcnt(0)
	v_mfma_f32_16x16x32_bf16 v[130:133], v[184:187], v[168:171], v[130:133]
	v_mfma_f32_16x16x32_bf16 v[126:129], v[184:187], v[176:179], v[126:129]
	v_mfma_f32_16x16x32_bf16 v[122:125], v[196:199], v[168:171], v[122:125]
	v_mfma_f32_16x16x32_bf16 v[118:121], v[196:199], v[176:179], v[118:121]
	v_mfma_f32_16x16x32_bf16 v[114:117], v[204:207], v[168:171], v[114:117]
	v_mfma_f32_16x16x32_bf16 v[110:113], v[204:207], v[176:179], v[110:113]
	v_mfma_f32_16x16x32_bf16 v[106:109], v[212:215], v[168:171], v[106:109]
	v_mfma_f32_16x16x32_bf16 v[102:105], v[212:215], v[176:179], v[102:105]
	v_mfma_f32_16x16x32_bf16 v[130:133], v[192:195], v[172:175], v[130:133]
	v_mfma_f32_16x16x32_bf16 v[126:129], v[192:195], v[180:183], v[126:129]
	v_mfma_f32_16x16x32_bf16 v[122:125], v[200:203], v[172:175], v[122:125]
	v_mfma_f32_16x16x32_bf16 v[118:121], v[200:203], v[180:183], v[118:121]
	v_mfma_f32_16x16x32_bf16 v[114:117], v[208:211], v[172:175], v[114:117]
	v_mfma_f32_16x16x32_bf16 v[110:113], v[208:211], v[180:183], v[110:113]
	v_mfma_f32_16x16x32_bf16 v[106:109], v[216:219], v[172:175], v[106:109]
	v_mfma_f32_16x16x32_bf16 v[102:105], v[216:219], v[180:183], v[102:105]
	s_setprio 0
	s_barrier
	v_lshl_add_u64 v[238:239], s[4:5], 0, v[136:137]
	v_readfirstlane_b32 s16, v144
	v_lshl_add_u64 v[242:243], v[238:239], 0, s[62:63]
	s_mov_b32 m0, s16
	s_nop 0
	ds_read_b128 v[220:223], v163
	ds_read_b128 v[224:227], v163 offset:1024
	ds_read_b128 v[228:231], v163 offset:2048
	ds_read_b128 v[232:235], v163 offset:3072
	global_load_lds_dwordx4 v[242:243], off
	v_lshl_add_u64 v[242:243], s[4:5], 0, v[138:139]
	v_readfirstlane_b32 s16, v150
	v_lshl_add_u64 v[244:245], v[242:243], 0, s[62:63]
	s_mov_b32 m0, s16
	s_nop 0
	global_load_lds_dwordx4 v[244:245], off
	s_barrier
	s_waitcnt lgkmcnt(0)
	s_setprio 1
	s_waitcnt lgkmcnt(0)
	v_mfma_f32_16x16x32_bf16 v[98:101], v[184:187], v[220:223], v[98:101]
	v_mfma_f32_16x16x32_bf16 v[94:97], v[184:187], v[228:231], v[94:97]
	v_mfma_f32_16x16x32_bf16 v[90:93], v[196:199], v[220:223], v[90:93]
	v_mfma_f32_16x16x32_bf16 v[86:89], v[196:199], v[228:231], v[86:89]
	v_mfma_f32_16x16x32_bf16 v[82:85], v[204:207], v[220:223], v[82:85]
	v_mfma_f32_16x16x32_bf16 v[78:81], v[204:207], v[228:231], v[78:81]
	v_mfma_f32_16x16x32_bf16 v[74:77], v[212:215], v[220:223], v[74:77]
	v_mfma_f32_16x16x32_bf16 v[70:73], v[212:215], v[228:231], v[70:73]
	v_mfma_f32_16x16x32_bf16 v[98:101], v[192:195], v[224:227], v[98:101]
	v_mfma_f32_16x16x32_bf16 v[94:97], v[192:195], v[232:235], v[94:97]
	v_mfma_f32_16x16x32_bf16 v[90:93], v[200:203], v[224:227], v[90:93]
	v_mfma_f32_16x16x32_bf16 v[86:89], v[200:203], v[232:235], v[86:89]
	v_mfma_f32_16x16x32_bf16 v[82:85], v[208:211], v[224:227], v[82:85]
	v_mfma_f32_16x16x32_bf16 v[78:81], v[208:211], v[232:235], v[78:81]
	v_mfma_f32_16x16x32_bf16 v[74:77], v[216:219], v[224:227], v[74:77]
	v_mfma_f32_16x16x32_bf16 v[70:73], v[216:219], v[232:235], v[70:73]
	s_setprio 0
	v_readfirstlane_b32 s16, v5
	v_lshl_add_u64 v[244:245], v[188:189], 0, s[92:93]
	s_mov_b32 m0, s16
	v_readfirstlane_b32 s16, v145
	s_barrier
	s_nop 0
	ds_read_b128 v[184:187], v149 offset:16384
	ds_read_b128 v[192:195], v149 offset:17408
	ds_read_b128 v[196:199], v148 offset:16384
	ds_read_b128 v[200:203], v148 offset:17408
	ds_read_b128 v[204:207], v147 offset:16384
	ds_read_b128 v[208:211], v147 offset:17408
	ds_read_b128 v[212:215], v146 offset:16384
	ds_read_b128 v[216:219], v146 offset:17408
	global_load_lds_dwordx4 v[244:245], off
	v_lshl_add_u64 v[244:245], v[190:191], 0, s[92:93]
	s_mov_b32 m0, s16
	s_nop 0
	global_load_lds_dwordx4 v[244:245], off
	s_barrier
	s_waitcnt lgkmcnt(0)
	s_setprio 1
	s_waitcnt lgkmcnt(0)
	v_mfma_f32_16x16x32_bf16 v[66:69], v[184:187], v[168:171], v[66:69]
	v_mfma_f32_16x16x32_bf16 v[62:65], v[184:187], v[176:179], v[62:65]
	v_mfma_f32_16x16x32_bf16 v[58:61], v[196:199], v[168:171], v[58:61]
	v_mfma_f32_16x16x32_bf16 v[54:57], v[196:199], v[176:179], v[54:57]
	v_mfma_f32_16x16x32_bf16 v[50:53], v[204:207], v[168:171], v[50:53]
	v_mfma_f32_16x16x32_bf16 v[46:49], v[204:207], v[176:179], v[46:49]
	v_mfma_f32_16x16x32_bf16 v[42:45], v[212:215], v[168:171], v[42:45]
	v_mfma_f32_16x16x32_bf16 v[38:41], v[212:215], v[176:179], v[38:41]
	v_mfma_f32_16x16x32_bf16 v[66:69], v[192:195], v[172:175], v[66:69]
	v_mfma_f32_16x16x32_bf16 v[62:65], v[192:195], v[180:183], v[62:65]
	v_mfma_f32_16x16x32_bf16 v[58:61], v[200:203], v[172:175], v[58:61]
	v_mfma_f32_16x16x32_bf16 v[54:57], v[200:203], v[180:183], v[54:57]
	v_mfma_f32_16x16x32_bf16 v[50:53], v[208:211], v[172:175], v[50:53]
	v_mfma_f32_16x16x32_bf16 v[46:49], v[208:211], v[180:183], v[46:49]
	v_mfma_f32_16x16x32_bf16 v[42:45], v[216:219], v[172:175], v[42:45]
	v_mfma_f32_16x16x32_bf16 v[38:41], v[216:219], v[180:183], v[38:41]
	s_setprio 0
	s_barrier
; #define STAGE(P, BASE, LD, br, kt) do { const long _g = (long)(br) * (LD) + (long)(kt) * 64; \
;     _Pragma("unroll") for (int _i = 0; _i < 2; ++_i) { const int _b = tid * 16 + _i * 8192; int _r, _c; stage_rc(_b, _r, _c); \
;       __builtin_amdgcn_global_load_lds((const G_AS1 unsigned*)((BASE) + _g + (long)_r * (LD) + _c), \
;         (LAS unsigned*)((char*)(P) + _b), 16, 0, 0); } } while (0)
; #define LDA(dst, b, h) _Pragma("unroll") for (int m = 0; m < 4; ++m) _Pragma("unroll") for (int k = 0; k < 2; ++k) \
;     dst[m][k] = *reinterpret_cast<const bf16x8*>((char*)SA(b, h) + lds_byte(wr * 64 + m * 16 + fr, k * 32 + fq * 8))
; #define LDB(dst, b, h) _Pragma("unroll") for (int n = 0; n < 2; ++n) _Pragma("unroll") for (int k = 0; k < 2; ++k) \
;     dst[n][k] = *reinterpret_cast<const bf16x8*>((char*)SB(b, h) + lds_byte(wc * 32 + n * 16 + fr, k * 32 + fq * 8))
; #define MMA(ai, bj, At_, Bt_) do { __builtin_amdgcn_s_setprio(1); \
;     _Pragma("unroll") for (int m = 0; m < 4; ++m) _Pragma("unroll") for (int n = 0; n < 2; ++n) _Pragma("unroll") for (int k = 0; k < 2; ++k) \
;       acc[ai][bj][m][n] = __builtin_amdgcn_mfma_f32_16x16x32_bf16(At_[m][k], Bt_[n][k], acc[ai][bj][m][n], 0, 0, 0); \
;     __builtin_amdgcn_s_setprio(0); } while (0)
; #define WAIT_V(n) asm volatile("s_waitcnt vmcnt(" #n ")" ::: "memory")
; #define WAIT_L(n) asm volatile("s_waitcnt lgkmcnt(" #n ")" ::: "memory")
; #define BAR __builtin_amdgcn_s_barrier()
; #define SCHED __builtin_amdgcn_sched_barrier(0)
; __device__ __forceinline__ void gemm256(const bf16_t* __restrict__ A, long lda, const bf16_t* __restrict__ Bt, long ldb, int K,
;                                         int brow, int bcol, char* smem, f32x4 (&acc)[2][2][4][2]) {
;     ...
;         STAGE(SB(0, 1), Bt, ldb, bcol + 128, t + 2);
;         WAIT_V(6); BAR; MMA(1, 1, At, B1); BAR;
;         LDB(B0, 1, 0); SCHED; LDA(At, 1, 0); STAGE(SA(0, 1), A, lda, brow + 128, t + 2);
;         WAIT_L(8); BAR; WAIT_L(0); MMA(0, 0, At, B0); BAR; SCHED;
;         LDB(B1, 1, 1); STAGE(SB(1, 0), Bt, ldb, bcol, t + 3);
;         BAR; WAIT_L(0); MMA(0, 1, At, B1); BAR;
;         LDA(At, 1, 1); STAGE(SA(1, 0), A, lda, brow, t + 3);
;         BAR; WAIT_L(0); MMA(1, 0, At, B0); BAR; SCHED;
	v_readfirstlane_b32 s16, v152
	v_lshl_add_u64 v[168:169], v[238:239], 0, s[66:67]
	s_mov_b32 m0, s16
	v_readfirstlane_b32 s16, v154
	global_load_lds_dwordx4 v[168:169], off
	v_lshl_add_u64 v[168:169], v[242:243], 0, s[66:67]
	s_mov_b32 m0, s16
	s_nop 0
	global_load_lds_dwordx4 v[168:169], off
	s_waitcnt vmcnt(6)
	s_barrier
	s_setprio 1
	v_mfma_f32_16x16x32_bf16 v[34:37], v[184:187], v[220:223], v[34:37]
	v_mfma_f32_16x16x32_bf16 v[30:33], v[184:187], v[228:231], v[30:33]
	v_mfma_f32_16x16x32_bf16 v[26:29], v[196:199], v[220:223], v[26:29]
	v_mfma_f32_16x16x32_bf16 v[22:25], v[196:199], v[228:231], v[22:25]
	v_mfma_f32_16x16x32_bf16 v[18:21], v[204:207], v[220:223], v[18:21]
	v_mfma_f32_16x16x32_bf16 v[14:17], v[204:207], v[228:231], v[14:17]
	v_mfma_f32_16x16x32_bf16 v[10:13], v[212:215], v[220:223], v[10:13]
	v_mfma_f32_16x16x32_bf16 v[6:9], v[212:215], v[228:231], v[6:9]
	v_mfma_f32_16x16x32_bf16 v[34:37], v[192:195], v[224:227], v[34:37]
	v_mfma_f32_16x16x32_bf16 v[30:33], v[192:195], v[232:235], v[30:33]
	v_mfma_f32_16x16x32_bf16 v[26:29], v[200:203], v[224:227], v[26:29]
	v_mfma_f32_16x16x32_bf16 v[22:25], v[200:203], v[232:235], v[22:25]
	v_mfma_f32_16x16x32_bf16 v[18:21], v[208:211], v[224:227], v[18:21]
	v_mfma_f32_16x16x32_bf16 v[14:17], v[208:211], v[232:235], v[14:17]
	v_mfma_f32_16x16x32_bf16 v[10:13], v[216:219], v[224:227], v[10:13]
	v_mfma_f32_16x16x32_bf16 v[6:9], v[216:219], v[232:235], v[6:9]
	s_setprio 0
	s_barrier
	s_nop 0
	ds_read_b128 v[168:171], v153
	ds_read_b128 v[172:175], v153 offset:1024
	ds_read_b128 v[176:179], v153 offset:2048
	ds_read_b128 v[180:183], v153 offset:3072
	v_readfirstlane_b32 s16, v155
	v_lshl_add_u64 v[220:221], v[188:189], 0, s[54:55]
	s_mov_b32 m0, s16
	v_readfirstlane_b32 s16, v156
	ds_read_b128 v[184:187], v149 offset:32768
	ds_read_b128 v[192:195], v149 offset:33792
	ds_read_b128 v[196:199], v148 offset:32768
	ds_read_b128 v[200:203], v148 offset:33792
	ds_read_b128 v[204:207], v147 offset:32768
	ds_read_b128 v[208:211], v147 offset:33792
	ds_read_b128 v[212:215], v146 offset:32768
	ds_read_b128 v[216:219], v146 offset:33792
	global_load_lds_dwordx4 v[220:221], off
	v_lshl_add_u64 v[220:221], v[190:191], 0, s[54:55]
	s_mov_b32 m0, s16
	s_nop 0
	global_load_lds_dwordx4 v[220:221], off
	s_waitcnt lgkmcnt(8)
	s_barrier
	s_waitcnt lgkmcnt(0)
	s_setprio 1
	s_waitcnt lgkmcnt(0)
	v_mfma_f32_16x16x32_bf16 v[130:133], v[184:187], v[168:171], v[130:133]
	v_mfma_f32_16x16x32_bf16 v[126:129], v[184:187], v[176:179], v[126:129]
	v_mfma_f32_16x16x32_bf16 v[122:125], v[196:199], v[168:171], v[122:125]
	v_mfma_f32_16x16x32_bf16 v[118:121], v[196:199], v[176:179], v[118:121]
	v_mfma_f32_16x16x32_bf16 v[114:117], v[204:207], v[168:171], v[114:117]
	v_mfma_f32_16x16x32_bf16 v[110:113], v[204:207], v[176:179], v[110:113]
	v_mfma_f32_16x16x32_bf16 v[106:109], v[212:215], v[168:171], v[106:109]
	v_mfma_f32_16x16x32_bf16 v[102:105], v[212:215], v[176:179], v[102:105]
	v_mfma_f32_16x16x32_bf16 v[130:133], v[192:195], v[172:175], v[130:133]
	v_mfma_f32_16x16x32_bf16 v[126:129], v[192:195], v[180:183], v[126:129]
	v_mfma_f32_16x16x32_bf16 v[122:125], v[200:203], v[172:175], v[122:125]
	v_mfma_f32_16x16x32_bf16 v[118:121], v[200:203], v[180:183], v[118:121]
	v_mfma_f32_16x16x32_bf16 v[114:117], v[208:211], v[172:175], v[114:117]
	v_mfma_f32_16x16x32_bf16 v[110:113], v[208:211], v[180:183], v[110:113]
	v_mfma_f32_16x16x32_bf16 v[106:109], v[216:219], v[172:175], v[106:109]
	v_mfma_f32_16x16x32_bf16 v[102:105], v[216:219], v[180:183], v[102:105]
	s_setprio 0
	s_barrier
	v_readfirstlane_b32 s16, v157
	v_lshl_add_u64 v[244:245], v[238:239], 0, s[48:49]
	s_mov_b32 m0, s16
	v_readfirstlane_b32 s16, v158
	s_nop 0
	ds_read_b128 v[220:223], v151
	ds_read_b128 v[224:227], v151 offset:1024
	ds_read_b128 v[228:231], v151 offset:2048
	ds_read_b128 v[232:235], v151 offset:3072
	global_load_lds_dwordx4 v[244:245], off
	v_lshl_add_u64 v[244:245], v[242:243], 0, s[48:49]
	s_mov_b32 m0, s16
	s_nop 0
	global_load_lds_dwordx4 v[244:245], off
	s_barrier
	s_waitcnt lgkmcnt(0)
	s_setprio 1
	s_waitcnt lgkmcnt(0)
	v_mfma_f32_16x16x32_bf16 v[98:101], v[184:187], v[220:223], v[98:101]
	v_mfma_f32_16x16x32_bf16 v[94:97], v[184:187], v[228:231], v[94:97]
	v_mfma_f32_16x16x32_bf16 v[90:93], v[196:199], v[220:223], v[90:93]
	v_mfma_f32_16x16x32_bf16 v[86:89], v[196:199], v[228:231], v[86:89]
	v_mfma_f32_16x16x32_bf16 v[82:85], v[204:207], v[220:223], v[82:85]
	v_mfma_f32_16x16x32_bf16 v[78:81], v[204:207], v[228:231], v[78:81]
	v_mfma_f32_16x16x32_bf16 v[74:77], v[212:215], v[220:223], v[74:77]
	v_mfma_f32_16x16x32_bf16 v[70:73], v[212:215], v[228:231], v[70:73]
	v_mfma_f32_16x16x32_bf16 v[98:101], v[192:195], v[224:227], v[98:101]
	v_mfma_f32_16x16x32_bf16 v[94:97], v[192:195], v[232:235], v[94:97]
	v_mfma_f32_16x16x32_bf16 v[90:93], v[200:203], v[224:227], v[90:93]
	v_mfma_f32_16x16x32_bf16 v[86:89], v[200:203], v[232:235], v[86:89]
	v_mfma_f32_16x16x32_bf16 v[82:85], v[208:211], v[224:227], v[82:85]
	v_mfma_f32_16x16x32_bf16 v[78:81], v[208:211], v[232:235], v[78:81]
	v_mfma_f32_16x16x32_bf16 v[74:77], v[216:219], v[224:227], v[74:77]
	v_mfma_f32_16x16x32_bf16 v[70:73], v[216:219], v[232:235], v[70:73]
	s_setprio 0
	v_readfirstlane_b32 s16, v159
	v_lshl_add_u64 v[188:189], v[188:189], 0, s[40:41]
	s_mov_b32 m0, s16
	v_readfirstlane_b32 s16, v160
	s_barrier
	s_nop 0
	ds_read_b128 v[184:187], v149 offset:49152
	ds_read_b128 v[192:195], v149 offset:50176
	ds_read_b128 v[196:199], v148 offset:49152
	ds_read_b128 v[200:203], v148 offset:50176
	ds_read_b128 v[204:207], v147 offset:49152
	ds_read_b128 v[208:211], v147 offset:50176
	ds_read_b128 v[212:215], v146 offset:49152
	ds_read_b128 v[216:219], v146 offset:50176
	global_load_lds_dwordx4 v[188:189], off
	v_lshl_add_u64 v[188:189], v[190:191], 0, s[40:41]
	s_mov_b32 m0, s16
	s_nop 0
	global_load_lds_dwordx4 v[188:189], off
	s_barrier
; #define STAGE(P, BASE, LD, br, kt) do { const long _g = (long)(br) * (LD) + (long)(kt) * 64; \
;     _Pragma("unroll") for (int _i = 0; _i < 2; ++_i) { const int _b = tid * 16 + _i * 8192; int _r, _c; stage_rc(_b, _r, _c); \
;       __builtin_amdgcn_global_load_lds((const G_AS1 unsigned*)((BASE) + _g + (long)_r * (LD) + _c), \
;         (LAS unsigned*)((char*)(P) + _b), 16, 0, 0); } } while (0)
; #define LDA(dst, b, h) _Pragma("unroll") for (int m = 0; m < 4; ++m) _Pragma("unroll") for (int k = 0; k < 2; ++k) \
;     dst[m][k] = *reinterpret_cast<const bf16x8*>((char*)SA(b, h) + lds_byte(wr * 64 + m * 16 + fr, k * 32 + fq * 8))
; #define LDB(dst, b, h) _Pragma("unroll") for (int n = 0; n < 2; ++n) _Pragma("unroll") for (int k = 0; k < 2; ++k) \
;     dst[n][k] = *reinterpret_cast<const bf16x8*>((char*)SB(b, h) + lds_byte(wc * 32 + n * 16 + fr, k * 32 + fq * 8))
; #define MMA(ai, bj, At_, Bt_) do { __builtin_amdgcn_s_setprio(1); \
;     _Pragma("unroll") for (int m = 0; m < 4; ++m) _Pragma("unroll") for (int n = 0; n < 2; ++n) _Pragma("unroll") for (int k = 0; k < 2; ++k) \
;       acc[ai][bj][m][n] = __builtin_amdgcn_mfma_f32_16x16x32_bf16(At_[m][k], Bt_[n][k], acc[ai][bj][m][n], 0, 0, 0); \
;     __builtin_amdgcn_s_setprio(0); } while (0)
; #define WAIT_V(n) asm volatile("s_waitcnt vmcnt(" #n ")" ::: "memory")
; #define WAIT_L(n) asm volatile("s_waitcnt lgkmcnt(" #n ")" ::: "memory")
; #define BAR __builtin_amdgcn_s_barrier()
; #define SCHED __builtin_amdgcn_sched_barrier(0)
; __device__ __forceinline__ void gemm256(const bf16_t* __restrict__ A, long lda, const bf16_t* __restrict__ Bt, long ldb, int K,
;                                         int brow, int bcol, char* smem, f32x4 (&acc)[2][2][4][2]) {
;     ...
;         BAR; WAIT_L(0); MMA(1, 0, At, B0); BAR; SCHED;
;         STAGE(SB(1, 1), Bt, ldb, bcol + 128, t + 3);
;         WAIT_V(6); BAR; MMA(1, 1, At, B1); BAR;
;     }
;     { LDB(B0, 0, 0); LDA(At, 0, 0); STAGE(SA(1, 1), A, lda, brow + 128, nt - 1);
;       BAR; WAIT_L(0); MMA(0, 0, At, B0); BAR;
;       LDB(B1, 0, 1); BAR; WAIT_L(0); MMA(0, 1, At, B1); BAR;
	s_waitcnt lgkmcnt(0)
	s_setprio 1
	s_waitcnt lgkmcnt(0)
	v_mfma_f32_16x16x32_bf16 v[66:69], v[184:187], v[168:171], v[66:69]
	v_mfma_f32_16x16x32_bf16 v[62:65], v[184:187], v[176:179], v[62:65]
	v_mfma_f32_16x16x32_bf16 v[58:61], v[196:199], v[168:171], v[58:61]
	v_mfma_f32_16x16x32_bf16 v[54:57], v[196:199], v[176:179], v[54:57]
	v_mfma_f32_16x16x32_bf16 v[50:53], v[204:207], v[168:171], v[50:53]
	v_mfma_f32_16x16x32_bf16 v[46:49], v[204:207], v[176:179], v[46:49]
	v_mfma_f32_16x16x32_bf16 v[42:45], v[212:215], v[168:171], v[42:45]
	v_mfma_f32_16x16x32_bf16 v[38:41], v[212:215], v[176:179], v[38:41]
	v_mfma_f32_16x16x32_bf16 v[66:69], v[192:195], v[172:175], v[66:69]
	v_mfma_f32_16x16x32_bf16 v[62:65], v[192:195], v[180:183], v[62:65]
	v_mfma_f32_16x16x32_bf16 v[58:61], v[200:203], v[172:175], v[58:61]
	v_mfma_f32_16x16x32_bf16 v[54:57], v[200:203], v[180:183], v[54:57]
	v_mfma_f32_16x16x32_bf16 v[50:53], v[208:211], v[172:175], v[50:53]
	v_mfma_f32_16x16x32_bf16 v[46:49], v[208:211], v[180:183], v[46:49]
	v_mfma_f32_16x16x32_bf16 v[42:45], v[216:219], v[172:175], v[42:45]
	v_mfma_f32_16x16x32_bf16 v[38:41], v[216:219], v[180:183], v[38:41]
	s_setprio 0
	s_barrier
	v_readfirstlane_b32 s16, v161
	v_lshl_add_u64 v[168:169], v[238:239], 0, s[42:43]
	s_mov_b32 m0, s16
	v_readfirstlane_b32 s16, v162
	global_load_lds_dwordx4 v[168:169], off
	v_lshl_add_u64 v[168:169], v[242:243], 0, s[42:43]
	s_mov_b32 m0, s16
	s_nop 0
	global_load_lds_dwordx4 v[168:169], off
	s_waitcnt vmcnt(6)
	s_barrier
	s_setprio 1
	v_mfma_f32_16x16x32_bf16 v[34:37], v[184:187], v[220:223], v[34:37]
	v_mfma_f32_16x16x32_bf16 v[30:33], v[184:187], v[228:231], v[30:33]
	v_mfma_f32_16x16x32_bf16 v[26:29], v[196:199], v[220:223], v[26:29]
	v_mfma_f32_16x16x32_bf16 v[22:25], v[196:199], v[228:231], v[22:25]
	v_mfma_f32_16x16x32_bf16 v[18:21], v[204:207], v[220:223], v[18:21]
	v_mfma_f32_16x16x32_bf16 v[14:17], v[204:207], v[228:231], v[14:17]
	v_mfma_f32_16x16x32_bf16 v[10:13], v[212:215], v[220:223], v[10:13]
	v_mfma_f32_16x16x32_bf16 v[6:9], v[212:215], v[228:231], v[6:9]
	v_mfma_f32_16x16x32_bf16 v[34:37], v[192:195], v[224:227], v[34:37]
	v_mfma_f32_16x16x32_bf16 v[30:33], v[192:195], v[232:235], v[30:33]
	v_mfma_f32_16x16x32_bf16 v[26:29], v[200:203], v[224:227], v[26:29]
	v_mfma_f32_16x16x32_bf16 v[22:25], v[200:203], v[232:235], v[22:25]
	v_mfma_f32_16x16x32_bf16 v[18:21], v[208:211], v[224:227], v[18:21]
	v_mfma_f32_16x16x32_bf16 v[14:17], v[208:211], v[232:235], v[14:17]
	v_mfma_f32_16x16x32_bf16 v[10:13], v[216:219], v[224:227], v[10:13]
	v_mfma_f32_16x16x32_bf16 v[6:9], v[216:219], v[232:235], v[6:9]
	s_setprio 0
	s_add_i32 s11, s11, 2
	v_lshl_add_u64 v[136:137], v[136:137], 0, s[44:45]
	v_lshl_add_u64 v[138:139], v[138:139], 0, s[44:45]
	v_lshl_add_u64 v[140:141], v[140:141], 0, s[44:45]
	s_cmp_lt_u32 s11, 12
	v_lshl_add_u64 v[142:143], v[142:143], 0, s[44:45]
	s_barrier
	s_cbranch_scc1 .LBB0_365
	s_mov_b64 s[16:17], 0x780
	v_readfirstlane_b32 s11, v165
	v_lshl_add_u64 v[2:3], v[2:3], 0, s[16:17]
	s_mov_b32 m0, s11
	v_readfirstlane_b32 s11, v166
	s_nop 0
	ds_read_b128 v[136:139], v164
	ds_read_b128 v[140:143], v164 offset:1024
	ds_read_b128 v[154:157], v164 offset:2048
	ds_read_b128 v[158:161], v164 offset:3072
	ds_read_b128 v[168:171], v149
	ds_read_b128 v[172:175], v149 offset:1024
	ds_read_b128 v[176:179], v148
	ds_read_b128 v[180:183], v148 offset:1024
	ds_read_b128 v[184:187], v147
	ds_read_b128 v[192:195], v147 offset:1024
	ds_read_b128 v[196:199], v146
	ds_read_b128 v[200:203], v146 offset:1024
	global_load_lds_dwordx4 v[2:3], off
	v_lshl_add_u64 v[2:3], v[134:135], 0, s[16:17]
	s_mov_b32 m0, s11
	s_nop 0
	global_load_lds_dwordx4 v[2:3], off
	s_barrier
	s_waitcnt lgkmcnt(0)
	s_setprio 1
	s_waitcnt lgkmcnt(0)
	v_mfma_f32_16x16x32_bf16 v[130:133], v[168:171], v[136:139], v[130:133]
	v_mfma_f32_16x16x32_bf16 v[122:125], v[176:179], v[136:139], v[122:125]
	v_mfma_f32_16x16x32_bf16 v[114:117], v[184:187], v[136:139], v[114:117]
	v_mfma_f32_16x16x32_bf16 v[106:109], v[196:199], v[136:139], v[106:109]
	v_mfma_f32_16x16x32_bf16 v[130:133], v[172:175], v[140:143], v[130:133]
	v_mfma_f32_16x16x32_bf16 v[126:129], v[168:171], v[154:157], v[126:129]
	v_mfma_f32_16x16x32_bf16 v[122:125], v[180:183], v[140:143], v[122:125]
	v_mfma_f32_16x16x32_bf16 v[118:121], v[176:179], v[154:157], v[118:121]
	v_mfma_f32_16x16x32_bf16 v[114:117], v[192:195], v[140:143], v[114:117]
	v_mfma_f32_16x16x32_bf16 v[110:113], v[184:187], v[154:157], v[110:113]
	v_mfma_f32_16x16x32_bf16 v[106:109], v[200:203], v[140:143], v[106:109]
	v_mfma_f32_16x16x32_bf16 v[102:105], v[196:199], v[154:157], v[102:105]
	v_mfma_f32_16x16x32_bf16 v[164:167], v[172:175], v[158:161], v[126:129]
	v_mfma_f32_16x16x32_bf16 v[204:207], v[180:183], v[158:161], v[118:121]
	v_mfma_f32_16x16x32_bf16 v[208:211], v[192:195], v[158:161], v[110:113]
	v_mfma_f32_16x16x32_bf16 v[212:215], v[200:203], v[158:161], v[102:105]
	s_setprio 0
	s_barrier
	s_nop 0
	s_nop 0
	ds_read_b128 v[102:105], v163
	ds_read_b128 v[110:113], v163 offset:1024
	ds_read_b128 v[118:121], v163 offset:2048
	ds_read_b128 v[126:129], v163 offset:3072
	s_barrier
; #define LDA(dst, b, h) _Pragma("unroll") for (int m = 0; m < 4; ++m) _Pragma("unroll") for (int k = 0; k < 2; ++k) \
;     dst[m][k] = *reinterpret_cast<const bf16x8*>((char*)SA(b, h) + lds_byte(wr * 64 + m * 16 + fr, k * 32 + fq * 8))
; #define LDB(dst, b, h) _Pragma("unroll") for (int n = 0; n < 2; ++n) _Pragma("unroll") for (int k = 0; k < 2; ++k) \
;     dst[n][k] = *reinterpret_cast<const bf16x8*>((char*)SB(b, h) + lds_byte(wc * 32 + n * 16 + fr, k * 32 + fq * 8))
; #define MMA(ai, bj, At_, Bt_) do { __builtin_amdgcn_s_setprio(1); \
;     _Pragma("unroll") for (int m = 0; m < 4; ++m) _Pragma("unroll") for (int n = 0; n < 2; ++n) _Pragma("unroll") for (int k = 0; k < 2; ++k) \
;       acc[ai][bj][m][n] = __builtin_amdgcn_mfma_f32_16x16x32_bf16(At_[m][k], Bt_[n][k], acc[ai][bj][m][n], 0, 0, 0); \
;     __builtin_amdgcn_s_setprio(0); } while (0)
; #define WAIT_V(n) asm volatile("s_waitcnt vmcnt(" #n ")" ::: "memory")
; #define WAIT_L(n) asm volatile("s_waitcnt lgkmcnt(" #n ")" ::: "memory")
; #define BAR __builtin_amdgcn_s_barrier()
; __device__ __forceinline__ void gemm256(const bf16_t* __restrict__ A, long lda, const bf16_t* __restrict__ Bt, long ldb, int K,
;                                         int brow, int bcol, char* smem, f32x4 (&acc)[2][2][4][2]) {
;     ...
;       LDB(B1, 0, 1); BAR; WAIT_L(0); MMA(0, 1, At, B1); BAR;
;       LDA(At, 0, 1); WAIT_V(4); BAR; WAIT_L(0); MMA(1, 0, At, B0); MMA(1, 1, At, B1); BAR; }
;     { LDB(B0, 1, 0); LDA(At, 1, 0); WAIT_V(2); BAR; WAIT_L(0); MMA(0, 0, At, B0); BAR;
	s_waitcnt lgkmcnt(0)
	s_setprio 1
	s_waitcnt lgkmcnt(3)
	v_mfma_f32_16x16x32_bf16 v[98:101], v[168:171], v[102:105], v[98:101]
	v_mfma_f32_16x16x32_bf16 v[90:93], v[176:179], v[102:105], v[90:93]
	v_mfma_f32_16x16x32_bf16 v[82:85], v[184:187], v[102:105], v[82:85]
	v_mfma_f32_16x16x32_bf16 v[74:77], v[196:199], v[102:105], v[74:77]
	s_waitcnt lgkmcnt(2)
	v_mfma_f32_16x16x32_bf16 v[98:101], v[172:175], v[110:113], v[98:101]
	s_waitcnt lgkmcnt(1)
	v_mfma_f32_16x16x32_bf16 v[94:97], v[168:171], v[118:121], v[94:97]
	v_mfma_f32_16x16x32_bf16 v[90:93], v[180:183], v[110:113], v[90:93]
	v_mfma_f32_16x16x32_bf16 v[86:89], v[176:179], v[118:121], v[86:89]
	v_mfma_f32_16x16x32_bf16 v[82:85], v[192:195], v[110:113], v[82:85]
	v_mfma_f32_16x16x32_bf16 v[78:81], v[184:187], v[118:121], v[78:81]
	v_mfma_f32_16x16x32_bf16 v[74:77], v[200:203], v[110:113], v[74:77]
	v_mfma_f32_16x16x32_bf16 v[70:73], v[196:199], v[118:121], v[70:73]
	s_waitcnt lgkmcnt(0)
	v_mfma_f32_16x16x32_bf16 v[168:171], v[172:175], v[126:129], v[94:97]
	v_mfma_f32_16x16x32_bf16 v[172:175], v[180:183], v[126:129], v[86:89]
	v_mfma_f32_16x16x32_bf16 v[176:179], v[192:195], v[126:129], v[78:81]
	v_mfma_f32_16x16x32_bf16 v[180:183], v[200:203], v[126:129], v[70:73]
	s_setprio 0
	s_barrier
	s_nop 0
	ds_read_b128 v[70:73], v149 offset:16384
	ds_read_b128 v[78:81], v149 offset:17408
	ds_read_b128 v[86:89], v148 offset:16384
	ds_read_b128 v[94:97], v148 offset:17408
	ds_read_b128 v[184:187], v147 offset:16384
	ds_read_b128 v[192:195], v147 offset:17408
	ds_read_b128 v[196:199], v146 offset:16384
	ds_read_b128 v[200:203], v146 offset:17408
	s_waitcnt vmcnt(4)
	s_barrier
	s_waitcnt lgkmcnt(0)
	s_setprio 1
	s_waitcnt lgkmcnt(7)
	v_mfma_f32_16x16x32_bf16 v[66:69], v[70:73], v[136:139], v[66:69]
	s_waitcnt lgkmcnt(5)
	v_mfma_f32_16x16x32_bf16 v[58:61], v[86:89], v[136:139], v[58:61]
	s_waitcnt lgkmcnt(3)
	v_mfma_f32_16x16x32_bf16 v[50:53], v[184:187], v[136:139], v[50:53]
	s_waitcnt lgkmcnt(1)
	v_mfma_f32_16x16x32_bf16 v[42:45], v[196:199], v[136:139], v[42:45]
	v_mfma_f32_16x16x32_bf16 v[66:69], v[78:81], v[140:143], v[66:69]
	v_mfma_f32_16x16x32_bf16 v[62:65], v[70:73], v[154:157], v[62:65]
	v_mfma_f32_16x16x32_bf16 v[58:61], v[94:97], v[140:143], v[58:61]
	v_mfma_f32_16x16x32_bf16 v[54:57], v[86:89], v[154:157], v[54:57]
	v_mfma_f32_16x16x32_bf16 v[50:53], v[192:195], v[140:143], v[50:53]
	v_mfma_f32_16x16x32_bf16 v[46:49], v[184:187], v[154:157], v[46:49]
	s_waitcnt lgkmcnt(0)
	v_mfma_f32_16x16x32_bf16 v[42:45], v[200:203], v[140:143], v[42:45]
	v_mfma_f32_16x16x32_bf16 v[38:41], v[196:199], v[154:157], v[38:41]
	v_mfma_f32_16x16x32_bf16 v[216:219], v[78:81], v[158:161], v[62:65]
	v_mfma_f32_16x16x32_bf16 v[220:223], v[94:97], v[158:161], v[54:57]
	v_mfma_f32_16x16x32_bf16 v[224:227], v[192:195], v[158:161], v[46:49]
	v_mfma_f32_16x16x32_bf16 v[134:137], v[200:203], v[158:161], v[38:41]
	s_setprio 0
	s_setprio 1
	v_mfma_f32_16x16x32_bf16 v[34:37], v[70:73], v[102:105], v[34:37]
	v_mfma_f32_16x16x32_bf16 v[26:29], v[86:89], v[102:105], v[26:29]
	v_mfma_f32_16x16x32_bf16 v[18:21], v[184:187], v[102:105], v[18:21]
	v_mfma_f32_16x16x32_bf16 v[10:13], v[196:199], v[102:105], v[10:13]
	v_mfma_f32_16x16x32_bf16 v[34:37], v[78:81], v[110:113], v[34:37]
	v_mfma_f32_16x16x32_bf16 v[30:33], v[70:73], v[118:121], v[30:33]
	v_mfma_f32_16x16x32_bf16 v[26:29], v[94:97], v[110:113], v[26:29]
	v_mfma_f32_16x16x32_bf16 v[22:25], v[86:89], v[118:121], v[22:25]
	v_mfma_f32_16x16x32_bf16 v[18:21], v[192:195], v[110:113], v[18:21]
	v_mfma_f32_16x16x32_bf16 v[14:17], v[184:187], v[118:121], v[14:17]
	v_mfma_f32_16x16x32_bf16 v[10:13], v[200:203], v[110:113], v[10:13]
	v_mfma_f32_16x16x32_bf16 v[6:9], v[196:199], v[118:121], v[6:9]
	v_mfma_f32_16x16x32_bf16 v[138:141], v[78:81], v[126:129], v[30:33]
	v_mfma_f32_16x16x32_bf16 v[142:145], v[94:97], v[126:129], v[22:25]
	v_mfma_f32_16x16x32_bf16 v[154:157], v[192:195], v[126:129], v[14:17]
	v_mfma_f32_16x16x32_bf16 v[158:161], v[200:203], v[126:129], v[6:9]
	s_setprio 0
	s_barrier
	s_nop 1
	ds_read_b128 v[6:9], v153
	ds_read_b128 v[14:17], v153 offset:1024
	ds_read_b128 v[184:187], v153 offset:2048
	ds_read_b128 v[192:195], v153 offset:3072
	ds_read_b128 v[22:25], v149 offset:32768
	ds_read_b128 v[30:33], v149 offset:33792
	ds_read_b128 v[38:41], v148 offset:32768
	ds_read_b128 v[46:49], v148 offset:33792
	ds_read_b128 v[54:57], v147 offset:32768
	ds_read_b128 v[62:65], v147 offset:33792
	ds_read_b128 v[196:199], v146 offset:32768
	ds_read_b128 v[200:203], v146 offset:33792
	s_waitcnt vmcnt(2)
	s_barrier
; #define LDA(dst, b, h) _Pragma("unroll") for (int m = 0; m < 4; ++m) _Pragma("unroll") for (int k = 0; k < 2; ++k) \
;     dst[m][k] = *reinterpret_cast<const bf16x8*>((char*)SA(b, h) + lds_byte(wr * 64 + m * 16 + fr, k * 32 + fq * 8))
; #define LDB(dst, b, h) _Pragma("unroll") for (int n = 0; n < 2; ++n) _Pragma("unroll") for (int k = 0; k < 2; ++k) \
;     dst[n][k] = *reinterpret_cast<const bf16x8*>((char*)SB(b, h) + lds_byte(wc * 32 + n * 16 + fr, k * 32 + fq * 8))
; #define MMA(ai, bj, At_, Bt_) do { __builtin_amdgcn_s_setprio(1); \
;     _Pragma("unroll") for (int m = 0; m < 4; ++m) _Pragma("unroll") for (int n = 0; n < 2; ++n) _Pragma("unroll") for (int k = 0; k < 2; ++k) \
;       acc[ai][bj][m][n] = __builtin_amdgcn_mfma_f32_16x16x32_bf16(At_[m][k], Bt_[n][k], acc[ai][bj][m][n], 0, 0, 0); \
;     __builtin_amdgcn_s_setprio(0); } while (0)
; #define WAIT_V(n) asm volatile("s_waitcnt vmcnt(" #n ")" ::: "memory")
; #define WAIT_L(n) asm volatile("s_waitcnt lgkmcnt(" #n ")" ::: "memory")
; #define BAR __builtin_amdgcn_s_barrier()
; __device__ __forceinline__ void gemm256(const bf16_t* __restrict__ A, long lda, const bf16_t* __restrict__ Bt, long ldb, int K,
;                                         int brow, int bcol, char* smem, f32x4 (&acc)[2][2][4][2]) {
;     ...
;     { LDB(B0, 1, 0); LDA(At, 1, 0); WAIT_V(2); BAR; WAIT_L(0); MMA(0, 0, At, B0); BAR;
;       LDB(B1, 1, 1); WAIT_V(0); BAR; WAIT_L(0); MMA(0, 1, At, B1); BAR;
;       LDA(At, 1, 1); BAR; WAIT_L(0); MMA(1, 0, At, B0); MMA(1, 1, At, B1); BAR; }
;     if (wr == 0) BAR;
	s_waitcnt lgkmcnt(0)
	s_setprio 1
	s_waitcnt lgkmcnt(7)
	v_mfma_f32_16x16x32_bf16 v[70:73], v[22:25], v[6:9], v[130:133]
	s_waitcnt lgkmcnt(6)
	v_mfma_f32_16x16x32_bf16 v[126:129], v[30:33], v[14:17], v[70:73]
	v_mfma_f32_16x16x32_bf16 v[70:73], v[22:25], v[184:187], v[164:167]
	v_mfma_f32_16x16x32_bf16 v[118:121], v[30:33], v[192:195], v[70:73]
	s_waitcnt lgkmcnt(5)
	v_mfma_f32_16x16x32_bf16 v[70:73], v[38:41], v[6:9], v[122:125]
	s_waitcnt lgkmcnt(4)
	v_mfma_f32_16x16x32_bf16 v[110:113], v[46:49], v[14:17], v[70:73]
	v_mfma_f32_16x16x32_bf16 v[70:73], v[38:41], v[184:187], v[204:207]
	v_mfma_f32_16x16x32_bf16 v[102:105], v[46:49], v[192:195], v[70:73]
	s_waitcnt lgkmcnt(3)
	v_mfma_f32_16x16x32_bf16 v[70:73], v[54:57], v[6:9], v[114:117]
	s_waitcnt lgkmcnt(2)
	v_mfma_f32_16x16x32_bf16 v[94:97], v[62:65], v[14:17], v[70:73]
	v_mfma_f32_16x16x32_bf16 v[70:73], v[54:57], v[184:187], v[208:211]
	v_mfma_f32_16x16x32_bf16 v[86:89], v[62:65], v[192:195], v[70:73]
	s_waitcnt lgkmcnt(1)
	v_mfma_f32_16x16x32_bf16 v[70:73], v[196:199], v[6:9], v[106:109]
	s_waitcnt lgkmcnt(0)
	v_mfma_f32_16x16x32_bf16 v[78:81], v[200:203], v[14:17], v[70:73]
	v_mfma_f32_16x16x32_bf16 v[70:73], v[196:199], v[184:187], v[212:215]
	v_mfma_f32_16x16x32_bf16 v[70:73], v[200:203], v[192:195], v[70:73]
	s_setprio 0
	s_barrier
	ds_read_b128 v[162:165], v151
	ds_read_b128 v[204:207], v151 offset:1024
	ds_read_b128 v[208:211], v151 offset:2048
	ds_read_b128 v[150:153], v151 offset:3072
	s_waitcnt vmcnt(0)
	s_barrier
	s_waitcnt lgkmcnt(0)
	s_setprio 1
	s_waitcnt lgkmcnt(3)
	v_mfma_f32_16x16x32_bf16 v[98:101], v[22:25], v[162:165], v[98:101]
	s_waitcnt lgkmcnt(1)
	v_mfma_f32_16x16x32_bf16 v[22:25], v[22:25], v[208:211], v[168:171]
	s_waitcnt lgkmcnt(0)
	v_mfma_f32_16x16x32_bf16 v[122:125], v[30:33], v[150:153], v[22:25]
	v_mfma_f32_16x16x32_bf16 v[22:25], v[38:41], v[162:165], v[90:93]
	v_mfma_f32_16x16x32_bf16 v[114:117], v[46:49], v[204:207], v[22:25]
	v_mfma_f32_16x16x32_bf16 v[22:25], v[38:41], v[208:211], v[172:175]
	v_mfma_f32_16x16x32_bf16 v[106:109], v[46:49], v[150:153], v[22:25]
	v_mfma_f32_16x16x32_bf16 v[22:25], v[54:57], v[162:165], v[82:85]
	v_mfma_f32_16x16x32_bf16 v[130:133], v[30:33], v[204:207], v[98:101]
	v_mfma_f32_16x16x32_bf16 v[98:101], v[62:65], v[204:207], v[22:25]
	v_mfma_f32_16x16x32_bf16 v[22:25], v[54:57], v[208:211], v[176:179]
	v_mfma_f32_16x16x32_bf16 v[90:93], v[62:65], v[150:153], v[22:25]
	v_mfma_f32_16x16x32_bf16 v[22:25], v[196:199], v[162:165], v[74:77]
	v_mfma_f32_16x16x32_bf16 v[82:85], v[200:203], v[204:207], v[22:25]
	v_mfma_f32_16x16x32_bf16 v[22:25], v[196:199], v[208:211], v[180:183]
	v_mfma_f32_16x16x32_bf16 v[74:77], v[200:203], v[150:153], v[22:25]
	s_setprio 0
	s_barrier
	ds_read_b128 v[166:169], v149 offset:49152
	ds_read_b128 v[170:173], v149 offset:50176
	ds_read_b128 v[174:177], v148 offset:49152
	ds_read_b128 v[178:181], v148 offset:50176
	ds_read_b128 v[196:199], v147 offset:49152
	ds_read_b128 v[200:203], v147 offset:50176
	ds_read_b128 v[212:215], v146 offset:49152
	ds_read_b128 v[146:149], v146 offset:50176
	s_barrier
	s_waitcnt lgkmcnt(0)
	s_setprio 1
	s_waitcnt lgkmcnt(7)
	v_mfma_f32_16x16x32_bf16 v[22:25], v[166:169], v[6:9], v[66:69]
	s_waitcnt lgkmcnt(6)
	v_mfma_f32_16x16x32_bf16 v[62:65], v[170:173], v[14:17], v[22:25]
	v_mfma_f32_16x16x32_bf16 v[22:25], v[166:169], v[184:187], v[216:219]
	v_mfma_f32_16x16x32_bf16 v[54:57], v[170:173], v[192:195], v[22:25]
	s_waitcnt lgkmcnt(5)
	v_mfma_f32_16x16x32_bf16 v[22:25], v[174:177], v[6:9], v[58:61]
	s_waitcnt lgkmcnt(4)
	v_mfma_f32_16x16x32_bf16 v[46:49], v[178:181], v[14:17], v[22:25]
	v_mfma_f32_16x16x32_bf16 v[22:25], v[174:177], v[184:187], v[220:223]
	v_mfma_f32_16x16x32_bf16 v[38:41], v[178:181], v[192:195], v[22:25]
	s_waitcnt lgkmcnt(3)
	v_mfma_f32_16x16x32_bf16 v[22:25], v[196:199], v[6:9], v[50:53]
	s_waitcnt lgkmcnt(1)
	v_mfma_f32_16x16x32_bf16 v[6:9], v[212:215], v[6:9], v[42:45]
	v_mfma_f32_16x16x32_bf16 v[30:33], v[200:203], v[14:17], v[22:25]
	v_mfma_f32_16x16x32_bf16 v[22:25], v[196:199], v[184:187], v[224:227]
	s_waitcnt lgkmcnt(0)
	v_mfma_f32_16x16x32_bf16 v[14:17], v[146:149], v[14:17], v[6:9]
	v_mfma_f32_16x16x32_bf16 v[6:9], v[212:215], v[184:187], v[134:137]
	v_mfma_f32_16x16x32_bf16 v[22:25], v[200:203], v[192:195], v[22:25]
	v_mfma_f32_16x16x32_bf16 v[6:9], v[146:149], v[192:195], v[6:9]
	s_setprio 0
	s_setprio 1
	v_mfma_f32_16x16x32_bf16 v[34:37], v[166:169], v[162:165], v[34:37]
	v_mfma_f32_16x16x32_bf16 v[66:69], v[170:173], v[204:207], v[34:37]
	v_mfma_f32_16x16x32_bf16 v[34:37], v[166:169], v[208:211], v[138:141]
	v_mfma_f32_16x16x32_bf16 v[26:29], v[174:177], v[162:165], v[26:29]
	v_mfma_f32_16x16x32_bf16 v[18:21], v[196:199], v[162:165], v[18:21]
	v_mfma_f32_16x16x32_bf16 v[58:61], v[170:173], v[150:153], v[34:37]
	v_mfma_f32_16x16x32_bf16 v[50:53], v[178:181], v[204:207], v[26:29]
	v_mfma_f32_16x16x32_bf16 v[26:29], v[174:177], v[208:211], v[142:145]
	v_mfma_f32_16x16x32_bf16 v[34:37], v[200:203], v[204:207], v[18:21]
	v_mfma_f32_16x16x32_bf16 v[18:21], v[196:199], v[208:211], v[154:157]
	v_mfma_f32_16x16x32_bf16 v[10:13], v[212:215], v[162:165], v[10:13]
	v_mfma_f32_16x16x32_bf16 v[42:45], v[178:181], v[150:153], v[26:29]
	v_mfma_f32_16x16x32_bf16 v[26:29], v[200:203], v[150:153], v[18:21]
	v_mfma_f32_16x16x32_bf16 v[18:21], v[146:149], v[204:207], v[10:13]
	v_mfma_f32_16x16x32_bf16 v[10:13], v[212:215], v[208:211], v[158:161]
	v_mfma_f32_16x16x32_bf16 v[10:13], v[146:149], v[150:153], v[10:13]
	s_setprio 0
	v_cmp_gt_u32_e32 vcc, s78, v0
	s_barrier
	s_and_saveexec_b64 s[16:17], vcc
	s_cbranch_execz .LBB0_361
	s_barrier
	s_branch .LBB0_361

; #define STAGE(P, BASE, LD, br, kt) do { const long _g = (long)(br) * (LD) + (long)(kt) * 64; \
;     _Pragma("unroll") for (int _i = 0; _i < 2; ++_i) { const int _b = tid * 16 + _i * 8192; int _r, _c; stage_rc(_b, _r, _c); \
;       __builtin_amdgcn_global_load_lds((const G_AS1 unsigned*)((BASE) + _g + (long)_r * (LD) + _c), \
;         (LAS unsigned*)((char*)(P) + _b), 16, 0, 0); } } while (0)
; #define LDA(dst, b, h) _Pragma("unroll") for (int m = 0; m < 4; ++m) _Pragma("unroll") for (int k = 0; k < 2; ++k) \
;     dst[m][k] = *reinterpret_cast<const bf16x8*>((char*)SA(b, h) + lds_byte(wr * 64 + m * 16 + fr, k * 32 + fq * 8))
; #define LDB(dst, b, h) _Pragma("unroll") for (int n = 0; n < 2; ++n) _Pragma("unroll") for (int k = 0; k < 2; ++k) \
;     dst[n][k] = *reinterpret_cast<const bf16x8*>((char*)SB(b, h) + lds_byte(wc * 32 + n * 16 + fr, k * 32 + fq * 8))
; #define MMA(ai, bj, At_, Bt_) do { __builtin_amdgcn_s_setprio(1); \
;     _Pragma("unroll") for (int m = 0; m < 4; ++m) _Pragma("unroll") for (int n = 0; n < 2; ++n) _Pragma("unroll") for (int k = 0; k < 2; ++k) \
;       acc[ai][bj][m][n] = __builtin_amdgcn_mfma_f32_16x16x32_bf16(At_[m][k], Bt_[n][k], acc[ai][bj][m][n], 0, 0, 0); \
;     __builtin_amdgcn_s_setprio(0); } while (0)
; #define WAIT_V(n) asm volatile("s_waitcnt vmcnt(" #n ")" ::: "memory")
; #define WAIT_L(n) asm volatile("s_waitcnt lgkmcnt(" #n ")" ::: "memory")
; #define BAR __builtin_amdgcn_s_barrier()
; #define SCHED __builtin_amdgcn_sched_barrier(0)
; __device__ __forceinline__ void gemm256(const bf16_t* __restrict__ A, long lda, const bf16_t* __restrict__ Bt, long ldb, int K,
;                                         int brow, int bcol, char* smem, f32x4 (&acc)[2][2][4][2]) {
;     ...
;     if (wr == 1) BAR;
;     WAIT_V(4); BAR;
;     STAGE(SB(1, 0), Bt, ldb, bcol, 1); STAGE(SA(1, 0), A, lda, brow, 1); STAGE(SB(1, 1), Bt, ldb, bcol + 128, 1);
;     WAIT_V(6); BAR;
;     for (int t = 0; t < nt - 2; t += 2) {
;         LDB(B0, 0, 0); SCHED; LDA(At, 0, 0); STAGE(SA(1, 1), A, lda, brow + 128, t + 1);
;         WAIT_L(8); BAR; WAIT_L(0); MMA(0, 0, At, B0); BAR; SCHED;
;         LDB(B1, 0, 1); STAGE(SB(0, 0), Bt, ldb, bcol, t + 2);
;         BAR; WAIT_L(0); MMA(0, 1, At, B1); BAR;
.LBB0_412:
	s_or_b64 exec, exec, s[20:21]
	v_add_u32_e32 v32, 0x18000, v21
	v_lshl_add_u64 v[30:31], v[12:13], 0, s[58:59]
	v_readfirstlane_b32 s46, v32
	v_add_u32_e32 v32, 0x1a000, v21
	s_mov_b32 m0, s46
	v_readfirstlane_b32 s35, v32
	v_add_u32_e32 v32, 0x8000, v21
	s_waitcnt vmcnt(4)
	s_barrier
	global_load_lds_dwordx4 v[30:31], off
	v_lshl_add_u64 v[30:31], v[18:19], 0, s[58:59]
	s_mov_b32 m0, s35
	v_readfirstlane_b32 s25, v32
	v_add_u32_e32 v32, 0xa000, v21
	global_load_lds_dwordx4 v[30:31], off
	v_lshl_add_u64 v[30:31], v[14:15], 0, s[58:59]
	s_mov_b32 m0, s25
	v_readfirstlane_b32 s24, v32
	s_add_u32 s50, s16, 0xb0080
	global_load_lds_dwordx4 v[30:31], off
	v_lshl_add_u64 v[30:31], v[16:17], 0, s[58:59]
	s_mov_b32 m0, s24
	s_addc_u32 s51, s17, 0
	v_add_u32_e32 v32, 0x1c000, v21
	global_load_lds_dwordx4 v[30:31], off
	v_lshl_add_u64 v[30:31], s[50:51], 0, v[2:3]
	v_readfirstlane_b32 s21, v32
	v_lshl_add_u64 v[30:31], v[30:31], 0, v[6:7]
	s_mov_b32 m0, s21
	v_add_u32_e32 v32, 0x1e000, v21
	global_load_lds_dwordx4 v[30:31], off
	v_lshl_add_u64 v[30:31], s[50:51], 0, v[8:9]
	v_readfirstlane_b32 s20, v32
	v_lshl_add_u64 v[30:31], v[30:31], 0, v[10:11]
	s_mov_b32 m0, s20
	v_and_b32_e32 v20, 15, v0
	global_load_lds_dwordx4 v[30:31], off
	v_lshlrev_b32_e32 v32, 2, v0
	v_and_b32_e32 v29, 48, v0
	v_lshlrev_b32_e32 v20, 6, v20
	v_and_b32_e32 v32, 32, v32
	v_lshlrev_b32_e32 v30, 6, v0
	v_or_b32_e32 v31, v20, v29
	v_bitop3_b32 v20, v20, v32, v29 bitop3:0x36
	s_movk_i32 s47, 0x3000
	v_and_or_b32 v33, v30, s47, v20
	s_movk_i32 s47, 0x3c0
	v_or_b32_e32 v218, 0x10000, v33
	v_lshlrev_b32_e32 v5, 13, v5
	v_and_or_b32 v29, v30, s47, v29
	s_waitcnt vmcnt(6)
	s_barrier
	v_or_b32_e32 v219, 0x10400, v33
	v_or_b32_e32 v220, 0x10800, v33
	v_or_b32_e32 v221, 0x10c00, v33
	v_bitop3_b32 v20, v31, v5, v32 bitop3:0xde
	v_bitop3_b32 v5, v5, v29, v32 bitop3:0xf6
	v_or_b32_e32 v222, 0x14000, v33
	v_or_b32_e32 v223, 0x14400, v33
	v_or_b32_e32 v224, 0x14800, v33
	v_or_b32_e32 v225, 0x14c00, v33
	v_or_b32_e32 v226, 0x18000, v33
	v_or_b32_e32 v227, 0x18400, v33
	v_or_b32_e32 v228, 0x18800, v33
	v_or_b32_e32 v229, 0x18c00, v33
	v_or_b32_e32 v230, 0x1c000, v33
	v_or_b32_e32 v231, 0x1c400, v33
	v_or_b32_e32 v232, 0x1c800, v33
	v_or_b32_e32 v233, 0x1cc00, v33
	s_nop 0
	ds_read_b128 v[30:33], v218
	ds_read_b128 v[34:37], v219
	ds_read_b128 v[38:41], v220
	ds_read_b128 v[42:45], v221
	s_add_u32 s74, s18, 0xb0080
	s_addc_u32 s75, s19, 0
	v_add_u32_e32 v29, 0xc000, v21
	v_lshl_add_u64 v[78:79], s[74:75], 0, v[2:3]
	v_readfirstlane_b32 s50, v29
	v_lshl_add_u64 v[78:79], v[78:79], 0, v[6:7]
	s_mov_b32 m0, s50
	v_add_u32_e32 v29, 0xe000, v21
	ds_read_b128 v[46:49], v20
	ds_read_b128 v[50:53], v20 offset:1024
	ds_read_b128 v[54:57], v5 offset:2048
	ds_read_b128 v[58:61], v5 offset:3072
	ds_read_b128 v[62:65], v5 offset:4096
	ds_read_b128 v[66:69], v5 offset:5120
	ds_read_b128 v[70:73], v5 offset:6144
	ds_read_b128 v[74:77], v5 offset:7168
	global_load_lds_dwordx4 v[78:79], off
	v_lshl_add_u64 v[78:79], s[74:75], 0, v[8:9]
	v_readfirstlane_b32 s47, v29
	v_lshl_add_u64 v[78:79], v[78:79], 0, v[10:11]
	s_mov_b32 m0, s47
	s_nop 0
	global_load_lds_dwordx4 v[78:79], off
	s_waitcnt lgkmcnt(8)
	s_barrier
	s_waitcnt lgkmcnt(0)
	s_setprio 1
	s_waitcnt lgkmcnt(0)
	v_mfma_f32_16x16x32_bf16 v[78:81], v[46:49], v[30:33], 0
	v_mfma_f32_16x16x32_bf16 v[82:85], v[46:49], v[38:41], 0
	v_mfma_f32_16x16x32_bf16 v[86:89], v[54:57], v[30:33], 0
	v_mfma_f32_16x16x32_bf16 v[90:93], v[54:57], v[38:41], 0
	v_mfma_f32_16x16x32_bf16 v[94:97], v[62:65], v[30:33], 0
	v_mfma_f32_16x16x32_bf16 v[98:101], v[62:65], v[38:41], 0
	v_mfma_f32_16x16x32_bf16 v[102:105], v[70:73], v[30:33], 0
	v_mfma_f32_16x16x32_bf16 v[106:109], v[70:73], v[38:41], 0
	v_mfma_f32_16x16x32_bf16 v[78:81], v[50:53], v[34:37], v[78:81]
	v_mfma_f32_16x16x32_bf16 v[82:85], v[50:53], v[42:45], v[82:85]
	v_mfma_f32_16x16x32_bf16 v[86:89], v[58:61], v[34:37], v[86:89]
	v_mfma_f32_16x16x32_bf16 v[90:93], v[58:61], v[42:45], v[90:93]
	v_mfma_f32_16x16x32_bf16 v[94:97], v[66:69], v[34:37], v[94:97]
	v_mfma_f32_16x16x32_bf16 v[98:101], v[66:69], v[42:45], v[98:101]
	v_mfma_f32_16x16x32_bf16 v[102:105], v[74:77], v[34:37], v[102:105]
	v_mfma_f32_16x16x32_bf16 v[106:109], v[74:77], v[42:45], v[106:109]
	s_setprio 0
	s_barrier
	v_readfirstlane_b32 s51, v27
	v_lshl_add_u64 v[126:127], v[12:13], 0, s[44:45]
	s_mov_b32 m0, s51
	v_readfirstlane_b32 s51, v28
	s_nop 0
	ds_read_b128 v[110:113], v222
	ds_read_b128 v[114:117], v223
	ds_read_b128 v[118:121], v224
	ds_read_b128 v[122:125], v225
	global_load_lds_dwordx4 v[126:127], off
	v_lshl_add_u64 v[126:127], v[18:19], 0, s[44:45]
	s_mov_b32 m0, s51
	s_nop 0
	global_load_lds_dwordx4 v[126:127], off
	s_barrier
	s_waitcnt lgkmcnt(0)
	s_setprio 1
	s_waitcnt lgkmcnt(0)
	v_mfma_f32_16x16x32_bf16 v[126:129], v[46:49], v[110:113], 0
	v_mfma_f32_16x16x32_bf16 v[46:49], v[46:49], v[118:121], 0
	v_mfma_f32_16x16x32_bf16 v[126:129], v[50:53], v[114:117], v[126:129]
	v_mfma_f32_16x16x32_bf16 v[46:49], v[50:53], v[122:125], v[46:49]
	v_mfma_f32_16x16x32_bf16 v[50:53], v[54:57], v[110:113], 0
	v_mfma_f32_16x16x32_bf16 v[54:57], v[54:57], v[118:121], 0
	v_mfma_f32_16x16x32_bf16 v[50:53], v[58:61], v[114:117], v[50:53]
	v_mfma_f32_16x16x32_bf16 v[54:57], v[58:61], v[122:125], v[54:57]
	v_mfma_f32_16x16x32_bf16 v[58:61], v[62:65], v[110:113], 0
	v_mfma_f32_16x16x32_bf16 v[62:65], v[62:65], v[118:121], 0
	v_mfma_f32_16x16x32_bf16 v[58:61], v[66:69], v[114:117], v[58:61]
	v_mfma_f32_16x16x32_bf16 v[62:65], v[66:69], v[122:125], v[62:65]
	v_mfma_f32_16x16x32_bf16 v[66:69], v[70:73], v[110:113], 0
	v_mfma_f32_16x16x32_bf16 v[70:73], v[70:73], v[118:121], 0
	v_mfma_f32_16x16x32_bf16 v[66:69], v[74:77], v[114:117], v[66:69]
	v_mfma_f32_16x16x32_bf16 v[70:73], v[74:77], v[122:125], v[70:73]
	s_setprio 0
	v_readfirstlane_b32 s51, v21
	v_lshl_add_u64 v[28:29], v[14:15], 0, s[44:45]
	s_mov_b32 m0, s51
	v_readfirstlane_b32 s51, v24
	s_barrier
; #define STAGE(P, BASE, LD, br, kt) do { const long _g = (long)(br) * (LD) + (long)(kt) * 64; \
;     _Pragma("unroll") for (int _i = 0; _i < 2; ++_i) { const int _b = tid * 16 + _i * 8192; int _r, _c; stage_rc(_b, _r, _c); \
;       __builtin_amdgcn_global_load_lds((const G_AS1 unsigned*)((BASE) + _g + (long)_r * (LD) + _c), \
;         (LAS unsigned*)((char*)(P) + _b), 16, 0, 0); } } while (0)
; #define LDA(dst, b, h) _Pragma("unroll") for (int m = 0; m < 4; ++m) _Pragma("unroll") for (int k = 0; k < 2; ++k) \
;     dst[m][k] = *reinterpret_cast<const bf16x8*>((char*)SA(b, h) + lds_byte(wr * 64 + m * 16 + fr, k * 32 + fq * 8))
; #define LDB(dst, b, h) _Pragma("unroll") for (int n = 0; n < 2; ++n) _Pragma("unroll") for (int k = 0; k < 2; ++k) \
;     dst[n][k] = *reinterpret_cast<const bf16x8*>((char*)SB(b, h) + lds_byte(wc * 32 + n * 16 + fr, k * 32 + fq * 8))
; #define MMA(ai, bj, At_, Bt_) do { __builtin_amdgcn_s_setprio(1); \
;     _Pragma("unroll") for (int m = 0; m < 4; ++m) _Pragma("unroll") for (int n = 0; n < 2; ++n) _Pragma("unroll") for (int k = 0; k < 2; ++k) \
;       acc[ai][bj][m][n] = __builtin_amdgcn_mfma_f32_16x16x32_bf16(At_[m][k], Bt_[n][k], acc[ai][bj][m][n], 0, 0, 0); \
;     __builtin_amdgcn_s_setprio(0); } while (0)
; #define WAIT_V(n) asm volatile("s_waitcnt vmcnt(" #n ")" ::: "memory")
; #define WAIT_L(n) asm volatile("s_waitcnt lgkmcnt(" #n ")" ::: "memory")
; #define BAR __builtin_amdgcn_s_barrier()
; #define SCHED __builtin_amdgcn_sched_barrier(0)
; __device__ __forceinline__ void gemm256(const bf16_t* __restrict__ A, long lda, const bf16_t* __restrict__ Bt, long ldb, int K,
;                                         int brow, int bcol, char* smem, f32x4 (&acc)[2][2][4][2]) {
;     ...
;         LDA(At, 0, 1); STAGE(SA(0, 0), A, lda, brow, t + 2);
;         BAR; WAIT_L(0); MMA(1, 0, At, B0); BAR; SCHED;
;         STAGE(SB(0, 1), Bt, ldb, bcol + 128, t + 2);
;         WAIT_V(6); BAR; MMA(1, 1, At, B1); BAR;
;         LDB(B0, 1, 0); SCHED; LDA(At, 1, 0); STAGE(SA(0, 1), A, lda, brow + 128, t + 2);
;         WAIT_L(8); BAR; WAIT_L(0); MMA(0, 0, At, B0); BAR; SCHED;
;         LDB(B1, 1, 1); STAGE(SB(1, 0), Bt, ldb, bcol, t + 3);
;         BAR; WAIT_L(0); MMA(0, 1, At, B1); BAR;
	s_nop 0
	ds_read_b128 v[74:77], v20 offset:16384
	ds_read_b128 v[130:133], v20 offset:17408
	ds_read_b128 v[134:137], v5 offset:18432
	ds_read_b128 v[138:141], v5 offset:19456
	ds_read_b128 v[142:145], v5 offset:20480
	ds_read_b128 v[146:149], v5 offset:21504
	ds_read_b128 v[150:153], v5 offset:22528
	ds_read_b128 v[154:157], v5 offset:23552
	global_load_lds_dwordx4 v[28:29], off
	v_lshl_add_u64 v[28:29], v[16:17], 0, s[44:45]
	s_mov_b32 m0, s51
	s_nop 0
	global_load_lds_dwordx4 v[28:29], off
	s_barrier
	s_waitcnt lgkmcnt(0)
	s_setprio 1
	s_waitcnt lgkmcnt(0)
	v_mfma_f32_16x16x32_bf16 v[158:161], v[74:77], v[30:33], 0
	v_mfma_f32_16x16x32_bf16 v[166:169], v[134:137], v[30:33], 0
	v_mfma_f32_16x16x32_bf16 v[174:177], v[142:145], v[30:33], 0
	v_mfma_f32_16x16x32_bf16 v[28:31], v[150:153], v[30:33], 0
	v_mfma_f32_16x16x32_bf16 v[158:161], v[130:133], v[34:37], v[158:161]
	v_mfma_f32_16x16x32_bf16 v[166:169], v[138:141], v[34:37], v[166:169]
	v_mfma_f32_16x16x32_bf16 v[174:177], v[146:149], v[34:37], v[174:177]
	v_mfma_f32_16x16x32_bf16 v[28:31], v[154:157], v[34:37], v[28:31]
	v_mfma_f32_16x16x32_bf16 v[32:35], v[150:153], v[38:41], 0
	v_mfma_f32_16x16x32_bf16 v[162:165], v[74:77], v[38:41], 0
	v_mfma_f32_16x16x32_bf16 v[170:173], v[134:137], v[38:41], 0
	v_mfma_f32_16x16x32_bf16 v[178:181], v[142:145], v[38:41], 0
	v_mfma_f32_16x16x32_bf16 v[32:35], v[154:157], v[42:45], v[32:35]
	v_mfma_f32_16x16x32_bf16 v[162:165], v[130:133], v[42:45], v[162:165]
	v_mfma_f32_16x16x32_bf16 v[170:173], v[138:141], v[42:45], v[170:173]
	v_mfma_f32_16x16x32_bf16 v[178:181], v[146:149], v[42:45], v[178:181]
	s_setprio 0
	s_barrier
	s_add_u32 s74, s16, 0xb0100
	s_addc_u32 s75, s17, 0
	v_lshl_add_u64 v[36:37], s[74:75], 0, v[2:3]
	v_readfirstlane_b32 s51, v25
	v_lshl_add_u64 v[36:37], v[36:37], 0, v[6:7]
	s_mov_b32 m0, s51
	v_lshl_add_u64 v[24:25], s[74:75], 0, v[8:9]
	v_readfirstlane_b32 s51, v26
	global_load_lds_dwordx4 v[36:37], off
	v_lshl_add_u64 v[24:25], v[24:25], 0, v[10:11]
	s_mov_b32 m0, s51
	s_nop 0
	global_load_lds_dwordx4 v[24:25], off
	s_waitcnt vmcnt(6)
	s_barrier
	s_setprio 1
	v_mfma_f32_16x16x32_bf16 v[24:27], v[74:77], v[110:113], 0
	v_mfma_f32_16x16x32_bf16 v[36:39], v[74:77], v[118:121], 0
	v_mfma_f32_16x16x32_bf16 v[24:27], v[130:133], v[114:117], v[24:27]
	v_mfma_f32_16x16x32_bf16 v[36:39], v[130:133], v[122:125], v[36:39]
	v_mfma_f32_16x16x32_bf16 v[40:43], v[134:137], v[110:113], 0
	v_mfma_f32_16x16x32_bf16 v[130:133], v[142:145], v[110:113], 0
	v_mfma_f32_16x16x32_bf16 v[110:113], v[150:153], v[110:113], 0
	v_mfma_f32_16x16x32_bf16 v[40:43], v[138:141], v[114:117], v[40:43]
	v_mfma_f32_16x16x32_bf16 v[74:77], v[134:137], v[118:121], 0
	v_mfma_f32_16x16x32_bf16 v[130:133], v[146:149], v[114:117], v[130:133]
	v_mfma_f32_16x16x32_bf16 v[110:113], v[154:157], v[114:117], v[110:113]
	v_mfma_f32_16x16x32_bf16 v[114:117], v[150:153], v[118:121], 0
	v_mfma_f32_16x16x32_bf16 v[74:77], v[138:141], v[122:125], v[74:77]
	v_mfma_f32_16x16x32_bf16 v[134:137], v[142:145], v[118:121], 0
	v_mfma_f32_16x16x32_bf16 v[114:117], v[154:157], v[122:125], v[114:117]
	v_mfma_f32_16x16x32_bf16 v[134:137], v[146:149], v[122:125], v[134:137]
	s_setprio 0
	s_barrier
	s_nop 0
	ds_read_b128 v[118:121], v226
	ds_read_b128 v[122:125], v227
	ds_read_b128 v[138:141], v228
	ds_read_b128 v[142:145], v229
	s_add_u32 s74, s18, 0xb0100
	s_addc_u32 s75, s19, 0
	v_lshl_add_u64 v[44:45], s[74:75], 0, v[2:3]
	v_readfirstlane_b32 s51, v22
	v_lshl_add_u64 v[44:45], v[44:45], 0, v[6:7]
	s_mov_b32 m0, s51
	ds_read_b128 v[146:149], v20 offset:32768
	ds_read_b128 v[150:153], v20 offset:33792
	ds_read_b128 v[154:157], v5 offset:34816
	ds_read_b128 v[182:185], v5 offset:35840
	ds_read_b128 v[186:189], v5 offset:36864
	ds_read_b128 v[190:193], v5 offset:37888
	ds_read_b128 v[194:197], v5 offset:38912
	ds_read_b128 v[198:201], v5 offset:39936
	global_load_lds_dwordx4 v[44:45], off
	v_lshl_add_u64 v[44:45], s[74:75], 0, v[8:9]
	v_readfirstlane_b32 s51, v23
	v_lshl_add_u64 v[44:45], v[44:45], 0, v[10:11]
	s_mov_b32 m0, s51
	s_nop 0
	global_load_lds_dwordx4 v[44:45], off
	s_waitcnt lgkmcnt(8)
	s_barrier
	s_waitcnt lgkmcnt(0)
	s_setprio 1
	s_waitcnt lgkmcnt(0)
	v_mfma_f32_16x16x32_bf16 v[78:81], v[146:149], v[118:121], v[78:81]
	v_mfma_f32_16x16x32_bf16 v[82:85], v[146:149], v[138:141], v[82:85]
	v_mfma_f32_16x16x32_bf16 v[86:89], v[154:157], v[118:121], v[86:89]
	v_mfma_f32_16x16x32_bf16 v[90:93], v[154:157], v[138:141], v[90:93]
	v_mfma_f32_16x16x32_bf16 v[94:97], v[186:189], v[118:121], v[94:97]
	v_mfma_f32_16x16x32_bf16 v[98:101], v[186:189], v[138:141], v[98:101]
	v_mfma_f32_16x16x32_bf16 v[102:105], v[194:197], v[118:121], v[102:105]
	v_mfma_f32_16x16x32_bf16 v[106:109], v[194:197], v[138:141], v[106:109]
	v_mfma_f32_16x16x32_bf16 v[78:81], v[150:153], v[122:125], v[78:81]
	v_mfma_f32_16x16x32_bf16 v[82:85], v[150:153], v[142:145], v[82:85]
	v_mfma_f32_16x16x32_bf16 v[86:89], v[182:185], v[122:125], v[86:89]
	v_mfma_f32_16x16x32_bf16 v[90:93], v[182:185], v[142:145], v[90:93]
	v_mfma_f32_16x16x32_bf16 v[94:97], v[190:193], v[122:125], v[94:97]
	v_mfma_f32_16x16x32_bf16 v[98:101], v[190:193], v[142:145], v[98:101]
	v_mfma_f32_16x16x32_bf16 v[102:105], v[198:201], v[122:125], v[102:105]
	v_mfma_f32_16x16x32_bf16 v[106:109], v[198:201], v[142:145], v[106:109]
	s_setprio 0
	s_barrier
	s_mov_b64 s[74:75], 0x180
	s_mov_b32 m0, s46
	v_lshl_add_u64 v[12:13], v[12:13], 0, s[74:75]
	s_nop 0
	ds_read_b128 v[202:205], v230
	ds_read_b128 v[206:209], v231
	ds_read_b128 v[210:213], v232
	ds_read_b128 v[214:217], v233
	global_load_lds_dwordx4 v[12:13], off
	v_lshl_add_u64 v[12:13], v[18:19], 0, s[74:75]
	s_mov_b32 m0, s35
	s_nop 0
	global_load_lds_dwordx4 v[12:13], off
	s_barrier
; #define STAGE(P, BASE, LD, br, kt) do { const long _g = (long)(br) * (LD) + (long)(kt) * 64; \
;     _Pragma("unroll") for (int _i = 0; _i < 2; ++_i) { const int _b = tid * 16 + _i * 8192; int _r, _c; stage_rc(_b, _r, _c); \
;       __builtin_amdgcn_global_load_lds((const G_AS1 unsigned*)((BASE) + _g + (long)_r * (LD) + _c), \
;         (LAS unsigned*)((char*)(P) + _b), 16, 0, 0); } } while (0)
; #define LDA(dst, b, h) _Pragma("unroll") for (int m = 0; m < 4; ++m) _Pragma("unroll") for (int k = 0; k < 2; ++k) \
;     dst[m][k] = *reinterpret_cast<const bf16x8*>((char*)SA(b, h) + lds_byte(wr * 64 + m * 16 + fr, k * 32 + fq * 8))
; #define LDB(dst, b, h) _Pragma("unroll") for (int n = 0; n < 2; ++n) _Pragma("unroll") for (int k = 0; k < 2; ++k) \
;     dst[n][k] = *reinterpret_cast<const bf16x8*>((char*)SB(b, h) + lds_byte(wc * 32 + n * 16 + fr, k * 32 + fq * 8))
; #define MMA(ai, bj, At_, Bt_) do { __builtin_amdgcn_s_setprio(1); \
;     _Pragma("unroll") for (int m = 0; m < 4; ++m) _Pragma("unroll") for (int n = 0; n < 2; ++n) _Pragma("unroll") for (int k = 0; k < 2; ++k) \
;       acc[ai][bj][m][n] = __builtin_amdgcn_mfma_f32_16x16x32_bf16(At_[m][k], Bt_[n][k], acc[ai][bj][m][n], 0, 0, 0); \
;     __builtin_amdgcn_s_setprio(0); } while (0)
; #define WAIT_V(n) asm volatile("s_waitcnt vmcnt(" #n ")" ::: "memory")
; #define WAIT_L(n) asm volatile("s_waitcnt lgkmcnt(" #n ")" ::: "memory")
; #define BAR __builtin_amdgcn_s_barrier()
; #define SCHED __builtin_amdgcn_sched_barrier(0)
; __device__ __forceinline__ void gemm256(const bf16_t* __restrict__ A, long lda, const bf16_t* __restrict__ Bt, long ldb, int K,
;                                         int brow, int bcol, char* smem, f32x4 (&acc)[2][2][4][2]) {
;     ...
;         BAR; WAIT_L(0); MMA(0, 1, At, B1); BAR;
;         LDA(At, 1, 1); STAGE(SA(1, 0), A, lda, brow, t + 3);
;         BAR; WAIT_L(0); MMA(1, 0, At, B0); BAR; SCHED;
;         STAGE(SB(1, 1), Bt, ldb, bcol + 128, t + 3);
;         WAIT_V(6); BAR; MMA(1, 1, At, B1); BAR;
;     }
;     { LDB(B0, 0, 0); LDA(At, 0, 0); STAGE(SA(1, 1), A, lda, brow + 128, nt - 1);
;       BAR; WAIT_L(0); MMA(0, 0, At, B0); BAR;
	s_waitcnt lgkmcnt(0)
	s_setprio 1
	s_waitcnt lgkmcnt(0)
	v_mfma_f32_16x16x32_bf16 v[126:129], v[146:149], v[202:205], v[126:129]
	v_mfma_f32_16x16x32_bf16 v[44:47], v[146:149], v[210:213], v[46:49]
	v_mfma_f32_16x16x32_bf16 v[48:51], v[154:157], v[202:205], v[50:53]
	v_mfma_f32_16x16x32_bf16 v[52:55], v[154:157], v[210:213], v[54:57]
	v_mfma_f32_16x16x32_bf16 v[56:59], v[186:189], v[202:205], v[58:61]
	v_mfma_f32_16x16x32_bf16 v[60:63], v[186:189], v[210:213], v[62:65]
	v_mfma_f32_16x16x32_bf16 v[64:67], v[194:197], v[202:205], v[66:69]
	v_mfma_f32_16x16x32_bf16 v[68:71], v[194:197], v[210:213], v[70:73]
	v_mfma_f32_16x16x32_bf16 v[126:129], v[150:153], v[206:209], v[126:129]
	v_mfma_f32_16x16x32_bf16 v[44:47], v[150:153], v[214:217], v[44:47]
	v_mfma_f32_16x16x32_bf16 v[48:51], v[182:185], v[206:209], v[48:51]
	v_mfma_f32_16x16x32_bf16 v[52:55], v[182:185], v[214:217], v[52:55]
	v_mfma_f32_16x16x32_bf16 v[56:59], v[190:193], v[206:209], v[56:59]
	v_mfma_f32_16x16x32_bf16 v[60:63], v[190:193], v[214:217], v[60:63]
	v_mfma_f32_16x16x32_bf16 v[64:67], v[198:201], v[206:209], v[64:67]
	v_mfma_f32_16x16x32_bf16 v[68:71], v[198:201], v[214:217], v[68:71]
	s_setprio 0
	s_mov_b32 m0, s25
	v_lshl_add_u64 v[12:13], v[14:15], 0, s[74:75]
	s_barrier
	s_nop 0
	ds_read_b128 v[146:149], v20 offset:49152
	ds_read_b128 v[150:153], v20 offset:50176
	ds_read_b128 v[154:157], v5 offset:51200
	ds_read_b128 v[182:185], v5 offset:52224
	ds_read_b128 v[186:189], v5 offset:53248
	ds_read_b128 v[190:193], v5 offset:54272
	ds_read_b128 v[194:197], v5 offset:55296
	ds_read_b128 v[198:201], v5 offset:56320
	global_load_lds_dwordx4 v[12:13], off
	v_lshl_add_u64 v[12:13], v[16:17], 0, s[74:75]
	s_mov_b32 m0, s24
	s_nop 0
	global_load_lds_dwordx4 v[12:13], off
	s_barrier
	s_waitcnt lgkmcnt(0)
	s_setprio 1
	s_waitcnt lgkmcnt(0)
	v_mfma_f32_16x16x32_bf16 v[12:15], v[146:149], v[118:121], v[158:161]
	v_mfma_f32_16x16x32_bf16 v[16:19], v[146:149], v[138:141], v[162:165]
	v_mfma_f32_16x16x32_bf16 v[28:31], v[194:197], v[118:121], v[28:31]
	v_mfma_f32_16x16x32_bf16 v[32:35], v[194:197], v[138:141], v[32:35]
	v_mfma_f32_16x16x32_bf16 v[12:15], v[150:153], v[122:125], v[12:15]
	v_mfma_f32_16x16x32_bf16 v[16:19], v[150:153], v[142:145], v[16:19]
	v_mfma_f32_16x16x32_bf16 v[158:161], v[154:157], v[118:121], v[166:169]
	v_mfma_f32_16x16x32_bf16 v[162:165], v[154:157], v[138:141], v[170:173]
	v_mfma_f32_16x16x32_bf16 v[166:169], v[186:189], v[118:121], v[174:177]
	v_mfma_f32_16x16x32_bf16 v[170:173], v[186:189], v[138:141], v[178:181]
	v_mfma_f32_16x16x32_bf16 v[28:31], v[198:201], v[122:125], v[28:31]
	v_mfma_f32_16x16x32_bf16 v[32:35], v[198:201], v[142:145], v[32:35]
	v_mfma_f32_16x16x32_bf16 v[158:161], v[182:185], v[122:125], v[158:161]
	v_mfma_f32_16x16x32_bf16 v[162:165], v[182:185], v[142:145], v[162:165]
	v_mfma_f32_16x16x32_bf16 v[166:169], v[190:193], v[122:125], v[166:169]
	v_mfma_f32_16x16x32_bf16 v[170:173], v[190:193], v[142:145], v[170:173]
	s_setprio 0
	s_barrier
	s_add_u32 s16, s16, 0xb0180
	s_addc_u32 s17, s17, 0
	v_lshl_add_u64 v[22:23], s[16:17], 0, v[2:3]
	s_mov_b32 m0, s21
	v_lshl_add_u64 v[22:23], v[22:23], 0, v[6:7]
	global_load_lds_dwordx4 v[22:23], off
	v_lshl_add_u64 v[22:23], s[16:17], 0, v[8:9]
	v_lshl_add_u64 v[22:23], v[22:23], 0, v[10:11]
	s_mov_b32 m0, s20
	s_nop 0
	global_load_lds_dwordx4 v[22:23], off
	s_waitcnt vmcnt(6)
	s_barrier
	s_setprio 1
	v_mfma_f32_16x16x32_bf16 v[22:25], v[146:149], v[202:205], v[24:27]
	v_mfma_f32_16x16x32_bf16 v[36:39], v[146:149], v[210:213], v[36:39]
	v_mfma_f32_16x16x32_bf16 v[40:43], v[154:157], v[202:205], v[40:43]
	v_mfma_f32_16x16x32_bf16 v[72:75], v[154:157], v[210:213], v[74:77]
	v_mfma_f32_16x16x32_bf16 v[118:121], v[186:189], v[202:205], v[130:133]
	v_mfma_f32_16x16x32_bf16 v[122:125], v[186:189], v[210:213], v[134:137]
	v_mfma_f32_16x16x32_bf16 v[110:113], v[194:197], v[202:205], v[110:113]
	v_mfma_f32_16x16x32_bf16 v[114:117], v[194:197], v[210:213], v[114:117]
	v_mfma_f32_16x16x32_bf16 v[22:25], v[150:153], v[206:209], v[22:25]
	v_mfma_f32_16x16x32_bf16 v[36:39], v[150:153], v[214:217], v[36:39]
	v_mfma_f32_16x16x32_bf16 v[40:43], v[182:185], v[206:209], v[40:43]
	v_mfma_f32_16x16x32_bf16 v[72:75], v[182:185], v[214:217], v[72:75]
	v_mfma_f32_16x16x32_bf16 v[118:121], v[190:193], v[206:209], v[118:121]
	v_mfma_f32_16x16x32_bf16 v[122:125], v[190:193], v[214:217], v[122:125]
	v_mfma_f32_16x16x32_bf16 v[110:113], v[198:201], v[206:209], v[110:113]
	v_mfma_f32_16x16x32_bf16 v[114:117], v[198:201], v[214:217], v[114:117]
	s_setprio 0
	s_add_u32 s16, s18, 0xb0180
	s_addc_u32 s17, s19, 0
	v_lshl_add_u64 v[2:3], s[16:17], 0, v[2:3]
	s_mov_b32 m0, s50
	v_lshl_add_u64 v[2:3], v[2:3], 0, v[6:7]
	s_barrier
	s_nop 0
	ds_read_b128 v[130:133], v218
	ds_read_b128 v[134:137], v219
	ds_read_b128 v[138:141], v220
	ds_read_b128 v[142:145], v221
	ds_read_b128 v[146:149], v20
	ds_read_b128 v[150:153], v20 offset:1024
	ds_read_b128 v[154:157], v5 offset:2048
	ds_read_b128 v[174:177], v5 offset:3072
	ds_read_b128 v[178:181], v5 offset:4096
	ds_read_b128 v[182:185], v5 offset:5120
	ds_read_b128 v[186:189], v5 offset:6144
	ds_read_b128 v[190:193], v5 offset:7168
	global_load_lds_dwordx4 v[2:3], off
	v_lshl_add_u64 v[2:3], s[16:17], 0, v[8:9]
	v_lshl_add_u64 v[2:3], v[2:3], 0, v[10:11]
	s_mov_b32 m0, s47
	s_nop 0
	global_load_lds_dwordx4 v[2:3], off
	s_barrier
; #define LDA(dst, b, h) _Pragma("unroll") for (int m = 0; m < 4; ++m) _Pragma("unroll") for (int k = 0; k < 2; ++k) \
;     dst[m][k] = *reinterpret_cast<const bf16x8*>((char*)SA(b, h) + lds_byte(wr * 64 + m * 16 + fr, k * 32 + fq * 8))
; #define LDB(dst, b, h) _Pragma("unroll") for (int n = 0; n < 2; ++n) _Pragma("unroll") for (int k = 0; k < 2; ++k) \
;     dst[n][k] = *reinterpret_cast<const bf16x8*>((char*)SB(b, h) + lds_byte(wc * 32 + n * 16 + fr, k * 32 + fq * 8))
; #define MMA(ai, bj, At_, Bt_) do { __builtin_amdgcn_s_setprio(1); \
;     _Pragma("unroll") for (int m = 0; m < 4; ++m) _Pragma("unroll") for (int n = 0; n < 2; ++n) _Pragma("unroll") for (int k = 0; k < 2; ++k) \
;       acc[ai][bj][m][n] = __builtin_amdgcn_mfma_f32_16x16x32_bf16(At_[m][k], Bt_[n][k], acc[ai][bj][m][n], 0, 0, 0); \
;     __builtin_amdgcn_s_setprio(0); } while (0)
; #define WAIT_V(n) asm volatile("s_waitcnt vmcnt(" #n ")" ::: "memory")
; #define WAIT_L(n) asm volatile("s_waitcnt lgkmcnt(" #n ")" ::: "memory")
; #define BAR __builtin_amdgcn_s_barrier()
; __device__ __forceinline__ void gemm256(const bf16_t* __restrict__ A, long lda, const bf16_t* __restrict__ Bt, long ldb, int K,
;                                         int brow, int bcol, char* smem, f32x4 (&acc)[2][2][4][2]) {
;     ...
;       BAR; WAIT_L(0); MMA(0, 0, At, B0); BAR;
;       LDB(B1, 0, 1); BAR; WAIT_L(0); MMA(0, 1, At, B1); BAR;
;       LDA(At, 0, 1); WAIT_V(4); BAR; WAIT_L(0); MMA(1, 0, At, B0); MMA(1, 1, At, B1); BAR; }
	s_waitcnt lgkmcnt(0)
	s_setprio 1
	s_waitcnt lgkmcnt(0)
	v_mfma_f32_16x16x32_bf16 v[6:9], v[146:149], v[130:133], v[78:81]
	v_mfma_f32_16x16x32_bf16 v[76:79], v[146:149], v[138:141], v[82:85]
	v_mfma_f32_16x16x32_bf16 v[80:83], v[154:157], v[130:133], v[86:89]
	v_mfma_f32_16x16x32_bf16 v[84:87], v[154:157], v[138:141], v[90:93]
	v_mfma_f32_16x16x32_bf16 v[88:91], v[178:181], v[130:133], v[94:97]
	v_mfma_f32_16x16x32_bf16 v[92:95], v[178:181], v[138:141], v[98:101]
	v_mfma_f32_16x16x32_bf16 v[96:99], v[186:189], v[130:133], v[102:105]
	v_mfma_f32_16x16x32_bf16 v[6:9], v[150:153], v[134:137], v[6:9]
	v_mfma_f32_16x16x32_bf16 v[76:79], v[150:153], v[142:145], v[76:79]
	v_mfma_f32_16x16x32_bf16 v[80:83], v[174:177], v[134:137], v[80:83]
	v_mfma_f32_16x16x32_bf16 v[84:87], v[174:177], v[142:145], v[84:87]
	v_mfma_f32_16x16x32_bf16 v[88:91], v[182:185], v[134:137], v[88:91]
	v_mfma_f32_16x16x32_bf16 v[92:95], v[182:185], v[142:145], v[92:95]
	v_mfma_f32_16x16x32_bf16 v[96:99], v[190:193], v[134:137], v[96:99]
	v_mfma_f32_16x16x32_bf16 v[100:103], v[186:189], v[138:141], v[106:109]
	v_mfma_f32_16x16x32_bf16 v[194:197], v[190:193], v[142:145], v[100:103]
	s_setprio 0
	s_barrier
	s_nop 0
	s_nop 3
	ds_read_b128 v[100:103], v222
	ds_read_b128 v[104:107], v223
	ds_read_b128 v[198:201], v224
	ds_read_b128 v[202:205], v225
	s_barrier
	s_waitcnt lgkmcnt(0)
	s_setprio 1
	s_waitcnt lgkmcnt(3)
	v_mfma_f32_16x16x32_bf16 v[126:129], v[146:149], v[100:103], v[126:129]
	s_waitcnt lgkmcnt(1)
	v_mfma_f32_16x16x32_bf16 v[44:47], v[146:149], v[198:201], v[44:47]
	v_mfma_f32_16x16x32_bf16 v[48:51], v[154:157], v[100:103], v[48:51]
	v_mfma_f32_16x16x32_bf16 v[52:55], v[154:157], v[198:201], v[52:55]
	v_mfma_f32_16x16x32_bf16 v[56:59], v[178:181], v[100:103], v[56:59]
	v_mfma_f32_16x16x32_bf16 v[60:63], v[178:181], v[198:201], v[60:63]
	v_mfma_f32_16x16x32_bf16 v[64:67], v[186:189], v[100:103], v[64:67]
	v_mfma_f32_16x16x32_bf16 v[126:129], v[150:153], v[104:107], v[126:129]
	s_waitcnt lgkmcnt(0)
	v_mfma_f32_16x16x32_bf16 v[44:47], v[150:153], v[202:205], v[44:47]
	v_mfma_f32_16x16x32_bf16 v[48:51], v[174:177], v[104:107], v[48:51]
	v_mfma_f32_16x16x32_bf16 v[52:55], v[174:177], v[202:205], v[52:55]
	v_mfma_f32_16x16x32_bf16 v[56:59], v[182:185], v[104:107], v[56:59]
	v_mfma_f32_16x16x32_bf16 v[60:63], v[182:185], v[202:205], v[60:63]
	v_mfma_f32_16x16x32_bf16 v[64:67], v[190:193], v[104:107], v[64:67]
	v_mfma_f32_16x16x32_bf16 v[68:71], v[186:189], v[198:201], v[68:71]
	v_mfma_f32_16x16x32_bf16 v[146:149], v[190:193], v[202:205], v[68:71]
	s_setprio 0
	s_barrier
	s_nop 4
	ds_read_b128 v[68:71], v20 offset:16384
	ds_read_b128 v[150:153], v20 offset:17408
	ds_read_b128 v[154:157], v5 offset:18432
	ds_read_b128 v[174:177], v5 offset:19456
	ds_read_b128 v[178:181], v5 offset:20480
	ds_read_b128 v[182:185], v5 offset:21504
	ds_read_b128 v[186:189], v5 offset:22528
	ds_read_b128 v[190:193], v5 offset:23552
	s_waitcnt vmcnt(4)
	s_barrier
	s_waitcnt lgkmcnt(0)
	s_setprio 1
	s_waitcnt lgkmcnt(7)
	v_mfma_f32_16x16x32_bf16 v[10:13], v[68:71], v[130:133], v[12:15]
	s_waitcnt lgkmcnt(5)
	v_mfma_f32_16x16x32_bf16 v[158:161], v[154:157], v[130:133], v[158:161]
	s_waitcnt lgkmcnt(3)
	v_mfma_f32_16x16x32_bf16 v[166:169], v[178:181], v[130:133], v[166:169]
	s_waitcnt lgkmcnt(1)
	v_mfma_f32_16x16x32_bf16 v[26:29], v[186:189], v[130:133], v[28:31]
	v_mfma_f32_16x16x32_bf16 v[10:13], v[150:153], v[134:137], v[10:13]
	v_mfma_f32_16x16x32_bf16 v[14:17], v[68:71], v[138:141], v[16:19]
	v_mfma_f32_16x16x32_bf16 v[158:161], v[174:177], v[134:137], v[158:161]
	v_mfma_f32_16x16x32_bf16 v[166:169], v[182:185], v[134:137], v[166:169]
	s_waitcnt lgkmcnt(0)
	v_mfma_f32_16x16x32_bf16 v[134:137], v[190:193], v[134:137], v[26:29]
	v_mfma_f32_16x16x32_bf16 v[26:29], v[186:189], v[138:141], v[32:35]
	v_mfma_f32_16x16x32_bf16 v[14:17], v[150:153], v[142:145], v[14:17]
	v_mfma_f32_16x16x32_bf16 v[162:165], v[154:157], v[138:141], v[162:165]
	v_mfma_f32_16x16x32_bf16 v[170:173], v[178:181], v[138:141], v[170:173]
	v_mfma_f32_16x16x32_bf16 v[30:33], v[190:193], v[142:145], v[26:29]
	v_mfma_f32_16x16x32_bf16 v[162:165], v[174:177], v[142:145], v[162:165]
	v_mfma_f32_16x16x32_bf16 v[170:173], v[182:185], v[142:145], v[170:173]
	s_setprio 0
	s_setprio 1
	v_mfma_f32_16x16x32_bf16 v[22:25], v[68:71], v[100:103], v[22:25]
	v_mfma_f32_16x16x32_bf16 v[138:141], v[150:153], v[104:107], v[22:25]
	v_mfma_f32_16x16x32_bf16 v[22:25], v[68:71], v[198:201], v[36:39]
	v_mfma_f32_16x16x32_bf16 v[34:37], v[150:153], v[202:205], v[22:25]
	v_mfma_f32_16x16x32_bf16 v[22:25], v[154:157], v[100:103], v[40:43]
	v_mfma_f32_16x16x32_bf16 v[142:145], v[174:177], v[104:107], v[22:25]
	v_mfma_f32_16x16x32_bf16 v[22:25], v[154:157], v[198:201], v[72:75]
	v_mfma_f32_16x16x32_bf16 v[150:153], v[174:177], v[202:205], v[22:25]
	v_mfma_f32_16x16x32_bf16 v[22:25], v[178:181], v[100:103], v[118:121]
	v_mfma_f32_16x16x32_bf16 v[154:157], v[182:185], v[104:107], v[22:25]
	v_mfma_f32_16x16x32_bf16 v[22:25], v[178:181], v[198:201], v[122:125]
	v_mfma_f32_16x16x32_bf16 v[174:177], v[182:185], v[202:205], v[22:25]
	v_mfma_f32_16x16x32_bf16 v[22:25], v[186:189], v[100:103], v[110:113]
	v_mfma_f32_16x16x32_bf16 v[178:181], v[190:193], v[104:107], v[22:25]
	v_mfma_f32_16x16x32_bf16 v[22:25], v[186:189], v[198:201], v[114:117]
	v_mfma_f32_16x16x32_bf16 v[182:185], v[190:193], v[202:205], v[22:25]
	s_setprio 0
	s_barrier
; #define LDA(dst, b, h) _Pragma("unroll") for (int m = 0; m < 4; ++m) _Pragma("unroll") for (int k = 0; k < 2; ++k) \
;     dst[m][k] = *reinterpret_cast<const bf16x8*>((char*)SA(b, h) + lds_byte(wr * 64 + m * 16 + fr, k * 32 + fq * 8))
; #define LDB(dst, b, h) _Pragma("unroll") for (int n = 0; n < 2; ++n) _Pragma("unroll") for (int k = 0; k < 2; ++k) \
;     dst[n][k] = *reinterpret_cast<const bf16x8*>((char*)SB(b, h) + lds_byte(wc * 32 + n * 16 + fr, k * 32 + fq * 8))
; #define MMA(ai, bj, At_, Bt_) do { __builtin_amdgcn_s_setprio(1); \
;     _Pragma("unroll") for (int m = 0; m < 4; ++m) _Pragma("unroll") for (int n = 0; n < 2; ++n) _Pragma("unroll") for (int k = 0; k < 2; ++k) \
;       acc[ai][bj][m][n] = __builtin_amdgcn_mfma_f32_16x16x32_bf16(At_[m][k], Bt_[n][k], acc[ai][bj][m][n], 0, 0, 0); \
;     __builtin_amdgcn_s_setprio(0); } while (0)
; #define WAIT_V(n) asm volatile("s_waitcnt vmcnt(" #n ")" ::: "memory")
; #define WAIT_L(n) asm volatile("s_waitcnt lgkmcnt(" #n ")" ::: "memory")
; #define BAR __builtin_amdgcn_s_barrier()
; __device__ __forceinline__ void gemm256(const bf16_t* __restrict__ A, long lda, const bf16_t* __restrict__ Bt, long ldb, int K,
;                                         int brow, int bcol, char* smem, f32x4 (&acc)[2][2][4][2]) {
;     ...
;     { LDB(B0, 1, 0); LDA(At, 1, 0); WAIT_V(2); BAR; WAIT_L(0); MMA(0, 0, At, B0); BAR;
;       LDB(B1, 1, 1); WAIT_V(0); BAR; WAIT_L(0); MMA(0, 1, At, B1); BAR;
;       LDA(At, 1, 1); BAR; WAIT_L(0); MMA(1, 0, At, B0); MMA(1, 1, At, B1); BAR; }
;     if (wr == 0) BAR;
	ds_read_b128 v[186:189], v226
	ds_read_b128 v[190:193], v227
	ds_read_b128 v[198:201], v228
	ds_read_b128 v[202:205], v229
	s_nop 0
	ds_read_b128 v[22:25], v20 offset:32768
	ds_read_b128 v[26:29], v20 offset:33792
	ds_read_b128 v[38:41], v5 offset:34816
	ds_read_b128 v[114:117], v5 offset:35840
	ds_read_b128 v[206:209], v5 offset:36864
	ds_read_b128 v[210:213], v5 offset:37888
	ds_read_b128 v[214:217], v5 offset:38912
	ds_read_b128 v[218:221], v5 offset:39936
	s_waitcnt vmcnt(2)
	s_barrier
	s_waitcnt lgkmcnt(0)
	s_setprio 1
	s_waitcnt lgkmcnt(7)
	v_mfma_f32_16x16x32_bf16 v[6:9], v[22:25], v[186:189], v[6:9]
	s_waitcnt lgkmcnt(6)
	v_mfma_f32_16x16x32_bf16 v[118:121], v[26:29], v[190:193], v[6:9]
	v_mfma_f32_16x16x32_bf16 v[6:9], v[22:25], v[198:201], v[76:79]
	v_mfma_f32_16x16x32_bf16 v[122:125], v[26:29], v[202:205], v[6:9]
	s_waitcnt lgkmcnt(5)
	v_mfma_f32_16x16x32_bf16 v[6:9], v[38:41], v[186:189], v[80:83]
	s_waitcnt lgkmcnt(4)
	v_mfma_f32_16x16x32_bf16 v[102:105], v[114:117], v[190:193], v[6:9]
	v_mfma_f32_16x16x32_bf16 v[6:9], v[38:41], v[198:201], v[84:87]
	v_mfma_f32_16x16x32_bf16 v[106:109], v[114:117], v[202:205], v[6:9]
	s_waitcnt lgkmcnt(3)
	v_mfma_f32_16x16x32_bf16 v[6:9], v[206:209], v[186:189], v[88:91]
	s_waitcnt lgkmcnt(2)
	v_mfma_f32_16x16x32_bf16 v[86:89], v[210:213], v[190:193], v[6:9]
	v_mfma_f32_16x16x32_bf16 v[6:9], v[206:209], v[198:201], v[92:95]
	v_mfma_f32_16x16x32_bf16 v[90:93], v[210:213], v[202:205], v[6:9]
	s_waitcnt lgkmcnt(1)
	v_mfma_f32_16x16x32_bf16 v[6:9], v[214:217], v[186:189], v[96:99]
	s_waitcnt lgkmcnt(0)
	v_mfma_f32_16x16x32_bf16 v[70:73], v[218:221], v[190:193], v[6:9]
	v_mfma_f32_16x16x32_bf16 v[6:9], v[214:217], v[198:201], v[194:197]
	v_mfma_f32_16x16x32_bf16 v[74:77], v[218:221], v[202:205], v[6:9]
	s_setprio 0
	s_barrier
	ds_read_b128 v[194:197], v230
	ds_read_b128 v[222:225], v231
	ds_read_b128 v[226:229], v232
	ds_read_b128 v[230:233], v233
	s_waitcnt vmcnt(0)
	s_barrier
	s_waitcnt lgkmcnt(0)
	s_setprio 1
	s_waitcnt lgkmcnt(3)
	v_mfma_f32_16x16x32_bf16 v[6:9], v[22:25], v[194:197], v[126:129]
	s_waitcnt lgkmcnt(2)
	v_mfma_f32_16x16x32_bf16 v[126:129], v[26:29], v[222:225], v[6:9]
	s_waitcnt lgkmcnt(1)
	v_mfma_f32_16x16x32_bf16 v[6:9], v[22:25], v[226:229], v[44:47]
	s_waitcnt lgkmcnt(0)
	v_mfma_f32_16x16x32_bf16 v[130:133], v[26:29], v[230:233], v[6:9]
	v_mfma_f32_16x16x32_bf16 v[6:9], v[38:41], v[194:197], v[48:51]
	v_mfma_f32_16x16x32_bf16 v[110:113], v[114:117], v[222:225], v[6:9]
	v_mfma_f32_16x16x32_bf16 v[6:9], v[38:41], v[226:229], v[52:55]
	v_mfma_f32_16x16x32_bf16 v[114:117], v[114:117], v[230:233], v[6:9]
	v_mfma_f32_16x16x32_bf16 v[6:9], v[206:209], v[194:197], v[56:59]
	v_mfma_f32_16x16x32_bf16 v[94:97], v[210:213], v[222:225], v[6:9]
	v_mfma_f32_16x16x32_bf16 v[6:9], v[206:209], v[226:229], v[60:63]
	v_mfma_f32_16x16x32_bf16 v[98:101], v[210:213], v[230:233], v[6:9]
	v_mfma_f32_16x16x32_bf16 v[6:9], v[214:217], v[194:197], v[64:67]
	v_mfma_f32_16x16x32_bf16 v[78:81], v[218:221], v[222:225], v[6:9]
	v_mfma_f32_16x16x32_bf16 v[6:9], v[214:217], v[226:229], v[146:149]
	v_mfma_f32_16x16x32_bf16 v[82:85], v[218:221], v[230:233], v[6:9]
	s_setprio 0
	s_barrier
	ds_read_b128 v[46:49], v20 offset:49152
	ds_read_b128 v[18:21], v20 offset:50176
	ds_read_b128 v[50:53], v5 offset:51200
	ds_read_b128 v[146:149], v5 offset:52224
	ds_read_b128 v[206:209], v5 offset:53248
	ds_read_b128 v[210:213], v5 offset:54272
	ds_read_b128 v[214:217], v5 offset:55296
	ds_read_b128 v[218:221], v5 offset:56320
	s_barrier
	s_waitcnt lgkmcnt(0)
	s_setprio 1
	s_waitcnt lgkmcnt(7)
	v_mfma_f32_16x16x32_bf16 v[6:9], v[46:49], v[186:189], v[10:13]
	s_waitcnt lgkmcnt(6)
	v_mfma_f32_16x16x32_bf16 v[58:61], v[18:21], v[190:193], v[6:9]
	v_mfma_f32_16x16x32_bf16 v[6:9], v[46:49], v[198:201], v[14:17]
	v_mfma_f32_16x16x32_bf16 v[54:57], v[18:21], v[202:205], v[6:9]
	s_waitcnt lgkmcnt(5)
	v_mfma_f32_16x16x32_bf16 v[6:9], v[50:53], v[186:189], v[158:161]
	s_waitcnt lgkmcnt(4)
	v_mfma_f32_16x16x32_bf16 v[38:41], v[146:149], v[190:193], v[6:9]
	v_mfma_f32_16x16x32_bf16 v[6:9], v[50:53], v[198:201], v[162:165]
	v_mfma_f32_16x16x32_bf16 v[42:45], v[146:149], v[202:205], v[6:9]
	s_waitcnt lgkmcnt(3)
	v_mfma_f32_16x16x32_bf16 v[6:9], v[206:209], v[186:189], v[166:169]
	s_waitcnt lgkmcnt(2)
	v_mfma_f32_16x16x32_bf16 v[22:25], v[210:213], v[190:193], v[6:9]
	v_mfma_f32_16x16x32_bf16 v[6:9], v[206:209], v[198:201], v[170:173]
	v_mfma_f32_16x16x32_bf16 v[26:29], v[210:213], v[202:205], v[6:9]
	s_waitcnt lgkmcnt(1)
	v_mfma_f32_16x16x32_bf16 v[6:9], v[214:217], v[186:189], v[134:137]
	s_waitcnt lgkmcnt(0)
	v_mfma_f32_16x16x32_bf16 v[10:13], v[218:221], v[190:193], v[6:9]
	v_mfma_f32_16x16x32_bf16 v[6:9], v[214:217], v[198:201], v[30:33]
	v_mfma_f32_16x16x32_bf16 v[6:9], v[218:221], v[202:205], v[6:9]
	s_setprio 0
	s_setprio 1
	v_mfma_f32_16x16x32_bf16 v[14:17], v[46:49], v[194:197], v[138:141]
	v_mfma_f32_16x16x32_bf16 v[62:65], v[18:21], v[222:225], v[14:17]
	v_mfma_f32_16x16x32_bf16 v[14:17], v[46:49], v[226:229], v[34:37]
	v_mfma_f32_16x16x32_bf16 v[66:69], v[18:21], v[230:233], v[14:17]
	v_mfma_f32_16x16x32_bf16 v[14:17], v[50:53], v[194:197], v[142:145]
	v_mfma_f32_16x16x32_bf16 v[46:49], v[146:149], v[222:225], v[14:17]
	v_mfma_f32_16x16x32_bf16 v[14:17], v[50:53], v[226:229], v[150:153]
	v_mfma_f32_16x16x32_bf16 v[50:53], v[146:149], v[230:233], v[14:17]
	v_mfma_f32_16x16x32_bf16 v[14:17], v[206:209], v[194:197], v[154:157]
	v_mfma_f32_16x16x32_bf16 v[30:33], v[210:213], v[222:225], v[14:17]
	v_mfma_f32_16x16x32_bf16 v[14:17], v[206:209], v[226:229], v[174:177]
	v_mfma_f32_16x16x32_bf16 v[34:37], v[210:213], v[230:233], v[14:17]
	v_mfma_f32_16x16x32_bf16 v[14:17], v[214:217], v[194:197], v[178:181]
	v_mfma_f32_16x16x32_bf16 v[18:21], v[214:217], v[226:229], v[182:185]
	v_mfma_f32_16x16x32_bf16 v[14:17], v[218:221], v[222:225], v[14:17]
	v_mfma_f32_16x16x32_bf16 v[18:21], v[218:221], v[230:233], v[18:21]
	s_setprio 0
	v_cmp_gt_u32_e32 vcc, s78, v0
	s_barrier
	s_and_saveexec_b64 s[16:17], vcc
	s_cbranch_execz .LBB0_414
	s_barrier

; #define STAGE(P, BASE, LD, br, kt) do { const long _g = (long)(br) * (LD) + (long)(kt) * 64; \
;     _Pragma("unroll") for (int _i = 0; _i < 2; ++_i) { const int _b = tid * 16 + _i * 8192; int _r, _c; stage_rc(_b, _r, _c); \
;       __builtin_amdgcn_global_load_lds((const G_AS1 unsigned*)((BASE) + _g + (long)_r * (LD) + _c), \
;         (LAS unsigned*)((char*)(P) + _b), 16, 0, 0); } } while (0)
; #define LDA(dst, b, h) _Pragma("unroll") for (int m = 0; m < 4; ++m) _Pragma("unroll") for (int k = 0; k < 2; ++k) \
;     dst[m][k] = *reinterpret_cast<const bf16x8*>((char*)SA(b, h) + lds_byte(wr * 64 + m * 16 + fr, k * 32 + fq * 8))
; #define LDB(dst, b, h) _Pragma("unroll") for (int n = 0; n < 2; ++n) _Pragma("unroll") for (int k = 0; k < 2; ++k) \
;     dst[n][k] = *reinterpret_cast<const bf16x8*>((char*)SB(b, h) + lds_byte(wc * 32 + n * 16 + fr, k * 32 + fq * 8))
; #define MMA(ai, bj, At_, Bt_) do { __builtin_amdgcn_s_setprio(1); \
;     _Pragma("unroll") for (int m = 0; m < 4; ++m) _Pragma("unroll") for (int n = 0; n < 2; ++n) _Pragma("unroll") for (int k = 0; k < 2; ++k) \
;       acc[ai][bj][m][n] = __builtin_amdgcn_mfma_f32_16x16x32_bf16(At_[m][k], Bt_[n][k], acc[ai][bj][m][n], 0, 0, 0); \
;     __builtin_amdgcn_s_setprio(0); } while (0)
; #define WAIT_L(n) asm volatile("s_waitcnt lgkmcnt(" #n ")" ::: "memory")
; #define BAR __builtin_amdgcn_s_barrier()
; #define SCHED __builtin_amdgcn_sched_barrier(0)
; __device__ __forceinline__ void gemm256(const bf16_t* __restrict__ A, long lda, const bf16_t* __restrict__ Bt, long ldb, int K,
;                                         int brow, int bcol, char* smem, f32x4 (&acc)[2][2][4][2]) {
;     ...
;         LDB(B0, 0, 0); SCHED; LDA(At, 0, 0); STAGE(SA(1, 1), A, lda, brow + 128, t + 1);
;         WAIT_L(8); BAR; WAIT_L(0); MMA(0, 0, At, B0); BAR; SCHED;
;         LDB(B1, 0, 1); STAGE(SB(0, 0), Bt, ldb, bcol, t + 2);
;         BAR; WAIT_L(0); MMA(0, 1, At, B1); BAR;
;         LDA(At, 0, 1); STAGE(SA(0, 0), A, lda, brow, t + 2);
;         BAR; WAIT_L(0); MMA(1, 0, At, B0); BAR; SCHED;
.LBB0_419:
	s_nop 0
	ds_read_b128 v[172:175], v168
	ds_read_b128 v[176:179], v168 offset:1024
	ds_read_b128 v[180:183], v168 offset:2048
	ds_read_b128 v[184:187], v168 offset:3072
	v_add_u32_e32 v169, 0xc000, v5
	v_lshl_add_u64 v[238:239], s[8:9], 0, v[144:145]
	v_readfirstlane_b32 s19, v169
	v_lshl_add_u64 v[170:171], v[238:239], 0, s[76:77]
	s_mov_b32 m0, s19
	ds_read_b128 v[192:195], v153
	ds_read_b128 v[196:199], v153 offset:1024
	ds_read_b128 v[200:203], v151
	ds_read_b128 v[204:207], v151 offset:1024
	ds_read_b128 v[208:211], v150
	ds_read_b128 v[212:215], v150 offset:1024
	ds_read_b128 v[216:219], v149
	ds_read_b128 v[220:223], v149 offset:1024
	global_load_lds_dwordx4 v[170:171], off
	v_add_u32_e32 v170, 0xe000, v5
	v_lshl_add_u64 v[242:243], s[8:9], 0, v[146:147]
	v_readfirstlane_b32 s19, v170
	v_lshl_add_u64 v[188:189], v[242:243], 0, s[76:77]
	s_mov_b32 m0, s19
	s_nop 0
	global_load_lds_dwordx4 v[188:189], off
	s_waitcnt lgkmcnt(8)
	s_barrier
	s_waitcnt lgkmcnt(0)
	s_setprio 1
	s_waitcnt lgkmcnt(0)
	v_mfma_f32_16x16x32_bf16 v[130:133], v[192:195], v[172:175], v[130:133]
	v_mfma_f32_16x16x32_bf16 v[126:129], v[192:195], v[180:183], v[126:129]
	v_mfma_f32_16x16x32_bf16 v[122:125], v[200:203], v[172:175], v[122:125]
	v_mfma_f32_16x16x32_bf16 v[118:121], v[200:203], v[180:183], v[118:121]
	v_mfma_f32_16x16x32_bf16 v[114:117], v[208:211], v[172:175], v[114:117]
	v_mfma_f32_16x16x32_bf16 v[110:113], v[208:211], v[180:183], v[110:113]
	v_mfma_f32_16x16x32_bf16 v[106:109], v[216:219], v[172:175], v[106:109]
	v_mfma_f32_16x16x32_bf16 v[102:105], v[216:219], v[180:183], v[102:105]
	v_mfma_f32_16x16x32_bf16 v[130:133], v[196:199], v[176:179], v[130:133]
	v_mfma_f32_16x16x32_bf16 v[126:129], v[196:199], v[184:187], v[126:129]
	v_mfma_f32_16x16x32_bf16 v[122:125], v[204:207], v[176:179], v[122:125]
	v_mfma_f32_16x16x32_bf16 v[118:121], v[204:207], v[184:187], v[118:121]
	v_mfma_f32_16x16x32_bf16 v[114:117], v[212:215], v[176:179], v[114:117]
	v_mfma_f32_16x16x32_bf16 v[110:113], v[212:215], v[184:187], v[110:113]
	v_mfma_f32_16x16x32_bf16 v[106:109], v[220:223], v[176:179], v[106:109]
	v_mfma_f32_16x16x32_bf16 v[102:105], v[220:223], v[184:187], v[102:105]
	s_setprio 0
	s_barrier
	v_lshl_add_u64 v[244:245], s[8:9], 0, v[140:141]
	v_readfirstlane_b32 s19, v148
	v_lshl_add_u64 v[250:251], v[244:245], 0, s[56:57]
	s_mov_b32 m0, s19
	s_nop 0
	ds_read_b128 v[224:227], v166
	ds_read_b128 v[228:231], v166 offset:1024
	ds_read_b128 v[232:235], v166 offset:2048
	ds_read_b128 v[188:191], v166 offset:3072
	global_load_lds_dwordx4 v[250:251], off
	v_lshl_add_u64 v[250:251], s[8:9], 0, v[142:143]
	v_readfirstlane_b32 s19, v155
	v_lshl_add_u64 v[252:253], v[250:251], 0, s[56:57]
	s_mov_b32 m0, s19
	s_nop 0
	global_load_lds_dwordx4 v[252:253], off
	s_barrier
	s_waitcnt lgkmcnt(0)
	s_setprio 1
	s_waitcnt lgkmcnt(0)
	v_mfma_f32_16x16x32_bf16 v[98:101], v[192:195], v[224:227], v[98:101]
	v_mfma_f32_16x16x32_bf16 v[94:97], v[192:195], v[232:235], v[94:97]
	v_mfma_f32_16x16x32_bf16 v[90:93], v[200:203], v[224:227], v[90:93]
	v_mfma_f32_16x16x32_bf16 v[86:89], v[200:203], v[232:235], v[86:89]
	v_mfma_f32_16x16x32_bf16 v[82:85], v[208:211], v[224:227], v[82:85]
	v_mfma_f32_16x16x32_bf16 v[78:81], v[208:211], v[232:235], v[78:81]
	v_mfma_f32_16x16x32_bf16 v[74:77], v[216:219], v[224:227], v[74:77]
	v_mfma_f32_16x16x32_bf16 v[70:73], v[216:219], v[232:235], v[70:73]
	v_mfma_f32_16x16x32_bf16 v[98:101], v[196:199], v[228:231], v[98:101]
	v_mfma_f32_16x16x32_bf16 v[94:97], v[196:199], v[188:191], v[94:97]
	v_mfma_f32_16x16x32_bf16 v[90:93], v[204:207], v[228:231], v[90:93]
	v_mfma_f32_16x16x32_bf16 v[86:89], v[204:207], v[188:191], v[86:89]
	v_mfma_f32_16x16x32_bf16 v[82:85], v[212:215], v[228:231], v[82:85]
	v_mfma_f32_16x16x32_bf16 v[78:81], v[212:215], v[188:191], v[78:81]
	v_mfma_f32_16x16x32_bf16 v[74:77], v[220:223], v[228:231], v[74:77]
	v_mfma_f32_16x16x32_bf16 v[70:73], v[220:223], v[188:191], v[70:73]
	s_setprio 0
	v_readfirstlane_b32 s19, v5
	v_lshl_add_u64 v[252:253], v[238:239], 0, s[88:89]
	s_mov_b32 m0, s19
	v_readfirstlane_b32 s19, v152
	s_barrier
	s_nop 0
	ds_read_b128 v[192:195], v153 offset:16384
	ds_read_b128 v[196:199], v153 offset:17408
	ds_read_b128 v[200:203], v151 offset:16384
	ds_read_b128 v[204:207], v151 offset:17408
	ds_read_b128 v[208:211], v150 offset:16384
	ds_read_b128 v[212:215], v150 offset:17408
	ds_read_b128 v[216:219], v149 offset:16384
	ds_read_b128 v[220:223], v149 offset:17408
	global_load_lds_dwordx4 v[252:253], off
	v_lshl_add_u64 v[252:253], v[242:243], 0, s[88:89]
	s_mov_b32 m0, s19
	s_nop 0
	global_load_lds_dwordx4 v[252:253], off
	s_barrier
	s_waitcnt lgkmcnt(0)
	s_setprio 1
	s_waitcnt lgkmcnt(0)
	v_mfma_f32_16x16x32_bf16 v[66:69], v[192:195], v[172:175], v[66:69]
	v_mfma_f32_16x16x32_bf16 v[62:65], v[192:195], v[180:183], v[62:65]
	v_mfma_f32_16x16x32_bf16 v[58:61], v[200:203], v[172:175], v[58:61]
	v_mfma_f32_16x16x32_bf16 v[54:57], v[200:203], v[180:183], v[54:57]
	v_mfma_f32_16x16x32_bf16 v[50:53], v[208:211], v[172:175], v[50:53]
	v_mfma_f32_16x16x32_bf16 v[46:49], v[208:211], v[180:183], v[46:49]
	v_mfma_f32_16x16x32_bf16 v[42:45], v[216:219], v[172:175], v[42:45]
	v_mfma_f32_16x16x32_bf16 v[38:41], v[216:219], v[180:183], v[38:41]
	v_mfma_f32_16x16x32_bf16 v[66:69], v[196:199], v[176:179], v[66:69]
	v_mfma_f32_16x16x32_bf16 v[62:65], v[196:199], v[184:187], v[62:65]
	v_mfma_f32_16x16x32_bf16 v[58:61], v[204:207], v[176:179], v[58:61]
	v_mfma_f32_16x16x32_bf16 v[54:57], v[204:207], v[184:187], v[54:57]
	v_mfma_f32_16x16x32_bf16 v[50:53], v[212:215], v[176:179], v[50:53]
	v_mfma_f32_16x16x32_bf16 v[46:49], v[212:215], v[184:187], v[46:49]
	v_mfma_f32_16x16x32_bf16 v[42:45], v[220:223], v[176:179], v[42:45]
	v_mfma_f32_16x16x32_bf16 v[38:41], v[220:223], v[184:187], v[38:41]
	s_setprio 0
	s_barrier
; #define STAGE(P, BASE, LD, br, kt) do { const long _g = (long)(br) * (LD) + (long)(kt) * 64; \
;     _Pragma("unroll") for (int _i = 0; _i < 2; ++_i) { const int _b = tid * 16 + _i * 8192; int _r, _c; stage_rc(_b, _r, _c); \
;       __builtin_amdgcn_global_load_lds((const G_AS1 unsigned*)((BASE) + _g + (long)_r * (LD) + _c), \
;         (LAS unsigned*)((char*)(P) + _b), 16, 0, 0); } } while (0)
; #define LDA(dst, b, h) _Pragma("unroll") for (int m = 0; m < 4; ++m) _Pragma("unroll") for (int k = 0; k < 2; ++k) \
;     dst[m][k] = *reinterpret_cast<const bf16x8*>((char*)SA(b, h) + lds_byte(wr * 64 + m * 16 + fr, k * 32 + fq * 8))
; #define LDB(dst, b, h) _Pragma("unroll") for (int n = 0; n < 2; ++n) _Pragma("unroll") for (int k = 0; k < 2; ++k) \
;     dst[n][k] = *reinterpret_cast<const bf16x8*>((char*)SB(b, h) + lds_byte(wc * 32 + n * 16 + fr, k * 32 + fq * 8))
; #define MMA(ai, bj, At_, Bt_) do { __builtin_amdgcn_s_setprio(1); \
;     _Pragma("unroll") for (int m = 0; m < 4; ++m) _Pragma("unroll") for (int n = 0; n < 2; ++n) _Pragma("unroll") for (int k = 0; k < 2; ++k) \
;       acc[ai][bj][m][n] = __builtin_amdgcn_mfma_f32_16x16x32_bf16(At_[m][k], Bt_[n][k], acc[ai][bj][m][n], 0, 0, 0); \
;     __builtin_amdgcn_s_setprio(0); } while (0)
; #define WAIT_V(n) asm volatile("s_waitcnt vmcnt(" #n ")" ::: "memory")
; #define WAIT_L(n) asm volatile("s_waitcnt lgkmcnt(" #n ")" ::: "memory")
; #define BAR __builtin_amdgcn_s_barrier()
; #define SCHED __builtin_amdgcn_sched_barrier(0)
; __device__ __forceinline__ void gemm256(const bf16_t* __restrict__ A, long lda, const bf16_t* __restrict__ Bt, long ldb, int K,
;                                         int brow, int bcol, char* smem, f32x4 (&acc)[2][2][4][2]) {
;     ...
;         STAGE(SB(0, 1), Bt, ldb, bcol + 128, t + 2);
;         WAIT_V(6); BAR; MMA(1, 1, At, B1); BAR;
;         LDB(B0, 1, 0); SCHED; LDA(At, 1, 0); STAGE(SA(0, 1), A, lda, brow + 128, t + 2);
;         WAIT_L(8); BAR; WAIT_L(0); MMA(0, 0, At, B0); BAR; SCHED;
;         LDB(B1, 1, 1); STAGE(SB(1, 0), Bt, ldb, bcol, t + 3);
;         BAR; WAIT_L(0); MMA(0, 1, At, B1); BAR;
;         LDA(At, 1, 1); STAGE(SA(1, 0), A, lda, brow, t + 3);
;         BAR; WAIT_L(0); MMA(1, 0, At, B0); BAR; SCHED;
	v_readfirstlane_b32 s19, v156
	v_lshl_add_u64 v[172:173], v[244:245], 0, s[2:3]
	s_mov_b32 m0, s19
	v_readfirstlane_b32 s19, v158
	global_load_lds_dwordx4 v[172:173], off
	v_lshl_add_u64 v[172:173], v[250:251], 0, s[2:3]
	s_mov_b32 m0, s19
	s_nop 0
	global_load_lds_dwordx4 v[172:173], off
	s_waitcnt vmcnt(6)
	s_barrier
	s_setprio 1
	v_mfma_f32_16x16x32_bf16 v[34:37], v[192:195], v[224:227], v[34:37]
	v_mfma_f32_16x16x32_bf16 v[30:33], v[192:195], v[232:235], v[30:33]
	v_mfma_f32_16x16x32_bf16 v[26:29], v[200:203], v[224:227], v[26:29]
	v_mfma_f32_16x16x32_bf16 v[22:25], v[200:203], v[232:235], v[22:25]
	v_mfma_f32_16x16x32_bf16 v[18:21], v[208:211], v[224:227], v[18:21]
	v_mfma_f32_16x16x32_bf16 v[14:17], v[208:211], v[232:235], v[14:17]
	v_mfma_f32_16x16x32_bf16 v[10:13], v[216:219], v[224:227], v[10:13]
	v_mfma_f32_16x16x32_bf16 v[6:9], v[216:219], v[232:235], v[6:9]
	v_mfma_f32_16x16x32_bf16 v[34:37], v[196:199], v[228:231], v[34:37]
	v_mfma_f32_16x16x32_bf16 v[30:33], v[196:199], v[188:191], v[30:33]
	v_mfma_f32_16x16x32_bf16 v[26:29], v[204:207], v[228:231], v[26:29]
	v_mfma_f32_16x16x32_bf16 v[22:25], v[204:207], v[188:191], v[22:25]
	v_mfma_f32_16x16x32_bf16 v[18:21], v[212:215], v[228:231], v[18:21]
	v_mfma_f32_16x16x32_bf16 v[14:17], v[212:215], v[188:191], v[14:17]
	v_mfma_f32_16x16x32_bf16 v[10:13], v[220:223], v[228:231], v[10:13]
	v_mfma_f32_16x16x32_bf16 v[6:9], v[220:223], v[188:191], v[6:9]
	s_setprio 0
	s_barrier
	s_nop 0
	ds_read_b128 v[172:175], v157
	ds_read_b128 v[176:179], v157 offset:1024
	ds_read_b128 v[180:183], v157 offset:2048
	ds_read_b128 v[184:187], v157 offset:3072
	v_readfirstlane_b32 s19, v159
	v_lshl_add_u64 v[220:221], v[238:239], 0, s[30:31]
	s_mov_b32 m0, s19
	v_readfirstlane_b32 s19, v160
	ds_read_b128 v[188:191], v153 offset:32768
	ds_read_b128 v[192:195], v153 offset:33792
	ds_read_b128 v[196:199], v151 offset:32768
	ds_read_b128 v[200:203], v151 offset:33792
	ds_read_b128 v[204:207], v150 offset:32768
	ds_read_b128 v[208:211], v150 offset:33792
	ds_read_b128 v[212:215], v149 offset:32768
	ds_read_b128 v[216:219], v149 offset:33792
	global_load_lds_dwordx4 v[220:221], off
	v_lshl_add_u64 v[220:221], v[242:243], 0, s[30:31]
	s_mov_b32 m0, s19
	s_nop 0
	global_load_lds_dwordx4 v[220:221], off
	s_waitcnt lgkmcnt(8)
	s_barrier
	s_waitcnt lgkmcnt(0)
	s_setprio 1
	s_waitcnt lgkmcnt(0)
	v_mfma_f32_16x16x32_bf16 v[130:133], v[188:191], v[172:175], v[130:133]
	v_mfma_f32_16x16x32_bf16 v[126:129], v[188:191], v[180:183], v[126:129]
	v_mfma_f32_16x16x32_bf16 v[122:125], v[196:199], v[172:175], v[122:125]
	v_mfma_f32_16x16x32_bf16 v[118:121], v[196:199], v[180:183], v[118:121]
	v_mfma_f32_16x16x32_bf16 v[114:117], v[204:207], v[172:175], v[114:117]
	v_mfma_f32_16x16x32_bf16 v[110:113], v[204:207], v[180:183], v[110:113]
	v_mfma_f32_16x16x32_bf16 v[106:109], v[212:215], v[172:175], v[106:109]
	v_mfma_f32_16x16x32_bf16 v[102:105], v[212:215], v[180:183], v[102:105]
	v_mfma_f32_16x16x32_bf16 v[130:133], v[192:195], v[176:179], v[130:133]
	v_mfma_f32_16x16x32_bf16 v[126:129], v[192:195], v[184:187], v[126:129]
	v_mfma_f32_16x16x32_bf16 v[122:125], v[200:203], v[176:179], v[122:125]
	v_mfma_f32_16x16x32_bf16 v[118:121], v[200:203], v[184:187], v[118:121]
	v_mfma_f32_16x16x32_bf16 v[114:117], v[208:211], v[176:179], v[114:117]
	v_mfma_f32_16x16x32_bf16 v[110:113], v[208:211], v[184:187], v[110:113]
	v_mfma_f32_16x16x32_bf16 v[106:109], v[216:219], v[176:179], v[106:109]
	v_mfma_f32_16x16x32_bf16 v[102:105], v[216:219], v[184:187], v[102:105]
	s_setprio 0
	s_barrier
	v_readfirstlane_b32 s19, v161
	v_lshl_add_u64 v[252:253], v[244:245], 0, s[84:85]
	s_mov_b32 m0, s19
	v_readfirstlane_b32 s19, v162
	s_nop 0
	ds_read_b128 v[220:223], v154
	ds_read_b128 v[224:227], v154 offset:1024
	ds_read_b128 v[228:231], v154 offset:2048
	ds_read_b128 v[232:235], v154 offset:3072
	global_load_lds_dwordx4 v[252:253], off
	v_lshl_add_u64 v[252:253], v[250:251], 0, s[84:85]
	s_mov_b32 m0, s19
	s_nop 0
	global_load_lds_dwordx4 v[252:253], off
	s_barrier
	s_waitcnt lgkmcnt(0)
	s_setprio 1
	s_waitcnt lgkmcnt(0)
	v_mfma_f32_16x16x32_bf16 v[98:101], v[188:191], v[220:223], v[98:101]
	v_mfma_f32_16x16x32_bf16 v[94:97], v[188:191], v[228:231], v[94:97]
	v_mfma_f32_16x16x32_bf16 v[90:93], v[196:199], v[220:223], v[90:93]
	v_mfma_f32_16x16x32_bf16 v[86:89], v[196:199], v[228:231], v[86:89]
	v_mfma_f32_16x16x32_bf16 v[82:85], v[204:207], v[220:223], v[82:85]
	v_mfma_f32_16x16x32_bf16 v[78:81], v[204:207], v[228:231], v[78:81]
	v_mfma_f32_16x16x32_bf16 v[74:77], v[212:215], v[220:223], v[74:77]
	v_mfma_f32_16x16x32_bf16 v[70:73], v[212:215], v[228:231], v[70:73]
	v_mfma_f32_16x16x32_bf16 v[98:101], v[192:195], v[224:227], v[98:101]
	v_mfma_f32_16x16x32_bf16 v[94:97], v[192:195], v[232:235], v[94:97]
	v_mfma_f32_16x16x32_bf16 v[90:93], v[200:203], v[224:227], v[90:93]
	v_mfma_f32_16x16x32_bf16 v[86:89], v[200:203], v[232:235], v[86:89]
	v_mfma_f32_16x16x32_bf16 v[82:85], v[208:211], v[224:227], v[82:85]
	v_mfma_f32_16x16x32_bf16 v[78:81], v[208:211], v[232:235], v[78:81]
	v_mfma_f32_16x16x32_bf16 v[74:77], v[216:219], v[224:227], v[74:77]
	v_mfma_f32_16x16x32_bf16 v[70:73], v[216:219], v[232:235], v[70:73]
	s_setprio 0
	v_readfirstlane_b32 s19, v163
	v_lshl_add_u64 v[238:239], v[238:239], 0, s[72:73]
	s_mov_b32 m0, s19
	v_readfirstlane_b32 s19, v164
	s_barrier
	s_nop 0
	ds_read_b128 v[188:191], v153 offset:49152
	ds_read_b128 v[192:195], v153 offset:50176
	ds_read_b128 v[196:199], v151 offset:49152
	ds_read_b128 v[200:203], v151 offset:50176
	ds_read_b128 v[204:207], v150 offset:49152
	ds_read_b128 v[208:211], v150 offset:50176
	ds_read_b128 v[212:215], v149 offset:49152
	ds_read_b128 v[216:219], v149 offset:50176
	global_load_lds_dwordx4 v[238:239], off
	v_lshl_add_u64 v[238:239], v[242:243], 0, s[72:73]
	s_mov_b32 m0, s19
	s_nop 0
	global_load_lds_dwordx4 v[238:239], off
	s_barrier
; #define STAGE(P, BASE, LD, br, kt) do { const long _g = (long)(br) * (LD) + (long)(kt) * 64; \
;     _Pragma("unroll") for (int _i = 0; _i < 2; ++_i) { const int _b = tid * 16 + _i * 8192; int _r, _c; stage_rc(_b, _r, _c); \
;       __builtin_amdgcn_global_load_lds((const G_AS1 unsigned*)((BASE) + _g + (long)_r * (LD) + _c), \
;         (LAS unsigned*)((char*)(P) + _b), 16, 0, 0); } } while (0)
; #define LDA(dst, b, h) _Pragma("unroll") for (int m = 0; m < 4; ++m) _Pragma("unroll") for (int k = 0; k < 2; ++k) \
;     dst[m][k] = *reinterpret_cast<const bf16x8*>((char*)SA(b, h) + lds_byte(wr * 64 + m * 16 + fr, k * 32 + fq * 8))
; #define LDB(dst, b, h) _Pragma("unroll") for (int n = 0; n < 2; ++n) _Pragma("unroll") for (int k = 0; k < 2; ++k) \
;     dst[n][k] = *reinterpret_cast<const bf16x8*>((char*)SB(b, h) + lds_byte(wc * 32 + n * 16 + fr, k * 32 + fq * 8))
; #define MMA(ai, bj, At_, Bt_) do { __builtin_amdgcn_s_setprio(1); \
;     _Pragma("unroll") for (int m = 0; m < 4; ++m) _Pragma("unroll") for (int n = 0; n < 2; ++n) _Pragma("unroll") for (int k = 0; k < 2; ++k) \
;       acc[ai][bj][m][n] = __builtin_amdgcn_mfma_f32_16x16x32_bf16(At_[m][k], Bt_[n][k], acc[ai][bj][m][n], 0, 0, 0); \
;     __builtin_amdgcn_s_setprio(0); } while (0)
; #define WAIT_V(n) asm volatile("s_waitcnt vmcnt(" #n ")" ::: "memory")
; #define WAIT_L(n) asm volatile("s_waitcnt lgkmcnt(" #n ")" ::: "memory")
; #define BAR __builtin_amdgcn_s_barrier()
; #define SCHED __builtin_amdgcn_sched_barrier(0)
; __device__ __forceinline__ void gemm256(const bf16_t* __restrict__ A, long lda, const bf16_t* __restrict__ Bt, long ldb, int K,
;                                         int brow, int bcol, char* smem, f32x4 (&acc)[2][2][4][2]) {
;     ...
;         BAR; WAIT_L(0); MMA(1, 0, At, B0); BAR; SCHED;
;         STAGE(SB(1, 1), Bt, ldb, bcol + 128, t + 3);
;         WAIT_V(6); BAR; MMA(1, 1, At, B1); BAR;
;     }
;     { LDB(B0, 0, 0); LDA(At, 0, 0); STAGE(SA(1, 1), A, lda, brow + 128, nt - 1);
;       BAR; WAIT_L(0); MMA(0, 0, At, B0); BAR;
;       LDB(B1, 0, 1); BAR; WAIT_L(0); MMA(0, 1, At, B1); BAR;
	s_waitcnt lgkmcnt(0)
	s_setprio 1
	s_waitcnt lgkmcnt(0)
	v_mfma_f32_16x16x32_bf16 v[66:69], v[188:191], v[172:175], v[66:69]
	v_mfma_f32_16x16x32_bf16 v[62:65], v[188:191], v[180:183], v[62:65]
	v_mfma_f32_16x16x32_bf16 v[58:61], v[196:199], v[172:175], v[58:61]
	v_mfma_f32_16x16x32_bf16 v[54:57], v[196:199], v[180:183], v[54:57]
	v_mfma_f32_16x16x32_bf16 v[50:53], v[204:207], v[172:175], v[50:53]
	v_mfma_f32_16x16x32_bf16 v[46:49], v[204:207], v[180:183], v[46:49]
	v_mfma_f32_16x16x32_bf16 v[42:45], v[212:215], v[172:175], v[42:45]
	v_mfma_f32_16x16x32_bf16 v[38:41], v[212:215], v[180:183], v[38:41]
	v_mfma_f32_16x16x32_bf16 v[66:69], v[192:195], v[176:179], v[66:69]
	v_mfma_f32_16x16x32_bf16 v[62:65], v[192:195], v[184:187], v[62:65]
	v_mfma_f32_16x16x32_bf16 v[58:61], v[200:203], v[176:179], v[58:61]
	v_mfma_f32_16x16x32_bf16 v[54:57], v[200:203], v[184:187], v[54:57]
	v_mfma_f32_16x16x32_bf16 v[50:53], v[208:211], v[176:179], v[50:53]
	v_mfma_f32_16x16x32_bf16 v[46:49], v[208:211], v[184:187], v[46:49]
	v_mfma_f32_16x16x32_bf16 v[42:45], v[216:219], v[176:179], v[42:45]
	v_mfma_f32_16x16x32_bf16 v[38:41], v[216:219], v[184:187], v[38:41]
	s_setprio 0
	s_barrier
	v_readfirstlane_b32 s19, v165
	v_lshl_add_u64 v[172:173], v[244:245], 0, s[80:81]
	s_mov_b32 m0, s19
	v_readfirstlane_b32 s19, v167
	global_load_lds_dwordx4 v[172:173], off
	v_lshl_add_u64 v[172:173], v[250:251], 0, s[80:81]
	s_mov_b32 m0, s19
	s_nop 0
	global_load_lds_dwordx4 v[172:173], off
	s_waitcnt vmcnt(6)
	s_barrier
	s_setprio 1
	v_mfma_f32_16x16x32_bf16 v[34:37], v[188:191], v[220:223], v[34:37]
	v_mfma_f32_16x16x32_bf16 v[30:33], v[188:191], v[228:231], v[30:33]
	v_mfma_f32_16x16x32_bf16 v[26:29], v[196:199], v[220:223], v[26:29]
	v_mfma_f32_16x16x32_bf16 v[22:25], v[196:199], v[228:231], v[22:25]
	v_mfma_f32_16x16x32_bf16 v[18:21], v[204:207], v[220:223], v[18:21]
	v_mfma_f32_16x16x32_bf16 v[14:17], v[204:207], v[228:231], v[14:17]
	v_mfma_f32_16x16x32_bf16 v[10:13], v[212:215], v[220:223], v[10:13]
	v_mfma_f32_16x16x32_bf16 v[6:9], v[212:215], v[228:231], v[6:9]
	v_mfma_f32_16x16x32_bf16 v[34:37], v[192:195], v[224:227], v[34:37]
	v_mfma_f32_16x16x32_bf16 v[30:33], v[192:195], v[232:235], v[30:33]
	v_mfma_f32_16x16x32_bf16 v[26:29], v[200:203], v[224:227], v[26:29]
	v_mfma_f32_16x16x32_bf16 v[22:25], v[200:203], v[232:235], v[22:25]
	v_mfma_f32_16x16x32_bf16 v[18:21], v[208:211], v[224:227], v[18:21]
	v_mfma_f32_16x16x32_bf16 v[14:17], v[208:211], v[232:235], v[14:17]
	v_mfma_f32_16x16x32_bf16 v[10:13], v[216:219], v[224:227], v[10:13]
	v_mfma_f32_16x16x32_bf16 v[6:9], v[216:219], v[232:235], v[6:9]
	s_setprio 0
	s_add_i32 s18, s18, 2
	v_lshl_add_u64 v[140:141], v[140:141], 0, s[44:45]
	v_lshl_add_u64 v[142:143], v[142:143], 0, s[44:45]
	v_lshl_add_u64 v[144:145], v[144:145], 0, s[44:45]
	s_cmp_lt_u32 s18, 40
	v_lshl_add_u64 v[146:147], v[146:147], 0, s[44:45]
	s_barrier
	s_cbranch_scc1 .LBB0_419
	s_add_u32 s16, s16, 0x1580
	s_addc_u32 s17, s17, 0
	v_lshl_add_u64 v[134:135], v[134:135], 1, s[16:17]
	v_readfirstlane_b32 s18, v169
	v_lshl_add_u64 v[2:3], v[2:3], 1, v[134:135]
	s_mov_b32 m0, s18
	s_nop 0
	ds_read_b128 v[140:143], v168
	ds_read_b128 v[144:147], v168 offset:1024
	ds_read_b128 v[158:161], v168 offset:2048
	ds_read_b128 v[162:165], v168 offset:3072
	ds_read_b128 v[172:175], v153
	ds_read_b128 v[176:179], v153 offset:1024
	ds_read_b128 v[180:183], v151
	ds_read_b128 v[184:187], v151 offset:1024
	ds_read_b128 v[188:191], v150
	ds_read_b128 v[192:195], v150 offset:1024
	ds_read_b128 v[196:199], v149
	ds_read_b128 v[200:203], v149 offset:1024
	global_load_lds_dwordx4 v[2:3], off
	v_lshl_add_u64 v[2:3], v[138:139], 1, s[16:17]
	v_readfirstlane_b32 s16, v170
	v_lshl_add_u64 v[2:3], v[136:137], 1, v[2:3]
	s_mov_b32 m0, s16
	s_nop 0
	global_load_lds_dwordx4 v[2:3], off
	s_barrier
	s_waitcnt lgkmcnt(0)
	s_setprio 1
	s_waitcnt lgkmcnt(0)
	v_mfma_f32_16x16x32_bf16 v[130:133], v[172:175], v[140:143], v[130:133]
	v_mfma_f32_16x16x32_bf16 v[126:129], v[172:175], v[158:161], v[126:129]
	v_mfma_f32_16x16x32_bf16 v[114:117], v[188:191], v[140:143], v[114:117]
	v_mfma_f32_16x16x32_bf16 v[110:113], v[188:191], v[158:161], v[110:113]
	v_mfma_f32_16x16x32_bf16 v[130:133], v[176:179], v[144:147], v[130:133]
	v_mfma_f32_16x16x32_bf16 v[126:129], v[176:179], v[162:165], v[126:129]
	v_mfma_f32_16x16x32_bf16 v[122:125], v[180:183], v[140:143], v[122:125]
	v_mfma_f32_16x16x32_bf16 v[118:121], v[180:183], v[158:161], v[118:121]
	v_mfma_f32_16x16x32_bf16 v[114:117], v[192:195], v[144:147], v[114:117]
	v_mfma_f32_16x16x32_bf16 v[110:113], v[192:195], v[162:165], v[110:113]
	v_mfma_f32_16x16x32_bf16 v[106:109], v[196:199], v[140:143], v[106:109]
	v_mfma_f32_16x16x32_bf16 v[102:105], v[196:199], v[158:161], v[102:105]
	v_mfma_f32_16x16x32_bf16 v[134:137], v[184:187], v[144:147], v[122:125]
	v_mfma_f32_16x16x32_bf16 v[168:171], v[184:187], v[162:165], v[118:121]
	v_mfma_f32_16x16x32_bf16 v[204:207], v[200:203], v[144:147], v[106:109]
	v_mfma_f32_16x16x32_bf16 v[208:211], v[200:203], v[162:165], v[102:105]
	s_setprio 0
	s_barrier
	s_nop 0
	s_nop 0
	ds_read_b128 v[102:105], v166
	ds_read_b128 v[106:109], v166 offset:1024
	ds_read_b128 v[118:121], v166 offset:2048
	ds_read_b128 v[122:125], v166 offset:3072
	s_barrier
; #define LDA(dst, b, h) _Pragma("unroll") for (int m = 0; m < 4; ++m) _Pragma("unroll") for (int k = 0; k < 2; ++k) \
;     dst[m][k] = *reinterpret_cast<const bf16x8*>((char*)SA(b, h) + lds_byte(wr * 64 + m * 16 + fr, k * 32 + fq * 8))
; #define LDB(dst, b, h) _Pragma("unroll") for (int n = 0; n < 2; ++n) _Pragma("unroll") for (int k = 0; k < 2; ++k) \
;     dst[n][k] = *reinterpret_cast<const bf16x8*>((char*)SB(b, h) + lds_byte(wc * 32 + n * 16 + fr, k * 32 + fq * 8))
; #define MMA(ai, bj, At_, Bt_) do { __builtin_amdgcn_s_setprio(1); \
;     _Pragma("unroll") for (int m = 0; m < 4; ++m) _Pragma("unroll") for (int n = 0; n < 2; ++n) _Pragma("unroll") for (int k = 0; k < 2; ++k) \
;       acc[ai][bj][m][n] = __builtin_amdgcn_mfma_f32_16x16x32_bf16(At_[m][k], Bt_[n][k], acc[ai][bj][m][n], 0, 0, 0); \
;     __builtin_amdgcn_s_setprio(0); } while (0)
; #define WAIT_V(n) asm volatile("s_waitcnt vmcnt(" #n ")" ::: "memory")
; #define WAIT_L(n) asm volatile("s_waitcnt lgkmcnt(" #n ")" ::: "memory")
; #define BAR __builtin_amdgcn_s_barrier()
; __device__ __forceinline__ void gemm256(const bf16_t* __restrict__ A, long lda, const bf16_t* __restrict__ Bt, long ldb, int K,
;                                         int brow, int bcol, char* smem, f32x4 (&acc)[2][2][4][2]) {
;     ...
;       LDB(B1, 0, 1); BAR; WAIT_L(0); MMA(0, 1, At, B1); BAR;
;       LDA(At, 0, 1); WAIT_V(4); BAR; WAIT_L(0); MMA(1, 0, At, B0); MMA(1, 1, At, B1); BAR; }
;     { LDB(B0, 1, 0); LDA(At, 1, 0); WAIT_V(2); BAR; WAIT_L(0); MMA(0, 0, At, B0); BAR;
	s_waitcnt lgkmcnt(0)
	s_setprio 1
	s_waitcnt lgkmcnt(3)
	v_mfma_f32_16x16x32_bf16 v[98:101], v[172:175], v[102:105], v[98:101]
	s_waitcnt lgkmcnt(1)
	v_mfma_f32_16x16x32_bf16 v[94:97], v[172:175], v[118:121], v[94:97]
	v_mfma_f32_16x16x32_bf16 v[82:85], v[188:191], v[102:105], v[82:85]
	v_mfma_f32_16x16x32_bf16 v[78:81], v[188:191], v[118:121], v[78:81]
	v_mfma_f32_16x16x32_bf16 v[98:101], v[176:179], v[106:109], v[98:101]
	s_waitcnt lgkmcnt(0)
	v_mfma_f32_16x16x32_bf16 v[94:97], v[176:179], v[122:125], v[94:97]
	v_mfma_f32_16x16x32_bf16 v[90:93], v[180:183], v[102:105], v[90:93]
	v_mfma_f32_16x16x32_bf16 v[86:89], v[180:183], v[118:121], v[86:89]
	v_mfma_f32_16x16x32_bf16 v[82:85], v[192:195], v[106:109], v[82:85]
	v_mfma_f32_16x16x32_bf16 v[78:81], v[192:195], v[122:125], v[78:81]
	v_mfma_f32_16x16x32_bf16 v[74:77], v[196:199], v[102:105], v[74:77]
	v_mfma_f32_16x16x32_bf16 v[70:73], v[196:199], v[118:121], v[70:73]
	v_mfma_f32_16x16x32_bf16 v[172:175], v[184:187], v[106:109], v[90:93]
	v_mfma_f32_16x16x32_bf16 v[176:179], v[184:187], v[122:125], v[86:89]
	v_mfma_f32_16x16x32_bf16 v[180:183], v[200:203], v[106:109], v[74:77]
	v_mfma_f32_16x16x32_bf16 v[184:187], v[200:203], v[122:125], v[70:73]
	s_setprio 0
	s_barrier
	s_nop 1
	ds_read_b128 v[70:73], v153 offset:16384
	ds_read_b128 v[74:77], v153 offset:17408
	ds_read_b128 v[86:89], v151 offset:16384
	ds_read_b128 v[90:93], v151 offset:17408
	ds_read_b128 v[188:191], v150 offset:16384
	ds_read_b128 v[192:195], v150 offset:17408
	ds_read_b128 v[196:199], v149 offset:16384
	ds_read_b128 v[200:203], v149 offset:17408
	s_waitcnt vmcnt(4)
	s_barrier
	s_waitcnt lgkmcnt(0)
	s_setprio 1
	s_waitcnt lgkmcnt(7)
	v_mfma_f32_16x16x32_bf16 v[66:69], v[70:73], v[140:143], v[66:69]
	v_mfma_f32_16x16x32_bf16 v[62:65], v[70:73], v[158:161], v[62:65]
	s_waitcnt lgkmcnt(3)
	v_mfma_f32_16x16x32_bf16 v[50:53], v[188:191], v[140:143], v[50:53]
	v_mfma_f32_16x16x32_bf16 v[46:49], v[188:191], v[158:161], v[46:49]
	v_mfma_f32_16x16x32_bf16 v[66:69], v[74:77], v[144:147], v[66:69]
	v_mfma_f32_16x16x32_bf16 v[62:65], v[74:77], v[162:165], v[62:65]
	v_mfma_f32_16x16x32_bf16 v[58:61], v[86:89], v[140:143], v[58:61]
	v_mfma_f32_16x16x32_bf16 v[54:57], v[86:89], v[158:161], v[54:57]
	s_waitcnt lgkmcnt(2)
	v_mfma_f32_16x16x32_bf16 v[50:53], v[192:195], v[144:147], v[50:53]
	v_mfma_f32_16x16x32_bf16 v[46:49], v[192:195], v[162:165], v[46:49]
	s_waitcnt lgkmcnt(1)
	v_mfma_f32_16x16x32_bf16 v[42:45], v[196:199], v[140:143], v[42:45]
	v_mfma_f32_16x16x32_bf16 v[38:41], v[196:199], v[158:161], v[38:41]
	v_mfma_f32_16x16x32_bf16 v[212:215], v[90:93], v[144:147], v[58:61]
	v_mfma_f32_16x16x32_bf16 v[216:219], v[90:93], v[162:165], v[54:57]
	s_waitcnt lgkmcnt(0)
	v_mfma_f32_16x16x32_bf16 v[138:141], v[200:203], v[144:147], v[42:45]
	v_mfma_f32_16x16x32_bf16 v[142:145], v[200:203], v[162:165], v[38:41]
	s_setprio 0
	s_setprio 1
	v_mfma_f32_16x16x32_bf16 v[34:37], v[70:73], v[102:105], v[34:37]
	v_mfma_f32_16x16x32_bf16 v[30:33], v[70:73], v[118:121], v[30:33]
	v_mfma_f32_16x16x32_bf16 v[18:21], v[188:191], v[102:105], v[18:21]
	v_mfma_f32_16x16x32_bf16 v[14:17], v[188:191], v[118:121], v[14:17]
	v_mfma_f32_16x16x32_bf16 v[34:37], v[74:77], v[106:109], v[34:37]
	v_mfma_f32_16x16x32_bf16 v[30:33], v[74:77], v[122:125], v[30:33]
	v_mfma_f32_16x16x32_bf16 v[26:29], v[86:89], v[102:105], v[26:29]
	v_mfma_f32_16x16x32_bf16 v[22:25], v[86:89], v[118:121], v[22:25]
	v_mfma_f32_16x16x32_bf16 v[18:21], v[192:195], v[106:109], v[18:21]
	v_mfma_f32_16x16x32_bf16 v[14:17], v[192:195], v[122:125], v[14:17]
	v_mfma_f32_16x16x32_bf16 v[10:13], v[196:199], v[102:105], v[10:13]
	v_mfma_f32_16x16x32_bf16 v[6:9], v[196:199], v[118:121], v[6:9]
	v_mfma_f32_16x16x32_bf16 v[158:161], v[90:93], v[106:109], v[26:29]
	v_mfma_f32_16x16x32_bf16 v[162:165], v[90:93], v[122:125], v[22:25]
	v_mfma_f32_16x16x32_bf16 v[188:191], v[200:203], v[106:109], v[10:13]
	v_mfma_f32_16x16x32_bf16 v[192:195], v[200:203], v[122:125], v[6:9]
	s_setprio 0
	s_barrier
	s_nop 1
	ds_read_b128 v[6:9], v157
	ds_read_b128 v[10:13], v157 offset:1024
	ds_read_b128 v[196:199], v157 offset:2048
	ds_read_b128 v[200:203], v157 offset:3072
	ds_read_b128 v[22:25], v153 offset:32768
	ds_read_b128 v[26:29], v153 offset:33792
	ds_read_b128 v[38:41], v151 offset:32768
	ds_read_b128 v[42:45], v151 offset:33792
	ds_read_b128 v[54:57], v150 offset:32768
	ds_read_b128 v[58:61], v150 offset:33792
	ds_read_b128 v[220:223], v149 offset:32768
	ds_read_b128 v[224:227], v149 offset:33792
	s_waitcnt vmcnt(2)
	s_barrier
; #define LDA(dst, b, h) _Pragma("unroll") for (int m = 0; m < 4; ++m) _Pragma("unroll") for (int k = 0; k < 2; ++k) \
;     dst[m][k] = *reinterpret_cast<const bf16x8*>((char*)SA(b, h) + lds_byte(wr * 64 + m * 16 + fr, k * 32 + fq * 8))
; #define LDB(dst, b, h) _Pragma("unroll") for (int n = 0; n < 2; ++n) _Pragma("unroll") for (int k = 0; k < 2; ++k) \
;     dst[n][k] = *reinterpret_cast<const bf16x8*>((char*)SB(b, h) + lds_byte(wc * 32 + n * 16 + fr, k * 32 + fq * 8))
; #define MMA(ai, bj, At_, Bt_) do { __builtin_amdgcn_s_setprio(1); \
;     _Pragma("unroll") for (int m = 0; m < 4; ++m) _Pragma("unroll") for (int n = 0; n < 2; ++n) _Pragma("unroll") for (int k = 0; k < 2; ++k) \
;       acc[ai][bj][m][n] = __builtin_amdgcn_mfma_f32_16x16x32_bf16(At_[m][k], Bt_[n][k], acc[ai][bj][m][n], 0, 0, 0); \
;     __builtin_amdgcn_s_setprio(0); } while (0)
; #define WAIT_V(n) asm volatile("s_waitcnt vmcnt(" #n ")" ::: "memory")
; #define WAIT_L(n) asm volatile("s_waitcnt lgkmcnt(" #n ")" ::: "memory")
; #define BAR __builtin_amdgcn_s_barrier()
; __device__ __forceinline__ void gemm256(const bf16_t* __restrict__ A, long lda, const bf16_t* __restrict__ Bt, long ldb, int K,
;                                         int brow, int bcol, char* smem, f32x4 (&acc)[2][2][4][2]) {
;     ...
;     { LDB(B0, 1, 0); LDA(At, 1, 0); WAIT_V(2); BAR; WAIT_L(0); MMA(0, 0, At, B0); BAR;
;       LDB(B1, 1, 1); WAIT_V(0); BAR; WAIT_L(0); MMA(0, 1, At, B1); BAR;
;       LDA(At, 1, 1); BAR; WAIT_L(0); MMA(1, 0, At, B0); MMA(1, 1, At, B1); BAR; }
;     if (wr == 0) BAR;
	s_waitcnt lgkmcnt(0)
	s_setprio 1
	s_waitcnt lgkmcnt(7)
	v_mfma_f32_16x16x32_bf16 v[70:73], v[22:25], v[6:9], v[130:133]
	s_waitcnt lgkmcnt(6)
	v_mfma_f32_16x16x32_bf16 v[122:125], v[26:29], v[10:13], v[70:73]
	v_mfma_f32_16x16x32_bf16 v[70:73], v[22:25], v[196:199], v[126:129]
	v_mfma_f32_16x16x32_bf16 v[118:121], v[26:29], v[200:203], v[70:73]
	s_waitcnt lgkmcnt(5)
	v_mfma_f32_16x16x32_bf16 v[70:73], v[38:41], v[6:9], v[134:137]
	s_waitcnt lgkmcnt(4)
	v_mfma_f32_16x16x32_bf16 v[106:109], v[42:45], v[10:13], v[70:73]
	v_mfma_f32_16x16x32_bf16 v[70:73], v[38:41], v[196:199], v[168:171]
	v_mfma_f32_16x16x32_bf16 v[102:105], v[42:45], v[200:203], v[70:73]
	s_waitcnt lgkmcnt(3)
	v_mfma_f32_16x16x32_bf16 v[70:73], v[54:57], v[6:9], v[114:117]
	s_waitcnt lgkmcnt(2)
	v_mfma_f32_16x16x32_bf16 v[90:93], v[58:61], v[10:13], v[70:73]
	v_mfma_f32_16x16x32_bf16 v[70:73], v[54:57], v[196:199], v[110:113]
	v_mfma_f32_16x16x32_bf16 v[86:89], v[58:61], v[200:203], v[70:73]
	s_waitcnt lgkmcnt(1)
	v_mfma_f32_16x16x32_bf16 v[70:73], v[220:223], v[6:9], v[204:207]
	s_waitcnt lgkmcnt(0)
	v_mfma_f32_16x16x32_bf16 v[74:77], v[224:227], v[10:13], v[70:73]
	v_mfma_f32_16x16x32_bf16 v[70:73], v[220:223], v[196:199], v[208:211]
	v_mfma_f32_16x16x32_bf16 v[70:73], v[224:227], v[200:203], v[70:73]
	s_setprio 0
	s_barrier
	ds_read_b128 v[134:137], v154
	ds_read_b128 v[166:169], v154 offset:1024
	ds_read_b128 v[204:207], v154 offset:2048
	ds_read_b128 v[154:157], v154 offset:3072
	s_waitcnt vmcnt(0)
	s_barrier
	s_waitcnt lgkmcnt(0)
	s_setprio 1
	s_waitcnt lgkmcnt(3)
	v_mfma_f32_16x16x32_bf16 v[98:101], v[22:25], v[134:137], v[98:101]
	s_waitcnt lgkmcnt(1)
	v_mfma_f32_16x16x32_bf16 v[22:25], v[22:25], v[204:207], v[94:97]
	s_waitcnt lgkmcnt(0)
	v_mfma_f32_16x16x32_bf16 v[126:129], v[26:29], v[154:157], v[22:25]
	v_mfma_f32_16x16x32_bf16 v[22:25], v[38:41], v[134:137], v[172:175]
	v_mfma_f32_16x16x32_bf16 v[114:117], v[42:45], v[166:169], v[22:25]
	v_mfma_f32_16x16x32_bf16 v[22:25], v[38:41], v[204:207], v[176:179]
	v_mfma_f32_16x16x32_bf16 v[110:113], v[42:45], v[154:157], v[22:25]
	v_mfma_f32_16x16x32_bf16 v[22:25], v[54:57], v[134:137], v[82:85]
	v_mfma_f32_16x16x32_bf16 v[130:133], v[26:29], v[166:169], v[98:101]
	v_mfma_f32_16x16x32_bf16 v[98:101], v[58:61], v[166:169], v[22:25]
	v_mfma_f32_16x16x32_bf16 v[22:25], v[54:57], v[204:207], v[78:81]
	v_mfma_f32_16x16x32_bf16 v[94:97], v[58:61], v[154:157], v[22:25]
	v_mfma_f32_16x16x32_bf16 v[22:25], v[220:223], v[134:137], v[180:183]
	v_mfma_f32_16x16x32_bf16 v[82:85], v[224:227], v[166:169], v[22:25]
	v_mfma_f32_16x16x32_bf16 v[22:25], v[220:223], v[204:207], v[184:187]
	v_mfma_f32_16x16x32_bf16 v[78:81], v[224:227], v[154:157], v[22:25]
	s_setprio 0
	s_barrier
	ds_read_b128 v[170:173], v153 offset:49152
	ds_read_b128 v[174:177], v153 offset:50176
	ds_read_b128 v[178:181], v151 offset:49152
	ds_read_b128 v[182:185], v151 offset:50176
	ds_read_b128 v[208:211], v150 offset:49152
	ds_read_b128 v[150:153], v150 offset:50176
	ds_read_b128 v[220:223], v149 offset:49152
	ds_read_b128 v[146:149], v149 offset:50176
	s_barrier
	s_waitcnt lgkmcnt(0)
	s_setprio 1
	s_waitcnt lgkmcnt(7)
	v_mfma_f32_16x16x32_bf16 v[22:25], v[170:173], v[6:9], v[66:69]
	s_waitcnt lgkmcnt(6)
	v_mfma_f32_16x16x32_bf16 v[58:61], v[174:177], v[10:13], v[22:25]
	v_mfma_f32_16x16x32_bf16 v[22:25], v[170:173], v[196:199], v[62:65]
	v_mfma_f32_16x16x32_bf16 v[54:57], v[174:177], v[200:203], v[22:25]
	s_waitcnt lgkmcnt(5)
	v_mfma_f32_16x16x32_bf16 v[22:25], v[178:181], v[6:9], v[212:215]
	s_waitcnt lgkmcnt(4)
	v_mfma_f32_16x16x32_bf16 v[42:45], v[182:185], v[10:13], v[22:25]
	v_mfma_f32_16x16x32_bf16 v[22:25], v[178:181], v[196:199], v[216:219]
	v_mfma_f32_16x16x32_bf16 v[38:41], v[182:185], v[200:203], v[22:25]
	s_waitcnt lgkmcnt(3)
	v_mfma_f32_16x16x32_bf16 v[22:25], v[208:211], v[6:9], v[50:53]
	s_waitcnt lgkmcnt(1)
	v_mfma_f32_16x16x32_bf16 v[6:9], v[220:223], v[6:9], v[138:141]
	v_mfma_f32_16x16x32_bf16 v[26:29], v[150:153], v[10:13], v[22:25]
	v_mfma_f32_16x16x32_bf16 v[22:25], v[208:211], v[196:199], v[46:49]
	s_waitcnt lgkmcnt(0)
	v_mfma_f32_16x16x32_bf16 v[10:13], v[146:149], v[10:13], v[6:9]
	v_mfma_f32_16x16x32_bf16 v[6:9], v[220:223], v[196:199], v[142:145]
	v_mfma_f32_16x16x32_bf16 v[22:25], v[150:153], v[200:203], v[22:25]
	v_mfma_f32_16x16x32_bf16 v[6:9], v[146:149], v[200:203], v[6:9]
	s_setprio 0
	s_setprio 1
	v_mfma_f32_16x16x32_bf16 v[30:33], v[170:173], v[204:207], v[30:33]
	v_mfma_f32_16x16x32_bf16 v[62:65], v[174:177], v[154:157], v[30:33]
	v_mfma_f32_16x16x32_bf16 v[30:33], v[178:181], v[134:137], v[158:161]
	v_mfma_f32_16x16x32_bf16 v[50:53], v[182:185], v[166:169], v[30:33]
	v_mfma_f32_16x16x32_bf16 v[30:33], v[178:181], v[204:207], v[162:165]
	v_mfma_f32_16x16x32_bf16 v[14:17], v[208:211], v[204:207], v[14:17]
	v_mfma_f32_16x16x32_bf16 v[34:37], v[170:173], v[134:137], v[34:37]
	v_mfma_f32_16x16x32_bf16 v[46:49], v[182:185], v[154:157], v[30:33]
	v_mfma_f32_16x16x32_bf16 v[18:21], v[208:211], v[134:137], v[18:21]
	v_mfma_f32_16x16x32_bf16 v[30:33], v[150:153], v[154:157], v[14:17]
	v_mfma_f32_16x16x32_bf16 v[14:17], v[220:223], v[134:137], v[188:191]
	v_mfma_f32_16x16x32_bf16 v[66:69], v[174:177], v[166:169], v[34:37]
	v_mfma_f32_16x16x32_bf16 v[34:37], v[150:153], v[166:169], v[18:21]
	v_mfma_f32_16x16x32_bf16 v[18:21], v[146:149], v[166:169], v[14:17]
	v_mfma_f32_16x16x32_bf16 v[14:17], v[220:223], v[204:207], v[192:195]
	v_mfma_f32_16x16x32_bf16 v[14:17], v[146:149], v[154:157], v[14:17]
	s_setprio 0
	v_cmp_gt_u32_e32 vcc, s78, v0
	s_barrier
	s_and_saveexec_b64 s[16:17], vcc
	s_cbranch_execz .LBB0_407
	s_barrier
	s_branch .LBB0_407

; #define STAGE(P, BASE, LD, br, kt) do { const long _g = (long)(br) * (LD) + (long)(kt) * 64; \
;     _Pragma("unroll") for (int _i = 0; _i < 2; ++_i) { const int _b = tid * 16 + _i * 8192; int _r, _c; stage_rc(_b, _r, _c); \
;       __builtin_amdgcn_global_load_lds((const G_AS1 unsigned*)((BASE) + _g + (long)_r * (LD) + _c), \
;         (LAS unsigned*)((char*)(P) + _b), 16, 0, 0); } } while (0)
; #define LDA(dst, b, h) _Pragma("unroll") for (int m = 0; m < 4; ++m) _Pragma("unroll") for (int k = 0; k < 2; ++k) \
;     dst[m][k] = *reinterpret_cast<const bf16x8*>((char*)SA(b, h) + lds_byte(wr * 64 + m * 16 + fr, k * 32 + fq * 8))
; #define LDB(dst, b, h) _Pragma("unroll") for (int n = 0; n < 2; ++n) _Pragma("unroll") for (int k = 0; k < 2; ++k) \
;     dst[n][k] = *reinterpret_cast<const bf16x8*>((char*)SB(b, h) + lds_byte(wc * 32 + n * 16 + fr, k * 32 + fq * 8))
; #define MMA(ai, bj, At_, Bt_) do { __builtin_amdgcn_s_setprio(1); \
;     _Pragma("unroll") for (int m = 0; m < 4; ++m) _Pragma("unroll") for (int n = 0; n < 2; ++n) _Pragma("unroll") for (int k = 0; k < 2; ++k) \
;       acc[ai][bj][m][n] = __builtin_amdgcn_mfma_f32_16x16x32_bf16(At_[m][k], Bt_[n][k], acc[ai][bj][m][n], 0, 0, 0); \
;     __builtin_amdgcn_s_setprio(0); } while (0)
; #define WAIT_L(n) asm volatile("s_waitcnt lgkmcnt(" #n ")" ::: "memory")
; #define BAR __builtin_amdgcn_s_barrier()
; #define SCHED __builtin_amdgcn_sched_barrier(0)
; __device__ __forceinline__ void gemm256(const bf16_t* __restrict__ A, long lda, const bf16_t* __restrict__ Bt, long ldb, int K,
;                                         int brow, int bcol, char* smem, f32x4 (&acc)[2][2][4][2]) {
;     ...
;         LDB(B0, 0, 0); SCHED; LDA(At, 0, 0); STAGE(SA(1, 1), A, lda, brow + 128, t + 1);
;         WAIT_L(8); BAR; WAIT_L(0); MMA(0, 0, At, B0); BAR; SCHED;
;         LDB(B1, 0, 1); STAGE(SB(0, 0), Bt, ldb, bcol, t + 2);
;         BAR; WAIT_L(0); MMA(0, 1, At, B1); BAR;
;         LDA(At, 0, 1); STAGE(SA(0, 0), A, lda, brow, t + 2);
;         BAR; WAIT_L(0); MMA(1, 0, At, B0); BAR; SCHED;
.LBB0_509:
	s_nop 0
	ds_read_b128 v[168:171], v164
	ds_read_b128 v[172:175], v164 offset:1024
	ds_read_b128 v[176:179], v164 offset:2048
	ds_read_b128 v[180:183], v164 offset:3072
	v_add_u32_e32 v165, 0xc000, v5
	v_lshl_add_u64 v[232:233], s[94:95], 0, v[142:143]
	v_readfirstlane_b32 s9, v165
	v_lshl_add_u64 v[166:167], v[232:233], 0, s[60:61]
	s_mov_b32 m0, s9
	ds_read_b128 v[184:187], v149
	ds_read_b128 v[188:191], v149 offset:1024
	ds_read_b128 v[192:195], v148
	ds_read_b128 v[196:199], v148 offset:1024
	ds_read_b128 v[200:203], v147
	ds_read_b128 v[204:207], v147 offset:1024
	ds_read_b128 v[208:211], v145
	ds_read_b128 v[212:215], v145 offset:1024
	global_load_lds_dwordx4 v[166:167], off
	v_add_u32_e32 v166, 0xe000, v5
	v_lshl_add_u64 v[234:235], s[94:95], 0, v[140:141]
	v_readfirstlane_b32 s9, v166
	v_lshl_add_u64 v[216:217], v[234:235], 0, s[60:61]
	s_mov_b32 m0, s9
	s_nop 0
	global_load_lds_dwordx4 v[216:217], off
	s_waitcnt lgkmcnt(8)
	s_barrier
	s_waitcnt lgkmcnt(0)
	s_setprio 1
	s_waitcnt lgkmcnt(0)
	v_mfma_f32_16x16x32_bf16 v[130:133], v[184:187], v[168:171], v[130:133]
	v_mfma_f32_16x16x32_bf16 v[126:129], v[184:187], v[176:179], v[126:129]
	v_mfma_f32_16x16x32_bf16 v[122:125], v[192:195], v[168:171], v[122:125]
	v_mfma_f32_16x16x32_bf16 v[118:121], v[192:195], v[176:179], v[118:121]
	v_mfma_f32_16x16x32_bf16 v[114:117], v[200:203], v[168:171], v[114:117]
	v_mfma_f32_16x16x32_bf16 v[110:113], v[200:203], v[176:179], v[110:113]
	v_mfma_f32_16x16x32_bf16 v[106:109], v[208:211], v[168:171], v[106:109]
	v_mfma_f32_16x16x32_bf16 v[102:105], v[208:211], v[176:179], v[102:105]
	v_mfma_f32_16x16x32_bf16 v[130:133], v[188:191], v[172:175], v[130:133]
	v_mfma_f32_16x16x32_bf16 v[126:129], v[188:191], v[180:183], v[126:129]
	v_mfma_f32_16x16x32_bf16 v[122:125], v[196:199], v[172:175], v[122:125]
	v_mfma_f32_16x16x32_bf16 v[118:121], v[196:199], v[180:183], v[118:121]
	v_mfma_f32_16x16x32_bf16 v[114:117], v[204:207], v[172:175], v[114:117]
	v_mfma_f32_16x16x32_bf16 v[110:113], v[204:207], v[180:183], v[110:113]
	v_mfma_f32_16x16x32_bf16 v[106:109], v[212:215], v[172:175], v[106:109]
	v_mfma_f32_16x16x32_bf16 v[102:105], v[212:215], v[180:183], v[102:105]
	s_setprio 0
	s_barrier
	v_lshl_add_u64 v[238:239], s[94:95], 0, v[138:139]
	v_readfirstlane_b32 s9, v144
	v_lshl_add_u64 v[242:243], v[238:239], 0, s[82:83]
	s_mov_b32 m0, s9
	s_nop 0
	ds_read_b128 v[216:219], v161
	ds_read_b128 v[220:223], v161 offset:1024
	ds_read_b128 v[224:227], v161 offset:2048
	ds_read_b128 v[228:231], v161 offset:3072
	global_load_lds_dwordx4 v[242:243], off
	v_lshl_add_u64 v[242:243], s[94:95], 0, v[136:137]
	v_readfirstlane_b32 s9, v150
	v_lshl_add_u64 v[244:245], v[242:243], 0, s[82:83]
	s_mov_b32 m0, s9
	s_nop 0
	global_load_lds_dwordx4 v[244:245], off
	s_barrier
	s_waitcnt lgkmcnt(0)
	s_setprio 1
	s_waitcnt lgkmcnt(0)
	v_mfma_f32_16x16x32_bf16 v[98:101], v[184:187], v[216:219], v[98:101]
	v_mfma_f32_16x16x32_bf16 v[94:97], v[184:187], v[224:227], v[94:97]
	v_mfma_f32_16x16x32_bf16 v[90:93], v[192:195], v[216:219], v[90:93]
	v_mfma_f32_16x16x32_bf16 v[86:89], v[192:195], v[224:227], v[86:89]
	v_mfma_f32_16x16x32_bf16 v[82:85], v[200:203], v[216:219], v[82:85]
	v_mfma_f32_16x16x32_bf16 v[78:81], v[200:203], v[224:227], v[78:81]
	v_mfma_f32_16x16x32_bf16 v[74:77], v[208:211], v[216:219], v[74:77]
	v_mfma_f32_16x16x32_bf16 v[70:73], v[208:211], v[224:227], v[70:73]
	v_mfma_f32_16x16x32_bf16 v[98:101], v[188:191], v[220:223], v[98:101]
	v_mfma_f32_16x16x32_bf16 v[94:97], v[188:191], v[228:231], v[94:97]
	v_mfma_f32_16x16x32_bf16 v[90:93], v[196:199], v[220:223], v[90:93]
	v_mfma_f32_16x16x32_bf16 v[86:89], v[196:199], v[228:231], v[86:89]
	v_mfma_f32_16x16x32_bf16 v[82:85], v[204:207], v[220:223], v[82:85]
	v_mfma_f32_16x16x32_bf16 v[78:81], v[204:207], v[228:231], v[78:81]
	v_mfma_f32_16x16x32_bf16 v[74:77], v[212:215], v[220:223], v[74:77]
	v_mfma_f32_16x16x32_bf16 v[70:73], v[212:215], v[228:231], v[70:73]
	s_setprio 0
	v_readfirstlane_b32 s9, v5
	v_lshl_add_u64 v[244:245], v[232:233], 0, s[92:93]
	s_mov_b32 m0, s9
	v_readfirstlane_b32 s9, v146
	s_barrier
	s_nop 0
	ds_read_b128 v[184:187], v149 offset:16384
	ds_read_b128 v[188:191], v149 offset:17408
	ds_read_b128 v[192:195], v148 offset:16384
	ds_read_b128 v[196:199], v148 offset:17408
	ds_read_b128 v[200:203], v147 offset:16384
	ds_read_b128 v[204:207], v147 offset:17408
	ds_read_b128 v[208:211], v145 offset:16384
	ds_read_b128 v[212:215], v145 offset:17408
	global_load_lds_dwordx4 v[244:245], off
	v_lshl_add_u64 v[244:245], v[234:235], 0, s[92:93]
	s_mov_b32 m0, s9
	s_nop 0
	global_load_lds_dwordx4 v[244:245], off
	s_barrier
	s_waitcnt lgkmcnt(0)
	s_setprio 1
	s_waitcnt lgkmcnt(0)
	v_mfma_f32_16x16x32_bf16 v[66:69], v[184:187], v[168:171], v[66:69]
	v_mfma_f32_16x16x32_bf16 v[62:65], v[184:187], v[176:179], v[62:65]
	v_mfma_f32_16x16x32_bf16 v[58:61], v[192:195], v[168:171], v[58:61]
	v_mfma_f32_16x16x32_bf16 v[54:57], v[192:195], v[176:179], v[54:57]
	v_mfma_f32_16x16x32_bf16 v[50:53], v[200:203], v[168:171], v[50:53]
	v_mfma_f32_16x16x32_bf16 v[46:49], v[200:203], v[176:179], v[46:49]
	v_mfma_f32_16x16x32_bf16 v[42:45], v[208:211], v[168:171], v[42:45]
	v_mfma_f32_16x16x32_bf16 v[38:41], v[208:211], v[176:179], v[38:41]
	v_mfma_f32_16x16x32_bf16 v[66:69], v[188:191], v[172:175], v[66:69]
	v_mfma_f32_16x16x32_bf16 v[62:65], v[188:191], v[180:183], v[62:65]
	v_mfma_f32_16x16x32_bf16 v[58:61], v[196:199], v[172:175], v[58:61]
	v_mfma_f32_16x16x32_bf16 v[54:57], v[196:199], v[180:183], v[54:57]
	v_mfma_f32_16x16x32_bf16 v[50:53], v[204:207], v[172:175], v[50:53]
	v_mfma_f32_16x16x32_bf16 v[46:49], v[204:207], v[180:183], v[46:49]
	v_mfma_f32_16x16x32_bf16 v[42:45], v[212:215], v[172:175], v[42:45]
	v_mfma_f32_16x16x32_bf16 v[38:41], v[212:215], v[180:183], v[38:41]
	s_setprio 0
	s_barrier
; #define STAGE(P, BASE, LD, br, kt) do { const long _g = (long)(br) * (LD) + (long)(kt) * 64; \
;     _Pragma("unroll") for (int _i = 0; _i < 2; ++_i) { const int _b = tid * 16 + _i * 8192; int _r, _c; stage_rc(_b, _r, _c); \
;       __builtin_amdgcn_global_load_lds((const G_AS1 unsigned*)((BASE) + _g + (long)_r * (LD) + _c), \
;         (LAS unsigned*)((char*)(P) + _b), 16, 0, 0); } } while (0)
; #define LDA(dst, b, h) _Pragma("unroll") for (int m = 0; m < 4; ++m) _Pragma("unroll") for (int k = 0; k < 2; ++k) \
;     dst[m][k] = *reinterpret_cast<const bf16x8*>((char*)SA(b, h) + lds_byte(wr * 64 + m * 16 + fr, k * 32 + fq * 8))
; #define LDB(dst, b, h) _Pragma("unroll") for (int n = 0; n < 2; ++n) _Pragma("unroll") for (int k = 0; k < 2; ++k) \
;     dst[n][k] = *reinterpret_cast<const bf16x8*>((char*)SB(b, h) + lds_byte(wc * 32 + n * 16 + fr, k * 32 + fq * 8))
; #define MMA(ai, bj, At_, Bt_) do { __builtin_amdgcn_s_setprio(1); \
;     _Pragma("unroll") for (int m = 0; m < 4; ++m) _Pragma("unroll") for (int n = 0; n < 2; ++n) _Pragma("unroll") for (int k = 0; k < 2; ++k) \
;       acc[ai][bj][m][n] = __builtin_amdgcn_mfma_f32_16x16x32_bf16(At_[m][k], Bt_[n][k], acc[ai][bj][m][n], 0, 0, 0); \
;     __builtin_amdgcn_s_setprio(0); } while (0)
; #define WAIT_V(n) asm volatile("s_waitcnt vmcnt(" #n ")" ::: "memory")
; #define WAIT_L(n) asm volatile("s_waitcnt lgkmcnt(" #n ")" ::: "memory")
; #define BAR __builtin_amdgcn_s_barrier()
; #define SCHED __builtin_amdgcn_sched_barrier(0)
; __device__ __forceinline__ void gemm256(const bf16_t* __restrict__ A, long lda, const bf16_t* __restrict__ Bt, long ldb, int K,
;                                         int brow, int bcol, char* smem, f32x4 (&acc)[2][2][4][2]) {
;     ...
;         STAGE(SB(0, 1), Bt, ldb, bcol + 128, t + 2);
;         WAIT_V(6); BAR; MMA(1, 1, At, B1); BAR;
;         LDB(B0, 1, 0); SCHED; LDA(At, 1, 0); STAGE(SA(0, 1), A, lda, brow + 128, t + 2);
;         WAIT_L(8); BAR; WAIT_L(0); MMA(0, 0, At, B0); BAR; SCHED;
;         LDB(B1, 1, 1); STAGE(SB(1, 0), Bt, ldb, bcol, t + 3);
;         BAR; WAIT_L(0); MMA(0, 1, At, B1); BAR;
;         LDA(At, 1, 1); STAGE(SA(1, 0), A, lda, brow, t + 3);
;         BAR; WAIT_L(0); MMA(1, 0, At, B0); BAR; SCHED;
	v_readfirstlane_b32 s9, v153
	v_lshl_add_u64 v[168:169], v[238:239], 0, s[90:91]
	s_mov_b32 m0, s9
	v_readfirstlane_b32 s9, v154
	global_load_lds_dwordx4 v[168:169], off
	v_lshl_add_u64 v[168:169], v[242:243], 0, s[90:91]
	s_mov_b32 m0, s9
	s_nop 0
	global_load_lds_dwordx4 v[168:169], off
	s_waitcnt vmcnt(6)
	s_barrier
	s_setprio 1
	v_mfma_f32_16x16x32_bf16 v[34:37], v[184:187], v[216:219], v[34:37]
	v_mfma_f32_16x16x32_bf16 v[30:33], v[184:187], v[224:227], v[30:33]
	v_mfma_f32_16x16x32_bf16 v[26:29], v[192:195], v[216:219], v[26:29]
	v_mfma_f32_16x16x32_bf16 v[22:25], v[192:195], v[224:227], v[22:25]
	v_mfma_f32_16x16x32_bf16 v[18:21], v[200:203], v[216:219], v[18:21]
	v_mfma_f32_16x16x32_bf16 v[14:17], v[200:203], v[224:227], v[14:17]
	v_mfma_f32_16x16x32_bf16 v[10:13], v[208:211], v[216:219], v[10:13]
	v_mfma_f32_16x16x32_bf16 v[6:9], v[208:211], v[224:227], v[6:9]
	v_mfma_f32_16x16x32_bf16 v[34:37], v[188:191], v[220:223], v[34:37]
	v_mfma_f32_16x16x32_bf16 v[30:33], v[188:191], v[228:231], v[30:33]
	v_mfma_f32_16x16x32_bf16 v[26:29], v[196:199], v[220:223], v[26:29]
	v_mfma_f32_16x16x32_bf16 v[22:25], v[196:199], v[228:231], v[22:25]
	v_mfma_f32_16x16x32_bf16 v[18:21], v[204:207], v[220:223], v[18:21]
	v_mfma_f32_16x16x32_bf16 v[14:17], v[204:207], v[228:231], v[14:17]
	v_mfma_f32_16x16x32_bf16 v[10:13], v[212:215], v[220:223], v[10:13]
	v_mfma_f32_16x16x32_bf16 v[6:9], v[212:215], v[228:231], v[6:9]
	s_setprio 0
	s_barrier
	s_nop 0
	ds_read_b128 v[168:171], v152
	ds_read_b128 v[172:175], v152 offset:1024
	ds_read_b128 v[176:179], v152 offset:2048
	ds_read_b128 v[180:183], v152 offset:3072
	v_readfirstlane_b32 s9, v155
	v_lshl_add_u64 v[216:217], v[232:233], 0, s[54:55]
	s_mov_b32 m0, s9
	v_readfirstlane_b32 s9, v156
	ds_read_b128 v[184:187], v149 offset:32768
	ds_read_b128 v[188:191], v149 offset:33792
	ds_read_b128 v[192:195], v148 offset:32768
	ds_read_b128 v[196:199], v148 offset:33792
	ds_read_b128 v[200:203], v147 offset:32768
	ds_read_b128 v[204:207], v147 offset:33792
	ds_read_b128 v[208:211], v145 offset:32768
	ds_read_b128 v[212:215], v145 offset:33792
	global_load_lds_dwordx4 v[216:217], off
	v_lshl_add_u64 v[216:217], v[234:235], 0, s[54:55]
	s_mov_b32 m0, s9
	s_nop 0
	global_load_lds_dwordx4 v[216:217], off
	s_waitcnt lgkmcnt(8)
	s_barrier
	s_waitcnt lgkmcnt(0)
	s_setprio 1
	s_waitcnt lgkmcnt(0)
	v_mfma_f32_16x16x32_bf16 v[130:133], v[184:187], v[168:171], v[130:133]
	v_mfma_f32_16x16x32_bf16 v[126:129], v[184:187], v[176:179], v[126:129]
	v_mfma_f32_16x16x32_bf16 v[122:125], v[192:195], v[168:171], v[122:125]
	v_mfma_f32_16x16x32_bf16 v[118:121], v[192:195], v[176:179], v[118:121]
	v_mfma_f32_16x16x32_bf16 v[114:117], v[200:203], v[168:171], v[114:117]
	v_mfma_f32_16x16x32_bf16 v[110:113], v[200:203], v[176:179], v[110:113]
	v_mfma_f32_16x16x32_bf16 v[106:109], v[208:211], v[168:171], v[106:109]
	v_mfma_f32_16x16x32_bf16 v[102:105], v[208:211], v[176:179], v[102:105]
	v_mfma_f32_16x16x32_bf16 v[130:133], v[188:191], v[172:175], v[130:133]
	v_mfma_f32_16x16x32_bf16 v[126:129], v[188:191], v[180:183], v[126:129]
	v_mfma_f32_16x16x32_bf16 v[122:125], v[196:199], v[172:175], v[122:125]
	v_mfma_f32_16x16x32_bf16 v[118:121], v[196:199], v[180:183], v[118:121]
	v_mfma_f32_16x16x32_bf16 v[114:117], v[204:207], v[172:175], v[114:117]
	v_mfma_f32_16x16x32_bf16 v[110:113], v[204:207], v[180:183], v[110:113]
	v_mfma_f32_16x16x32_bf16 v[106:109], v[212:215], v[172:175], v[106:109]
	v_mfma_f32_16x16x32_bf16 v[102:105], v[212:215], v[180:183], v[102:105]
	s_setprio 0
	s_barrier
	v_readfirstlane_b32 s9, v157
	v_lshl_add_u64 v[244:245], v[238:239], 0, s[86:87]
	s_mov_b32 m0, s9
	v_readfirstlane_b32 s9, v158
	s_nop 0
	ds_read_b128 v[216:219], v151
	ds_read_b128 v[220:223], v151 offset:1024
	ds_read_b128 v[224:227], v151 offset:2048
	ds_read_b128 v[228:231], v151 offset:3072
	global_load_lds_dwordx4 v[244:245], off
	v_lshl_add_u64 v[244:245], v[242:243], 0, s[86:87]
	s_mov_b32 m0, s9
	s_nop 0
	global_load_lds_dwordx4 v[244:245], off
	s_barrier
	s_waitcnt lgkmcnt(0)
	s_setprio 1
	s_waitcnt lgkmcnt(0)
	v_mfma_f32_16x16x32_bf16 v[98:101], v[184:187], v[216:219], v[98:101]
	v_mfma_f32_16x16x32_bf16 v[94:97], v[184:187], v[224:227], v[94:97]
	v_mfma_f32_16x16x32_bf16 v[90:93], v[192:195], v[216:219], v[90:93]
	v_mfma_f32_16x16x32_bf16 v[86:89], v[192:195], v[224:227], v[86:89]
	v_mfma_f32_16x16x32_bf16 v[82:85], v[200:203], v[216:219], v[82:85]
	v_mfma_f32_16x16x32_bf16 v[78:81], v[200:203], v[224:227], v[78:81]
	v_mfma_f32_16x16x32_bf16 v[74:77], v[208:211], v[216:219], v[74:77]
	v_mfma_f32_16x16x32_bf16 v[70:73], v[208:211], v[224:227], v[70:73]
	v_mfma_f32_16x16x32_bf16 v[98:101], v[188:191], v[220:223], v[98:101]
	v_mfma_f32_16x16x32_bf16 v[94:97], v[188:191], v[228:231], v[94:97]
	v_mfma_f32_16x16x32_bf16 v[90:93], v[196:199], v[220:223], v[90:93]
	v_mfma_f32_16x16x32_bf16 v[86:89], v[196:199], v[228:231], v[86:89]
	v_mfma_f32_16x16x32_bf16 v[82:85], v[204:207], v[220:223], v[82:85]
	v_mfma_f32_16x16x32_bf16 v[78:81], v[204:207], v[228:231], v[78:81]
	v_mfma_f32_16x16x32_bf16 v[74:77], v[212:215], v[220:223], v[74:77]
	v_mfma_f32_16x16x32_bf16 v[70:73], v[212:215], v[228:231], v[70:73]
	s_setprio 0
	v_readfirstlane_b32 s9, v159
	v_lshl_add_u64 v[232:233], v[232:233], 0, s[40:41]
	s_mov_b32 m0, s9
	v_readfirstlane_b32 s9, v160
	s_barrier
	s_nop 0
	ds_read_b128 v[184:187], v149 offset:49152
	ds_read_b128 v[188:191], v149 offset:50176
	ds_read_b128 v[192:195], v148 offset:49152
	ds_read_b128 v[196:199], v148 offset:50176
	ds_read_b128 v[200:203], v147 offset:49152
	ds_read_b128 v[204:207], v147 offset:50176
	ds_read_b128 v[208:211], v145 offset:49152
	ds_read_b128 v[212:215], v145 offset:50176
	global_load_lds_dwordx4 v[232:233], off
	v_lshl_add_u64 v[232:233], v[234:235], 0, s[40:41]
	s_mov_b32 m0, s9
	s_nop 0
	global_load_lds_dwordx4 v[232:233], off
	s_barrier
; #define STAGE(P, BASE, LD, br, kt) do { const long _g = (long)(br) * (LD) + (long)(kt) * 64; \
;     _Pragma("unroll") for (int _i = 0; _i < 2; ++_i) { const int _b = tid * 16 + _i * 8192; int _r, _c; stage_rc(_b, _r, _c); \
;       __builtin_amdgcn_global_load_lds((const G_AS1 unsigned*)((BASE) + _g + (long)_r * (LD) + _c), \
;         (LAS unsigned*)((char*)(P) + _b), 16, 0, 0); } } while (0)
; #define LDA(dst, b, h) _Pragma("unroll") for (int m = 0; m < 4; ++m) _Pragma("unroll") for (int k = 0; k < 2; ++k) \
;     dst[m][k] = *reinterpret_cast<const bf16x8*>((char*)SA(b, h) + lds_byte(wr * 64 + m * 16 + fr, k * 32 + fq * 8))
; #define LDB(dst, b, h) _Pragma("unroll") for (int n = 0; n < 2; ++n) _Pragma("unroll") for (int k = 0; k < 2; ++k) \
;     dst[n][k] = *reinterpret_cast<const bf16x8*>((char*)SB(b, h) + lds_byte(wc * 32 + n * 16 + fr, k * 32 + fq * 8))
; #define MMA(ai, bj, At_, Bt_) do { __builtin_amdgcn_s_setprio(1); \
;     _Pragma("unroll") for (int m = 0; m < 4; ++m) _Pragma("unroll") for (int n = 0; n < 2; ++n) _Pragma("unroll") for (int k = 0; k < 2; ++k) \
;       acc[ai][bj][m][n] = __builtin_amdgcn_mfma_f32_16x16x32_bf16(At_[m][k], Bt_[n][k], acc[ai][bj][m][n], 0, 0, 0); \
;     __builtin_amdgcn_s_setprio(0); } while (0)
; #define WAIT_V(n) asm volatile("s_waitcnt vmcnt(" #n ")" ::: "memory")
; #define WAIT_L(n) asm volatile("s_waitcnt lgkmcnt(" #n ")" ::: "memory")
; #define BAR __builtin_amdgcn_s_barrier()
; #define SCHED __builtin_amdgcn_sched_barrier(0)
; __device__ __forceinline__ void gemm256(const bf16_t* __restrict__ A, long lda, const bf16_t* __restrict__ Bt, long ldb, int K,
;                                         int brow, int bcol, char* smem, f32x4 (&acc)[2][2][4][2]) {
;     ...
;         BAR; WAIT_L(0); MMA(1, 0, At, B0); BAR; SCHED;
;         STAGE(SB(1, 1), Bt, ldb, bcol + 128, t + 3);
;         WAIT_V(6); BAR; MMA(1, 1, At, B1); BAR;
;     }
;     { LDB(B0, 0, 0); LDA(At, 0, 0); STAGE(SA(1, 1), A, lda, brow + 128, nt - 1);
;       BAR; WAIT_L(0); MMA(0, 0, At, B0); BAR;
;       LDB(B1, 0, 1); BAR; WAIT_L(0); MMA(0, 1, At, B1); BAR;
	s_waitcnt lgkmcnt(0)
	s_setprio 1
	s_waitcnt lgkmcnt(0)
	v_mfma_f32_16x16x32_bf16 v[66:69], v[184:187], v[168:171], v[66:69]
	v_mfma_f32_16x16x32_bf16 v[62:65], v[184:187], v[176:179], v[62:65]
	v_mfma_f32_16x16x32_bf16 v[58:61], v[192:195], v[168:171], v[58:61]
	v_mfma_f32_16x16x32_bf16 v[54:57], v[192:195], v[176:179], v[54:57]
	v_mfma_f32_16x16x32_bf16 v[50:53], v[200:203], v[168:171], v[50:53]
	v_mfma_f32_16x16x32_bf16 v[46:49], v[200:203], v[176:179], v[46:49]
	v_mfma_f32_16x16x32_bf16 v[42:45], v[208:211], v[168:171], v[42:45]
	v_mfma_f32_16x16x32_bf16 v[38:41], v[208:211], v[176:179], v[38:41]
	v_mfma_f32_16x16x32_bf16 v[66:69], v[188:191], v[172:175], v[66:69]
	v_mfma_f32_16x16x32_bf16 v[62:65], v[188:191], v[180:183], v[62:65]
	v_mfma_f32_16x16x32_bf16 v[58:61], v[196:199], v[172:175], v[58:61]
	v_mfma_f32_16x16x32_bf16 v[54:57], v[196:199], v[180:183], v[54:57]
	v_mfma_f32_16x16x32_bf16 v[50:53], v[204:207], v[172:175], v[50:53]
	v_mfma_f32_16x16x32_bf16 v[46:49], v[204:207], v[180:183], v[46:49]
	v_mfma_f32_16x16x32_bf16 v[42:45], v[212:215], v[172:175], v[42:45]
	v_mfma_f32_16x16x32_bf16 v[38:41], v[212:215], v[180:183], v[38:41]
	s_setprio 0
	s_barrier
	v_readfirstlane_b32 s9, v162
	v_lshl_add_u64 v[168:169], v[238:239], 0, s[70:71]
	s_mov_b32 m0, s9
	v_readfirstlane_b32 s9, v163
	global_load_lds_dwordx4 v[168:169], off
	v_lshl_add_u64 v[168:169], v[242:243], 0, s[70:71]
	s_mov_b32 m0, s9
	s_nop 0
	global_load_lds_dwordx4 v[168:169], off
	s_waitcnt vmcnt(6)
	s_barrier
	s_setprio 1
	v_mfma_f32_16x16x32_bf16 v[34:37], v[184:187], v[216:219], v[34:37]
	v_mfma_f32_16x16x32_bf16 v[30:33], v[184:187], v[224:227], v[30:33]
	v_mfma_f32_16x16x32_bf16 v[26:29], v[192:195], v[216:219], v[26:29]
	v_mfma_f32_16x16x32_bf16 v[22:25], v[192:195], v[224:227], v[22:25]
	v_mfma_f32_16x16x32_bf16 v[18:21], v[200:203], v[216:219], v[18:21]
	v_mfma_f32_16x16x32_bf16 v[14:17], v[200:203], v[224:227], v[14:17]
	v_mfma_f32_16x16x32_bf16 v[10:13], v[208:211], v[216:219], v[10:13]
	v_mfma_f32_16x16x32_bf16 v[6:9], v[208:211], v[224:227], v[6:9]
	v_mfma_f32_16x16x32_bf16 v[34:37], v[188:191], v[220:223], v[34:37]
	v_mfma_f32_16x16x32_bf16 v[30:33], v[188:191], v[228:231], v[30:33]
	v_mfma_f32_16x16x32_bf16 v[26:29], v[196:199], v[220:223], v[26:29]
	v_mfma_f32_16x16x32_bf16 v[22:25], v[196:199], v[228:231], v[22:25]
	v_mfma_f32_16x16x32_bf16 v[18:21], v[204:207], v[220:223], v[18:21]
	v_mfma_f32_16x16x32_bf16 v[14:17], v[204:207], v[228:231], v[14:17]
	v_mfma_f32_16x16x32_bf16 v[10:13], v[212:215], v[220:223], v[10:13]
	v_mfma_f32_16x16x32_bf16 v[6:9], v[212:215], v[228:231], v[6:9]
	s_setprio 0
	s_add_i32 s7, s7, 2
	v_lshl_add_u64 v[136:137], v[136:137], 0, s[44:45]
	v_lshl_add_u64 v[138:139], v[138:139], 0, s[44:45]
	v_lshl_add_u64 v[140:141], v[140:141], 0, s[44:45]
	s_cmp_lt_u32 s7, 12
	v_lshl_add_u64 v[142:143], v[142:143], 0, s[44:45]
	s_barrier
	s_cbranch_scc1 .LBB0_509
	s_mov_b64 s[10:11], 0x780
	v_readfirstlane_b32 s7, v165
	v_lshl_add_u64 v[2:3], v[2:3], 0, s[10:11]
	s_mov_b32 m0, s7
	v_readfirstlane_b32 s7, v166
	s_nop 0
	ds_read_b128 v[136:139], v164
	ds_read_b128 v[140:143], v164 offset:1024
	ds_read_b128 v[154:157], v164 offset:2048
	ds_read_b128 v[168:171], v164 offset:3072
	ds_read_b128 v[172:175], v149
	ds_read_b128 v[176:179], v149 offset:1024
	ds_read_b128 v[180:183], v148
	ds_read_b128 v[184:187], v148 offset:1024
	ds_read_b128 v[188:191], v147
	ds_read_b128 v[192:195], v147 offset:1024
	ds_read_b128 v[196:199], v145
	ds_read_b128 v[200:203], v145 offset:1024
	global_load_lds_dwordx4 v[2:3], off
	v_lshl_add_u64 v[2:3], v[134:135], 0, s[10:11]
	s_mov_b32 m0, s7
	s_nop 0
	global_load_lds_dwordx4 v[2:3], off
	s_barrier
	s_waitcnt lgkmcnt(0)
	s_setprio 1
	s_waitcnt lgkmcnt(0)
	v_mfma_f32_16x16x32_bf16 v[130:133], v[172:175], v[136:139], v[130:133]
	v_mfma_f32_16x16x32_bf16 v[126:129], v[172:175], v[154:157], v[126:129]
	v_mfma_f32_16x16x32_bf16 v[122:125], v[180:183], v[136:139], v[122:125]
	v_mfma_f32_16x16x32_bf16 v[118:121], v[180:183], v[154:157], v[118:121]
	v_mfma_f32_16x16x32_bf16 v[114:117], v[188:191], v[136:139], v[114:117]
	v_mfma_f32_16x16x32_bf16 v[110:113], v[188:191], v[154:157], v[110:113]
	v_mfma_f32_16x16x32_bf16 v[106:109], v[196:199], v[136:139], v[106:109]
	v_mfma_f32_16x16x32_bf16 v[102:105], v[196:199], v[154:157], v[102:105]
	v_mfma_f32_16x16x32_bf16 v[130:133], v[176:179], v[140:143], v[130:133]
	v_mfma_f32_16x16x32_bf16 v[126:129], v[176:179], v[168:171], v[126:129]
	v_mfma_f32_16x16x32_bf16 v[122:125], v[184:187], v[140:143], v[122:125]
	v_mfma_f32_16x16x32_bf16 v[118:121], v[184:187], v[168:171], v[118:121]
	v_mfma_f32_16x16x32_bf16 v[114:117], v[192:195], v[140:143], v[114:117]
	v_mfma_f32_16x16x32_bf16 v[110:113], v[192:195], v[168:171], v[110:113]
	v_mfma_f32_16x16x32_bf16 v[106:109], v[200:203], v[140:143], v[106:109]
	v_mfma_f32_16x16x32_bf16 v[102:105], v[200:203], v[168:171], v[102:105]
	s_setprio 0
	s_barrier
	s_nop 0
	ds_read_b128 v[162:165], v161
	ds_read_b128 v[204:207], v161 offset:1024
	ds_read_b128 v[208:211], v161 offset:2048
	ds_read_b128 v[158:161], v161 offset:3072
	s_barrier
; #define LDA(dst, b, h) _Pragma("unroll") for (int m = 0; m < 4; ++m) _Pragma("unroll") for (int k = 0; k < 2; ++k) \
;     dst[m][k] = *reinterpret_cast<const bf16x8*>((char*)SA(b, h) + lds_byte(wr * 64 + m * 16 + fr, k * 32 + fq * 8))
; #define LDB(dst, b, h) _Pragma("unroll") for (int n = 0; n < 2; ++n) _Pragma("unroll") for (int k = 0; k < 2; ++k) \
;     dst[n][k] = *reinterpret_cast<const bf16x8*>((char*)SB(b, h) + lds_byte(wc * 32 + n * 16 + fr, k * 32 + fq * 8))
; #define MMA(ai, bj, At_, Bt_) do { __builtin_amdgcn_s_setprio(1); \
;     _Pragma("unroll") for (int m = 0; m < 4; ++m) _Pragma("unroll") for (int n = 0; n < 2; ++n) _Pragma("unroll") for (int k = 0; k < 2; ++k) \
;       acc[ai][bj][m][n] = __builtin_amdgcn_mfma_f32_16x16x32_bf16(At_[m][k], Bt_[n][k], acc[ai][bj][m][n], 0, 0, 0); \
;     __builtin_amdgcn_s_setprio(0); } while (0)
; #define WAIT_V(n) asm volatile("s_waitcnt vmcnt(" #n ")" ::: "memory")
; #define WAIT_L(n) asm volatile("s_waitcnt lgkmcnt(" #n ")" ::: "memory")
; #define BAR __builtin_amdgcn_s_barrier()
; __device__ __forceinline__ void gemm256(const bf16_t* __restrict__ A, long lda, const bf16_t* __restrict__ Bt, long ldb, int K,
;                                         int brow, int bcol, char* smem, f32x4 (&acc)[2][2][4][2]) {
;     ...
;       LDB(B1, 0, 1); BAR; WAIT_L(0); MMA(0, 1, At, B1); BAR;
;       LDA(At, 0, 1); WAIT_V(4); BAR; WAIT_L(0); MMA(1, 0, At, B0); MMA(1, 1, At, B1); BAR; }
;     { LDB(B0, 1, 0); LDA(At, 1, 0); WAIT_V(2); BAR; WAIT_L(0); MMA(0, 0, At, B0); BAR;
	s_waitcnt lgkmcnt(0)
	s_setprio 1
	s_waitcnt lgkmcnt(3)
	v_mfma_f32_16x16x32_bf16 v[98:101], v[172:175], v[162:165], v[98:101]
	s_waitcnt lgkmcnt(1)
	v_mfma_f32_16x16x32_bf16 v[94:97], v[172:175], v[208:211], v[94:97]
	v_mfma_f32_16x16x32_bf16 v[90:93], v[180:183], v[162:165], v[90:93]
	v_mfma_f32_16x16x32_bf16 v[86:89], v[180:183], v[208:211], v[86:89]
	v_mfma_f32_16x16x32_bf16 v[82:85], v[188:191], v[162:165], v[82:85]
	v_mfma_f32_16x16x32_bf16 v[78:81], v[188:191], v[208:211], v[78:81]
	v_mfma_f32_16x16x32_bf16 v[74:77], v[196:199], v[162:165], v[74:77]
	v_mfma_f32_16x16x32_bf16 v[70:73], v[196:199], v[208:211], v[70:73]
	v_mfma_f32_16x16x32_bf16 v[98:101], v[176:179], v[204:207], v[98:101]
	s_waitcnt lgkmcnt(0)
	v_mfma_f32_16x16x32_bf16 v[94:97], v[176:179], v[158:161], v[94:97]
	v_mfma_f32_16x16x32_bf16 v[90:93], v[184:187], v[204:207], v[90:93]
	v_mfma_f32_16x16x32_bf16 v[86:89], v[184:187], v[158:161], v[86:89]
	v_mfma_f32_16x16x32_bf16 v[82:85], v[192:195], v[204:207], v[82:85]
	v_mfma_f32_16x16x32_bf16 v[78:81], v[192:195], v[158:161], v[78:81]
	v_mfma_f32_16x16x32_bf16 v[74:77], v[200:203], v[204:207], v[74:77]
	v_mfma_f32_16x16x32_bf16 v[70:73], v[200:203], v[158:161], v[70:73]
	s_setprio 0
	s_barrier
	ds_read_b128 v[172:175], v149 offset:16384
	ds_read_b128 v[176:179], v149 offset:17408
	ds_read_b128 v[180:183], v148 offset:16384
	ds_read_b128 v[184:187], v148 offset:17408
	ds_read_b128 v[188:191], v147 offset:16384
	ds_read_b128 v[192:195], v147 offset:17408
	ds_read_b128 v[196:199], v145 offset:16384
	ds_read_b128 v[200:203], v145 offset:17408
	s_waitcnt vmcnt(4)
	s_barrier
	s_waitcnt lgkmcnt(0)
	s_setprio 1
	s_waitcnt lgkmcnt(7)
	v_mfma_f32_16x16x32_bf16 v[66:69], v[172:175], v[136:139], v[66:69]
	v_mfma_f32_16x16x32_bf16 v[62:65], v[172:175], v[154:157], v[62:65]
	s_waitcnt lgkmcnt(5)
	v_mfma_f32_16x16x32_bf16 v[58:61], v[180:183], v[136:139], v[58:61]
	v_mfma_f32_16x16x32_bf16 v[54:57], v[180:183], v[154:157], v[54:57]
	s_waitcnt lgkmcnt(3)
	v_mfma_f32_16x16x32_bf16 v[50:53], v[188:191], v[136:139], v[50:53]
	v_mfma_f32_16x16x32_bf16 v[46:49], v[188:191], v[154:157], v[46:49]
	s_waitcnt lgkmcnt(1)
	v_mfma_f32_16x16x32_bf16 v[42:45], v[196:199], v[136:139], v[42:45]
	v_mfma_f32_16x16x32_bf16 v[38:41], v[196:199], v[154:157], v[38:41]
	v_mfma_f32_16x16x32_bf16 v[66:69], v[176:179], v[140:143], v[66:69]
	v_mfma_f32_16x16x32_bf16 v[62:65], v[176:179], v[168:171], v[62:65]
	v_mfma_f32_16x16x32_bf16 v[58:61], v[184:187], v[140:143], v[58:61]
	v_mfma_f32_16x16x32_bf16 v[54:57], v[184:187], v[168:171], v[54:57]
	v_mfma_f32_16x16x32_bf16 v[50:53], v[192:195], v[140:143], v[50:53]
	v_mfma_f32_16x16x32_bf16 v[46:49], v[192:195], v[168:171], v[46:49]
	s_waitcnt lgkmcnt(0)
	v_mfma_f32_16x16x32_bf16 v[42:45], v[200:203], v[140:143], v[42:45]
	v_mfma_f32_16x16x32_bf16 v[38:41], v[200:203], v[168:171], v[38:41]
	s_setprio 0
	s_setprio 1
	v_mfma_f32_16x16x32_bf16 v[34:37], v[172:175], v[162:165], v[34:37]
	v_mfma_f32_16x16x32_bf16 v[30:33], v[172:175], v[208:211], v[30:33]
	v_mfma_f32_16x16x32_bf16 v[26:29], v[180:183], v[162:165], v[26:29]
	v_mfma_f32_16x16x32_bf16 v[22:25], v[180:183], v[208:211], v[22:25]
	v_mfma_f32_16x16x32_bf16 v[18:21], v[188:191], v[162:165], v[18:21]
	v_mfma_f32_16x16x32_bf16 v[14:17], v[188:191], v[208:211], v[14:17]
	v_mfma_f32_16x16x32_bf16 v[10:13], v[196:199], v[162:165], v[10:13]
	v_mfma_f32_16x16x32_bf16 v[6:9], v[196:199], v[208:211], v[6:9]
	v_mfma_f32_16x16x32_bf16 v[34:37], v[176:179], v[204:207], v[34:37]
	v_mfma_f32_16x16x32_bf16 v[30:33], v[176:179], v[158:161], v[30:33]
	v_mfma_f32_16x16x32_bf16 v[26:29], v[184:187], v[204:207], v[26:29]
	v_mfma_f32_16x16x32_bf16 v[22:25], v[184:187], v[158:161], v[22:25]
	v_mfma_f32_16x16x32_bf16 v[18:21], v[192:195], v[204:207], v[18:21]
	v_mfma_f32_16x16x32_bf16 v[14:17], v[192:195], v[158:161], v[14:17]
	v_mfma_f32_16x16x32_bf16 v[10:13], v[200:203], v[204:207], v[10:13]
	v_mfma_f32_16x16x32_bf16 v[6:9], v[200:203], v[158:161], v[6:9]
	s_setprio 0
	s_barrier
	ds_read_b128 v[134:137], v152
	ds_read_b128 v[138:141], v152 offset:1024
	ds_read_b128 v[154:157], v152 offset:2048
	ds_read_b128 v[158:161], v152 offset:3072
	ds_read_b128 v[162:165], v149 offset:32768
	ds_read_b128 v[166:169], v149 offset:33792
	ds_read_b128 v[170:173], v148 offset:32768
	ds_read_b128 v[174:177], v148 offset:33792
	ds_read_b128 v[178:181], v147 offset:32768
	ds_read_b128 v[182:185], v147 offset:33792
	ds_read_b128 v[186:189], v145 offset:32768
	ds_read_b128 v[190:193], v145 offset:33792
	s_waitcnt vmcnt(2)
	s_barrier
; #define LDA(dst, b, h) _Pragma("unroll") for (int m = 0; m < 4; ++m) _Pragma("unroll") for (int k = 0; k < 2; ++k) \
;     dst[m][k] = *reinterpret_cast<const bf16x8*>((char*)SA(b, h) + lds_byte(wr * 64 + m * 16 + fr, k * 32 + fq * 8))
; #define LDB(dst, b, h) _Pragma("unroll") for (int n = 0; n < 2; ++n) _Pragma("unroll") for (int k = 0; k < 2; ++k) \
;     dst[n][k] = *reinterpret_cast<const bf16x8*>((char*)SB(b, h) + lds_byte(wc * 32 + n * 16 + fr, k * 32 + fq * 8))
; #define MMA(ai, bj, At_, Bt_) do { __builtin_amdgcn_s_setprio(1); \
;     _Pragma("unroll") for (int m = 0; m < 4; ++m) _Pragma("unroll") for (int n = 0; n < 2; ++n) _Pragma("unroll") for (int k = 0; k < 2; ++k) \
;       acc[ai][bj][m][n] = __builtin_amdgcn_mfma_f32_16x16x32_bf16(At_[m][k], Bt_[n][k], acc[ai][bj][m][n], 0, 0, 0); \
;     __builtin_amdgcn_s_setprio(0); } while (0)
; #define WAIT_V(n) asm volatile("s_waitcnt vmcnt(" #n ")" ::: "memory")
; #define WAIT_L(n) asm volatile("s_waitcnt lgkmcnt(" #n ")" ::: "memory")
; #define BAR __builtin_amdgcn_s_barrier()
; __device__ __forceinline__ void gemm256(const bf16_t* __restrict__ A, long lda, const bf16_t* __restrict__ Bt, long ldb, int K,
;                                         int brow, int bcol, char* smem, f32x4 (&acc)[2][2][4][2]) {
;     ...
;     { LDB(B0, 1, 0); LDA(At, 1, 0); WAIT_V(2); BAR; WAIT_L(0); MMA(0, 0, At, B0); BAR;
;       LDB(B1, 1, 1); WAIT_V(0); BAR; WAIT_L(0); MMA(0, 1, At, B1); BAR;
;       LDA(At, 1, 1); BAR; WAIT_L(0); MMA(1, 0, At, B0); MMA(1, 1, At, B1); BAR; }
;     if (wr == 0) BAR;
	s_waitcnt lgkmcnt(0)
	s_setprio 1
	s_waitcnt lgkmcnt(7)
	v_mfma_f32_16x16x32_bf16 v[130:133], v[162:165], v[134:137], v[130:133]
	v_mfma_f32_16x16x32_bf16 v[126:129], v[162:165], v[154:157], v[126:129]
	s_waitcnt lgkmcnt(5)
	v_mfma_f32_16x16x32_bf16 v[122:125], v[170:173], v[134:137], v[122:125]
	v_mfma_f32_16x16x32_bf16 v[118:121], v[170:173], v[154:157], v[118:121]
	s_waitcnt lgkmcnt(3)
	v_mfma_f32_16x16x32_bf16 v[114:117], v[178:181], v[134:137], v[114:117]
	v_mfma_f32_16x16x32_bf16 v[110:113], v[178:181], v[154:157], v[110:113]
	s_waitcnt lgkmcnt(1)
	v_mfma_f32_16x16x32_bf16 v[106:109], v[186:189], v[134:137], v[106:109]
	v_mfma_f32_16x16x32_bf16 v[102:105], v[186:189], v[154:157], v[102:105]
	v_mfma_f32_16x16x32_bf16 v[130:133], v[166:169], v[138:141], v[130:133]
	v_mfma_f32_16x16x32_bf16 v[126:129], v[166:169], v[158:161], v[126:129]
	v_mfma_f32_16x16x32_bf16 v[122:125], v[174:177], v[138:141], v[122:125]
	v_mfma_f32_16x16x32_bf16 v[118:121], v[174:177], v[158:161], v[118:121]
	v_mfma_f32_16x16x32_bf16 v[114:117], v[182:185], v[138:141], v[114:117]
	v_mfma_f32_16x16x32_bf16 v[110:113], v[182:185], v[158:161], v[110:113]
	s_waitcnt lgkmcnt(0)
	v_mfma_f32_16x16x32_bf16 v[106:109], v[190:193], v[138:141], v[106:109]
	v_mfma_f32_16x16x32_bf16 v[102:105], v[190:193], v[158:161], v[102:105]
	s_setprio 0
	s_barrier
	ds_read_b128 v[194:197], v151
	ds_read_b128 v[198:201], v151 offset:1024
	ds_read_b128 v[202:205], v151 offset:2048
	ds_read_b128 v[150:153], v151 offset:3072
	s_waitcnt vmcnt(0)
	s_barrier
	s_waitcnt lgkmcnt(0)
	s_setprio 1
	s_waitcnt lgkmcnt(3)
	v_mfma_f32_16x16x32_bf16 v[98:101], v[162:165], v[194:197], v[98:101]
	s_waitcnt lgkmcnt(1)
	v_mfma_f32_16x16x32_bf16 v[94:97], v[162:165], v[202:205], v[94:97]
	v_mfma_f32_16x16x32_bf16 v[90:93], v[170:173], v[194:197], v[90:93]
	v_mfma_f32_16x16x32_bf16 v[86:89], v[170:173], v[202:205], v[86:89]
	v_mfma_f32_16x16x32_bf16 v[82:85], v[178:181], v[194:197], v[82:85]
	v_mfma_f32_16x16x32_bf16 v[78:81], v[178:181], v[202:205], v[78:81]
	v_mfma_f32_16x16x32_bf16 v[74:77], v[186:189], v[194:197], v[74:77]
	v_mfma_f32_16x16x32_bf16 v[70:73], v[186:189], v[202:205], v[70:73]
	v_mfma_f32_16x16x32_bf16 v[98:101], v[166:169], v[198:201], v[98:101]
	s_waitcnt lgkmcnt(0)
	v_mfma_f32_16x16x32_bf16 v[94:97], v[166:169], v[150:153], v[94:97]
	v_mfma_f32_16x16x32_bf16 v[90:93], v[174:177], v[198:201], v[90:93]
	v_mfma_f32_16x16x32_bf16 v[86:89], v[174:177], v[150:153], v[86:89]
	v_mfma_f32_16x16x32_bf16 v[82:85], v[182:185], v[198:201], v[82:85]
	v_mfma_f32_16x16x32_bf16 v[78:81], v[182:185], v[150:153], v[78:81]
	v_mfma_f32_16x16x32_bf16 v[74:77], v[190:193], v[198:201], v[74:77]
	v_mfma_f32_16x16x32_bf16 v[70:73], v[190:193], v[150:153], v[70:73]
	s_setprio 0
	s_barrier
	ds_read_b128 v[162:165], v149 offset:49152
	ds_read_b128 v[166:169], v149 offset:50176
	ds_read_b128 v[170:173], v148 offset:49152
	ds_read_b128 v[174:177], v148 offset:50176
	ds_read_b128 v[178:181], v147 offset:49152
	ds_read_b128 v[146:149], v147 offset:50176
	ds_read_b128 v[182:185], v145 offset:49152
	ds_read_b128 v[142:145], v145 offset:50176
	s_barrier
	s_waitcnt lgkmcnt(0)
	s_setprio 1
	s_waitcnt lgkmcnt(7)
	v_mfma_f32_16x16x32_bf16 v[66:69], v[162:165], v[134:137], v[66:69]
	v_mfma_f32_16x16x32_bf16 v[62:65], v[162:165], v[154:157], v[62:65]
	s_waitcnt lgkmcnt(5)
	v_mfma_f32_16x16x32_bf16 v[58:61], v[170:173], v[134:137], v[58:61]
	v_mfma_f32_16x16x32_bf16 v[54:57], v[170:173], v[154:157], v[54:57]
	s_waitcnt lgkmcnt(3)
	v_mfma_f32_16x16x32_bf16 v[50:53], v[178:181], v[134:137], v[50:53]
	v_mfma_f32_16x16x32_bf16 v[46:49], v[178:181], v[154:157], v[46:49]
	s_waitcnt lgkmcnt(1)
	v_mfma_f32_16x16x32_bf16 v[42:45], v[182:185], v[134:137], v[42:45]
	v_mfma_f32_16x16x32_bf16 v[38:41], v[182:185], v[154:157], v[38:41]
	v_mfma_f32_16x16x32_bf16 v[66:69], v[166:169], v[138:141], v[66:69]
	v_mfma_f32_16x16x32_bf16 v[62:65], v[166:169], v[158:161], v[62:65]
	v_mfma_f32_16x16x32_bf16 v[58:61], v[174:177], v[138:141], v[58:61]
	v_mfma_f32_16x16x32_bf16 v[54:57], v[174:177], v[158:161], v[54:57]
	v_mfma_f32_16x16x32_bf16 v[50:53], v[146:149], v[138:141], v[50:53]
	v_mfma_f32_16x16x32_bf16 v[46:49], v[146:149], v[158:161], v[46:49]
	s_waitcnt lgkmcnt(0)
	v_mfma_f32_16x16x32_bf16 v[42:45], v[142:145], v[138:141], v[42:45]
	v_mfma_f32_16x16x32_bf16 v[38:41], v[142:145], v[158:161], v[38:41]
	s_setprio 0
	s_setprio 1
	v_mfma_f32_16x16x32_bf16 v[34:37], v[162:165], v[194:197], v[34:37]
	v_mfma_f32_16x16x32_bf16 v[30:33], v[162:165], v[202:205], v[30:33]
	v_mfma_f32_16x16x32_bf16 v[26:29], v[170:173], v[194:197], v[26:29]
	v_mfma_f32_16x16x32_bf16 v[22:25], v[170:173], v[202:205], v[22:25]
	v_mfma_f32_16x16x32_bf16 v[18:21], v[178:181], v[194:197], v[18:21]
	v_mfma_f32_16x16x32_bf16 v[14:17], v[178:181], v[202:205], v[14:17]
	v_mfma_f32_16x16x32_bf16 v[10:13], v[182:185], v[194:197], v[10:13]
	v_mfma_f32_16x16x32_bf16 v[6:9], v[182:185], v[202:205], v[6:9]
	v_mfma_f32_16x16x32_bf16 v[34:37], v[166:169], v[198:201], v[34:37]
	v_mfma_f32_16x16x32_bf16 v[30:33], v[166:169], v[150:153], v[30:33]
	v_mfma_f32_16x16x32_bf16 v[26:29], v[174:177], v[198:201], v[26:29]
	v_mfma_f32_16x16x32_bf16 v[22:25], v[174:177], v[150:153], v[22:25]
	v_mfma_f32_16x16x32_bf16 v[18:21], v[146:149], v[198:201], v[18:21]
	v_mfma_f32_16x16x32_bf16 v[14:17], v[146:149], v[150:153], v[14:17]
	v_mfma_f32_16x16x32_bf16 v[10:13], v[142:145], v[198:201], v[10:13]
	v_mfma_f32_16x16x32_bf16 v[6:9], v[142:145], v[150:153], v[6:9]
	s_setprio 0
	v_cmp_gt_u32_e32 vcc, s78, v0
	s_barrier
	s_and_saveexec_b64 s[10:11], vcc
	s_cbranch_execz .LBB0_512
	s_barrier

; #define STAGE(P, BASE, LD, br, kt) do { const long _g = (long)(br) * (LD) + (long)(kt) * 64; \
;     _Pragma("unroll") for (int _i = 0; _i < 2; ++_i) { const int _b = tid * 16 + _i * 8192; int _r, _c; stage_rc(_b, _r, _c); \
;       __builtin_amdgcn_global_load_lds((const G_AS1 unsigned*)((BASE) + _g + (long)_r * (LD) + _c), \
;         (LAS unsigned*)((char*)(P) + _b), 16, 0, 0); } } while (0)
; #define LDA(dst, b, h) _Pragma("unroll") for (int m = 0; m < 4; ++m) _Pragma("unroll") for (int k = 0; k < 2; ++k) \
;     dst[m][k] = *reinterpret_cast<const bf16x8*>((char*)SA(b, h) + lds_byte(wr * 64 + m * 16 + fr, k * 32 + fq * 8))
; #define LDB(dst, b, h) _Pragma("unroll") for (int n = 0; n < 2; ++n) _Pragma("unroll") for (int k = 0; k < 2; ++k) \
;     dst[n][k] = *reinterpret_cast<const bf16x8*>((char*)SB(b, h) + lds_byte(wc * 32 + n * 16 + fr, k * 32 + fq * 8))
; #define MMA(ai, bj, At_, Bt_) do { __builtin_amdgcn_s_setprio(1); \
;     _Pragma("unroll") for (int m = 0; m < 4; ++m) _Pragma("unroll") for (int n = 0; n < 2; ++n) _Pragma("unroll") for (int k = 0; k < 2; ++k) \
;       acc[ai][bj][m][n] = __builtin_amdgcn_mfma_f32_16x16x32_bf16(At_[m][k], Bt_[n][k], acc[ai][bj][m][n], 0, 0, 0); \
;     __builtin_amdgcn_s_setprio(0); } while (0)
; #define WAIT_V(n) asm volatile("s_waitcnt vmcnt(" #n ")" ::: "memory")
; #define WAIT_L(n) asm volatile("s_waitcnt lgkmcnt(" #n ")" ::: "memory")
; #define BAR __builtin_amdgcn_s_barrier()
; #define SCHED __builtin_amdgcn_sched_barrier(0)
; __device__ __forceinline__ void gemm256(const bf16_t* __restrict__ A, long lda, const bf16_t* __restrict__ Bt, long ldb, int K,
;                                         int brow, int bcol, char* smem, f32x4 (&acc)[2][2][4][2]) {
;     ...
;     if (wr == 1) BAR;
;     WAIT_V(4); BAR;
;     STAGE(SB(1, 0), Bt, ldb, bcol, 1); STAGE(SA(1, 0), A, lda, brow, 1); STAGE(SB(1, 1), Bt, ldb, bcol + 128, 1);
;     WAIT_V(6); BAR;
;     for (int t = 0; t < nt - 2; t += 2) {
;         LDB(B0, 0, 0); SCHED; LDA(At, 0, 0); STAGE(SA(1, 1), A, lda, brow + 128, t + 1);
;         WAIT_L(8); BAR; WAIT_L(0); MMA(0, 0, At, B0); BAR; SCHED;
;         LDB(B1, 0, 1); STAGE(SB(0, 0), Bt, ldb, bcol, t + 2);
;         BAR; WAIT_L(0); MMA(0, 1, At, B1); BAR;
.LBB0_1027:
	s_or_b64 exec, exec, s[12:13]
	v_add_u32_e32 v32, 0x18000, v21
	v_lshl_add_u64 v[30:31], v[8:9], 0, s[58:59]
	v_readfirstlane_b32 s19, v32
	v_add_u32_e32 v32, 0x1a000, v21
	s_mov_b32 m0, s19
	v_readfirstlane_b32 s18, v32
	v_add_u32_e32 v32, 0x8000, v21
	s_waitcnt vmcnt(4)
	s_barrier
	global_load_lds_dwordx4 v[30:31], off
	v_lshl_add_u64 v[30:31], v[18:19], 0, s[58:59]
	s_mov_b32 m0, s18
	v_readfirstlane_b32 s17, v32
	v_add_u32_e32 v32, 0xa000, v21
	v_lshlrev_b64 v[14:15], 10, v[14:15]
	global_load_lds_dwordx4 v[30:31], off
	v_lshl_add_u64 v[30:31], v[10:11], 0, s[58:59]
	s_mov_b32 m0, s17
	v_readfirstlane_b32 s16, v32
	s_add_u32 s20, s8, 0x40080
	global_load_lds_dwordx4 v[30:31], off
	v_lshl_add_u64 v[30:31], v[12:13], 0, s[58:59]
	s_mov_b32 m0, s16
	s_addc_u32 s21, s9, 0
	v_lshlrev_b64 v[14:15], 1, v[14:15]
	v_add_u32_e32 v32, 0x1c000, v21
	v_lshlrev_b64 v[16:17], 10, v[16:17]
	global_load_lds_dwordx4 v[30:31], off
	v_lshl_add_u64 v[30:31], s[20:21], 0, v[14:15]
	v_readfirstlane_b32 s13, v32
	v_lshl_add_u64 v[30:31], v[30:31], 0, v[2:3]
	s_mov_b32 m0, s13
	v_lshlrev_b64 v[16:17], 1, v[16:17]
	v_add_u32_e32 v32, 0x1e000, v21
	global_load_lds_dwordx4 v[30:31], off
	v_lshl_add_u64 v[30:31], s[20:21], 0, v[16:17]
	v_readfirstlane_b32 s12, v32
	v_lshl_add_u64 v[30:31], v[30:31], 0, v[6:7]
	s_mov_b32 m0, s12
	v_and_b32_e32 v20, 15, v0
	global_load_lds_dwordx4 v[30:31], off
	v_lshlrev_b32_e32 v32, 2, v0
	v_and_b32_e32 v29, 48, v0
	v_lshlrev_b32_e32 v20, 6, v20
	v_and_b32_e32 v32, 32, v32
	v_lshlrev_b32_e32 v30, 6, v0
	v_or_b32_e32 v31, v20, v29
	v_bitop3_b32 v20, v20, v32, v29 bitop3:0x36
	s_movk_i32 s20, 0x3000
	v_and_or_b32 v33, v30, s20, v20
	s_movk_i32 s20, 0x3c0
	v_or_b32_e32 v218, 0x10000, v33
	v_lshlrev_b32_e32 v5, 13, v5
	v_and_or_b32 v29, v30, s20, v29
	s_waitcnt vmcnt(6)
	s_barrier
	v_or_b32_e32 v219, 0x10400, v33
	v_or_b32_e32 v220, 0x10800, v33
	v_or_b32_e32 v221, 0x10c00, v33
	v_bitop3_b32 v20, v31, v5, v32 bitop3:0xde
	v_bitop3_b32 v5, v5, v29, v32 bitop3:0xf6
	v_or_b32_e32 v222, 0x14000, v33
	v_or_b32_e32 v223, 0x14400, v33
	v_or_b32_e32 v224, 0x14800, v33
	v_or_b32_e32 v225, 0x14c00, v33
	v_or_b32_e32 v226, 0x18000, v33
	v_or_b32_e32 v227, 0x18400, v33
	v_or_b32_e32 v228, 0x18800, v33
	v_or_b32_e32 v229, 0x18c00, v33
	v_or_b32_e32 v230, 0x1c000, v33
	v_or_b32_e32 v231, 0x1c400, v33
	v_or_b32_e32 v232, 0x1c800, v33
	v_or_b32_e32 v233, 0x1cc00, v33
	s_nop 0
	ds_read_b128 v[30:33], v218
	ds_read_b128 v[34:37], v219
	ds_read_b128 v[38:41], v220
	ds_read_b128 v[42:45], v221
	s_add_u32 s22, s10, 0x40080
	s_addc_u32 s23, s11, 0
	v_add_u32_e32 v29, 0xc000, v21
	v_lshl_add_u64 v[78:79], s[22:23], 0, v[14:15]
	v_readfirstlane_b32 s21, v29
	v_lshl_add_u64 v[78:79], v[78:79], 0, v[2:3]
	s_mov_b32 m0, s21
	v_add_u32_e32 v29, 0xe000, v21
	ds_read_b128 v[46:49], v20
	ds_read_b128 v[50:53], v20 offset:1024
	ds_read_b128 v[54:57], v5 offset:2048
	ds_read_b128 v[58:61], v5 offset:3072
	ds_read_b128 v[62:65], v5 offset:4096
	ds_read_b128 v[66:69], v5 offset:5120
	ds_read_b128 v[70:73], v5 offset:6144
	ds_read_b128 v[74:77], v5 offset:7168
	global_load_lds_dwordx4 v[78:79], off
	v_lshl_add_u64 v[78:79], s[22:23], 0, v[16:17]
	v_readfirstlane_b32 s20, v29
	v_lshl_add_u64 v[78:79], v[78:79], 0, v[6:7]
	s_mov_b32 m0, s20
	s_nop 0
	global_load_lds_dwordx4 v[78:79], off
	s_waitcnt lgkmcnt(8)
	s_barrier
	s_waitcnt lgkmcnt(0)
	s_setprio 1
	s_waitcnt lgkmcnt(0)
	v_mfma_f32_16x16x32_bf16 v[78:81], v[46:49], v[30:33], 0
	v_mfma_f32_16x16x32_bf16 v[82:85], v[46:49], v[38:41], 0
	v_mfma_f32_16x16x32_bf16 v[86:89], v[54:57], v[30:33], 0
	v_mfma_f32_16x16x32_bf16 v[90:93], v[54:57], v[38:41], 0
	v_mfma_f32_16x16x32_bf16 v[94:97], v[62:65], v[30:33], 0
	v_mfma_f32_16x16x32_bf16 v[98:101], v[62:65], v[38:41], 0
	v_mfma_f32_16x16x32_bf16 v[102:105], v[70:73], v[30:33], 0
	v_mfma_f32_16x16x32_bf16 v[106:109], v[70:73], v[38:41], 0
	v_mfma_f32_16x16x32_bf16 v[78:81], v[50:53], v[34:37], v[78:81]
	v_mfma_f32_16x16x32_bf16 v[82:85], v[50:53], v[42:45], v[82:85]
	v_mfma_f32_16x16x32_bf16 v[86:89], v[58:61], v[34:37], v[86:89]
	v_mfma_f32_16x16x32_bf16 v[90:93], v[58:61], v[42:45], v[90:93]
	v_mfma_f32_16x16x32_bf16 v[94:97], v[66:69], v[34:37], v[94:97]
	v_mfma_f32_16x16x32_bf16 v[98:101], v[66:69], v[42:45], v[98:101]
	v_mfma_f32_16x16x32_bf16 v[102:105], v[74:77], v[34:37], v[102:105]
	v_mfma_f32_16x16x32_bf16 v[106:109], v[74:77], v[42:45], v[106:109]
	s_setprio 0
	s_barrier
	v_readfirstlane_b32 s22, v27
	v_lshl_add_u64 v[126:127], v[8:9], 0, s[44:45]
	s_mov_b32 m0, s22
	v_readfirstlane_b32 s22, v28
	s_nop 0
	ds_read_b128 v[110:113], v222
	ds_read_b128 v[114:117], v223
	ds_read_b128 v[118:121], v224
	ds_read_b128 v[122:125], v225
	global_load_lds_dwordx4 v[126:127], off
	v_lshl_add_u64 v[126:127], v[18:19], 0, s[44:45]
	s_mov_b32 m0, s22
	s_nop 0
	global_load_lds_dwordx4 v[126:127], off
	s_barrier
	s_waitcnt lgkmcnt(0)
	s_setprio 1
	s_waitcnt lgkmcnt(0)
	v_mfma_f32_16x16x32_bf16 v[126:129], v[46:49], v[110:113], 0
	v_mfma_f32_16x16x32_bf16 v[46:49], v[46:49], v[118:121], 0
	v_mfma_f32_16x16x32_bf16 v[126:129], v[50:53], v[114:117], v[126:129]
	v_mfma_f32_16x16x32_bf16 v[46:49], v[50:53], v[122:125], v[46:49]
	v_mfma_f32_16x16x32_bf16 v[50:53], v[54:57], v[110:113], 0
	v_mfma_f32_16x16x32_bf16 v[54:57], v[54:57], v[118:121], 0
	v_mfma_f32_16x16x32_bf16 v[50:53], v[58:61], v[114:117], v[50:53]
	v_mfma_f32_16x16x32_bf16 v[54:57], v[58:61], v[122:125], v[54:57]
	v_mfma_f32_16x16x32_bf16 v[58:61], v[62:65], v[110:113], 0
	v_mfma_f32_16x16x32_bf16 v[62:65], v[62:65], v[118:121], 0
	v_mfma_f32_16x16x32_bf16 v[58:61], v[66:69], v[114:117], v[58:61]
	v_mfma_f32_16x16x32_bf16 v[62:65], v[66:69], v[122:125], v[62:65]
	v_mfma_f32_16x16x32_bf16 v[66:69], v[70:73], v[110:113], 0
	v_mfma_f32_16x16x32_bf16 v[70:73], v[70:73], v[118:121], 0
	v_mfma_f32_16x16x32_bf16 v[66:69], v[74:77], v[114:117], v[66:69]
	v_mfma_f32_16x16x32_bf16 v[70:73], v[74:77], v[122:125], v[70:73]
	s_setprio 0
	v_readfirstlane_b32 s22, v21
	v_lshl_add_u64 v[28:29], v[10:11], 0, s[44:45]
	s_mov_b32 m0, s22
	v_readfirstlane_b32 s22, v24
	s_barrier
; #define STAGE(P, BASE, LD, br, kt) do { const long _g = (long)(br) * (LD) + (long)(kt) * 64; \
;     _Pragma("unroll") for (int _i = 0; _i < 2; ++_i) { const int _b = tid * 16 + _i * 8192; int _r, _c; stage_rc(_b, _r, _c); \
;       __builtin_amdgcn_global_load_lds((const G_AS1 unsigned*)((BASE) + _g + (long)_r * (LD) + _c), \
;         (LAS unsigned*)((char*)(P) + _b), 16, 0, 0); } } while (0)
; #define LDA(dst, b, h) _Pragma("unroll") for (int m = 0; m < 4; ++m) _Pragma("unroll") for (int k = 0; k < 2; ++k) \
;     dst[m][k] = *reinterpret_cast<const bf16x8*>((char*)SA(b, h) + lds_byte(wr * 64 + m * 16 + fr, k * 32 + fq * 8))
; #define LDB(dst, b, h) _Pragma("unroll") for (int n = 0; n < 2; ++n) _Pragma("unroll") for (int k = 0; k < 2; ++k) \
;     dst[n][k] = *reinterpret_cast<const bf16x8*>((char*)SB(b, h) + lds_byte(wc * 32 + n * 16 + fr, k * 32 + fq * 8))
; #define MMA(ai, bj, At_, Bt_) do { __builtin_amdgcn_s_setprio(1); \
;     _Pragma("unroll") for (int m = 0; m < 4; ++m) _Pragma("unroll") for (int n = 0; n < 2; ++n) _Pragma("unroll") for (int k = 0; k < 2; ++k) \
;       acc[ai][bj][m][n] = __builtin_amdgcn_mfma_f32_16x16x32_bf16(At_[m][k], Bt_[n][k], acc[ai][bj][m][n], 0, 0, 0); \
;     __builtin_amdgcn_s_setprio(0); } while (0)
; #define WAIT_V(n) asm volatile("s_waitcnt vmcnt(" #n ")" ::: "memory")
; #define WAIT_L(n) asm volatile("s_waitcnt lgkmcnt(" #n ")" ::: "memory")
; #define BAR __builtin_amdgcn_s_barrier()
; #define SCHED __builtin_amdgcn_sched_barrier(0)
; __device__ __forceinline__ void gemm256(const bf16_t* __restrict__ A, long lda, const bf16_t* __restrict__ Bt, long ldb, int K,
;                                         int brow, int bcol, char* smem, f32x4 (&acc)[2][2][4][2]) {
;     ...
;         LDA(At, 0, 1); STAGE(SA(0, 0), A, lda, brow, t + 2);
;         BAR; WAIT_L(0); MMA(1, 0, At, B0); BAR; SCHED;
;         STAGE(SB(0, 1), Bt, ldb, bcol + 128, t + 2);
;         WAIT_V(6); BAR; MMA(1, 1, At, B1); BAR;
;         LDB(B0, 1, 0); SCHED; LDA(At, 1, 0); STAGE(SA(0, 1), A, lda, brow + 128, t + 2);
;         WAIT_L(8); BAR; WAIT_L(0); MMA(0, 0, At, B0); BAR; SCHED;
;         LDB(B1, 1, 1); STAGE(SB(1, 0), Bt, ldb, bcol, t + 3);
;         BAR; WAIT_L(0); MMA(0, 1, At, B1); BAR;
	s_nop 0
	ds_read_b128 v[74:77], v20 offset:16384
	ds_read_b128 v[130:133], v20 offset:17408
	ds_read_b128 v[134:137], v5 offset:18432
	ds_read_b128 v[138:141], v5 offset:19456
	ds_read_b128 v[142:145], v5 offset:20480
	ds_read_b128 v[146:149], v5 offset:21504
	ds_read_b128 v[150:153], v5 offset:22528
	ds_read_b128 v[154:157], v5 offset:23552
	global_load_lds_dwordx4 v[28:29], off
	v_lshl_add_u64 v[28:29], v[12:13], 0, s[44:45]
	s_mov_b32 m0, s22
	s_nop 0
	global_load_lds_dwordx4 v[28:29], off
	s_barrier
	s_waitcnt lgkmcnt(0)
	s_setprio 1
	s_waitcnt lgkmcnt(0)
	v_mfma_f32_16x16x32_bf16 v[158:161], v[74:77], v[30:33], 0
	v_mfma_f32_16x16x32_bf16 v[166:169], v[134:137], v[30:33], 0
	v_mfma_f32_16x16x32_bf16 v[174:177], v[142:145], v[30:33], 0
	v_mfma_f32_16x16x32_bf16 v[28:31], v[150:153], v[30:33], 0
	v_mfma_f32_16x16x32_bf16 v[158:161], v[130:133], v[34:37], v[158:161]
	v_mfma_f32_16x16x32_bf16 v[166:169], v[138:141], v[34:37], v[166:169]
	v_mfma_f32_16x16x32_bf16 v[174:177], v[146:149], v[34:37], v[174:177]
	v_mfma_f32_16x16x32_bf16 v[28:31], v[154:157], v[34:37], v[28:31]
	v_mfma_f32_16x16x32_bf16 v[32:35], v[150:153], v[38:41], 0
	v_mfma_f32_16x16x32_bf16 v[162:165], v[74:77], v[38:41], 0
	v_mfma_f32_16x16x32_bf16 v[170:173], v[134:137], v[38:41], 0
	v_mfma_f32_16x16x32_bf16 v[178:181], v[142:145], v[38:41], 0
	v_mfma_f32_16x16x32_bf16 v[32:35], v[154:157], v[42:45], v[32:35]
	v_mfma_f32_16x16x32_bf16 v[162:165], v[130:133], v[42:45], v[162:165]
	v_mfma_f32_16x16x32_bf16 v[170:173], v[138:141], v[42:45], v[170:173]
	v_mfma_f32_16x16x32_bf16 v[178:181], v[146:149], v[42:45], v[178:181]
	s_setprio 0
	s_barrier
	s_add_u32 s22, s8, 0x40100
	s_addc_u32 s23, s9, 0
	v_lshl_add_u64 v[36:37], s[22:23], 0, v[14:15]
	v_readfirstlane_b32 s24, v25
	v_lshl_add_u64 v[36:37], v[36:37], 0, v[2:3]
	s_mov_b32 m0, s24
	v_lshl_add_u64 v[24:25], s[22:23], 0, v[16:17]
	v_readfirstlane_b32 s22, v26
	global_load_lds_dwordx4 v[36:37], off
	v_lshl_add_u64 v[24:25], v[24:25], 0, v[6:7]
	s_mov_b32 m0, s22
	s_nop 0
	global_load_lds_dwordx4 v[24:25], off
	s_waitcnt vmcnt(6)
	s_barrier
	s_setprio 1
	v_mfma_f32_16x16x32_bf16 v[24:27], v[74:77], v[110:113], 0
	v_mfma_f32_16x16x32_bf16 v[36:39], v[74:77], v[118:121], 0
	v_mfma_f32_16x16x32_bf16 v[24:27], v[130:133], v[114:117], v[24:27]
	v_mfma_f32_16x16x32_bf16 v[36:39], v[130:133], v[122:125], v[36:39]
	v_mfma_f32_16x16x32_bf16 v[40:43], v[134:137], v[110:113], 0
	v_mfma_f32_16x16x32_bf16 v[130:133], v[142:145], v[110:113], 0
	v_mfma_f32_16x16x32_bf16 v[110:113], v[150:153], v[110:113], 0
	v_mfma_f32_16x16x32_bf16 v[40:43], v[138:141], v[114:117], v[40:43]
	v_mfma_f32_16x16x32_bf16 v[74:77], v[134:137], v[118:121], 0
	v_mfma_f32_16x16x32_bf16 v[130:133], v[146:149], v[114:117], v[130:133]
	v_mfma_f32_16x16x32_bf16 v[110:113], v[154:157], v[114:117], v[110:113]
	v_mfma_f32_16x16x32_bf16 v[114:117], v[150:153], v[118:121], 0
	v_mfma_f32_16x16x32_bf16 v[74:77], v[138:141], v[122:125], v[74:77]
	v_mfma_f32_16x16x32_bf16 v[134:137], v[142:145], v[118:121], 0
	v_mfma_f32_16x16x32_bf16 v[114:117], v[154:157], v[122:125], v[114:117]
	v_mfma_f32_16x16x32_bf16 v[134:137], v[146:149], v[122:125], v[134:137]
	s_setprio 0
	s_barrier
	s_nop 0
	ds_read_b128 v[118:121], v226
	ds_read_b128 v[122:125], v227
	ds_read_b128 v[138:141], v228
	ds_read_b128 v[142:145], v229
	s_add_u32 s22, s10, 0x40100
	s_addc_u32 s23, s11, 0
	v_lshl_add_u64 v[44:45], s[22:23], 0, v[14:15]
	v_readfirstlane_b32 s24, v22
	v_lshl_add_u64 v[44:45], v[44:45], 0, v[2:3]
	s_mov_b32 m0, s24
	ds_read_b128 v[146:149], v20 offset:32768
	ds_read_b128 v[150:153], v20 offset:33792
	ds_read_b128 v[154:157], v5 offset:34816
	ds_read_b128 v[182:185], v5 offset:35840
	ds_read_b128 v[186:189], v5 offset:36864
	ds_read_b128 v[190:193], v5 offset:37888
	ds_read_b128 v[194:197], v5 offset:38912
	ds_read_b128 v[198:201], v5 offset:39936
	global_load_lds_dwordx4 v[44:45], off
	v_lshl_add_u64 v[44:45], s[22:23], 0, v[16:17]
	v_readfirstlane_b32 s22, v23
	v_lshl_add_u64 v[44:45], v[44:45], 0, v[6:7]
	s_mov_b32 m0, s22
	s_nop 0
	global_load_lds_dwordx4 v[44:45], off
	s_waitcnt lgkmcnt(8)
	s_barrier
	s_waitcnt lgkmcnt(0)
	s_setprio 1
	s_waitcnt lgkmcnt(0)
	v_mfma_f32_16x16x32_bf16 v[78:81], v[146:149], v[118:121], v[78:81]
	v_mfma_f32_16x16x32_bf16 v[82:85], v[146:149], v[138:141], v[82:85]
	v_mfma_f32_16x16x32_bf16 v[86:89], v[154:157], v[118:121], v[86:89]
	v_mfma_f32_16x16x32_bf16 v[90:93], v[154:157], v[138:141], v[90:93]
	v_mfma_f32_16x16x32_bf16 v[94:97], v[186:189], v[118:121], v[94:97]
	v_mfma_f32_16x16x32_bf16 v[98:101], v[186:189], v[138:141], v[98:101]
	v_mfma_f32_16x16x32_bf16 v[102:105], v[194:197], v[118:121], v[102:105]
	v_mfma_f32_16x16x32_bf16 v[106:109], v[194:197], v[138:141], v[106:109]
	v_mfma_f32_16x16x32_bf16 v[78:81], v[150:153], v[122:125], v[78:81]
	v_mfma_f32_16x16x32_bf16 v[82:85], v[150:153], v[142:145], v[82:85]
	v_mfma_f32_16x16x32_bf16 v[86:89], v[182:185], v[122:125], v[86:89]
	v_mfma_f32_16x16x32_bf16 v[90:93], v[182:185], v[142:145], v[90:93]
	v_mfma_f32_16x16x32_bf16 v[94:97], v[190:193], v[122:125], v[94:97]
	v_mfma_f32_16x16x32_bf16 v[98:101], v[190:193], v[142:145], v[98:101]
	v_mfma_f32_16x16x32_bf16 v[102:105], v[198:201], v[122:125], v[102:105]
	v_mfma_f32_16x16x32_bf16 v[106:109], v[198:201], v[142:145], v[106:109]
	s_setprio 0
	s_barrier
	s_mov_b64 s[22:23], 0x180
	s_mov_b32 m0, s19
	v_lshl_add_u64 v[8:9], v[8:9], 0, s[22:23]
	s_nop 0
	ds_read_b128 v[202:205], v230
	ds_read_b128 v[206:209], v231
	ds_read_b128 v[210:213], v232
	ds_read_b128 v[214:217], v233
	global_load_lds_dwordx4 v[8:9], off
	v_lshl_add_u64 v[8:9], v[18:19], 0, s[22:23]
	s_mov_b32 m0, s18
	s_nop 0
	global_load_lds_dwordx4 v[8:9], off
	s_barrier
; #define STAGE(P, BASE, LD, br, kt) do { const long _g = (long)(br) * (LD) + (long)(kt) * 64; \
;     _Pragma("unroll") for (int _i = 0; _i < 2; ++_i) { const int _b = tid * 16 + _i * 8192; int _r, _c; stage_rc(_b, _r, _c); \
;       __builtin_amdgcn_global_load_lds((const G_AS1 unsigned*)((BASE) + _g + (long)_r * (LD) + _c), \
;         (LAS unsigned*)((char*)(P) + _b), 16, 0, 0); } } while (0)
; #define LDA(dst, b, h) _Pragma("unroll") for (int m = 0; m < 4; ++m) _Pragma("unroll") for (int k = 0; k < 2; ++k) \
;     dst[m][k] = *reinterpret_cast<const bf16x8*>((char*)SA(b, h) + lds_byte(wr * 64 + m * 16 + fr, k * 32 + fq * 8))
; #define LDB(dst, b, h) _Pragma("unroll") for (int n = 0; n < 2; ++n) _Pragma("unroll") for (int k = 0; k < 2; ++k) \
;     dst[n][k] = *reinterpret_cast<const bf16x8*>((char*)SB(b, h) + lds_byte(wc * 32 + n * 16 + fr, k * 32 + fq * 8))
; #define WAIT_V(n) asm volatile("s_waitcnt vmcnt(" #n ")" ::: "memory")
; #define WAIT_L(n) asm volatile("s_waitcnt lgkmcnt(" #n ")" ::: "memory")
; #define BAR __builtin_amdgcn_s_barrier()
; __device__ __forceinline__ void gemm256(const bf16_t* __restrict__ A, long lda, const bf16_t* __restrict__ Bt, long ldb, int K,
;                                         int brow, int bcol, char* smem, f32x4 (&acc)[2][2][4][2]) {
;     ...
;         LDB(B0, 0, 0); SCHED; LDA(At, 0, 0); STAGE(SA(1, 1), A, lda, brow + 128, t + 1);
;         WAIT_L(8); BAR; WAIT_L(0); MMA(0, 0, At, B0); BAR; SCHED;
;         LDB(B1, 0, 1); STAGE(SB(0, 0), Bt, ldb, bcol, t + 2);
;         BAR; WAIT_L(0); MMA(0, 1, At, B1); BAR;
;         LDA(At, 0, 1); STAGE(SA(0, 0), A, lda, brow, t + 2);
;         BAR; WAIT_L(0); MMA(1, 0, At, B0); BAR; SCHED;
;         STAGE(SB(0, 1), Bt, ldb, bcol + 128, t + 2);
;         WAIT_V(6); BAR; MMA(1, 1, At, B1); BAR;
;         LDB(B0, 1, 0); SCHED; LDA(At, 1, 0); STAGE(SA(0, 1), A, lda, brow + 128, t + 2);
;         WAIT_L(8); BAR; WAIT_L(0); MMA(0, 0, At, B0); BAR; SCHED;
;         LDB(B1, 1, 1); STAGE(SB(1, 0), Bt, ldb, bcol, t + 3);
;         BAR; WAIT_L(0); MMA(0, 1, At, B1); BAR;
;         LDA(At, 1, 1); STAGE(SA(1, 0), A, lda, brow, t + 3);
;         BAR; WAIT_L(0); MMA(1, 0, At, B0); BAR; SCHED;
;         STAGE(SB(1, 1), Bt, ldb, bcol + 128, t + 3);
;         WAIT_V(6); BAR; MMA(1, 1, At, B1); BAR;
;     }
;     { LDB(B0, 0, 0); LDA(At, 0, 0); STAGE(SA(1, 1), A, lda, brow + 128, nt - 1);
	s_waitcnt lgkmcnt(0)
	s_setprio 1
	s_waitcnt lgkmcnt(0)
	v_mfma_f32_16x16x32_bf16 v[126:129], v[146:149], v[202:205], v[126:129]
	v_mfma_f32_16x16x32_bf16 v[44:47], v[146:149], v[210:213], v[46:49]
	v_mfma_f32_16x16x32_bf16 v[48:51], v[154:157], v[202:205], v[50:53]
	v_mfma_f32_16x16x32_bf16 v[52:55], v[154:157], v[210:213], v[54:57]
	v_mfma_f32_16x16x32_bf16 v[56:59], v[186:189], v[202:205], v[58:61]
	v_mfma_f32_16x16x32_bf16 v[60:63], v[186:189], v[210:213], v[62:65]
	v_mfma_f32_16x16x32_bf16 v[64:67], v[194:197], v[202:205], v[66:69]
	v_mfma_f32_16x16x32_bf16 v[68:71], v[194:197], v[210:213], v[70:73]
	v_mfma_f32_16x16x32_bf16 v[126:129], v[150:153], v[206:209], v[126:129]
	v_mfma_f32_16x16x32_bf16 v[44:47], v[150:153], v[214:217], v[44:47]
	v_mfma_f32_16x16x32_bf16 v[48:51], v[182:185], v[206:209], v[48:51]
	v_mfma_f32_16x16x32_bf16 v[52:55], v[182:185], v[214:217], v[52:55]
	v_mfma_f32_16x16x32_bf16 v[56:59], v[190:193], v[206:209], v[56:59]
	v_mfma_f32_16x16x32_bf16 v[60:63], v[190:193], v[214:217], v[60:63]
	v_mfma_f32_16x16x32_bf16 v[64:67], v[198:201], v[206:209], v[64:67]
	v_mfma_f32_16x16x32_bf16 v[68:71], v[198:201], v[214:217], v[68:71]
	s_setprio 0
	s_mov_b32 m0, s17
	v_lshl_add_u64 v[8:9], v[10:11], 0, s[22:23]
	s_barrier
	s_nop 0
	ds_read_b128 v[146:149], v20 offset:49152
	ds_read_b128 v[150:153], v20 offset:50176
	ds_read_b128 v[154:157], v5 offset:51200
	ds_read_b128 v[182:185], v5 offset:52224
	ds_read_b128 v[186:189], v5 offset:53248
	ds_read_b128 v[190:193], v5 offset:54272
	ds_read_b128 v[194:197], v5 offset:55296
	ds_read_b128 v[198:201], v5 offset:56320
	global_load_lds_dwordx4 v[8:9], off
	v_lshl_add_u64 v[8:9], v[12:13], 0, s[22:23]
	s_mov_b32 m0, s16
	s_nop 0
	global_load_lds_dwordx4 v[8:9], off
	s_barrier
	s_waitcnt lgkmcnt(0)
	s_setprio 1
	s_waitcnt lgkmcnt(0)
	v_mfma_f32_16x16x32_bf16 v[8:11], v[146:149], v[118:121], v[158:161]
	v_mfma_f32_16x16x32_bf16 v[28:31], v[194:197], v[118:121], v[28:31]
	v_mfma_f32_16x16x32_bf16 v[32:35], v[194:197], v[138:141], v[32:35]
	v_mfma_f32_16x16x32_bf16 v[8:11], v[150:153], v[122:125], v[8:11]
	v_mfma_f32_16x16x32_bf16 v[158:161], v[146:149], v[138:141], v[162:165]
	v_mfma_f32_16x16x32_bf16 v[162:165], v[154:157], v[118:121], v[166:169]
	v_mfma_f32_16x16x32_bf16 v[166:169], v[154:157], v[138:141], v[170:173]
	v_mfma_f32_16x16x32_bf16 v[170:173], v[186:189], v[118:121], v[174:177]
	v_mfma_f32_16x16x32_bf16 v[174:177], v[186:189], v[138:141], v[178:181]
	v_mfma_f32_16x16x32_bf16 v[28:31], v[198:201], v[122:125], v[28:31]
	v_mfma_f32_16x16x32_bf16 v[32:35], v[198:201], v[142:145], v[32:35]
	v_mfma_f32_16x16x32_bf16 v[158:161], v[150:153], v[142:145], v[158:161]
	v_mfma_f32_16x16x32_bf16 v[162:165], v[182:185], v[122:125], v[162:165]
	v_mfma_f32_16x16x32_bf16 v[166:169], v[182:185], v[142:145], v[166:169]
	v_mfma_f32_16x16x32_bf16 v[170:173], v[190:193], v[122:125], v[170:173]
	v_mfma_f32_16x16x32_bf16 v[174:177], v[190:193], v[142:145], v[174:177]
	s_setprio 0
	s_barrier
	s_add_u32 s8, s8, 0x40180
	s_addc_u32 s9, s9, 0
	v_lshl_add_u64 v[12:13], s[8:9], 0, v[14:15]
	s_mov_b32 m0, s13
	v_lshl_add_u64 v[12:13], v[12:13], 0, v[2:3]
	global_load_lds_dwordx4 v[12:13], off
	v_lshl_add_u64 v[12:13], s[8:9], 0, v[16:17]
	v_lshl_add_u64 v[12:13], v[12:13], 0, v[6:7]
	s_mov_b32 m0, s12
	s_nop 0
	global_load_lds_dwordx4 v[12:13], off
	s_waitcnt vmcnt(6)
	s_barrier
	s_setprio 1
	v_mfma_f32_16x16x32_bf16 v[22:25], v[146:149], v[202:205], v[24:27]
	v_mfma_f32_16x16x32_bf16 v[36:39], v[146:149], v[210:213], v[36:39]
	v_mfma_f32_16x16x32_bf16 v[40:43], v[154:157], v[202:205], v[40:43]
	v_mfma_f32_16x16x32_bf16 v[72:75], v[154:157], v[210:213], v[74:77]
	v_mfma_f32_16x16x32_bf16 v[118:121], v[186:189], v[202:205], v[130:133]
	v_mfma_f32_16x16x32_bf16 v[122:125], v[186:189], v[210:213], v[134:137]
	v_mfma_f32_16x16x32_bf16 v[110:113], v[194:197], v[202:205], v[110:113]
	v_mfma_f32_16x16x32_bf16 v[114:117], v[194:197], v[210:213], v[114:117]
	v_mfma_f32_16x16x32_bf16 v[22:25], v[150:153], v[206:209], v[22:25]
	v_mfma_f32_16x16x32_bf16 v[36:39], v[150:153], v[214:217], v[36:39]
	v_mfma_f32_16x16x32_bf16 v[40:43], v[182:185], v[206:209], v[40:43]
	v_mfma_f32_16x16x32_bf16 v[72:75], v[182:185], v[214:217], v[72:75]
	v_mfma_f32_16x16x32_bf16 v[118:121], v[190:193], v[206:209], v[118:121]
	v_mfma_f32_16x16x32_bf16 v[122:125], v[190:193], v[214:217], v[122:125]
	v_mfma_f32_16x16x32_bf16 v[110:113], v[198:201], v[206:209], v[110:113]
	v_mfma_f32_16x16x32_bf16 v[114:117], v[198:201], v[214:217], v[114:117]
	s_setprio 0
	s_add_u32 s8, s10, 0x40180
	s_addc_u32 s9, s11, 0
	v_lshl_add_u64 v[12:13], s[8:9], 0, v[14:15]
	s_mov_b32 m0, s21
	v_lshl_add_u64 v[2:3], v[12:13], 0, v[2:3]
	s_barrier
	s_nop 0
	ds_read_b128 v[130:133], v218
	ds_read_b128 v[134:137], v219
	ds_read_b128 v[138:141], v220
	ds_read_b128 v[142:145], v221
	ds_read_b128 v[146:149], v20
	ds_read_b128 v[150:153], v20 offset:1024
	ds_read_b128 v[154:157], v5 offset:2048
	ds_read_b128 v[178:181], v5 offset:3072
	ds_read_b128 v[182:185], v5 offset:4096
	ds_read_b128 v[186:189], v5 offset:5120
	ds_read_b128 v[190:193], v5 offset:6144
	ds_read_b128 v[194:197], v5 offset:7168
	global_load_lds_dwordx4 v[2:3], off
	v_lshl_add_u64 v[2:3], s[8:9], 0, v[16:17]
	v_lshl_add_u64 v[2:3], v[2:3], 0, v[6:7]
	s_mov_b32 m0, s20
	s_nop 0
	global_load_lds_dwordx4 v[2:3], off
	s_barrier
; #define STAGE(P, BASE, LD, br, kt) do { const long _g = (long)(br) * (LD) + (long)(kt) * 64; \
;     _Pragma("unroll") for (int _i = 0; _i < 2; ++_i) { const int _b = tid * 16 + _i * 8192; int _r, _c; stage_rc(_b, _r, _c); \
;       __builtin_amdgcn_global_load_lds((const G_AS1 unsigned*)((BASE) + _g + (long)_r * (LD) + _c), \
;         (LAS unsigned*)((char*)(P) + _b), 16, 0, 0); } } while (0)
; #define LDA(dst, b, h) _Pragma("unroll") for (int m = 0; m < 4; ++m) _Pragma("unroll") for (int k = 0; k < 2; ++k) \
;     dst[m][k] = *reinterpret_cast<const bf16x8*>((char*)SA(b, h) + lds_byte(wr * 64 + m * 16 + fr, k * 32 + fq * 8))
; #define LDB(dst, b, h) _Pragma("unroll") for (int n = 0; n < 2; ++n) _Pragma("unroll") for (int k = 0; k < 2; ++k) \
;     dst[n][k] = *reinterpret_cast<const bf16x8*>((char*)SB(b, h) + lds_byte(wc * 32 + n * 16 + fr, k * 32 + fq * 8))
; #define MMA(ai, bj, At_, Bt_) do { __builtin_amdgcn_s_setprio(1); \
;     _Pragma("unroll") for (int m = 0; m < 4; ++m) _Pragma("unroll") for (int n = 0; n < 2; ++n) _Pragma("unroll") for (int k = 0; k < 2; ++k) \
;       acc[ai][bj][m][n] = __builtin_amdgcn_mfma_f32_16x16x32_bf16(At_[m][k], Bt_[n][k], acc[ai][bj][m][n], 0, 0, 0); \
;     __builtin_amdgcn_s_setprio(0); } while (0)
; #define WAIT_V(n) asm volatile("s_waitcnt vmcnt(" #n ")" ::: "memory")
; #define WAIT_L(n) asm volatile("s_waitcnt lgkmcnt(" #n ")" ::: "memory")
; #define BAR __builtin_amdgcn_s_barrier()
; __device__ __forceinline__ void gemm256(const bf16_t* __restrict__ A, long lda, const bf16_t* __restrict__ Bt, long ldb, int K,
;                                         int brow, int bcol, char* smem, f32x4 (&acc)[2][2][4][2]) {
;     ...
;     { LDB(B0, 0, 0); LDA(At, 0, 0); STAGE(SA(1, 1), A, lda, brow + 128, nt - 1);
;       BAR; WAIT_L(0); MMA(0, 0, At, B0); BAR;
;       LDB(B1, 0, 1); BAR; WAIT_L(0); MMA(0, 1, At, B1); BAR;
;       LDA(At, 0, 1); WAIT_V(4); BAR; WAIT_L(0); MMA(1, 0, At, B0); MMA(1, 1, At, B1); BAR; }
	s_waitcnt lgkmcnt(0)
	s_setprio 1
	s_waitcnt lgkmcnt(0)
	v_mfma_f32_16x16x32_bf16 v[12:15], v[146:149], v[130:133], v[78:81]
	v_mfma_f32_16x16x32_bf16 v[16:19], v[146:149], v[138:141], v[82:85]
	v_mfma_f32_16x16x32_bf16 v[76:79], v[154:157], v[130:133], v[86:89]
	v_mfma_f32_16x16x32_bf16 v[80:83], v[154:157], v[138:141], v[90:93]
	v_mfma_f32_16x16x32_bf16 v[84:87], v[182:185], v[130:133], v[94:97]
	v_mfma_f32_16x16x32_bf16 v[88:91], v[182:185], v[138:141], v[98:101]
	v_mfma_f32_16x16x32_bf16 v[94:97], v[190:193], v[130:133], v[102:105]
	v_mfma_f32_16x16x32_bf16 v[98:101], v[190:193], v[138:141], v[106:109]
	v_mfma_f32_16x16x32_bf16 v[12:15], v[150:153], v[134:137], v[12:15]
	v_mfma_f32_16x16x32_bf16 v[16:19], v[150:153], v[142:145], v[16:19]
	v_mfma_f32_16x16x32_bf16 v[76:79], v[178:181], v[134:137], v[76:79]
	v_mfma_f32_16x16x32_bf16 v[80:83], v[178:181], v[142:145], v[80:83]
	v_mfma_f32_16x16x32_bf16 v[84:87], v[186:189], v[134:137], v[84:87]
	v_mfma_f32_16x16x32_bf16 v[90:93], v[186:189], v[142:145], v[88:91]
	v_mfma_f32_16x16x32_bf16 v[94:97], v[194:197], v[134:137], v[94:97]
	v_mfma_f32_16x16x32_bf16 v[98:101], v[194:197], v[142:145], v[98:101]
	s_setprio 0
	s_barrier
	s_nop 0
	ds_read_b128 v[102:105], v222
	ds_read_b128 v[106:109], v223
	ds_read_b128 v[198:201], v224
	ds_read_b128 v[202:205], v225
	s_barrier
	s_waitcnt lgkmcnt(0)
	s_setprio 1
	s_waitcnt lgkmcnt(3)
	v_mfma_f32_16x16x32_bf16 v[126:129], v[146:149], v[102:105], v[126:129]
	s_waitcnt lgkmcnt(1)
	v_mfma_f32_16x16x32_bf16 v[44:47], v[146:149], v[198:201], v[44:47]
	v_mfma_f32_16x16x32_bf16 v[48:51], v[154:157], v[102:105], v[48:51]
	v_mfma_f32_16x16x32_bf16 v[52:55], v[154:157], v[198:201], v[52:55]
	v_mfma_f32_16x16x32_bf16 v[56:59], v[182:185], v[102:105], v[56:59]
	v_mfma_f32_16x16x32_bf16 v[60:63], v[182:185], v[198:201], v[60:63]
	v_mfma_f32_16x16x32_bf16 v[64:67], v[190:193], v[102:105], v[64:67]
	v_mfma_f32_16x16x32_bf16 v[126:129], v[150:153], v[106:109], v[126:129]
	s_waitcnt lgkmcnt(0)
	v_mfma_f32_16x16x32_bf16 v[44:47], v[150:153], v[202:205], v[44:47]
	v_mfma_f32_16x16x32_bf16 v[48:51], v[178:181], v[106:109], v[48:51]
	v_mfma_f32_16x16x32_bf16 v[52:55], v[178:181], v[202:205], v[52:55]
	v_mfma_f32_16x16x32_bf16 v[56:59], v[186:189], v[106:109], v[56:59]
	v_mfma_f32_16x16x32_bf16 v[60:63], v[186:189], v[202:205], v[60:63]
	v_mfma_f32_16x16x32_bf16 v[64:67], v[194:197], v[106:109], v[64:67]
	v_mfma_f32_16x16x32_bf16 v[68:71], v[190:193], v[198:201], v[68:71]
	v_mfma_f32_16x16x32_bf16 v[146:149], v[194:197], v[202:205], v[68:71]
	s_setprio 0
	s_barrier
	s_nop 4
	ds_read_b128 v[68:71], v20 offset:16384
	ds_read_b128 v[150:153], v20 offset:17408
	ds_read_b128 v[154:157], v5 offset:18432
	ds_read_b128 v[178:181], v5 offset:19456
	ds_read_b128 v[182:185], v5 offset:20480
	ds_read_b128 v[186:189], v5 offset:21504
	ds_read_b128 v[190:193], v5 offset:22528
	ds_read_b128 v[194:197], v5 offset:23552
	s_waitcnt vmcnt(4)
	s_barrier
	s_waitcnt lgkmcnt(0)
	s_setprio 1
	s_waitcnt lgkmcnt(7)
	v_mfma_f32_16x16x32_bf16 v[6:9], v[68:71], v[130:133], v[8:11]
	s_waitcnt lgkmcnt(5)
	v_mfma_f32_16x16x32_bf16 v[162:165], v[154:157], v[130:133], v[162:165]
	s_waitcnt lgkmcnt(3)
	v_mfma_f32_16x16x32_bf16 v[170:173], v[182:185], v[130:133], v[170:173]
	s_waitcnt lgkmcnt(1)
	v_mfma_f32_16x16x32_bf16 v[26:29], v[190:193], v[130:133], v[28:31]
	v_mfma_f32_16x16x32_bf16 v[6:9], v[150:153], v[134:137], v[6:9]
	v_mfma_f32_16x16x32_bf16 v[162:165], v[178:181], v[134:137], v[162:165]
	v_mfma_f32_16x16x32_bf16 v[170:173], v[186:189], v[134:137], v[170:173]
	s_waitcnt lgkmcnt(0)
	v_mfma_f32_16x16x32_bf16 v[134:137], v[194:197], v[134:137], v[26:29]
	v_mfma_f32_16x16x32_bf16 v[26:29], v[190:193], v[138:141], v[32:35]
	v_mfma_f32_16x16x32_bf16 v[158:161], v[68:71], v[138:141], v[158:161]
	v_mfma_f32_16x16x32_bf16 v[166:169], v[154:157], v[138:141], v[166:169]
	v_mfma_f32_16x16x32_bf16 v[174:177], v[182:185], v[138:141], v[174:177]
	v_mfma_f32_16x16x32_bf16 v[30:33], v[194:197], v[142:145], v[26:29]
	v_mfma_f32_16x16x32_bf16 v[158:161], v[150:153], v[142:145], v[158:161]
	v_mfma_f32_16x16x32_bf16 v[166:169], v[178:181], v[142:145], v[166:169]
	v_mfma_f32_16x16x32_bf16 v[174:177], v[186:189], v[142:145], v[174:177]
	s_setprio 0
	s_setprio 1
	v_mfma_f32_16x16x32_bf16 v[22:25], v[68:71], v[102:105], v[22:25]
	v_mfma_f32_16x16x32_bf16 v[138:141], v[150:153], v[106:109], v[22:25]
	v_mfma_f32_16x16x32_bf16 v[22:25], v[68:71], v[198:201], v[36:39]
	v_mfma_f32_16x16x32_bf16 v[34:37], v[150:153], v[202:205], v[22:25]
	v_mfma_f32_16x16x32_bf16 v[22:25], v[154:157], v[102:105], v[40:43]
	v_mfma_f32_16x16x32_bf16 v[142:145], v[178:181], v[106:109], v[22:25]
	v_mfma_f32_16x16x32_bf16 v[22:25], v[154:157], v[198:201], v[72:75]
	v_mfma_f32_16x16x32_bf16 v[150:153], v[178:181], v[202:205], v[22:25]
	v_mfma_f32_16x16x32_bf16 v[22:25], v[182:185], v[102:105], v[118:121]
	v_mfma_f32_16x16x32_bf16 v[154:157], v[186:189], v[106:109], v[22:25]
	v_mfma_f32_16x16x32_bf16 v[22:25], v[182:185], v[198:201], v[122:125]
	v_mfma_f32_16x16x32_bf16 v[178:181], v[186:189], v[202:205], v[22:25]
	v_mfma_f32_16x16x32_bf16 v[22:25], v[190:193], v[102:105], v[110:113]
	v_mfma_f32_16x16x32_bf16 v[182:185], v[194:197], v[106:109], v[22:25]
	v_mfma_f32_16x16x32_bf16 v[22:25], v[190:193], v[198:201], v[114:117]
	v_mfma_f32_16x16x32_bf16 v[186:189], v[194:197], v[202:205], v[22:25]
	s_setprio 0
	s_barrier
; #define LDA(dst, b, h) _Pragma("unroll") for (int m = 0; m < 4; ++m) _Pragma("unroll") for (int k = 0; k < 2; ++k) \
;     dst[m][k] = *reinterpret_cast<const bf16x8*>((char*)SA(b, h) + lds_byte(wr * 64 + m * 16 + fr, k * 32 + fq * 8))
; #define LDB(dst, b, h) _Pragma("unroll") for (int n = 0; n < 2; ++n) _Pragma("unroll") for (int k = 0; k < 2; ++k) \
;     dst[n][k] = *reinterpret_cast<const bf16x8*>((char*)SB(b, h) + lds_byte(wc * 32 + n * 16 + fr, k * 32 + fq * 8))
; #define MMA(ai, bj, At_, Bt_) do { __builtin_amdgcn_s_setprio(1); \
;     _Pragma("unroll") for (int m = 0; m < 4; ++m) _Pragma("unroll") for (int n = 0; n < 2; ++n) _Pragma("unroll") for (int k = 0; k < 2; ++k) \
;       acc[ai][bj][m][n] = __builtin_amdgcn_mfma_f32_16x16x32_bf16(At_[m][k], Bt_[n][k], acc[ai][bj][m][n], 0, 0, 0); \
;     __builtin_amdgcn_s_setprio(0); } while (0)
; #define WAIT_V(n) asm volatile("s_waitcnt vmcnt(" #n ")" ::: "memory")
; #define WAIT_L(n) asm volatile("s_waitcnt lgkmcnt(" #n ")" ::: "memory")
; #define BAR __builtin_amdgcn_s_barrier()
; __device__ __forceinline__ void gemm256(const bf16_t* __restrict__ A, long lda, const bf16_t* __restrict__ Bt, long ldb, int K,
;                                         int brow, int bcol, char* smem, f32x4 (&acc)[2][2][4][2]) {
;     ...
;     { LDB(B0, 1, 0); LDA(At, 1, 0); WAIT_V(2); BAR; WAIT_L(0); MMA(0, 0, At, B0); BAR;
;       LDB(B1, 1, 1); WAIT_V(0); BAR; WAIT_L(0); MMA(0, 1, At, B1); BAR;
;       LDA(At, 1, 1); BAR; WAIT_L(0); MMA(1, 0, At, B0); MMA(1, 1, At, B1); BAR; }
;     if (wr == 0) BAR;
	ds_read_b128 v[190:193], v226
	ds_read_b128 v[194:197], v227
	ds_read_b128 v[198:201], v228
	ds_read_b128 v[202:205], v229
	s_nop 0
	ds_read_b128 v[22:25], v20 offset:32768
	ds_read_b128 v[26:29], v20 offset:33792
	ds_read_b128 v[38:41], v5 offset:34816
	ds_read_b128 v[114:117], v5 offset:35840
	ds_read_b128 v[206:209], v5 offset:36864
	ds_read_b128 v[210:213], v5 offset:37888
	ds_read_b128 v[214:217], v5 offset:38912
	ds_read_b128 v[218:221], v5 offset:39936
	s_waitcnt vmcnt(2)
	s_barrier
	s_waitcnt lgkmcnt(0)
	s_setprio 1
	s_waitcnt lgkmcnt(7)
	v_mfma_f32_16x16x32_bf16 v[10:13], v[22:25], v[190:193], v[12:15]
	s_waitcnt lgkmcnt(6)
	v_mfma_f32_16x16x32_bf16 v[118:121], v[26:29], v[194:197], v[10:13]
	v_mfma_f32_16x16x32_bf16 v[10:13], v[22:25], v[198:201], v[16:19]
	v_mfma_f32_16x16x32_bf16 v[122:125], v[26:29], v[202:205], v[10:13]
	s_waitcnt lgkmcnt(5)
	v_mfma_f32_16x16x32_bf16 v[10:13], v[38:41], v[190:193], v[76:79]
	s_waitcnt lgkmcnt(4)
	v_mfma_f32_16x16x32_bf16 v[102:105], v[114:117], v[194:197], v[10:13]
	v_mfma_f32_16x16x32_bf16 v[10:13], v[38:41], v[198:201], v[80:83]
	v_mfma_f32_16x16x32_bf16 v[106:109], v[114:117], v[202:205], v[10:13]
	s_waitcnt lgkmcnt(3)
	v_mfma_f32_16x16x32_bf16 v[10:13], v[206:209], v[190:193], v[84:87]
	s_waitcnt lgkmcnt(2)
	v_mfma_f32_16x16x32_bf16 v[86:89], v[210:213], v[194:197], v[10:13]
	v_mfma_f32_16x16x32_bf16 v[10:13], v[206:209], v[198:201], v[90:93]
	v_mfma_f32_16x16x32_bf16 v[90:93], v[210:213], v[202:205], v[10:13]
	s_waitcnt lgkmcnt(1)
	v_mfma_f32_16x16x32_bf16 v[10:13], v[214:217], v[190:193], v[94:97]
	s_waitcnt lgkmcnt(0)
	v_mfma_f32_16x16x32_bf16 v[70:73], v[218:221], v[194:197], v[10:13]
	v_mfma_f32_16x16x32_bf16 v[10:13], v[214:217], v[198:201], v[98:101]
	v_mfma_f32_16x16x32_bf16 v[74:77], v[218:221], v[202:205], v[10:13]
	s_setprio 0
	s_barrier
	ds_read_b128 v[14:17], v230
	ds_read_b128 v[222:225], v231
	ds_read_b128 v[226:229], v232
	ds_read_b128 v[230:233], v233
	s_waitcnt vmcnt(0)
	s_barrier
	s_waitcnt lgkmcnt(0)
	s_setprio 1
	s_waitcnt lgkmcnt(3)
	v_mfma_f32_16x16x32_bf16 v[10:13], v[22:25], v[14:17], v[126:129]
	s_waitcnt lgkmcnt(2)
	v_mfma_f32_16x16x32_bf16 v[126:129], v[26:29], v[222:225], v[10:13]
	s_waitcnt lgkmcnt(1)
	v_mfma_f32_16x16x32_bf16 v[10:13], v[22:25], v[226:229], v[44:47]
	s_waitcnt lgkmcnt(0)
	v_mfma_f32_16x16x32_bf16 v[130:133], v[26:29], v[230:233], v[10:13]
	v_mfma_f32_16x16x32_bf16 v[10:13], v[38:41], v[14:17], v[48:51]
	v_mfma_f32_16x16x32_bf16 v[110:113], v[114:117], v[222:225], v[10:13]
	v_mfma_f32_16x16x32_bf16 v[10:13], v[38:41], v[226:229], v[52:55]
	v_mfma_f32_16x16x32_bf16 v[114:117], v[114:117], v[230:233], v[10:13]
	v_mfma_f32_16x16x32_bf16 v[10:13], v[206:209], v[14:17], v[56:59]
	v_mfma_f32_16x16x32_bf16 v[94:97], v[210:213], v[222:225], v[10:13]
	v_mfma_f32_16x16x32_bf16 v[10:13], v[206:209], v[226:229], v[60:63]
	v_mfma_f32_16x16x32_bf16 v[98:101], v[210:213], v[230:233], v[10:13]
	v_mfma_f32_16x16x32_bf16 v[10:13], v[214:217], v[14:17], v[64:67]
	v_mfma_f32_16x16x32_bf16 v[78:81], v[218:221], v[222:225], v[10:13]
	v_mfma_f32_16x16x32_bf16 v[10:13], v[214:217], v[226:229], v[146:149]
	v_mfma_f32_16x16x32_bf16 v[82:85], v[218:221], v[230:233], v[10:13]
	s_setprio 0
	s_barrier
	ds_read_b128 v[46:49], v20 offset:49152
	ds_read_b128 v[18:21], v20 offset:50176
	ds_read_b128 v[50:53], v5 offset:51200
	ds_read_b128 v[146:149], v5 offset:52224
	ds_read_b128 v[206:209], v5 offset:53248
	ds_read_b128 v[210:213], v5 offset:54272
	ds_read_b128 v[214:217], v5 offset:55296
	ds_read_b128 v[218:221], v5 offset:56320
	s_barrier
	s_waitcnt lgkmcnt(0)
	s_setprio 1
	s_waitcnt lgkmcnt(7)
	v_mfma_f32_16x16x32_bf16 v[6:9], v[46:49], v[190:193], v[6:9]
	s_waitcnt lgkmcnt(6)
	v_mfma_f32_16x16x32_bf16 v[58:61], v[18:21], v[194:197], v[6:9]
	v_mfma_f32_16x16x32_bf16 v[6:9], v[46:49], v[198:201], v[158:161]
	v_mfma_f32_16x16x32_bf16 v[54:57], v[18:21], v[202:205], v[6:9]
	s_waitcnt lgkmcnt(5)
	v_mfma_f32_16x16x32_bf16 v[6:9], v[50:53], v[190:193], v[162:165]
	s_waitcnt lgkmcnt(4)
	v_mfma_f32_16x16x32_bf16 v[38:41], v[146:149], v[194:197], v[6:9]
	v_mfma_f32_16x16x32_bf16 v[6:9], v[50:53], v[198:201], v[166:169]
	v_mfma_f32_16x16x32_bf16 v[42:45], v[146:149], v[202:205], v[6:9]
	s_waitcnt lgkmcnt(3)
	v_mfma_f32_16x16x32_bf16 v[6:9], v[206:209], v[190:193], v[170:173]
	s_waitcnt lgkmcnt(2)
	v_mfma_f32_16x16x32_bf16 v[22:25], v[210:213], v[194:197], v[6:9]
	v_mfma_f32_16x16x32_bf16 v[6:9], v[206:209], v[198:201], v[174:177]
	v_mfma_f32_16x16x32_bf16 v[26:29], v[210:213], v[202:205], v[6:9]
	s_waitcnt lgkmcnt(1)
	v_mfma_f32_16x16x32_bf16 v[6:9], v[214:217], v[190:193], v[134:137]
	s_waitcnt lgkmcnt(0)
	v_mfma_f32_16x16x32_bf16 v[10:13], v[218:221], v[194:197], v[6:9]
	v_mfma_f32_16x16x32_bf16 v[6:9], v[214:217], v[198:201], v[30:33]
	v_mfma_f32_16x16x32_bf16 v[6:9], v[218:221], v[202:205], v[6:9]
	s_setprio 0
	s_setprio 1
	v_mfma_f32_16x16x32_bf16 v[30:33], v[46:49], v[14:17], v[138:141]
	v_mfma_f32_16x16x32_bf16 v[62:65], v[18:21], v[222:225], v[30:33]
	v_mfma_f32_16x16x32_bf16 v[30:33], v[46:49], v[226:229], v[34:37]
	v_mfma_f32_16x16x32_bf16 v[66:69], v[18:21], v[230:233], v[30:33]
	v_mfma_f32_16x16x32_bf16 v[18:21], v[50:53], v[14:17], v[142:145]
	v_mfma_f32_16x16x32_bf16 v[46:49], v[146:149], v[222:225], v[18:21]
	v_mfma_f32_16x16x32_bf16 v[18:21], v[50:53], v[226:229], v[150:153]
	v_mfma_f32_16x16x32_bf16 v[50:53], v[146:149], v[230:233], v[18:21]
	v_mfma_f32_16x16x32_bf16 v[18:21], v[206:209], v[14:17], v[154:157]
	v_mfma_f32_16x16x32_bf16 v[30:33], v[210:213], v[222:225], v[18:21]
	v_mfma_f32_16x16x32_bf16 v[18:21], v[206:209], v[226:229], v[178:181]
	v_mfma_f32_16x16x32_bf16 v[34:37], v[210:213], v[230:233], v[18:21]
	v_mfma_f32_16x16x32_bf16 v[14:17], v[214:217], v[14:17], v[182:185]
	v_mfma_f32_16x16x32_bf16 v[18:21], v[214:217], v[226:229], v[186:189]
	v_mfma_f32_16x16x32_bf16 v[14:17], v[218:221], v[222:225], v[14:17]
	v_mfma_f32_16x16x32_bf16 v[18:21], v[218:221], v[230:233], v[18:21]
	s_setprio 0
	v_cmp_gt_u32_e32 vcc, s78, v0
	s_barrier
	s_and_saveexec_b64 s[8:9], vcc
	s_cbranch_execz .LBB0_1029
	s_barrier

; #define STAGE(P, BASE, LD, br, kt) do { const long _g = (long)(br) * (LD) + (long)(kt) * 64; \
;     _Pragma("unroll") for (int _i = 0; _i < 2; ++_i) { const int _b = tid * 16 + _i * 8192; int _r, _c; stage_rc(_b, _r, _c); \
;       __builtin_amdgcn_global_load_lds((const G_AS1 unsigned*)((BASE) + _g + (long)_r * (LD) + _c), \
;         (LAS unsigned*)((char*)(P) + _b), 16, 0, 0); } } while (0)
; #define LDA(dst, b, h) _Pragma("unroll") for (int m = 0; m < 4; ++m) _Pragma("unroll") for (int k = 0; k < 2; ++k) \
;     dst[m][k] = *reinterpret_cast<const bf16x8*>((char*)SA(b, h) + lds_byte(wr * 64 + m * 16 + fr, k * 32 + fq * 8))
; #define LDB(dst, b, h) _Pragma("unroll") for (int n = 0; n < 2; ++n) _Pragma("unroll") for (int k = 0; k < 2; ++k) \
;     dst[n][k] = *reinterpret_cast<const bf16x8*>((char*)SB(b, h) + lds_byte(wc * 32 + n * 16 + fr, k * 32 + fq * 8))
; #define MMA(ai, bj, At_, Bt_) do { __builtin_amdgcn_s_setprio(1); \
;     _Pragma("unroll") for (int m = 0; m < 4; ++m) _Pragma("unroll") for (int n = 0; n < 2; ++n) _Pragma("unroll") for (int k = 0; k < 2; ++k) \
;       acc[ai][bj][m][n] = __builtin_amdgcn_mfma_f32_16x16x32_bf16(At_[m][k], Bt_[n][k], acc[ai][bj][m][n], 0, 0, 0); \
;     __builtin_amdgcn_s_setprio(0); } while (0)
; #define WAIT_L(n) asm volatile("s_waitcnt lgkmcnt(" #n ")" ::: "memory")
; #define BAR __builtin_amdgcn_s_barrier()
; #define SCHED __builtin_amdgcn_sched_barrier(0)
; __device__ __forceinline__ void gemm256(const bf16_t* __restrict__ A, long lda, const bf16_t* __restrict__ Bt, long ldb, int K,
;                                         int brow, int bcol, char* smem, f32x4 (&acc)[2][2][4][2]) {
;     ...
;         LDB(B0, 0, 0); SCHED; LDA(At, 0, 0); STAGE(SA(1, 1), A, lda, brow + 128, t + 1);
;         WAIT_L(8); BAR; WAIT_L(0); MMA(0, 0, At, B0); BAR; SCHED;
;         LDB(B1, 0, 1); STAGE(SB(0, 0), Bt, ldb, bcol, t + 2);
;         BAR; WAIT_L(0); MMA(0, 1, At, B1); BAR;
;         LDA(At, 0, 1); STAGE(SA(0, 0), A, lda, brow, t + 2);
;         BAR; WAIT_L(0); MMA(1, 0, At, B0); BAR; SCHED;
.LBB0_1034:
	s_nop 0
	ds_read_b128 v[168:171], v164
	ds_read_b128 v[172:175], v164 offset:1024
	ds_read_b128 v[176:179], v164 offset:2048
	ds_read_b128 v[180:183], v164 offset:3072
	v_add_u32_e32 v165, 0xc000, v5
	v_lshl_add_u64 v[232:233], s[6:7], 0, v[140:141]
	v_readfirstlane_b32 s11, v165
	v_lshl_add_u64 v[166:167], v[232:233], 0, s[60:61]
	s_mov_b32 m0, s11
	ds_read_b128 v[184:187], v147
	ds_read_b128 v[188:191], v147 offset:1024
	ds_read_b128 v[192:195], v146
	ds_read_b128 v[196:199], v146 offset:1024
	ds_read_b128 v[200:203], v145
	ds_read_b128 v[204:207], v145 offset:1024
	ds_read_b128 v[208:211], v144
	ds_read_b128 v[212:215], v144 offset:1024
	global_load_lds_dwordx4 v[166:167], off
	v_add_u32_e32 v166, 0xe000, v5
	v_lshl_add_u64 v[234:235], s[6:7], 0, v[142:143]
	v_readfirstlane_b32 s11, v166
	v_lshl_add_u64 v[216:217], v[234:235], 0, s[60:61]
	s_mov_b32 m0, s11
	s_nop 0
	global_load_lds_dwordx4 v[216:217], off
	s_waitcnt lgkmcnt(8)
	s_barrier
	s_waitcnt lgkmcnt(0)
	s_setprio 1
	s_waitcnt lgkmcnt(0)
	v_mfma_f32_16x16x32_bf16 v[130:133], v[184:187], v[168:171], v[130:133]
	v_mfma_f32_16x16x32_bf16 v[126:129], v[184:187], v[176:179], v[126:129]
	v_mfma_f32_16x16x32_bf16 v[122:125], v[192:195], v[168:171], v[122:125]
	v_mfma_f32_16x16x32_bf16 v[118:121], v[192:195], v[176:179], v[118:121]
	v_mfma_f32_16x16x32_bf16 v[114:117], v[200:203], v[168:171], v[114:117]
	v_mfma_f32_16x16x32_bf16 v[110:113], v[200:203], v[176:179], v[110:113]
	v_mfma_f32_16x16x32_bf16 v[106:109], v[208:211], v[168:171], v[106:109]
	v_mfma_f32_16x16x32_bf16 v[102:105], v[208:211], v[176:179], v[102:105]
	v_mfma_f32_16x16x32_bf16 v[130:133], v[188:191], v[172:175], v[130:133]
	v_mfma_f32_16x16x32_bf16 v[126:129], v[188:191], v[180:183], v[126:129]
	v_mfma_f32_16x16x32_bf16 v[122:125], v[196:199], v[172:175], v[122:125]
	v_mfma_f32_16x16x32_bf16 v[118:121], v[196:199], v[180:183], v[118:121]
	v_mfma_f32_16x16x32_bf16 v[114:117], v[204:207], v[172:175], v[114:117]
	v_mfma_f32_16x16x32_bf16 v[110:113], v[204:207], v[180:183], v[110:113]
	v_mfma_f32_16x16x32_bf16 v[106:109], v[212:215], v[172:175], v[106:109]
	v_mfma_f32_16x16x32_bf16 v[102:105], v[212:215], v[180:183], v[102:105]
	s_setprio 0
	s_barrier
	v_lshl_add_u64 v[238:239], s[6:7], 0, v[136:137]
	v_readfirstlane_b32 s11, v148
	v_lshl_add_u64 v[242:243], v[238:239], 0, s[12:13]
	s_mov_b32 m0, s11
	s_nop 0
	ds_read_b128 v[216:219], v161
	ds_read_b128 v[220:223], v161 offset:1024
	ds_read_b128 v[224:227], v161 offset:2048
	ds_read_b128 v[228:231], v161 offset:3072
	global_load_lds_dwordx4 v[242:243], off
	v_lshl_add_u64 v[242:243], s[6:7], 0, v[138:139]
	v_readfirstlane_b32 s11, v151
	v_lshl_add_u64 v[244:245], v[242:243], 0, s[12:13]
	s_mov_b32 m0, s11
	s_nop 0
	global_load_lds_dwordx4 v[244:245], off
	s_barrier
	s_waitcnt lgkmcnt(0)
	s_setprio 1
	s_waitcnt lgkmcnt(0)
	v_mfma_f32_16x16x32_bf16 v[98:101], v[184:187], v[216:219], v[98:101]
	v_mfma_f32_16x16x32_bf16 v[94:97], v[184:187], v[224:227], v[94:97]
	v_mfma_f32_16x16x32_bf16 v[90:93], v[192:195], v[216:219], v[90:93]
	v_mfma_f32_16x16x32_bf16 v[86:89], v[192:195], v[224:227], v[86:89]
	v_mfma_f32_16x16x32_bf16 v[82:85], v[200:203], v[216:219], v[82:85]
	v_mfma_f32_16x16x32_bf16 v[78:81], v[200:203], v[224:227], v[78:81]
	v_mfma_f32_16x16x32_bf16 v[74:77], v[208:211], v[216:219], v[74:77]
	v_mfma_f32_16x16x32_bf16 v[70:73], v[208:211], v[224:227], v[70:73]
	v_mfma_f32_16x16x32_bf16 v[98:101], v[188:191], v[220:223], v[98:101]
	v_mfma_f32_16x16x32_bf16 v[94:97], v[188:191], v[228:231], v[94:97]
	v_mfma_f32_16x16x32_bf16 v[90:93], v[196:199], v[220:223], v[90:93]
	v_mfma_f32_16x16x32_bf16 v[86:89], v[196:199], v[228:231], v[86:89]
	v_mfma_f32_16x16x32_bf16 v[82:85], v[204:207], v[220:223], v[82:85]
	v_mfma_f32_16x16x32_bf16 v[78:81], v[204:207], v[228:231], v[78:81]
	v_mfma_f32_16x16x32_bf16 v[74:77], v[212:215], v[220:223], v[74:77]
	v_mfma_f32_16x16x32_bf16 v[70:73], v[212:215], v[228:231], v[70:73]
	s_setprio 0
	v_readfirstlane_b32 s11, v5
	v_lshl_add_u64 v[244:245], v[232:233], 0, s[92:93]
	s_mov_b32 m0, s11
	v_readfirstlane_b32 s11, v149
	s_barrier
	s_nop 0
	ds_read_b128 v[184:187], v147 offset:16384
	ds_read_b128 v[188:191], v147 offset:17408
	ds_read_b128 v[192:195], v146 offset:16384
	ds_read_b128 v[196:199], v146 offset:17408
	ds_read_b128 v[200:203], v145 offset:16384
	ds_read_b128 v[204:207], v145 offset:17408
	ds_read_b128 v[208:211], v144 offset:16384
	ds_read_b128 v[212:215], v144 offset:17408
	global_load_lds_dwordx4 v[244:245], off
	v_lshl_add_u64 v[244:245], v[234:235], 0, s[92:93]
	s_mov_b32 m0, s11
	s_nop 0
	global_load_lds_dwordx4 v[244:245], off
	s_barrier
	s_waitcnt lgkmcnt(0)
	s_setprio 1
	s_waitcnt lgkmcnt(0)
	v_mfma_f32_16x16x32_bf16 v[66:69], v[184:187], v[168:171], v[66:69]
	v_mfma_f32_16x16x32_bf16 v[62:65], v[184:187], v[176:179], v[62:65]
	v_mfma_f32_16x16x32_bf16 v[58:61], v[192:195], v[168:171], v[58:61]
	v_mfma_f32_16x16x32_bf16 v[54:57], v[192:195], v[176:179], v[54:57]
	v_mfma_f32_16x16x32_bf16 v[50:53], v[200:203], v[168:171], v[50:53]
	v_mfma_f32_16x16x32_bf16 v[46:49], v[200:203], v[176:179], v[46:49]
	v_mfma_f32_16x16x32_bf16 v[42:45], v[208:211], v[168:171], v[42:45]
	v_mfma_f32_16x16x32_bf16 v[38:41], v[208:211], v[176:179], v[38:41]
	v_mfma_f32_16x16x32_bf16 v[66:69], v[188:191], v[172:175], v[66:69]
	v_mfma_f32_16x16x32_bf16 v[62:65], v[188:191], v[180:183], v[62:65]
	v_mfma_f32_16x16x32_bf16 v[58:61], v[196:199], v[172:175], v[58:61]
	v_mfma_f32_16x16x32_bf16 v[54:57], v[196:199], v[180:183], v[54:57]
	v_mfma_f32_16x16x32_bf16 v[50:53], v[204:207], v[172:175], v[50:53]
	v_mfma_f32_16x16x32_bf16 v[46:49], v[204:207], v[180:183], v[46:49]
	v_mfma_f32_16x16x32_bf16 v[42:45], v[212:215], v[172:175], v[42:45]
	v_mfma_f32_16x16x32_bf16 v[38:41], v[212:215], v[180:183], v[38:41]
	s_setprio 0
	s_barrier
; #define STAGE(P, BASE, LD, br, kt) do { const long _g = (long)(br) * (LD) + (long)(kt) * 64; \
;     _Pragma("unroll") for (int _i = 0; _i < 2; ++_i) { const int _b = tid * 16 + _i * 8192; int _r, _c; stage_rc(_b, _r, _c); \
;       __builtin_amdgcn_global_load_lds((const G_AS1 unsigned*)((BASE) + _g + (long)_r * (LD) + _c), \
;         (LAS unsigned*)((char*)(P) + _b), 16, 0, 0); } } while (0)
; #define LDA(dst, b, h) _Pragma("unroll") for (int m = 0; m < 4; ++m) _Pragma("unroll") for (int k = 0; k < 2; ++k) \
;     dst[m][k] = *reinterpret_cast<const bf16x8*>((char*)SA(b, h) + lds_byte(wr * 64 + m * 16 + fr, k * 32 + fq * 8))
; #define LDB(dst, b, h) _Pragma("unroll") for (int n = 0; n < 2; ++n) _Pragma("unroll") for (int k = 0; k < 2; ++k) \
;     dst[n][k] = *reinterpret_cast<const bf16x8*>((char*)SB(b, h) + lds_byte(wc * 32 + n * 16 + fr, k * 32 + fq * 8))
; #define MMA(ai, bj, At_, Bt_) do { __builtin_amdgcn_s_setprio(1); \
;     _Pragma("unroll") for (int m = 0; m < 4; ++m) _Pragma("unroll") for (int n = 0; n < 2; ++n) _Pragma("unroll") for (int k = 0; k < 2; ++k) \
;       acc[ai][bj][m][n] = __builtin_amdgcn_mfma_f32_16x16x32_bf16(At_[m][k], Bt_[n][k], acc[ai][bj][m][n], 0, 0, 0); \
;     __builtin_amdgcn_s_setprio(0); } while (0)
; #define WAIT_V(n) asm volatile("s_waitcnt vmcnt(" #n ")" ::: "memory")
; #define WAIT_L(n) asm volatile("s_waitcnt lgkmcnt(" #n ")" ::: "memory")
; #define BAR __builtin_amdgcn_s_barrier()
; #define SCHED __builtin_amdgcn_sched_barrier(0)
; __device__ __forceinline__ void gemm256(const bf16_t* __restrict__ A, long lda, const bf16_t* __restrict__ Bt, long ldb, int K,
;                                         int brow, int bcol, char* smem, f32x4 (&acc)[2][2][4][2]) {
;     ...
;         STAGE(SB(0, 1), Bt, ldb, bcol + 128, t + 2);
;         WAIT_V(6); BAR; MMA(1, 1, At, B1); BAR;
;         LDB(B0, 1, 0); SCHED; LDA(At, 1, 0); STAGE(SA(0, 1), A, lda, brow + 128, t + 2);
;         WAIT_L(8); BAR; WAIT_L(0); MMA(0, 0, At, B0); BAR; SCHED;
;         LDB(B1, 1, 1); STAGE(SB(1, 0), Bt, ldb, bcol, t + 3);
;         BAR; WAIT_L(0); MMA(0, 1, At, B1); BAR;
	v_readfirstlane_b32 s11, v153
	v_lshl_add_u64 v[168:169], v[238:239], 0, s[14:15]
	s_mov_b32 m0, s11
	v_readfirstlane_b32 s11, v154
	global_load_lds_dwordx4 v[168:169], off
	v_lshl_add_u64 v[168:169], v[242:243], 0, s[14:15]
	s_mov_b32 m0, s11
	s_nop 0
	global_load_lds_dwordx4 v[168:169], off
	s_waitcnt vmcnt(6)
	s_barrier
	s_setprio 1
	v_mfma_f32_16x16x32_bf16 v[34:37], v[184:187], v[216:219], v[34:37]
	v_mfma_f32_16x16x32_bf16 v[30:33], v[184:187], v[224:227], v[30:33]
	v_mfma_f32_16x16x32_bf16 v[26:29], v[192:195], v[216:219], v[26:29]
	v_mfma_f32_16x16x32_bf16 v[22:25], v[192:195], v[224:227], v[22:25]
	v_mfma_f32_16x16x32_bf16 v[18:21], v[200:203], v[216:219], v[18:21]
	v_mfma_f32_16x16x32_bf16 v[14:17], v[200:203], v[224:227], v[14:17]
	v_mfma_f32_16x16x32_bf16 v[10:13], v[208:211], v[216:219], v[10:13]
	v_mfma_f32_16x16x32_bf16 v[6:9], v[208:211], v[224:227], v[6:9]
	v_mfma_f32_16x16x32_bf16 v[34:37], v[188:191], v[220:223], v[34:37]
	v_mfma_f32_16x16x32_bf16 v[30:33], v[188:191], v[228:231], v[30:33]
	v_mfma_f32_16x16x32_bf16 v[26:29], v[196:199], v[220:223], v[26:29]
	v_mfma_f32_16x16x32_bf16 v[22:25], v[196:199], v[228:231], v[22:25]
	v_mfma_f32_16x16x32_bf16 v[18:21], v[204:207], v[220:223], v[18:21]
	v_mfma_f32_16x16x32_bf16 v[14:17], v[204:207], v[228:231], v[14:17]
	v_mfma_f32_16x16x32_bf16 v[10:13], v[212:215], v[220:223], v[10:13]
	v_mfma_f32_16x16x32_bf16 v[6:9], v[212:215], v[228:231], v[6:9]
	s_setprio 0
	s_barrier
	s_nop 0
	ds_read_b128 v[168:171], v152
	ds_read_b128 v[172:175], v152 offset:1024
	ds_read_b128 v[176:179], v152 offset:2048
	ds_read_b128 v[180:183], v152 offset:3072
	v_readfirstlane_b32 s11, v155
	v_lshl_add_u64 v[216:217], v[232:233], 0, s[54:55]
	s_mov_b32 m0, s11
	v_readfirstlane_b32 s11, v156
	ds_read_b128 v[184:187], v147 offset:32768
	ds_read_b128 v[188:191], v147 offset:33792
	ds_read_b128 v[192:195], v146 offset:32768
	ds_read_b128 v[196:199], v146 offset:33792
	ds_read_b128 v[200:203], v145 offset:32768
	ds_read_b128 v[204:207], v145 offset:33792
	ds_read_b128 v[208:211], v144 offset:32768
	ds_read_b128 v[212:215], v144 offset:33792
	global_load_lds_dwordx4 v[216:217], off
	v_lshl_add_u64 v[216:217], v[234:235], 0, s[54:55]
	s_mov_b32 m0, s11
	s_nop 0
	global_load_lds_dwordx4 v[216:217], off
	s_waitcnt lgkmcnt(8)
	s_barrier
	s_waitcnt lgkmcnt(0)
	s_setprio 1
	s_waitcnt lgkmcnt(0)
	v_mfma_f32_16x16x32_bf16 v[130:133], v[184:187], v[168:171], v[130:133]
	v_mfma_f32_16x16x32_bf16 v[126:129], v[184:187], v[176:179], v[126:129]
	v_mfma_f32_16x16x32_bf16 v[122:125], v[192:195], v[168:171], v[122:125]
	v_mfma_f32_16x16x32_bf16 v[118:121], v[192:195], v[176:179], v[118:121]
	v_mfma_f32_16x16x32_bf16 v[114:117], v[200:203], v[168:171], v[114:117]
	v_mfma_f32_16x16x32_bf16 v[110:113], v[200:203], v[176:179], v[110:113]
	v_mfma_f32_16x16x32_bf16 v[106:109], v[208:211], v[168:171], v[106:109]
	v_mfma_f32_16x16x32_bf16 v[102:105], v[208:211], v[176:179], v[102:105]
	v_mfma_f32_16x16x32_bf16 v[130:133], v[188:191], v[172:175], v[130:133]
	v_mfma_f32_16x16x32_bf16 v[126:129], v[188:191], v[180:183], v[126:129]
	v_mfma_f32_16x16x32_bf16 v[122:125], v[196:199], v[172:175], v[122:125]
	v_mfma_f32_16x16x32_bf16 v[118:121], v[196:199], v[180:183], v[118:121]
	v_mfma_f32_16x16x32_bf16 v[114:117], v[204:207], v[172:175], v[114:117]
	v_mfma_f32_16x16x32_bf16 v[110:113], v[204:207], v[180:183], v[110:113]
	v_mfma_f32_16x16x32_bf16 v[106:109], v[212:215], v[172:175], v[106:109]
	v_mfma_f32_16x16x32_bf16 v[102:105], v[212:215], v[180:183], v[102:105]
	s_setprio 0
	s_barrier
	v_readfirstlane_b32 s11, v157
	v_lshl_add_u64 v[244:245], v[238:239], 0, s[16:17]
	s_mov_b32 m0, s11
	v_readfirstlane_b32 s11, v158
	s_nop 0
	ds_read_b128 v[216:219], v150
	ds_read_b128 v[220:223], v150 offset:1024
	ds_read_b128 v[224:227], v150 offset:2048
	ds_read_b128 v[228:231], v150 offset:3072
	global_load_lds_dwordx4 v[244:245], off
	v_lshl_add_u64 v[244:245], v[242:243], 0, s[16:17]
	s_mov_b32 m0, s11
	s_nop 0
	global_load_lds_dwordx4 v[244:245], off
	s_barrier
	s_waitcnt lgkmcnt(0)
	s_setprio 1
	s_waitcnt lgkmcnt(0)
	v_mfma_f32_16x16x32_bf16 v[98:101], v[184:187], v[216:219], v[98:101]
	v_mfma_f32_16x16x32_bf16 v[94:97], v[184:187], v[224:227], v[94:97]
	v_mfma_f32_16x16x32_bf16 v[90:93], v[192:195], v[216:219], v[90:93]
	v_mfma_f32_16x16x32_bf16 v[86:89], v[192:195], v[224:227], v[86:89]
	v_mfma_f32_16x16x32_bf16 v[82:85], v[200:203], v[216:219], v[82:85]
	v_mfma_f32_16x16x32_bf16 v[78:81], v[200:203], v[224:227], v[78:81]
	v_mfma_f32_16x16x32_bf16 v[74:77], v[208:211], v[216:219], v[74:77]
	v_mfma_f32_16x16x32_bf16 v[70:73], v[208:211], v[224:227], v[70:73]
	v_mfma_f32_16x16x32_bf16 v[98:101], v[188:191], v[220:223], v[98:101]
	v_mfma_f32_16x16x32_bf16 v[94:97], v[188:191], v[228:231], v[94:97]
	v_mfma_f32_16x16x32_bf16 v[90:93], v[196:199], v[220:223], v[90:93]
	v_mfma_f32_16x16x32_bf16 v[86:89], v[196:199], v[228:231], v[86:89]
	v_mfma_f32_16x16x32_bf16 v[82:85], v[204:207], v[220:223], v[82:85]
	v_mfma_f32_16x16x32_bf16 v[78:81], v[204:207], v[228:231], v[78:81]
	v_mfma_f32_16x16x32_bf16 v[74:77], v[212:215], v[220:223], v[74:77]
	v_mfma_f32_16x16x32_bf16 v[70:73], v[212:215], v[228:231], v[70:73]
	s_setprio 0
	v_readfirstlane_b32 s11, v159
	v_lshl_add_u64 v[232:233], v[232:233], 0, s[40:41]
	s_mov_b32 m0, s11
	v_readfirstlane_b32 s11, v160
	s_barrier
	s_nop 0
	ds_read_b128 v[184:187], v147 offset:49152
	ds_read_b128 v[188:191], v147 offset:50176
	ds_read_b128 v[192:195], v146 offset:49152
	ds_read_b128 v[196:199], v146 offset:50176
	ds_read_b128 v[200:203], v145 offset:49152
	ds_read_b128 v[204:207], v145 offset:50176
	ds_read_b128 v[208:211], v144 offset:49152
	ds_read_b128 v[212:215], v144 offset:50176
	global_load_lds_dwordx4 v[232:233], off
	v_lshl_add_u64 v[232:233], v[234:235], 0, s[40:41]
	s_mov_b32 m0, s11
	s_nop 0
	global_load_lds_dwordx4 v[232:233], off
	s_barrier
; #define STAGE(P, BASE, LD, br, kt) do { const long _g = (long)(br) * (LD) + (long)(kt) * 64; \
;     _Pragma("unroll") for (int _i = 0; _i < 2; ++_i) { const int _b = tid * 16 + _i * 8192; int _r, _c; stage_rc(_b, _r, _c); \
;       __builtin_amdgcn_global_load_lds((const G_AS1 unsigned*)((BASE) + _g + (long)_r * (LD) + _c), \
;         (LAS unsigned*)((char*)(P) + _b), 16, 0, 0); } } while (0)
; #define LDA(dst, b, h) _Pragma("unroll") for (int m = 0; m < 4; ++m) _Pragma("unroll") for (int k = 0; k < 2; ++k) \
;     dst[m][k] = *reinterpret_cast<const bf16x8*>((char*)SA(b, h) + lds_byte(wr * 64 + m * 16 + fr, k * 32 + fq * 8))
; #define LDB(dst, b, h) _Pragma("unroll") for (int n = 0; n < 2; ++n) _Pragma("unroll") for (int k = 0; k < 2; ++k) \
;     dst[n][k] = *reinterpret_cast<const bf16x8*>((char*)SB(b, h) + lds_byte(wc * 32 + n * 16 + fr, k * 32 + fq * 8))
; #define MMA(ai, bj, At_, Bt_) do { __builtin_amdgcn_s_setprio(1); \
;     _Pragma("unroll") for (int m = 0; m < 4; ++m) _Pragma("unroll") for (int n = 0; n < 2; ++n) _Pragma("unroll") for (int k = 0; k < 2; ++k) \
;       acc[ai][bj][m][n] = __builtin_amdgcn_mfma_f32_16x16x32_bf16(At_[m][k], Bt_[n][k], acc[ai][bj][m][n], 0, 0, 0); \
;     __builtin_amdgcn_s_setprio(0); } while (0)
; #define WAIT_V(n) asm volatile("s_waitcnt vmcnt(" #n ")" ::: "memory")
; #define WAIT_L(n) asm volatile("s_waitcnt lgkmcnt(" #n ")" ::: "memory")
; #define BAR __builtin_amdgcn_s_barrier()
; #define SCHED __builtin_amdgcn_sched_barrier(0)
; __device__ __forceinline__ void gemm256(const bf16_t* __restrict__ A, long lda, const bf16_t* __restrict__ Bt, long ldb, int K,
;                                         int brow, int bcol, char* smem, f32x4 (&acc)[2][2][4][2]) {
;     ...
;         LDA(At, 1, 1); STAGE(SA(1, 0), A, lda, brow, t + 3);
;         BAR; WAIT_L(0); MMA(1, 0, At, B0); BAR; SCHED;
;         STAGE(SB(1, 1), Bt, ldb, bcol + 128, t + 3);
;         WAIT_V(6); BAR; MMA(1, 1, At, B1); BAR;
;     }
;     { LDB(B0, 0, 0); LDA(At, 0, 0); STAGE(SA(1, 1), A, lda, brow + 128, nt - 1);
;       BAR; WAIT_L(0); MMA(0, 0, At, B0); BAR;
;       LDB(B1, 0, 1); BAR; WAIT_L(0); MMA(0, 1, At, B1); BAR;
;       LDA(At, 0, 1); WAIT_V(4); BAR; WAIT_L(0); MMA(1, 0, At, B0); MMA(1, 1, At, B1); BAR; }
	s_waitcnt lgkmcnt(0)
	s_setprio 1
	s_waitcnt lgkmcnt(0)
	v_mfma_f32_16x16x32_bf16 v[66:69], v[184:187], v[168:171], v[66:69]
	v_mfma_f32_16x16x32_bf16 v[62:65], v[184:187], v[176:179], v[62:65]
	v_mfma_f32_16x16x32_bf16 v[58:61], v[192:195], v[168:171], v[58:61]
	v_mfma_f32_16x16x32_bf16 v[54:57], v[192:195], v[176:179], v[54:57]
	v_mfma_f32_16x16x32_bf16 v[50:53], v[200:203], v[168:171], v[50:53]
	v_mfma_f32_16x16x32_bf16 v[46:49], v[200:203], v[176:179], v[46:49]
	v_mfma_f32_16x16x32_bf16 v[42:45], v[208:211], v[168:171], v[42:45]
	v_mfma_f32_16x16x32_bf16 v[38:41], v[208:211], v[176:179], v[38:41]
	v_mfma_f32_16x16x32_bf16 v[66:69], v[188:191], v[172:175], v[66:69]
	v_mfma_f32_16x16x32_bf16 v[62:65], v[188:191], v[180:183], v[62:65]
	v_mfma_f32_16x16x32_bf16 v[58:61], v[196:199], v[172:175], v[58:61]
	v_mfma_f32_16x16x32_bf16 v[54:57], v[196:199], v[180:183], v[54:57]
	v_mfma_f32_16x16x32_bf16 v[50:53], v[204:207], v[172:175], v[50:53]
	v_mfma_f32_16x16x32_bf16 v[46:49], v[204:207], v[180:183], v[46:49]
	v_mfma_f32_16x16x32_bf16 v[42:45], v[212:215], v[172:175], v[42:45]
	v_mfma_f32_16x16x32_bf16 v[38:41], v[212:215], v[180:183], v[38:41]
	s_setprio 0
	s_barrier
	v_readfirstlane_b32 s11, v162
	v_lshl_add_u64 v[168:169], v[238:239], 0, s[18:19]
	s_mov_b32 m0, s11
	v_readfirstlane_b32 s11, v163
	global_load_lds_dwordx4 v[168:169], off
	v_lshl_add_u64 v[168:169], v[242:243], 0, s[18:19]
	s_mov_b32 m0, s11
	s_nop 0
	global_load_lds_dwordx4 v[168:169], off
	s_waitcnt vmcnt(6)
	s_barrier
	s_setprio 1
	v_mfma_f32_16x16x32_bf16 v[34:37], v[184:187], v[216:219], v[34:37]
	v_mfma_f32_16x16x32_bf16 v[30:33], v[184:187], v[224:227], v[30:33]
	v_mfma_f32_16x16x32_bf16 v[26:29], v[192:195], v[216:219], v[26:29]
	v_mfma_f32_16x16x32_bf16 v[22:25], v[192:195], v[224:227], v[22:25]
	v_mfma_f32_16x16x32_bf16 v[18:21], v[200:203], v[216:219], v[18:21]
	v_mfma_f32_16x16x32_bf16 v[14:17], v[200:203], v[224:227], v[14:17]
	v_mfma_f32_16x16x32_bf16 v[10:13], v[208:211], v[216:219], v[10:13]
	v_mfma_f32_16x16x32_bf16 v[6:9], v[208:211], v[224:227], v[6:9]
	v_mfma_f32_16x16x32_bf16 v[34:37], v[188:191], v[220:223], v[34:37]
	v_mfma_f32_16x16x32_bf16 v[30:33], v[188:191], v[228:231], v[30:33]
	v_mfma_f32_16x16x32_bf16 v[26:29], v[196:199], v[220:223], v[26:29]
	v_mfma_f32_16x16x32_bf16 v[22:25], v[196:199], v[228:231], v[22:25]
	v_mfma_f32_16x16x32_bf16 v[18:21], v[204:207], v[220:223], v[18:21]
	v_mfma_f32_16x16x32_bf16 v[14:17], v[204:207], v[228:231], v[14:17]
	v_mfma_f32_16x16x32_bf16 v[10:13], v[212:215], v[220:223], v[10:13]
	v_mfma_f32_16x16x32_bf16 v[6:9], v[212:215], v[228:231], v[6:9]
	s_setprio 0
	s_add_i32 s9, s9, 2
	v_lshl_add_u64 v[136:137], v[136:137], 0, s[44:45]
	v_lshl_add_u64 v[138:139], v[138:139], 0, s[44:45]
	v_lshl_add_u64 v[140:141], v[140:141], 0, s[44:45]
	s_cmp_lt_u32 s9, 12
	v_lshl_add_u64 v[142:143], v[142:143], 0, s[44:45]
	s_barrier
	s_cbranch_scc1 .LBB0_1034
	s_mov_b64 s[12:13], 0x780
	v_readfirstlane_b32 s9, v165
	v_lshl_add_u64 v[2:3], v[2:3], 0, s[12:13]
	s_mov_b32 m0, s9
	v_readfirstlane_b32 s9, v166
	s_nop 0
	ds_read_b128 v[136:139], v164
	ds_read_b128 v[140:143], v164 offset:1024
	ds_read_b128 v[154:157], v164 offset:2048
	ds_read_b128 v[168:171], v164 offset:3072
	ds_read_b128 v[172:175], v147
	ds_read_b128 v[176:179], v147 offset:1024
	ds_read_b128 v[180:183], v146
	ds_read_b128 v[184:187], v146 offset:1024
	ds_read_b128 v[188:191], v145
	ds_read_b128 v[192:195], v145 offset:1024
	ds_read_b128 v[196:199], v144
	ds_read_b128 v[200:203], v144 offset:1024
	global_load_lds_dwordx4 v[2:3], off
	v_lshl_add_u64 v[2:3], v[134:135], 0, s[12:13]
	s_mov_b32 m0, s9
	s_nop 0
	global_load_lds_dwordx4 v[2:3], off
	s_barrier
	s_waitcnt lgkmcnt(0)
	s_setprio 1
	s_waitcnt lgkmcnt(0)
	v_mfma_f32_16x16x32_bf16 v[130:133], v[172:175], v[136:139], v[130:133]
	v_mfma_f32_16x16x32_bf16 v[126:129], v[172:175], v[154:157], v[126:129]
	v_mfma_f32_16x16x32_bf16 v[114:117], v[188:191], v[136:139], v[114:117]
	v_mfma_f32_16x16x32_bf16 v[110:113], v[188:191], v[154:157], v[110:113]
	v_mfma_f32_16x16x32_bf16 v[130:133], v[176:179], v[140:143], v[130:133]
	v_mfma_f32_16x16x32_bf16 v[126:129], v[176:179], v[168:171], v[126:129]
	v_mfma_f32_16x16x32_bf16 v[122:125], v[180:183], v[136:139], v[122:125]
	v_mfma_f32_16x16x32_bf16 v[118:121], v[180:183], v[154:157], v[118:121]
	v_mfma_f32_16x16x32_bf16 v[114:117], v[192:195], v[140:143], v[114:117]
	v_mfma_f32_16x16x32_bf16 v[110:113], v[192:195], v[168:171], v[110:113]
	v_mfma_f32_16x16x32_bf16 v[106:109], v[196:199], v[136:139], v[106:109]
	v_mfma_f32_16x16x32_bf16 v[102:105], v[196:199], v[154:157], v[102:105]
	v_mfma_f32_16x16x32_bf16 v[162:165], v[184:187], v[140:143], v[122:125]
	v_mfma_f32_16x16x32_bf16 v[204:207], v[184:187], v[168:171], v[118:121]
	v_mfma_f32_16x16x32_bf16 v[208:211], v[200:203], v[140:143], v[106:109]
	v_mfma_f32_16x16x32_bf16 v[212:215], v[200:203], v[168:171], v[102:105]
	s_setprio 0
	s_barrier
	s_nop 0
	s_nop 0
	ds_read_b128 v[102:105], v161
	ds_read_b128 v[106:109], v161 offset:1024
	ds_read_b128 v[118:121], v161 offset:2048
	ds_read_b128 v[122:125], v161 offset:3072
	s_barrier
; #define LDA(dst, b, h) _Pragma("unroll") for (int m = 0; m < 4; ++m) _Pragma("unroll") for (int k = 0; k < 2; ++k) \
;     dst[m][k] = *reinterpret_cast<const bf16x8*>((char*)SA(b, h) + lds_byte(wr * 64 + m * 16 + fr, k * 32 + fq * 8))
; #define LDB(dst, b, h) _Pragma("unroll") for (int n = 0; n < 2; ++n) _Pragma("unroll") for (int k = 0; k < 2; ++k) \
;     dst[n][k] = *reinterpret_cast<const bf16x8*>((char*)SB(b, h) + lds_byte(wc * 32 + n * 16 + fr, k * 32 + fq * 8))
; #define MMA(ai, bj, At_, Bt_) do { __builtin_amdgcn_s_setprio(1); \
;     _Pragma("unroll") for (int m = 0; m < 4; ++m) _Pragma("unroll") for (int n = 0; n < 2; ++n) _Pragma("unroll") for (int k = 0; k < 2; ++k) \
;       acc[ai][bj][m][n] = __builtin_amdgcn_mfma_f32_16x16x32_bf16(At_[m][k], Bt_[n][k], acc[ai][bj][m][n], 0, 0, 0); \
;     __builtin_amdgcn_s_setprio(0); } while (0)
; #define WAIT_V(n) asm volatile("s_waitcnt vmcnt(" #n ")" ::: "memory")
; #define WAIT_L(n) asm volatile("s_waitcnt lgkmcnt(" #n ")" ::: "memory")
; #define BAR __builtin_amdgcn_s_barrier()
; __device__ __forceinline__ void gemm256(const bf16_t* __restrict__ A, long lda, const bf16_t* __restrict__ Bt, long ldb, int K,
;                                         int brow, int bcol, char* smem, f32x4 (&acc)[2][2][4][2]) {
;     ...
;       LDB(B1, 0, 1); BAR; WAIT_L(0); MMA(0, 1, At, B1); BAR;
;       LDA(At, 0, 1); WAIT_V(4); BAR; WAIT_L(0); MMA(1, 0, At, B0); MMA(1, 1, At, B1); BAR; }
;     { LDB(B0, 1, 0); LDA(At, 1, 0); WAIT_V(2); BAR; WAIT_L(0); MMA(0, 0, At, B0); BAR;
	s_waitcnt lgkmcnt(0)
	s_setprio 1
	s_waitcnt lgkmcnt(3)
	v_mfma_f32_16x16x32_bf16 v[98:101], v[172:175], v[102:105], v[98:101]
	s_waitcnt lgkmcnt(1)
	v_mfma_f32_16x16x32_bf16 v[94:97], v[172:175], v[118:121], v[94:97]
	v_mfma_f32_16x16x32_bf16 v[82:85], v[188:191], v[102:105], v[82:85]
	v_mfma_f32_16x16x32_bf16 v[78:81], v[188:191], v[118:121], v[78:81]
	v_mfma_f32_16x16x32_bf16 v[98:101], v[176:179], v[106:109], v[98:101]
	s_waitcnt lgkmcnt(0)
	v_mfma_f32_16x16x32_bf16 v[94:97], v[176:179], v[122:125], v[94:97]
	v_mfma_f32_16x16x32_bf16 v[90:93], v[180:183], v[102:105], v[90:93]
	v_mfma_f32_16x16x32_bf16 v[86:89], v[180:183], v[118:121], v[86:89]
	v_mfma_f32_16x16x32_bf16 v[82:85], v[192:195], v[106:109], v[82:85]
	v_mfma_f32_16x16x32_bf16 v[78:81], v[192:195], v[122:125], v[78:81]
	v_mfma_f32_16x16x32_bf16 v[74:77], v[196:199], v[102:105], v[74:77]
	v_mfma_f32_16x16x32_bf16 v[70:73], v[196:199], v[118:121], v[70:73]
	v_mfma_f32_16x16x32_bf16 v[158:161], v[184:187], v[106:109], v[90:93]
	v_mfma_f32_16x16x32_bf16 v[172:175], v[184:187], v[122:125], v[86:89]
	v_mfma_f32_16x16x32_bf16 v[176:179], v[200:203], v[106:109], v[74:77]
	v_mfma_f32_16x16x32_bf16 v[180:183], v[200:203], v[122:125], v[70:73]
	s_setprio 0
	s_barrier
	s_nop 1
	ds_read_b128 v[70:73], v147 offset:16384
	ds_read_b128 v[74:77], v147 offset:17408
	ds_read_b128 v[86:89], v146 offset:16384
	ds_read_b128 v[90:93], v146 offset:17408
	ds_read_b128 v[184:187], v145 offset:16384
	ds_read_b128 v[188:191], v145 offset:17408
	ds_read_b128 v[192:195], v144 offset:16384
	ds_read_b128 v[196:199], v144 offset:17408
	s_waitcnt vmcnt(4)
	s_barrier
	s_waitcnt lgkmcnt(0)
	s_setprio 1
	s_waitcnt lgkmcnt(7)
	v_mfma_f32_16x16x32_bf16 v[66:69], v[70:73], v[136:139], v[66:69]
	v_mfma_f32_16x16x32_bf16 v[62:65], v[70:73], v[154:157], v[62:65]
	s_waitcnt lgkmcnt(3)
	v_mfma_f32_16x16x32_bf16 v[50:53], v[184:187], v[136:139], v[50:53]
	v_mfma_f32_16x16x32_bf16 v[46:49], v[184:187], v[154:157], v[46:49]
	v_mfma_f32_16x16x32_bf16 v[66:69], v[74:77], v[140:143], v[66:69]
	v_mfma_f32_16x16x32_bf16 v[62:65], v[74:77], v[168:171], v[62:65]
	v_mfma_f32_16x16x32_bf16 v[58:61], v[86:89], v[136:139], v[58:61]
	v_mfma_f32_16x16x32_bf16 v[54:57], v[86:89], v[154:157], v[54:57]
	s_waitcnt lgkmcnt(2)
	v_mfma_f32_16x16x32_bf16 v[50:53], v[188:191], v[140:143], v[50:53]
	v_mfma_f32_16x16x32_bf16 v[46:49], v[188:191], v[168:171], v[46:49]
	s_waitcnt lgkmcnt(1)
	v_mfma_f32_16x16x32_bf16 v[42:45], v[192:195], v[136:139], v[42:45]
	v_mfma_f32_16x16x32_bf16 v[38:41], v[192:195], v[154:157], v[38:41]
	v_mfma_f32_16x16x32_bf16 v[200:203], v[90:93], v[140:143], v[58:61]
	v_mfma_f32_16x16x32_bf16 v[216:219], v[90:93], v[168:171], v[54:57]
	s_waitcnt lgkmcnt(0)
	v_mfma_f32_16x16x32_bf16 v[134:137], v[196:199], v[140:143], v[42:45]
	v_mfma_f32_16x16x32_bf16 v[138:141], v[196:199], v[168:171], v[38:41]
	s_setprio 0
	s_setprio 1
	v_mfma_f32_16x16x32_bf16 v[34:37], v[70:73], v[102:105], v[34:37]
	v_mfma_f32_16x16x32_bf16 v[30:33], v[70:73], v[118:121], v[30:33]
	v_mfma_f32_16x16x32_bf16 v[18:21], v[184:187], v[102:105], v[18:21]
	v_mfma_f32_16x16x32_bf16 v[14:17], v[184:187], v[118:121], v[14:17]
	v_mfma_f32_16x16x32_bf16 v[34:37], v[74:77], v[106:109], v[34:37]
	v_mfma_f32_16x16x32_bf16 v[30:33], v[74:77], v[122:125], v[30:33]
	v_mfma_f32_16x16x32_bf16 v[26:29], v[86:89], v[102:105], v[26:29]
	v_mfma_f32_16x16x32_bf16 v[22:25], v[86:89], v[118:121], v[22:25]
	v_mfma_f32_16x16x32_bf16 v[18:21], v[188:191], v[106:109], v[18:21]
	v_mfma_f32_16x16x32_bf16 v[14:17], v[188:191], v[122:125], v[14:17]
	v_mfma_f32_16x16x32_bf16 v[10:13], v[192:195], v[102:105], v[10:13]
	v_mfma_f32_16x16x32_bf16 v[6:9], v[192:195], v[118:121], v[6:9]
	v_mfma_f32_16x16x32_bf16 v[154:157], v[90:93], v[106:109], v[26:29]
	v_mfma_f32_16x16x32_bf16 v[166:169], v[90:93], v[122:125], v[22:25]
	v_mfma_f32_16x16x32_bf16 v[184:187], v[196:199], v[106:109], v[10:13]
	v_mfma_f32_16x16x32_bf16 v[188:191], v[196:199], v[122:125], v[6:9]
	s_setprio 0
	s_barrier
	s_nop 1
	ds_read_b128 v[6:9], v152
	ds_read_b128 v[10:13], v152 offset:1024
	ds_read_b128 v[192:195], v152 offset:2048
	ds_read_b128 v[196:199], v152 offset:3072
	ds_read_b128 v[22:25], v147 offset:32768
	ds_read_b128 v[26:29], v147 offset:33792
	ds_read_b128 v[38:41], v146 offset:32768
	ds_read_b128 v[42:45], v146 offset:33792
	ds_read_b128 v[54:57], v145 offset:32768
	ds_read_b128 v[58:61], v145 offset:33792
	ds_read_b128 v[220:223], v144 offset:32768
	ds_read_b128 v[224:227], v144 offset:33792
	s_waitcnt vmcnt(2)
	s_barrier
; #define LDA(dst, b, h) _Pragma("unroll") for (int m = 0; m < 4; ++m) _Pragma("unroll") for (int k = 0; k < 2; ++k) \
;     dst[m][k] = *reinterpret_cast<const bf16x8*>((char*)SA(b, h) + lds_byte(wr * 64 + m * 16 + fr, k * 32 + fq * 8))
; #define LDB(dst, b, h) _Pragma("unroll") for (int n = 0; n < 2; ++n) _Pragma("unroll") for (int k = 0; k < 2; ++k) \
;     dst[n][k] = *reinterpret_cast<const bf16x8*>((char*)SB(b, h) + lds_byte(wc * 32 + n * 16 + fr, k * 32 + fq * 8))
; #define MMA(ai, bj, At_, Bt_) do { __builtin_amdgcn_s_setprio(1); \
;     _Pragma("unroll") for (int m = 0; m < 4; ++m) _Pragma("unroll") for (int n = 0; n < 2; ++n) _Pragma("unroll") for (int k = 0; k < 2; ++k) \
;       acc[ai][bj][m][n] = __builtin_amdgcn_mfma_f32_16x16x32_bf16(At_[m][k], Bt_[n][k], acc[ai][bj][m][n], 0, 0, 0); \
;     __builtin_amdgcn_s_setprio(0); } while (0)
; #define WAIT_V(n) asm volatile("s_waitcnt vmcnt(" #n ")" ::: "memory")
; #define WAIT_L(n) asm volatile("s_waitcnt lgkmcnt(" #n ")" ::: "memory")
; #define BAR __builtin_amdgcn_s_barrier()
; __device__ __forceinline__ void gemm256(const bf16_t* __restrict__ A, long lda, const bf16_t* __restrict__ Bt, long ldb, int K,
;                                         int brow, int bcol, char* smem, f32x4 (&acc)[2][2][4][2]) {
;     ...
;     { LDB(B0, 1, 0); LDA(At, 1, 0); WAIT_V(2); BAR; WAIT_L(0); MMA(0, 0, At, B0); BAR;
;       LDB(B1, 1, 1); WAIT_V(0); BAR; WAIT_L(0); MMA(0, 1, At, B1); BAR;
;       LDA(At, 1, 1); BAR; WAIT_L(0); MMA(1, 0, At, B0); MMA(1, 1, At, B1); BAR; }
;     if (wr == 0) BAR;
	s_waitcnt lgkmcnt(0)
	s_setprio 1
	s_waitcnt lgkmcnt(7)
	v_mfma_f32_16x16x32_bf16 v[70:73], v[22:25], v[6:9], v[130:133]
	s_waitcnt lgkmcnt(6)
	v_mfma_f32_16x16x32_bf16 v[122:125], v[26:29], v[10:13], v[70:73]
	v_mfma_f32_16x16x32_bf16 v[70:73], v[22:25], v[192:195], v[126:129]
	v_mfma_f32_16x16x32_bf16 v[118:121], v[26:29], v[196:199], v[70:73]
	s_waitcnt lgkmcnt(5)
	v_mfma_f32_16x16x32_bf16 v[70:73], v[38:41], v[6:9], v[162:165]
	s_waitcnt lgkmcnt(4)
	v_mfma_f32_16x16x32_bf16 v[106:109], v[42:45], v[10:13], v[70:73]
	v_mfma_f32_16x16x32_bf16 v[70:73], v[38:41], v[192:195], v[204:207]
	v_mfma_f32_16x16x32_bf16 v[102:105], v[42:45], v[196:199], v[70:73]
	s_waitcnt lgkmcnt(3)
	v_mfma_f32_16x16x32_bf16 v[70:73], v[54:57], v[6:9], v[114:117]
	s_waitcnt lgkmcnt(2)
	v_mfma_f32_16x16x32_bf16 v[90:93], v[58:61], v[10:13], v[70:73]
	v_mfma_f32_16x16x32_bf16 v[70:73], v[54:57], v[192:195], v[110:113]
	v_mfma_f32_16x16x32_bf16 v[86:89], v[58:61], v[196:199], v[70:73]
	s_waitcnt lgkmcnt(1)
	v_mfma_f32_16x16x32_bf16 v[70:73], v[220:223], v[6:9], v[208:211]
	s_waitcnt lgkmcnt(0)
	v_mfma_f32_16x16x32_bf16 v[74:77], v[224:227], v[10:13], v[70:73]
	v_mfma_f32_16x16x32_bf16 v[70:73], v[220:223], v[192:195], v[212:215]
	v_mfma_f32_16x16x32_bf16 v[70:73], v[224:227], v[196:199], v[70:73]
	s_setprio 0
	s_barrier
	ds_read_b128 v[162:165], v150
	ds_read_b128 v[204:207], v150 offset:1024
	ds_read_b128 v[208:211], v150 offset:2048
	ds_read_b128 v[148:151], v150 offset:3072
	s_waitcnt vmcnt(0)
	s_barrier
	s_waitcnt lgkmcnt(0)
	s_setprio 1
	s_waitcnt lgkmcnt(3)
	v_mfma_f32_16x16x32_bf16 v[98:101], v[22:25], v[162:165], v[98:101]
	s_waitcnt lgkmcnt(1)
	v_mfma_f32_16x16x32_bf16 v[22:25], v[22:25], v[208:211], v[94:97]
	s_waitcnt lgkmcnt(0)
	v_mfma_f32_16x16x32_bf16 v[126:129], v[26:29], v[148:151], v[22:25]
	v_mfma_f32_16x16x32_bf16 v[22:25], v[38:41], v[162:165], v[158:161]
	v_mfma_f32_16x16x32_bf16 v[114:117], v[42:45], v[204:207], v[22:25]
	v_mfma_f32_16x16x32_bf16 v[22:25], v[38:41], v[208:211], v[172:175]
	v_mfma_f32_16x16x32_bf16 v[110:113], v[42:45], v[148:151], v[22:25]
	v_mfma_f32_16x16x32_bf16 v[22:25], v[54:57], v[162:165], v[82:85]
	v_mfma_f32_16x16x32_bf16 v[130:133], v[26:29], v[204:207], v[98:101]
	v_mfma_f32_16x16x32_bf16 v[98:101], v[58:61], v[204:207], v[22:25]
	v_mfma_f32_16x16x32_bf16 v[22:25], v[54:57], v[208:211], v[78:81]
	v_mfma_f32_16x16x32_bf16 v[94:97], v[58:61], v[148:151], v[22:25]
	v_mfma_f32_16x16x32_bf16 v[22:25], v[220:223], v[162:165], v[176:179]
	v_mfma_f32_16x16x32_bf16 v[82:85], v[224:227], v[204:207], v[22:25]
	v_mfma_f32_16x16x32_bf16 v[22:25], v[220:223], v[208:211], v[180:183]
	v_mfma_f32_16x16x32_bf16 v[78:81], v[224:227], v[148:151], v[22:25]
	s_setprio 0
	s_barrier
	ds_read_b128 v[158:161], v147 offset:49152
	ds_read_b128 v[170:173], v147 offset:50176
	ds_read_b128 v[174:177], v146 offset:49152
	ds_read_b128 v[178:181], v146 offset:50176
	ds_read_b128 v[212:215], v145 offset:49152
	ds_read_b128 v[220:223], v145 offset:50176
	ds_read_b128 v[224:227], v144 offset:49152
	ds_read_b128 v[142:145], v144 offset:50176
	s_barrier
	s_waitcnt lgkmcnt(0)
	s_setprio 1
	s_waitcnt lgkmcnt(7)
	v_mfma_f32_16x16x32_bf16 v[22:25], v[158:161], v[6:9], v[66:69]
	s_waitcnt lgkmcnt(6)
	v_mfma_f32_16x16x32_bf16 v[58:61], v[170:173], v[10:13], v[22:25]
	v_mfma_f32_16x16x32_bf16 v[22:25], v[158:161], v[192:195], v[62:65]
	v_mfma_f32_16x16x32_bf16 v[54:57], v[170:173], v[196:199], v[22:25]
	s_waitcnt lgkmcnt(5)
	v_mfma_f32_16x16x32_bf16 v[22:25], v[174:177], v[6:9], v[200:203]
	s_waitcnt lgkmcnt(4)
	v_mfma_f32_16x16x32_bf16 v[42:45], v[178:181], v[10:13], v[22:25]
	v_mfma_f32_16x16x32_bf16 v[22:25], v[174:177], v[192:195], v[216:219]
	v_mfma_f32_16x16x32_bf16 v[38:41], v[178:181], v[196:199], v[22:25]
	s_waitcnt lgkmcnt(3)
	v_mfma_f32_16x16x32_bf16 v[22:25], v[212:215], v[6:9], v[50:53]
	s_waitcnt lgkmcnt(1)
	v_mfma_f32_16x16x32_bf16 v[6:9], v[224:227], v[6:9], v[134:137]
	v_mfma_f32_16x16x32_bf16 v[26:29], v[220:223], v[10:13], v[22:25]
	v_mfma_f32_16x16x32_bf16 v[22:25], v[212:215], v[192:195], v[46:49]
	s_waitcnt lgkmcnt(0)
	v_mfma_f32_16x16x32_bf16 v[10:13], v[142:145], v[10:13], v[6:9]
	v_mfma_f32_16x16x32_bf16 v[6:9], v[224:227], v[192:195], v[138:141]
	v_mfma_f32_16x16x32_bf16 v[22:25], v[220:223], v[196:199], v[22:25]
	v_mfma_f32_16x16x32_bf16 v[6:9], v[142:145], v[196:199], v[6:9]
	s_setprio 0
	s_setprio 1
	v_mfma_f32_16x16x32_bf16 v[30:33], v[158:161], v[208:211], v[30:33]
	v_mfma_f32_16x16x32_bf16 v[62:65], v[170:173], v[148:151], v[30:33]
	v_mfma_f32_16x16x32_bf16 v[30:33], v[174:177], v[162:165], v[154:157]
	v_mfma_f32_16x16x32_bf16 v[50:53], v[178:181], v[204:207], v[30:33]
	v_mfma_f32_16x16x32_bf16 v[30:33], v[174:177], v[208:211], v[166:169]
	v_mfma_f32_16x16x32_bf16 v[14:17], v[212:215], v[208:211], v[14:17]
	v_mfma_f32_16x16x32_bf16 v[34:37], v[158:161], v[162:165], v[34:37]
	v_mfma_f32_16x16x32_bf16 v[46:49], v[178:181], v[148:151], v[30:33]
	v_mfma_f32_16x16x32_bf16 v[18:21], v[212:215], v[162:165], v[18:21]
	v_mfma_f32_16x16x32_bf16 v[30:33], v[220:223], v[148:151], v[14:17]
	v_mfma_f32_16x16x32_bf16 v[14:17], v[224:227], v[162:165], v[184:187]
	v_mfma_f32_16x16x32_bf16 v[66:69], v[170:173], v[204:207], v[34:37]
	v_mfma_f32_16x16x32_bf16 v[34:37], v[220:223], v[204:207], v[18:21]
	v_mfma_f32_16x16x32_bf16 v[18:21], v[142:145], v[204:207], v[14:17]
	v_mfma_f32_16x16x32_bf16 v[14:17], v[224:227], v[208:211], v[188:191]
	v_mfma_f32_16x16x32_bf16 v[14:17], v[142:145], v[148:151], v[14:17]
	s_setprio 0
	v_cmp_gt_u32_e32 vcc, s78, v0
	s_barrier
	s_and_saveexec_b64 s[12:13], vcc
	s_cbranch_execz .LBB0_1022
	s_barrier
	s_branch .LBB0_1022

; #define STAGE(P, BASE, LD, br, kt) do { const long _g = (long)(br) * (LD) + (long)(kt) * 64; \
;     _Pragma("unroll") for (int _i = 0; _i < 2; ++_i) { const int _b = tid * 16 + _i * 8192; int _r, _c; stage_rc(_b, _r, _c); \
;       __builtin_amdgcn_global_load_lds((const G_AS1 unsigned*)((BASE) + _g + (long)_r * (LD) + _c), \
;         (LAS unsigned*)((char*)(P) + _b), 16, 0, 0); } } while (0)
; #define LDA(dst, b, h) _Pragma("unroll") for (int m = 0; m < 4; ++m) _Pragma("unroll") for (int k = 0; k < 2; ++k) \
;     dst[m][k] = *reinterpret_cast<const bf16x8*>((char*)SA(b, h) + lds_byte(wr * 64 + m * 16 + fr, k * 32 + fq * 8))
; #define LDB(dst, b, h) _Pragma("unroll") for (int n = 0; n < 2; ++n) _Pragma("unroll") for (int k = 0; k < 2; ++k) \
;     dst[n][k] = *reinterpret_cast<const bf16x8*>((char*)SB(b, h) + lds_byte(wc * 32 + n * 16 + fr, k * 32 + fq * 8))
; #define MMA(ai, bj, At_, Bt_) do { __builtin_amdgcn_s_setprio(1); \
;     _Pragma("unroll") for (int m = 0; m < 4; ++m) _Pragma("unroll") for (int n = 0; n < 2; ++n) _Pragma("unroll") for (int k = 0; k < 2; ++k) \
;       acc[ai][bj][m][n] = __builtin_amdgcn_mfma_f32_16x16x32_bf16(At_[m][k], Bt_[n][k], acc[ai][bj][m][n], 0, 0, 0); \
;     __builtin_amdgcn_s_setprio(0); } while (0)
; #define WAIT_L(n) asm volatile("s_waitcnt lgkmcnt(" #n ")" ::: "memory")
; #define BAR __builtin_amdgcn_s_barrier()
; #define SCHED __builtin_amdgcn_sched_barrier(0)
; __device__ __forceinline__ void gemm256(const bf16_t* __restrict__ A, long lda, const bf16_t* __restrict__ Bt, long ldb, int K,
;                                         int brow, int bcol, char* smem, f32x4 (&acc)[2][2][4][2]) {
;     ...
;         LDB(B0, 0, 0); SCHED; LDA(At, 0, 0); STAGE(SA(1, 1), A, lda, brow + 128, t + 1);
;         WAIT_L(8); BAR; WAIT_L(0); MMA(0, 0, At, B0); BAR; SCHED;
;         LDB(B1, 0, 1); STAGE(SB(0, 0), Bt, ldb, bcol, t + 2);
;         BAR; WAIT_L(0); MMA(0, 1, At, B1); BAR;
;         LDA(At, 0, 1); STAGE(SA(0, 0), A, lda, brow, t + 2);
;         BAR; WAIT_L(0); MMA(1, 0, At, B0); BAR; SCHED;
.LBB0_1082:
	s_nop 0
	ds_read_b128 v[168:171], v164
	ds_read_b128 v[172:175], v164 offset:1024
	ds_read_b128 v[176:179], v164 offset:2048
	ds_read_b128 v[180:183], v164 offset:3072
	v_add_u32_e32 v165, 0xc000, v5
	v_lshl_add_u64 v[232:233], s[4:5], 0, v[140:141]
	v_readfirstlane_b32 s11, v165
	v_lshl_add_u64 v[166:167], v[232:233], 0, s[60:61]
	s_mov_b32 m0, s11
	ds_read_b128 v[184:187], v148
	ds_read_b128 v[188:191], v148 offset:1024
	ds_read_b128 v[192:195], v147
	ds_read_b128 v[196:199], v147 offset:1024
	ds_read_b128 v[200:203], v145
	ds_read_b128 v[204:207], v145 offset:1024
	ds_read_b128 v[208:211], v144
	ds_read_b128 v[212:215], v144 offset:1024
	global_load_lds_dwordx4 v[166:167], off
	v_add_u32_e32 v166, 0xe000, v5
	v_lshl_add_u64 v[234:235], s[4:5], 0, v[142:143]
	v_readfirstlane_b32 s11, v166
	v_lshl_add_u64 v[216:217], v[234:235], 0, s[60:61]
	s_mov_b32 m0, s11
	s_nop 0
	global_load_lds_dwordx4 v[216:217], off
	s_waitcnt lgkmcnt(8)
	s_barrier
	s_waitcnt lgkmcnt(0)
	s_setprio 1
	s_waitcnt lgkmcnt(0)
	v_mfma_f32_16x16x32_bf16 v[130:133], v[184:187], v[168:171], v[130:133]
	v_mfma_f32_16x16x32_bf16 v[126:129], v[184:187], v[176:179], v[126:129]
	v_mfma_f32_16x16x32_bf16 v[122:125], v[192:195], v[168:171], v[122:125]
	v_mfma_f32_16x16x32_bf16 v[118:121], v[192:195], v[176:179], v[118:121]
	v_mfma_f32_16x16x32_bf16 v[114:117], v[200:203], v[168:171], v[114:117]
	v_mfma_f32_16x16x32_bf16 v[110:113], v[200:203], v[176:179], v[110:113]
	v_mfma_f32_16x16x32_bf16 v[106:109], v[208:211], v[168:171], v[106:109]
	v_mfma_f32_16x16x32_bf16 v[102:105], v[208:211], v[176:179], v[102:105]
	v_mfma_f32_16x16x32_bf16 v[130:133], v[188:191], v[172:175], v[130:133]
	v_mfma_f32_16x16x32_bf16 v[126:129], v[188:191], v[180:183], v[126:129]
	v_mfma_f32_16x16x32_bf16 v[122:125], v[196:199], v[172:175], v[122:125]
	v_mfma_f32_16x16x32_bf16 v[118:121], v[196:199], v[180:183], v[118:121]
	v_mfma_f32_16x16x32_bf16 v[114:117], v[204:207], v[172:175], v[114:117]
	v_mfma_f32_16x16x32_bf16 v[110:113], v[204:207], v[180:183], v[110:113]
	v_mfma_f32_16x16x32_bf16 v[106:109], v[212:215], v[172:175], v[106:109]
	v_mfma_f32_16x16x32_bf16 v[102:105], v[212:215], v[180:183], v[102:105]
	s_setprio 0
	s_barrier
	v_lshl_add_u64 v[238:239], s[4:5], 0, v[136:137]
	v_readfirstlane_b32 s11, v146
	v_lshl_add_u64 v[242:243], v[238:239], 0, s[68:69]
	s_mov_b32 m0, s11
	s_nop 0
	ds_read_b128 v[216:219], v161
	ds_read_b128 v[220:223], v161 offset:1024
	ds_read_b128 v[224:227], v161 offset:2048
	ds_read_b128 v[228:231], v161 offset:3072
	global_load_lds_dwordx4 v[242:243], off
	v_lshl_add_u64 v[242:243], s[4:5], 0, v[138:139]
	v_readfirstlane_b32 s11, v151
	v_lshl_add_u64 v[244:245], v[242:243], 0, s[68:69]
	s_mov_b32 m0, s11
	s_nop 0
	global_load_lds_dwordx4 v[244:245], off
	s_barrier
	s_waitcnt lgkmcnt(0)
	s_setprio 1
	s_waitcnt lgkmcnt(0)
	v_mfma_f32_16x16x32_bf16 v[98:101], v[184:187], v[216:219], v[98:101]
	v_mfma_f32_16x16x32_bf16 v[94:97], v[184:187], v[224:227], v[94:97]
	v_mfma_f32_16x16x32_bf16 v[90:93], v[192:195], v[216:219], v[90:93]
	v_mfma_f32_16x16x32_bf16 v[86:89], v[192:195], v[224:227], v[86:89]
	v_mfma_f32_16x16x32_bf16 v[82:85], v[200:203], v[216:219], v[82:85]
	v_mfma_f32_16x16x32_bf16 v[78:81], v[200:203], v[224:227], v[78:81]
	v_mfma_f32_16x16x32_bf16 v[74:77], v[208:211], v[216:219], v[74:77]
	v_mfma_f32_16x16x32_bf16 v[70:73], v[208:211], v[224:227], v[70:73]
	v_mfma_f32_16x16x32_bf16 v[98:101], v[188:191], v[220:223], v[98:101]
	v_mfma_f32_16x16x32_bf16 v[94:97], v[188:191], v[228:231], v[94:97]
	v_mfma_f32_16x16x32_bf16 v[90:93], v[196:199], v[220:223], v[90:93]
	v_mfma_f32_16x16x32_bf16 v[86:89], v[196:199], v[228:231], v[86:89]
	v_mfma_f32_16x16x32_bf16 v[82:85], v[204:207], v[220:223], v[82:85]
	v_mfma_f32_16x16x32_bf16 v[78:81], v[204:207], v[228:231], v[78:81]
	v_mfma_f32_16x16x32_bf16 v[74:77], v[212:215], v[220:223], v[74:77]
	v_mfma_f32_16x16x32_bf16 v[70:73], v[212:215], v[228:231], v[70:73]
	s_setprio 0
	v_readfirstlane_b32 s11, v5
	v_lshl_add_u64 v[244:245], v[232:233], 0, s[92:93]
	s_mov_b32 m0, s11
	v_readfirstlane_b32 s11, v149
	s_barrier
	s_nop 0
	ds_read_b128 v[184:187], v148 offset:16384
	ds_read_b128 v[188:191], v148 offset:17408
	ds_read_b128 v[192:195], v147 offset:16384
	ds_read_b128 v[196:199], v147 offset:17408
	ds_read_b128 v[200:203], v145 offset:16384
	ds_read_b128 v[204:207], v145 offset:17408
	ds_read_b128 v[208:211], v144 offset:16384
	ds_read_b128 v[212:215], v144 offset:17408
	global_load_lds_dwordx4 v[244:245], off
	v_lshl_add_u64 v[244:245], v[234:235], 0, s[92:93]
	s_mov_b32 m0, s11
	s_nop 0
	global_load_lds_dwordx4 v[244:245], off
	s_barrier
	s_waitcnt lgkmcnt(0)
	s_setprio 1
	s_waitcnt lgkmcnt(0)
	v_mfma_f32_16x16x32_bf16 v[66:69], v[184:187], v[168:171], v[66:69]
	v_mfma_f32_16x16x32_bf16 v[62:65], v[184:187], v[176:179], v[62:65]
	v_mfma_f32_16x16x32_bf16 v[58:61], v[192:195], v[168:171], v[58:61]
	v_mfma_f32_16x16x32_bf16 v[54:57], v[192:195], v[176:179], v[54:57]
	v_mfma_f32_16x16x32_bf16 v[50:53], v[200:203], v[168:171], v[50:53]
	v_mfma_f32_16x16x32_bf16 v[46:49], v[200:203], v[176:179], v[46:49]
	v_mfma_f32_16x16x32_bf16 v[42:45], v[208:211], v[168:171], v[42:45]
	v_mfma_f32_16x16x32_bf16 v[38:41], v[208:211], v[176:179], v[38:41]
	v_mfma_f32_16x16x32_bf16 v[66:69], v[188:191], v[172:175], v[66:69]
	v_mfma_f32_16x16x32_bf16 v[62:65], v[188:191], v[180:183], v[62:65]
	v_mfma_f32_16x16x32_bf16 v[58:61], v[196:199], v[172:175], v[58:61]
	v_mfma_f32_16x16x32_bf16 v[54:57], v[196:199], v[180:183], v[54:57]
	v_mfma_f32_16x16x32_bf16 v[50:53], v[204:207], v[172:175], v[50:53]
	v_mfma_f32_16x16x32_bf16 v[46:49], v[204:207], v[180:183], v[46:49]
	v_mfma_f32_16x16x32_bf16 v[42:45], v[212:215], v[172:175], v[42:45]
	v_mfma_f32_16x16x32_bf16 v[38:41], v[212:215], v[180:183], v[38:41]
	s_setprio 0
	s_barrier
; #define STAGE(P, BASE, LD, br, kt) do { const long _g = (long)(br) * (LD) + (long)(kt) * 64; \
;     _Pragma("unroll") for (int _i = 0; _i < 2; ++_i) { const int _b = tid * 16 + _i * 8192; int _r, _c; stage_rc(_b, _r, _c); \
;       __builtin_amdgcn_global_load_lds((const G_AS1 unsigned*)((BASE) + _g + (long)_r * (LD) + _c), \
;         (LAS unsigned*)((char*)(P) + _b), 16, 0, 0); } } while (0)
; #define LDA(dst, b, h) _Pragma("unroll") for (int m = 0; m < 4; ++m) _Pragma("unroll") for (int k = 0; k < 2; ++k) \
;     dst[m][k] = *reinterpret_cast<const bf16x8*>((char*)SA(b, h) + lds_byte(wr * 64 + m * 16 + fr, k * 32 + fq * 8))
; #define LDB(dst, b, h) _Pragma("unroll") for (int n = 0; n < 2; ++n) _Pragma("unroll") for (int k = 0; k < 2; ++k) \
;     dst[n][k] = *reinterpret_cast<const bf16x8*>((char*)SB(b, h) + lds_byte(wc * 32 + n * 16 + fr, k * 32 + fq * 8))
; #define MMA(ai, bj, At_, Bt_) do { __builtin_amdgcn_s_setprio(1); \
;     _Pragma("unroll") for (int m = 0; m < 4; ++m) _Pragma("unroll") for (int n = 0; n < 2; ++n) _Pragma("unroll") for (int k = 0; k < 2; ++k) \
;       acc[ai][bj][m][n] = __builtin_amdgcn_mfma_f32_16x16x32_bf16(At_[m][k], Bt_[n][k], acc[ai][bj][m][n], 0, 0, 0); \
;     __builtin_amdgcn_s_setprio(0); } while (0)
; #define WAIT_V(n) asm volatile("s_waitcnt vmcnt(" #n ")" ::: "memory")
; #define WAIT_L(n) asm volatile("s_waitcnt lgkmcnt(" #n ")" ::: "memory")
; #define BAR __builtin_amdgcn_s_barrier()
; #define SCHED __builtin_amdgcn_sched_barrier(0)
; __device__ __forceinline__ void gemm256(const bf16_t* __restrict__ A, long lda, const bf16_t* __restrict__ Bt, long ldb, int K,
;                                         int brow, int bcol, char* smem, f32x4 (&acc)[2][2][4][2]) {
;     ...
;         STAGE(SB(0, 1), Bt, ldb, bcol + 128, t + 2);
;         WAIT_V(6); BAR; MMA(1, 1, At, B1); BAR;
;         LDB(B0, 1, 0); SCHED; LDA(At, 1, 0); STAGE(SA(0, 1), A, lda, brow + 128, t + 2);
;         WAIT_L(8); BAR; WAIT_L(0); MMA(0, 0, At, B0); BAR; SCHED;
;         LDB(B1, 1, 1); STAGE(SB(1, 0), Bt, ldb, bcol, t + 3);
;         BAR; WAIT_L(0); MMA(0, 1, At, B1); BAR;
	v_readfirstlane_b32 s11, v153
	v_lshl_add_u64 v[168:169], v[238:239], 0, s[36:37]
	s_mov_b32 m0, s11
	v_readfirstlane_b32 s11, v154
	global_load_lds_dwordx4 v[168:169], off
	v_lshl_add_u64 v[168:169], v[242:243], 0, s[36:37]
	s_mov_b32 m0, s11
	s_nop 0
	global_load_lds_dwordx4 v[168:169], off
	s_waitcnt vmcnt(6)
	s_barrier
	s_setprio 1
	v_mfma_f32_16x16x32_bf16 v[34:37], v[184:187], v[216:219], v[34:37]
	v_mfma_f32_16x16x32_bf16 v[30:33], v[184:187], v[224:227], v[30:33]
	v_mfma_f32_16x16x32_bf16 v[26:29], v[192:195], v[216:219], v[26:29]
	v_mfma_f32_16x16x32_bf16 v[22:25], v[192:195], v[224:227], v[22:25]
	v_mfma_f32_16x16x32_bf16 v[18:21], v[200:203], v[216:219], v[18:21]
	v_mfma_f32_16x16x32_bf16 v[14:17], v[200:203], v[224:227], v[14:17]
	v_mfma_f32_16x16x32_bf16 v[10:13], v[208:211], v[216:219], v[10:13]
	v_mfma_f32_16x16x32_bf16 v[6:9], v[208:211], v[224:227], v[6:9]
	v_mfma_f32_16x16x32_bf16 v[34:37], v[188:191], v[220:223], v[34:37]
	v_mfma_f32_16x16x32_bf16 v[30:33], v[188:191], v[228:231], v[30:33]
	v_mfma_f32_16x16x32_bf16 v[26:29], v[196:199], v[220:223], v[26:29]
	v_mfma_f32_16x16x32_bf16 v[22:25], v[196:199], v[228:231], v[22:25]
	v_mfma_f32_16x16x32_bf16 v[18:21], v[204:207], v[220:223], v[18:21]
	v_mfma_f32_16x16x32_bf16 v[14:17], v[204:207], v[228:231], v[14:17]
	v_mfma_f32_16x16x32_bf16 v[10:13], v[212:215], v[220:223], v[10:13]
	v_mfma_f32_16x16x32_bf16 v[6:9], v[212:215], v[228:231], v[6:9]
	s_setprio 0
	s_barrier
	s_nop 0
	ds_read_b128 v[168:171], v152
	ds_read_b128 v[172:175], v152 offset:1024
	ds_read_b128 v[176:179], v152 offset:2048
	ds_read_b128 v[180:183], v152 offset:3072
	v_readfirstlane_b32 s11, v155
	v_lshl_add_u64 v[216:217], v[232:233], 0, s[54:55]
	s_mov_b32 m0, s11
	v_readfirstlane_b32 s11, v156
	ds_read_b128 v[184:187], v148 offset:32768
	ds_read_b128 v[188:191], v148 offset:33792
	ds_read_b128 v[192:195], v147 offset:32768
	ds_read_b128 v[196:199], v147 offset:33792
	ds_read_b128 v[200:203], v145 offset:32768
	ds_read_b128 v[204:207], v145 offset:33792
	ds_read_b128 v[208:211], v144 offset:32768
	ds_read_b128 v[212:215], v144 offset:33792
	global_load_lds_dwordx4 v[216:217], off
	v_lshl_add_u64 v[216:217], v[234:235], 0, s[54:55]
	s_mov_b32 m0, s11
	s_nop 0
	global_load_lds_dwordx4 v[216:217], off
	s_waitcnt lgkmcnt(8)
	s_barrier
	s_waitcnt lgkmcnt(0)
	s_setprio 1
	s_waitcnt lgkmcnt(0)
	v_mfma_f32_16x16x32_bf16 v[130:133], v[184:187], v[168:171], v[130:133]
	v_mfma_f32_16x16x32_bf16 v[126:129], v[184:187], v[176:179], v[126:129]
	v_mfma_f32_16x16x32_bf16 v[122:125], v[192:195], v[168:171], v[122:125]
	v_mfma_f32_16x16x32_bf16 v[118:121], v[192:195], v[176:179], v[118:121]
	v_mfma_f32_16x16x32_bf16 v[114:117], v[200:203], v[168:171], v[114:117]
	v_mfma_f32_16x16x32_bf16 v[110:113], v[200:203], v[176:179], v[110:113]
	v_mfma_f32_16x16x32_bf16 v[106:109], v[208:211], v[168:171], v[106:109]
	v_mfma_f32_16x16x32_bf16 v[102:105], v[208:211], v[176:179], v[102:105]
	v_mfma_f32_16x16x32_bf16 v[130:133], v[188:191], v[172:175], v[130:133]
	v_mfma_f32_16x16x32_bf16 v[126:129], v[188:191], v[180:183], v[126:129]
	v_mfma_f32_16x16x32_bf16 v[122:125], v[196:199], v[172:175], v[122:125]
	v_mfma_f32_16x16x32_bf16 v[118:121], v[196:199], v[180:183], v[118:121]
	v_mfma_f32_16x16x32_bf16 v[114:117], v[204:207], v[172:175], v[114:117]
	v_mfma_f32_16x16x32_bf16 v[110:113], v[204:207], v[180:183], v[110:113]
	v_mfma_f32_16x16x32_bf16 v[106:109], v[212:215], v[172:175], v[106:109]
	v_mfma_f32_16x16x32_bf16 v[102:105], v[212:215], v[180:183], v[102:105]
	s_setprio 0
	s_barrier
	v_readfirstlane_b32 s11, v157
	v_lshl_add_u64 v[244:245], v[238:239], 0, s[38:39]
	s_mov_b32 m0, s11
	v_readfirstlane_b32 s11, v158
	s_nop 0
	ds_read_b128 v[216:219], v150
	ds_read_b128 v[220:223], v150 offset:1024
	ds_read_b128 v[224:227], v150 offset:2048
	ds_read_b128 v[228:231], v150 offset:3072
	global_load_lds_dwordx4 v[244:245], off
	v_lshl_add_u64 v[244:245], v[242:243], 0, s[38:39]
	s_mov_b32 m0, s11
	s_nop 0
	global_load_lds_dwordx4 v[244:245], off
	s_barrier
	s_waitcnt lgkmcnt(0)
	s_setprio 1
	s_waitcnt lgkmcnt(0)
	v_mfma_f32_16x16x32_bf16 v[98:101], v[184:187], v[216:219], v[98:101]
	v_mfma_f32_16x16x32_bf16 v[94:97], v[184:187], v[224:227], v[94:97]
	v_mfma_f32_16x16x32_bf16 v[90:93], v[192:195], v[216:219], v[90:93]
	v_mfma_f32_16x16x32_bf16 v[86:89], v[192:195], v[224:227], v[86:89]
	v_mfma_f32_16x16x32_bf16 v[82:85], v[200:203], v[216:219], v[82:85]
	v_mfma_f32_16x16x32_bf16 v[78:81], v[200:203], v[224:227], v[78:81]
	v_mfma_f32_16x16x32_bf16 v[74:77], v[208:211], v[216:219], v[74:77]
	v_mfma_f32_16x16x32_bf16 v[70:73], v[208:211], v[224:227], v[70:73]
	v_mfma_f32_16x16x32_bf16 v[98:101], v[188:191], v[220:223], v[98:101]
	v_mfma_f32_16x16x32_bf16 v[94:97], v[188:191], v[228:231], v[94:97]
	v_mfma_f32_16x16x32_bf16 v[90:93], v[196:199], v[220:223], v[90:93]
	v_mfma_f32_16x16x32_bf16 v[86:89], v[196:199], v[228:231], v[86:89]
	v_mfma_f32_16x16x32_bf16 v[82:85], v[204:207], v[220:223], v[82:85]
	v_mfma_f32_16x16x32_bf16 v[78:81], v[204:207], v[228:231], v[78:81]
	v_mfma_f32_16x16x32_bf16 v[74:77], v[212:215], v[220:223], v[74:77]
	v_mfma_f32_16x16x32_bf16 v[70:73], v[212:215], v[228:231], v[70:73]
	s_setprio 0
	v_readfirstlane_b32 s11, v159
	v_lshl_add_u64 v[232:233], v[232:233], 0, s[40:41]
	s_mov_b32 m0, s11
	v_readfirstlane_b32 s11, v160
	s_barrier
	s_nop 0
	ds_read_b128 v[184:187], v148 offset:49152
	ds_read_b128 v[188:191], v148 offset:50176
	ds_read_b128 v[192:195], v147 offset:49152
	ds_read_b128 v[196:199], v147 offset:50176
	ds_read_b128 v[200:203], v145 offset:49152
	ds_read_b128 v[204:207], v145 offset:50176
	ds_read_b128 v[208:211], v144 offset:49152
	ds_read_b128 v[212:215], v144 offset:50176
	global_load_lds_dwordx4 v[232:233], off
	v_lshl_add_u64 v[232:233], v[234:235], 0, s[40:41]
	s_mov_b32 m0, s11
	s_nop 0
	global_load_lds_dwordx4 v[232:233], off
	s_barrier
; #define STAGE(P, BASE, LD, br, kt) do { const long _g = (long)(br) * (LD) + (long)(kt) * 64; \
;     _Pragma("unroll") for (int _i = 0; _i < 2; ++_i) { const int _b = tid * 16 + _i * 8192; int _r, _c; stage_rc(_b, _r, _c); \
;       __builtin_amdgcn_global_load_lds((const G_AS1 unsigned*)((BASE) + _g + (long)_r * (LD) + _c), \
;         (LAS unsigned*)((char*)(P) + _b), 16, 0, 0); } } while (0)
; #define LDA(dst, b, h) _Pragma("unroll") for (int m = 0; m < 4; ++m) _Pragma("unroll") for (int k = 0; k < 2; ++k) \
;     dst[m][k] = *reinterpret_cast<const bf16x8*>((char*)SA(b, h) + lds_byte(wr * 64 + m * 16 + fr, k * 32 + fq * 8))
; #define LDB(dst, b, h) _Pragma("unroll") for (int n = 0; n < 2; ++n) _Pragma("unroll") for (int k = 0; k < 2; ++k) \
;     dst[n][k] = *reinterpret_cast<const bf16x8*>((char*)SB(b, h) + lds_byte(wc * 32 + n * 16 + fr, k * 32 + fq * 8))
; #define MMA(ai, bj, At_, Bt_) do { __builtin_amdgcn_s_setprio(1); \
;     _Pragma("unroll") for (int m = 0; m < 4; ++m) _Pragma("unroll") for (int n = 0; n < 2; ++n) _Pragma("unroll") for (int k = 0; k < 2; ++k) \
;       acc[ai][bj][m][n] = __builtin_amdgcn_mfma_f32_16x16x32_bf16(At_[m][k], Bt_[n][k], acc[ai][bj][m][n], 0, 0, 0); \
;     __builtin_amdgcn_s_setprio(0); } while (0)
; #define WAIT_V(n) asm volatile("s_waitcnt vmcnt(" #n ")" ::: "memory")
; #define WAIT_L(n) asm volatile("s_waitcnt lgkmcnt(" #n ")" ::: "memory")
; #define BAR __builtin_amdgcn_s_barrier()
; #define SCHED __builtin_amdgcn_sched_barrier(0)
; __device__ __forceinline__ void gemm256(const bf16_t* __restrict__ A, long lda, const bf16_t* __restrict__ Bt, long ldb, int K,
;                                         int brow, int bcol, char* smem, f32x4 (&acc)[2][2][4][2]) {
;     ...
;         LDA(At, 1, 1); STAGE(SA(1, 0), A, lda, brow, t + 3);
;         BAR; WAIT_L(0); MMA(1, 0, At, B0); BAR; SCHED;
;         STAGE(SB(1, 1), Bt, ldb, bcol + 128, t + 3);
;         WAIT_V(6); BAR; MMA(1, 1, At, B1); BAR;
;     }
;     { LDB(B0, 0, 0); LDA(At, 0, 0); STAGE(SA(1, 1), A, lda, brow + 128, nt - 1);
;       BAR; WAIT_L(0); MMA(0, 0, At, B0); BAR;
;       LDB(B1, 0, 1); BAR; WAIT_L(0); MMA(0, 1, At, B1); BAR;
;       LDA(At, 0, 1); WAIT_V(4); BAR; WAIT_L(0); MMA(1, 0, At, B0); MMA(1, 1, At, B1); BAR; }
	s_waitcnt lgkmcnt(0)
	s_setprio 1
	s_waitcnt lgkmcnt(0)
	v_mfma_f32_16x16x32_bf16 v[66:69], v[184:187], v[168:171], v[66:69]
	v_mfma_f32_16x16x32_bf16 v[62:65], v[184:187], v[176:179], v[62:65]
	v_mfma_f32_16x16x32_bf16 v[58:61], v[192:195], v[168:171], v[58:61]
	v_mfma_f32_16x16x32_bf16 v[54:57], v[192:195], v[176:179], v[54:57]
	v_mfma_f32_16x16x32_bf16 v[50:53], v[200:203], v[168:171], v[50:53]
	v_mfma_f32_16x16x32_bf16 v[46:49], v[200:203], v[176:179], v[46:49]
	v_mfma_f32_16x16x32_bf16 v[42:45], v[208:211], v[168:171], v[42:45]
	v_mfma_f32_16x16x32_bf16 v[38:41], v[208:211], v[176:179], v[38:41]
	v_mfma_f32_16x16x32_bf16 v[66:69], v[188:191], v[172:175], v[66:69]
	v_mfma_f32_16x16x32_bf16 v[62:65], v[188:191], v[180:183], v[62:65]
	v_mfma_f32_16x16x32_bf16 v[58:61], v[196:199], v[172:175], v[58:61]
	v_mfma_f32_16x16x32_bf16 v[54:57], v[196:199], v[180:183], v[54:57]
	v_mfma_f32_16x16x32_bf16 v[50:53], v[204:207], v[172:175], v[50:53]
	v_mfma_f32_16x16x32_bf16 v[46:49], v[204:207], v[180:183], v[46:49]
	v_mfma_f32_16x16x32_bf16 v[42:45], v[212:215], v[172:175], v[42:45]
	v_mfma_f32_16x16x32_bf16 v[38:41], v[212:215], v[180:183], v[38:41]
	s_setprio 0
	s_barrier
	v_readfirstlane_b32 s11, v162
	v_lshl_add_u64 v[168:169], v[238:239], 0, s[64:65]
	s_mov_b32 m0, s11
	v_readfirstlane_b32 s11, v163
	global_load_lds_dwordx4 v[168:169], off
	v_lshl_add_u64 v[168:169], v[242:243], 0, s[64:65]
	s_mov_b32 m0, s11
	s_nop 0
	global_load_lds_dwordx4 v[168:169], off
	s_waitcnt vmcnt(6)
	s_barrier
	s_setprio 1
	v_mfma_f32_16x16x32_bf16 v[34:37], v[184:187], v[216:219], v[34:37]
	v_mfma_f32_16x16x32_bf16 v[30:33], v[184:187], v[224:227], v[30:33]
	v_mfma_f32_16x16x32_bf16 v[26:29], v[192:195], v[216:219], v[26:29]
	v_mfma_f32_16x16x32_bf16 v[22:25], v[192:195], v[224:227], v[22:25]
	v_mfma_f32_16x16x32_bf16 v[18:21], v[200:203], v[216:219], v[18:21]
	v_mfma_f32_16x16x32_bf16 v[14:17], v[200:203], v[224:227], v[14:17]
	v_mfma_f32_16x16x32_bf16 v[10:13], v[208:211], v[216:219], v[10:13]
	v_mfma_f32_16x16x32_bf16 v[6:9], v[208:211], v[224:227], v[6:9]
	v_mfma_f32_16x16x32_bf16 v[34:37], v[188:191], v[220:223], v[34:37]
	v_mfma_f32_16x16x32_bf16 v[30:33], v[188:191], v[228:231], v[30:33]
	v_mfma_f32_16x16x32_bf16 v[26:29], v[196:199], v[220:223], v[26:29]
	v_mfma_f32_16x16x32_bf16 v[22:25], v[196:199], v[228:231], v[22:25]
	v_mfma_f32_16x16x32_bf16 v[18:21], v[204:207], v[220:223], v[18:21]
	v_mfma_f32_16x16x32_bf16 v[14:17], v[204:207], v[228:231], v[14:17]
	v_mfma_f32_16x16x32_bf16 v[10:13], v[212:215], v[220:223], v[10:13]
	v_mfma_f32_16x16x32_bf16 v[6:9], v[212:215], v[228:231], v[6:9]
	s_setprio 0
	s_add_i32 s9, s9, 2
	v_lshl_add_u64 v[136:137], v[136:137], 0, s[44:45]
	v_lshl_add_u64 v[138:139], v[138:139], 0, s[44:45]
	v_lshl_add_u64 v[140:141], v[140:141], 0, s[44:45]
	s_cmp_lt_u32 s9, 12
	v_lshl_add_u64 v[142:143], v[142:143], 0, s[44:45]
	s_barrier
	s_cbranch_scc1 .LBB0_1082
	s_mov_b64 s[12:13], 0x780
	v_readfirstlane_b32 s9, v165
	v_lshl_add_u64 v[2:3], v[2:3], 0, s[12:13]
	s_mov_b32 m0, s9
	v_readfirstlane_b32 s9, v166
	s_nop 0
	ds_read_b128 v[136:139], v164
	ds_read_b128 v[140:143], v164 offset:1024
	ds_read_b128 v[154:157], v164 offset:2048
	ds_read_b128 v[168:171], v164 offset:3072
	ds_read_b128 v[172:175], v148
	ds_read_b128 v[176:179], v148 offset:1024
	ds_read_b128 v[180:183], v147
	ds_read_b128 v[184:187], v147 offset:1024
	ds_read_b128 v[188:191], v145
	ds_read_b128 v[192:195], v145 offset:1024
	ds_read_b128 v[196:199], v144
	ds_read_b128 v[200:203], v144 offset:1024
	global_load_lds_dwordx4 v[2:3], off
	v_lshl_add_u64 v[2:3], v[134:135], 0, s[12:13]
	s_mov_b32 m0, s9
	s_nop 0
	global_load_lds_dwordx4 v[2:3], off
	s_barrier
	s_waitcnt lgkmcnt(0)
	s_setprio 1
	s_waitcnt lgkmcnt(0)
	v_mfma_f32_16x16x32_bf16 v[130:133], v[172:175], v[136:139], v[130:133]
	v_mfma_f32_16x16x32_bf16 v[126:129], v[172:175], v[154:157], v[126:129]
	v_mfma_f32_16x16x32_bf16 v[122:125], v[180:183], v[136:139], v[122:125]
	v_mfma_f32_16x16x32_bf16 v[118:121], v[180:183], v[154:157], v[118:121]
	v_mfma_f32_16x16x32_bf16 v[114:117], v[188:191], v[136:139], v[114:117]
	v_mfma_f32_16x16x32_bf16 v[110:113], v[188:191], v[154:157], v[110:113]
	v_mfma_f32_16x16x32_bf16 v[106:109], v[196:199], v[136:139], v[106:109]
	v_mfma_f32_16x16x32_bf16 v[102:105], v[196:199], v[154:157], v[102:105]
	v_mfma_f32_16x16x32_bf16 v[130:133], v[176:179], v[140:143], v[130:133]
	v_mfma_f32_16x16x32_bf16 v[126:129], v[176:179], v[168:171], v[126:129]
	v_mfma_f32_16x16x32_bf16 v[122:125], v[184:187], v[140:143], v[122:125]
	v_mfma_f32_16x16x32_bf16 v[118:121], v[184:187], v[168:171], v[118:121]
	v_mfma_f32_16x16x32_bf16 v[114:117], v[192:195], v[140:143], v[114:117]
	v_mfma_f32_16x16x32_bf16 v[110:113], v[192:195], v[168:171], v[110:113]
	v_mfma_f32_16x16x32_bf16 v[106:109], v[200:203], v[140:143], v[106:109]
	v_mfma_f32_16x16x32_bf16 v[102:105], v[200:203], v[168:171], v[102:105]
	s_setprio 0
	s_barrier
	s_nop 0
	ds_read_b128 v[162:165], v161
	ds_read_b128 v[204:207], v161 offset:1024
	ds_read_b128 v[208:211], v161 offset:2048
	ds_read_b128 v[158:161], v161 offset:3072
	s_barrier
; #define LDA(dst, b, h) _Pragma("unroll") for (int m = 0; m < 4; ++m) _Pragma("unroll") for (int k = 0; k < 2; ++k) \
;     dst[m][k] = *reinterpret_cast<const bf16x8*>((char*)SA(b, h) + lds_byte(wr * 64 + m * 16 + fr, k * 32 + fq * 8))
; #define LDB(dst, b, h) _Pragma("unroll") for (int n = 0; n < 2; ++n) _Pragma("unroll") for (int k = 0; k < 2; ++k) \
;     dst[n][k] = *reinterpret_cast<const bf16x8*>((char*)SB(b, h) + lds_byte(wc * 32 + n * 16 + fr, k * 32 + fq * 8))
; #define MMA(ai, bj, At_, Bt_) do { __builtin_amdgcn_s_setprio(1); \
;     _Pragma("unroll") for (int m = 0; m < 4; ++m) _Pragma("unroll") for (int n = 0; n < 2; ++n) _Pragma("unroll") for (int k = 0; k < 2; ++k) \
;       acc[ai][bj][m][n] = __builtin_amdgcn_mfma_f32_16x16x32_bf16(At_[m][k], Bt_[n][k], acc[ai][bj][m][n], 0, 0, 0); \
;     __builtin_amdgcn_s_setprio(0); } while (0)
; #define WAIT_V(n) asm volatile("s_waitcnt vmcnt(" #n ")" ::: "memory")
; #define WAIT_L(n) asm volatile("s_waitcnt lgkmcnt(" #n ")" ::: "memory")
; #define BAR __builtin_amdgcn_s_barrier()
; __device__ __forceinline__ void gemm256(const bf16_t* __restrict__ A, long lda, const bf16_t* __restrict__ Bt, long ldb, int K,
;                                         int brow, int bcol, char* smem, f32x4 (&acc)[2][2][4][2]) {
;     ...
;       LDB(B1, 0, 1); BAR; WAIT_L(0); MMA(0, 1, At, B1); BAR;
;       LDA(At, 0, 1); WAIT_V(4); BAR; WAIT_L(0); MMA(1, 0, At, B0); MMA(1, 1, At, B1); BAR; }
;     { LDB(B0, 1, 0); LDA(At, 1, 0); WAIT_V(2); BAR; WAIT_L(0); MMA(0, 0, At, B0); BAR;
	s_waitcnt lgkmcnt(0)
	s_setprio 1
	s_waitcnt lgkmcnt(1)
	v_mfma_f32_16x16x32_bf16 v[94:97], v[172:175], v[208:211], v[94:97]
	v_mfma_f32_16x16x32_bf16 v[90:93], v[180:183], v[162:165], v[90:93]
	v_mfma_f32_16x16x32_bf16 v[86:89], v[180:183], v[208:211], v[86:89]
	v_mfma_f32_16x16x32_bf16 v[82:85], v[188:191], v[162:165], v[82:85]
	v_mfma_f32_16x16x32_bf16 v[78:81], v[188:191], v[208:211], v[78:81]
	v_mfma_f32_16x16x32_bf16 v[74:77], v[196:199], v[162:165], v[74:77]
	v_mfma_f32_16x16x32_bf16 v[70:73], v[196:199], v[208:211], v[70:73]
	v_mfma_f32_16x16x32_bf16 v[98:101], v[172:175], v[162:165], v[98:101]
	s_waitcnt lgkmcnt(0)
	v_mfma_f32_16x16x32_bf16 v[94:97], v[176:179], v[158:161], v[94:97]
	v_mfma_f32_16x16x32_bf16 v[90:93], v[184:187], v[204:207], v[90:93]
	v_mfma_f32_16x16x32_bf16 v[86:89], v[184:187], v[158:161], v[86:89]
	v_mfma_f32_16x16x32_bf16 v[82:85], v[192:195], v[204:207], v[82:85]
	v_mfma_f32_16x16x32_bf16 v[78:81], v[192:195], v[158:161], v[78:81]
	v_mfma_f32_16x16x32_bf16 v[74:77], v[200:203], v[204:207], v[74:77]
	v_mfma_f32_16x16x32_bf16 v[70:73], v[200:203], v[158:161], v[70:73]
	v_mfma_f32_16x16x32_bf16 v[212:215], v[176:179], v[204:207], v[98:101]
	s_setprio 0
	s_barrier
	s_nop 0
	ds_read_b128 v[98:101], v148 offset:16384
	ds_read_b128 v[172:175], v148 offset:17408
	ds_read_b128 v[176:179], v147 offset:16384
	ds_read_b128 v[180:183], v147 offset:17408
	ds_read_b128 v[184:187], v145 offset:16384
	ds_read_b128 v[188:191], v145 offset:17408
	ds_read_b128 v[192:195], v144 offset:16384
	ds_read_b128 v[196:199], v144 offset:17408
	s_waitcnt vmcnt(4)
	s_barrier
	s_waitcnt lgkmcnt(0)
	s_setprio 1
	s_waitcnt lgkmcnt(7)
	v_mfma_f32_16x16x32_bf16 v[62:65], v[98:101], v[154:157], v[62:65]
	s_waitcnt lgkmcnt(5)
	v_mfma_f32_16x16x32_bf16 v[58:61], v[176:179], v[136:139], v[58:61]
	v_mfma_f32_16x16x32_bf16 v[54:57], v[176:179], v[154:157], v[54:57]
	s_waitcnt lgkmcnt(3)
	v_mfma_f32_16x16x32_bf16 v[50:53], v[184:187], v[136:139], v[50:53]
	v_mfma_f32_16x16x32_bf16 v[46:49], v[184:187], v[154:157], v[46:49]
	s_waitcnt lgkmcnt(1)
	v_mfma_f32_16x16x32_bf16 v[42:45], v[192:195], v[136:139], v[42:45]
	v_mfma_f32_16x16x32_bf16 v[38:41], v[192:195], v[154:157], v[38:41]
	v_mfma_f32_16x16x32_bf16 v[66:69], v[98:101], v[136:139], v[66:69]
	v_mfma_f32_16x16x32_bf16 v[62:65], v[172:175], v[168:171], v[62:65]
	v_mfma_f32_16x16x32_bf16 v[58:61], v[180:183], v[140:143], v[58:61]
	v_mfma_f32_16x16x32_bf16 v[54:57], v[180:183], v[168:171], v[54:57]
	v_mfma_f32_16x16x32_bf16 v[50:53], v[188:191], v[140:143], v[50:53]
	v_mfma_f32_16x16x32_bf16 v[46:49], v[188:191], v[168:171], v[46:49]
	s_waitcnt lgkmcnt(0)
	v_mfma_f32_16x16x32_bf16 v[42:45], v[196:199], v[140:143], v[42:45]
	v_mfma_f32_16x16x32_bf16 v[38:41], v[196:199], v[168:171], v[38:41]
	v_mfma_f32_16x16x32_bf16 v[200:203], v[172:175], v[140:143], v[66:69]
	s_setprio 0
	s_setprio 1
	v_mfma_f32_16x16x32_bf16 v[34:37], v[98:101], v[162:165], v[34:37]
	v_mfma_f32_16x16x32_bf16 v[30:33], v[98:101], v[208:211], v[30:33]
	v_mfma_f32_16x16x32_bf16 v[26:29], v[176:179], v[162:165], v[26:29]
	v_mfma_f32_16x16x32_bf16 v[22:25], v[176:179], v[208:211], v[22:25]
	v_mfma_f32_16x16x32_bf16 v[18:21], v[184:187], v[162:165], v[18:21]
	v_mfma_f32_16x16x32_bf16 v[14:17], v[184:187], v[208:211], v[14:17]
	v_mfma_f32_16x16x32_bf16 v[10:13], v[192:195], v[162:165], v[10:13]
	v_mfma_f32_16x16x32_bf16 v[6:9], v[192:195], v[208:211], v[6:9]
	v_mfma_f32_16x16x32_bf16 v[34:37], v[172:175], v[204:207], v[34:37]
	v_mfma_f32_16x16x32_bf16 v[30:33], v[172:175], v[158:161], v[30:33]
	v_mfma_f32_16x16x32_bf16 v[26:29], v[180:183], v[204:207], v[26:29]
	v_mfma_f32_16x16x32_bf16 v[22:25], v[180:183], v[158:161], v[22:25]
	v_mfma_f32_16x16x32_bf16 v[18:21], v[188:191], v[204:207], v[18:21]
	v_mfma_f32_16x16x32_bf16 v[14:17], v[188:191], v[158:161], v[14:17]
	v_mfma_f32_16x16x32_bf16 v[10:13], v[196:199], v[204:207], v[10:13]
	v_mfma_f32_16x16x32_bf16 v[6:9], v[196:199], v[158:161], v[6:9]
	s_setprio 0
	s_barrier
	ds_read_b128 v[134:137], v152
	ds_read_b128 v[138:141], v152 offset:1024
	ds_read_b128 v[154:157], v152 offset:2048
	ds_read_b128 v[158:161], v152 offset:3072
	ds_read_b128 v[66:69], v148 offset:32768
	ds_read_b128 v[162:165], v148 offset:33792
	ds_read_b128 v[166:169], v147 offset:32768
	ds_read_b128 v[170:173], v147 offset:33792
	ds_read_b128 v[174:177], v145 offset:32768
	ds_read_b128 v[178:181], v145 offset:33792
	ds_read_b128 v[182:185], v144 offset:32768
	ds_read_b128 v[186:189], v144 offset:33792
	s_waitcnt vmcnt(2)
	s_barrier
; #define LDA(dst, b, h) _Pragma("unroll") for (int m = 0; m < 4; ++m) _Pragma("unroll") for (int k = 0; k < 2; ++k) \
;     dst[m][k] = *reinterpret_cast<const bf16x8*>((char*)SA(b, h) + lds_byte(wr * 64 + m * 16 + fr, k * 32 + fq * 8))
; #define LDB(dst, b, h) _Pragma("unroll") for (int n = 0; n < 2; ++n) _Pragma("unroll") for (int k = 0; k < 2; ++k) \
;     dst[n][k] = *reinterpret_cast<const bf16x8*>((char*)SB(b, h) + lds_byte(wc * 32 + n * 16 + fr, k * 32 + fq * 8))
; #define MMA(ai, bj, At_, Bt_) do { __builtin_amdgcn_s_setprio(1); \
;     _Pragma("unroll") for (int m = 0; m < 4; ++m) _Pragma("unroll") for (int n = 0; n < 2; ++n) _Pragma("unroll") for (int k = 0; k < 2; ++k) \
;       acc[ai][bj][m][n] = __builtin_amdgcn_mfma_f32_16x16x32_bf16(At_[m][k], Bt_[n][k], acc[ai][bj][m][n], 0, 0, 0); \
;     __builtin_amdgcn_s_setprio(0); } while (0)
; #define WAIT_V(n) asm volatile("s_waitcnt vmcnt(" #n ")" ::: "memory")
; #define WAIT_L(n) asm volatile("s_waitcnt lgkmcnt(" #n ")" ::: "memory")
; #define BAR __builtin_amdgcn_s_barrier()
; __device__ __forceinline__ void gemm256(const bf16_t* __restrict__ A, long lda, const bf16_t* __restrict__ Bt, long ldb, int K,
;                                         int brow, int bcol, char* smem, f32x4 (&acc)[2][2][4][2]) {
;     ...
;     { LDB(B0, 1, 0); LDA(At, 1, 0); WAIT_V(2); BAR; WAIT_L(0); MMA(0, 0, At, B0); BAR;
;       LDB(B1, 1, 1); WAIT_V(0); BAR; WAIT_L(0); MMA(0, 1, At, B1); BAR;
;       LDA(At, 1, 1); BAR; WAIT_L(0); MMA(1, 0, At, B0); MMA(1, 1, At, B1); BAR; }
;     if (wr == 0) BAR;
	s_waitcnt lgkmcnt(0)
	s_setprio 1
	s_waitcnt lgkmcnt(7)
	v_mfma_f32_16x16x32_bf16 v[98:101], v[66:69], v[134:137], v[130:133]
	s_waitcnt lgkmcnt(6)
	v_mfma_f32_16x16x32_bf16 v[130:133], v[162:165], v[138:141], v[98:101]
	v_mfma_f32_16x16x32_bf16 v[98:101], v[66:69], v[154:157], v[126:129]
	v_mfma_f32_16x16x32_bf16 v[126:129], v[162:165], v[158:161], v[98:101]
	s_waitcnt lgkmcnt(5)
	v_mfma_f32_16x16x32_bf16 v[98:101], v[166:169], v[134:137], v[122:125]
	s_waitcnt lgkmcnt(4)
	v_mfma_f32_16x16x32_bf16 v[122:125], v[170:173], v[138:141], v[98:101]
	v_mfma_f32_16x16x32_bf16 v[98:101], v[166:169], v[154:157], v[118:121]
	v_mfma_f32_16x16x32_bf16 v[118:121], v[170:173], v[158:161], v[98:101]
	s_waitcnt lgkmcnt(3)
	v_mfma_f32_16x16x32_bf16 v[98:101], v[174:177], v[134:137], v[114:117]
	s_waitcnt lgkmcnt(2)
	v_mfma_f32_16x16x32_bf16 v[114:117], v[178:181], v[138:141], v[98:101]
	v_mfma_f32_16x16x32_bf16 v[98:101], v[174:177], v[154:157], v[110:113]
	v_mfma_f32_16x16x32_bf16 v[110:113], v[178:181], v[158:161], v[98:101]
	s_waitcnt lgkmcnt(1)
	v_mfma_f32_16x16x32_bf16 v[98:101], v[182:185], v[134:137], v[106:109]
	s_waitcnt lgkmcnt(0)
	v_mfma_f32_16x16x32_bf16 v[106:109], v[186:189], v[138:141], v[98:101]
	v_mfma_f32_16x16x32_bf16 v[98:101], v[182:185], v[154:157], v[102:105]
	v_mfma_f32_16x16x32_bf16 v[98:101], v[186:189], v[158:161], v[98:101]
	s_setprio 0
	s_barrier
	ds_read_b128 v[190:193], v150
	ds_read_b128 v[194:197], v150 offset:1024
	ds_read_b128 v[204:207], v150 offset:2048
	ds_read_b128 v[150:153], v150 offset:3072
	s_waitcnt vmcnt(0)
	s_barrier
	s_waitcnt lgkmcnt(0)
	s_setprio 1
	s_waitcnt lgkmcnt(3)
	v_mfma_f32_16x16x32_bf16 v[102:105], v[66:69], v[190:193], v[212:215]
	s_waitcnt lgkmcnt(1)
	v_mfma_f32_16x16x32_bf16 v[66:69], v[66:69], v[204:207], v[94:97]
	s_waitcnt lgkmcnt(0)
	v_mfma_f32_16x16x32_bf16 v[94:97], v[162:165], v[150:153], v[66:69]
	v_mfma_f32_16x16x32_bf16 v[66:69], v[166:169], v[190:193], v[90:93]
	v_mfma_f32_16x16x32_bf16 v[90:93], v[170:173], v[194:197], v[66:69]
	v_mfma_f32_16x16x32_bf16 v[66:69], v[166:169], v[204:207], v[86:89]
	v_mfma_f32_16x16x32_bf16 v[86:89], v[170:173], v[150:153], v[66:69]
	v_mfma_f32_16x16x32_bf16 v[66:69], v[174:177], v[190:193], v[82:85]
	v_mfma_f32_16x16x32_bf16 v[82:85], v[178:181], v[194:197], v[66:69]
	v_mfma_f32_16x16x32_bf16 v[66:69], v[174:177], v[204:207], v[78:81]
	v_mfma_f32_16x16x32_bf16 v[78:81], v[178:181], v[150:153], v[66:69]
	v_mfma_f32_16x16x32_bf16 v[66:69], v[182:185], v[190:193], v[74:77]
	v_mfma_f32_16x16x32_bf16 v[74:77], v[186:189], v[194:197], v[66:69]
	v_mfma_f32_16x16x32_bf16 v[66:69], v[182:185], v[204:207], v[70:73]
	v_mfma_f32_16x16x32_bf16 v[102:105], v[162:165], v[194:197], v[102:105]
	v_mfma_f32_16x16x32_bf16 v[66:69], v[186:189], v[150:153], v[66:69]
	s_setprio 0
	s_barrier
	ds_read_b128 v[162:165], v148 offset:49152
	ds_read_b128 v[166:169], v148 offset:50176
	ds_read_b128 v[170:173], v147 offset:49152
	ds_read_b128 v[146:149], v147 offset:50176
	ds_read_b128 v[174:177], v145 offset:49152
	ds_read_b128 v[178:181], v145 offset:50176
	ds_read_b128 v[182:185], v144 offset:49152
	ds_read_b128 v[142:145], v144 offset:50176
	s_barrier
	s_waitcnt lgkmcnt(0)
	s_setprio 1
	s_waitcnt lgkmcnt(7)
	v_mfma_f32_16x16x32_bf16 v[70:73], v[162:165], v[134:137], v[200:203]
	v_mfma_f32_16x16x32_bf16 v[62:65], v[162:165], v[154:157], v[62:65]
	s_waitcnt lgkmcnt(5)
	v_mfma_f32_16x16x32_bf16 v[58:61], v[170:173], v[134:137], v[58:61]
	v_mfma_f32_16x16x32_bf16 v[54:57], v[170:173], v[154:157], v[54:57]
	s_waitcnt lgkmcnt(3)
	v_mfma_f32_16x16x32_bf16 v[50:53], v[174:177], v[134:137], v[50:53]
	v_mfma_f32_16x16x32_bf16 v[46:49], v[174:177], v[154:157], v[46:49]
	s_waitcnt lgkmcnt(1)
	v_mfma_f32_16x16x32_bf16 v[42:45], v[182:185], v[134:137], v[42:45]
	v_mfma_f32_16x16x32_bf16 v[38:41], v[182:185], v[154:157], v[38:41]
	v_mfma_f32_16x16x32_bf16 v[70:73], v[166:169], v[138:141], v[70:73]
	v_mfma_f32_16x16x32_bf16 v[62:65], v[166:169], v[158:161], v[62:65]
	v_mfma_f32_16x16x32_bf16 v[58:61], v[146:149], v[138:141], v[58:61]
	v_mfma_f32_16x16x32_bf16 v[54:57], v[146:149], v[158:161], v[54:57]
	v_mfma_f32_16x16x32_bf16 v[50:53], v[178:181], v[138:141], v[50:53]
	v_mfma_f32_16x16x32_bf16 v[46:49], v[178:181], v[158:161], v[46:49]
	s_waitcnt lgkmcnt(0)
	v_mfma_f32_16x16x32_bf16 v[42:45], v[142:145], v[138:141], v[42:45]
	v_mfma_f32_16x16x32_bf16 v[38:41], v[142:145], v[158:161], v[38:41]
	s_setprio 0
	s_setprio 1
	v_mfma_f32_16x16x32_bf16 v[34:37], v[162:165], v[190:193], v[34:37]
	v_mfma_f32_16x16x32_bf16 v[30:33], v[162:165], v[204:207], v[30:33]
	v_mfma_f32_16x16x32_bf16 v[26:29], v[170:173], v[190:193], v[26:29]
	v_mfma_f32_16x16x32_bf16 v[22:25], v[170:173], v[204:207], v[22:25]
	v_mfma_f32_16x16x32_bf16 v[18:21], v[174:177], v[190:193], v[18:21]
	v_mfma_f32_16x16x32_bf16 v[14:17], v[174:177], v[204:207], v[14:17]
	v_mfma_f32_16x16x32_bf16 v[10:13], v[182:185], v[190:193], v[10:13]
	v_mfma_f32_16x16x32_bf16 v[6:9], v[182:185], v[204:207], v[6:9]
	v_mfma_f32_16x16x32_bf16 v[34:37], v[166:169], v[194:197], v[34:37]
	v_mfma_f32_16x16x32_bf16 v[30:33], v[166:169], v[150:153], v[30:33]
	v_mfma_f32_16x16x32_bf16 v[26:29], v[146:149], v[194:197], v[26:29]
	v_mfma_f32_16x16x32_bf16 v[22:25], v[146:149], v[150:153], v[22:25]
	v_mfma_f32_16x16x32_bf16 v[18:21], v[178:181], v[194:197], v[18:21]
	v_mfma_f32_16x16x32_bf16 v[14:17], v[178:181], v[150:153], v[14:17]
	v_mfma_f32_16x16x32_bf16 v[10:13], v[142:145], v[194:197], v[10:13]
	v_mfma_f32_16x16x32_bf16 v[6:9], v[142:145], v[150:153], v[6:9]
	s_setprio 0
	v_cmp_gt_u32_e32 vcc, s78, v0
	s_barrier
	s_and_saveexec_b64 s[12:13], vcc
	s_cbranch_execz .LBB0_1078
	s_barrier
	s_branch .LBB0_1078

; #define STAGE(P, BASE, LD, br, kt) do { const long _g = (long)(br) * (LD) + (long)(kt) * 64; \
;     _Pragma("unroll") for (int _i = 0; _i < 2; ++_i) { const int _b = tid * 16 + _i * 8192; int _r, _c; stage_rc(_b, _r, _c); \
;       __builtin_amdgcn_global_load_lds((const G_AS1 unsigned*)((BASE) + _g + (long)_r * (LD) + _c), \
;         (LAS unsigned*)((char*)(P) + _b), 16, 0, 0); } } while (0)
; #define LDA(dst, b, h) _Pragma("unroll") for (int m = 0; m < 4; ++m) _Pragma("unroll") for (int k = 0; k < 2; ++k) \
;     dst[m][k] = *reinterpret_cast<const bf16x8*>((char*)SA(b, h) + lds_byte(wr * 64 + m * 16 + fr, k * 32 + fq * 8))
; #define LDB(dst, b, h) _Pragma("unroll") for (int n = 0; n < 2; ++n) _Pragma("unroll") for (int k = 0; k < 2; ++k) \
;     dst[n][k] = *reinterpret_cast<const bf16x8*>((char*)SB(b, h) + lds_byte(wc * 32 + n * 16 + fr, k * 32 + fq * 8))
; #define MMA(ai, bj, At_, Bt_) do { __builtin_amdgcn_s_setprio(1); \
;     _Pragma("unroll") for (int m = 0; m < 4; ++m) _Pragma("unroll") for (int n = 0; n < 2; ++n) _Pragma("unroll") for (int k = 0; k < 2; ++k) \
;       acc[ai][bj][m][n] = __builtin_amdgcn_mfma_f32_16x16x32_bf16(At_[m][k], Bt_[n][k], acc[ai][bj][m][n], 0, 0, 0); \
;     __builtin_amdgcn_s_setprio(0); } while (0)
; #define WAIT_L(n) asm volatile("s_waitcnt lgkmcnt(" #n ")" ::: "memory")
; #define BAR __builtin_amdgcn_s_barrier()
; #define SCHED __builtin_amdgcn_sched_barrier(0)
; __device__ __forceinline__ void gemm256(const bf16_t* __restrict__ A, long lda, const bf16_t* __restrict__ Bt, long ldb, int K,
;                                         int brow, int bcol, char* smem, f32x4 (&acc)[2][2][4][2]) {
;     ...
;         LDB(B0, 0, 0); SCHED; LDA(At, 0, 0); STAGE(SA(1, 1), A, lda, brow + 128, t + 1);
;         WAIT_L(8); BAR; WAIT_L(0); MMA(0, 0, At, B0); BAR; SCHED;
;         LDB(B1, 0, 1); STAGE(SB(0, 0), Bt, ldb, bcol, t + 2);
;         BAR; WAIT_L(0); MMA(0, 1, At, B1); BAR;
;         LDA(At, 0, 1); STAGE(SA(0, 0), A, lda, brow, t + 2);
;         BAR; WAIT_L(0); MMA(1, 0, At, B0); BAR; SCHED;
.LBB0_1555:
	s_nop 0
	ds_read_b128 v[168:171], v164
	ds_read_b128 v[172:175], v164 offset:1024
	ds_read_b128 v[176:179], v164 offset:2048
	ds_read_b128 v[180:183], v164 offset:3072
	v_add_u32_e32 v165, 0xc000, v5
	v_lshl_add_u64 v[232:233], s[4:5], 0, v[140:141]
	v_readfirstlane_b32 s7, v165
	v_lshl_add_u64 v[166:167], v[232:233], 0, s[8:9]
	s_mov_b32 m0, s7
	ds_read_b128 v[184:187], v147
	ds_read_b128 v[188:191], v147 offset:1024
	ds_read_b128 v[192:195], v146
	ds_read_b128 v[196:199], v146 offset:1024
	ds_read_b128 v[200:203], v145
	ds_read_b128 v[204:207], v145 offset:1024
	ds_read_b128 v[208:211], v144
	ds_read_b128 v[212:215], v144 offset:1024
	global_load_lds_dwordx4 v[166:167], off
	v_add_u32_e32 v166, 0xe000, v5
	v_lshl_add_u64 v[234:235], s[4:5], 0, v[142:143]
	v_readfirstlane_b32 s7, v166
	v_lshl_add_u64 v[216:217], v[234:235], 0, s[8:9]
	s_mov_b32 m0, s7
	s_nop 0
	global_load_lds_dwordx4 v[216:217], off
	s_waitcnt lgkmcnt(8)
	s_barrier
	s_waitcnt lgkmcnt(0)
	s_setprio 1
	s_waitcnt lgkmcnt(0)
	v_mfma_f32_16x16x32_bf16 v[130:133], v[184:187], v[168:171], v[130:133]
	v_mfma_f32_16x16x32_bf16 v[126:129], v[184:187], v[176:179], v[126:129]
	v_mfma_f32_16x16x32_bf16 v[122:125], v[192:195], v[168:171], v[122:125]
	v_mfma_f32_16x16x32_bf16 v[118:121], v[192:195], v[176:179], v[118:121]
	v_mfma_f32_16x16x32_bf16 v[114:117], v[200:203], v[168:171], v[114:117]
	v_mfma_f32_16x16x32_bf16 v[110:113], v[200:203], v[176:179], v[110:113]
	v_mfma_f32_16x16x32_bf16 v[106:109], v[208:211], v[168:171], v[106:109]
	v_mfma_f32_16x16x32_bf16 v[102:105], v[208:211], v[176:179], v[102:105]
	v_mfma_f32_16x16x32_bf16 v[130:133], v[188:191], v[172:175], v[130:133]
	v_mfma_f32_16x16x32_bf16 v[126:129], v[188:191], v[180:183], v[126:129]
	v_mfma_f32_16x16x32_bf16 v[122:125], v[196:199], v[172:175], v[122:125]
	v_mfma_f32_16x16x32_bf16 v[118:121], v[196:199], v[180:183], v[118:121]
	v_mfma_f32_16x16x32_bf16 v[114:117], v[204:207], v[172:175], v[114:117]
	v_mfma_f32_16x16x32_bf16 v[110:113], v[204:207], v[180:183], v[110:113]
	v_mfma_f32_16x16x32_bf16 v[106:109], v[212:215], v[172:175], v[106:109]
	v_mfma_f32_16x16x32_bf16 v[102:105], v[212:215], v[180:183], v[102:105]
	s_setprio 0
	s_barrier
	v_lshl_add_u64 v[238:239], s[4:5], 0, v[136:137]
	v_readfirstlane_b32 s7, v148
	v_lshl_add_u64 v[242:243], v[238:239], 0, s[16:17]
	s_mov_b32 m0, s7
	s_nop 0
	ds_read_b128 v[216:219], v161
	ds_read_b128 v[220:223], v161 offset:1024
	ds_read_b128 v[224:227], v161 offset:2048
	ds_read_b128 v[228:231], v161 offset:3072
	global_load_lds_dwordx4 v[242:243], off
	v_lshl_add_u64 v[242:243], s[4:5], 0, v[138:139]
	v_readfirstlane_b32 s7, v151
	v_lshl_add_u64 v[244:245], v[242:243], 0, s[16:17]
	s_mov_b32 m0, s7
	s_nop 0
	global_load_lds_dwordx4 v[244:245], off
	s_barrier
	s_waitcnt lgkmcnt(0)
	s_setprio 1
	s_waitcnt lgkmcnt(0)
	v_mfma_f32_16x16x32_bf16 v[98:101], v[184:187], v[216:219], v[98:101]
	v_mfma_f32_16x16x32_bf16 v[94:97], v[184:187], v[224:227], v[94:97]
	v_mfma_f32_16x16x32_bf16 v[90:93], v[192:195], v[216:219], v[90:93]
	v_mfma_f32_16x16x32_bf16 v[86:89], v[192:195], v[224:227], v[86:89]
	v_mfma_f32_16x16x32_bf16 v[82:85], v[200:203], v[216:219], v[82:85]
	v_mfma_f32_16x16x32_bf16 v[78:81], v[200:203], v[224:227], v[78:81]
	v_mfma_f32_16x16x32_bf16 v[74:77], v[208:211], v[216:219], v[74:77]
	v_mfma_f32_16x16x32_bf16 v[70:73], v[208:211], v[224:227], v[70:73]
	v_mfma_f32_16x16x32_bf16 v[98:101], v[188:191], v[220:223], v[98:101]
	v_mfma_f32_16x16x32_bf16 v[94:97], v[188:191], v[228:231], v[94:97]
	v_mfma_f32_16x16x32_bf16 v[90:93], v[196:199], v[220:223], v[90:93]
	v_mfma_f32_16x16x32_bf16 v[86:89], v[196:199], v[228:231], v[86:89]
	v_mfma_f32_16x16x32_bf16 v[82:85], v[204:207], v[220:223], v[82:85]
	v_mfma_f32_16x16x32_bf16 v[78:81], v[204:207], v[228:231], v[78:81]
	v_mfma_f32_16x16x32_bf16 v[74:77], v[212:215], v[220:223], v[74:77]
	v_mfma_f32_16x16x32_bf16 v[70:73], v[212:215], v[228:231], v[70:73]
	s_setprio 0
	v_readfirstlane_b32 s7, v5
	v_lshl_add_u64 v[244:245], v[232:233], 0, s[20:21]
	s_mov_b32 m0, s7
	v_readfirstlane_b32 s7, v149
	s_barrier
	s_nop 0
	ds_read_b128 v[184:187], v147 offset:16384
	ds_read_b128 v[188:191], v147 offset:17408
	ds_read_b128 v[192:195], v146 offset:16384
	ds_read_b128 v[196:199], v146 offset:17408
	ds_read_b128 v[200:203], v145 offset:16384
	ds_read_b128 v[204:207], v145 offset:17408
	ds_read_b128 v[208:211], v144 offset:16384
	ds_read_b128 v[212:215], v144 offset:17408
	global_load_lds_dwordx4 v[244:245], off
	v_lshl_add_u64 v[244:245], v[234:235], 0, s[20:21]
	s_mov_b32 m0, s7
	s_nop 0
	global_load_lds_dwordx4 v[244:245], off
	s_barrier
	s_waitcnt lgkmcnt(0)
	s_setprio 1
	s_waitcnt lgkmcnt(0)
	v_mfma_f32_16x16x32_bf16 v[66:69], v[184:187], v[168:171], v[66:69]
	v_mfma_f32_16x16x32_bf16 v[62:65], v[184:187], v[176:179], v[62:65]
	v_mfma_f32_16x16x32_bf16 v[58:61], v[192:195], v[168:171], v[58:61]
	v_mfma_f32_16x16x32_bf16 v[54:57], v[192:195], v[176:179], v[54:57]
	v_mfma_f32_16x16x32_bf16 v[50:53], v[200:203], v[168:171], v[50:53]
	v_mfma_f32_16x16x32_bf16 v[46:49], v[200:203], v[176:179], v[46:49]
	v_mfma_f32_16x16x32_bf16 v[42:45], v[208:211], v[168:171], v[42:45]
	v_mfma_f32_16x16x32_bf16 v[38:41], v[208:211], v[176:179], v[38:41]
	v_mfma_f32_16x16x32_bf16 v[66:69], v[188:191], v[172:175], v[66:69]
	v_mfma_f32_16x16x32_bf16 v[62:65], v[188:191], v[180:183], v[62:65]
	v_mfma_f32_16x16x32_bf16 v[58:61], v[196:199], v[172:175], v[58:61]
	v_mfma_f32_16x16x32_bf16 v[54:57], v[196:199], v[180:183], v[54:57]
	v_mfma_f32_16x16x32_bf16 v[50:53], v[204:207], v[172:175], v[50:53]
	v_mfma_f32_16x16x32_bf16 v[46:49], v[204:207], v[180:183], v[46:49]
	v_mfma_f32_16x16x32_bf16 v[42:45], v[212:215], v[172:175], v[42:45]
	v_mfma_f32_16x16x32_bf16 v[38:41], v[212:215], v[180:183], v[38:41]
	s_setprio 0
	s_barrier
; #define STAGE(P, BASE, LD, br, kt) do { const long _g = (long)(br) * (LD) + (long)(kt) * 64; \
;     _Pragma("unroll") for (int _i = 0; _i < 2; ++_i) { const int _b = tid * 16 + _i * 8192; int _r, _c; stage_rc(_b, _r, _c); \
;       __builtin_amdgcn_global_load_lds((const G_AS1 unsigned*)((BASE) + _g + (long)_r * (LD) + _c), \
;         (LAS unsigned*)((char*)(P) + _b), 16, 0, 0); } } while (0)
; #define LDA(dst, b, h) _Pragma("unroll") for (int m = 0; m < 4; ++m) _Pragma("unroll") for (int k = 0; k < 2; ++k) \
;     dst[m][k] = *reinterpret_cast<const bf16x8*>((char*)SA(b, h) + lds_byte(wr * 64 + m * 16 + fr, k * 32 + fq * 8))
; #define LDB(dst, b, h) _Pragma("unroll") for (int n = 0; n < 2; ++n) _Pragma("unroll") for (int k = 0; k < 2; ++k) \
;     dst[n][k] = *reinterpret_cast<const bf16x8*>((char*)SB(b, h) + lds_byte(wc * 32 + n * 16 + fr, k * 32 + fq * 8))
; #define MMA(ai, bj, At_, Bt_) do { __builtin_amdgcn_s_setprio(1); \
;     _Pragma("unroll") for (int m = 0; m < 4; ++m) _Pragma("unroll") for (int n = 0; n < 2; ++n) _Pragma("unroll") for (int k = 0; k < 2; ++k) \
;       acc[ai][bj][m][n] = __builtin_amdgcn_mfma_f32_16x16x32_bf16(At_[m][k], Bt_[n][k], acc[ai][bj][m][n], 0, 0, 0); \
;     __builtin_amdgcn_s_setprio(0); } while (0)
; #define WAIT_V(n) asm volatile("s_waitcnt vmcnt(" #n ")" ::: "memory")
; #define WAIT_L(n) asm volatile("s_waitcnt lgkmcnt(" #n ")" ::: "memory")
; #define BAR __builtin_amdgcn_s_barrier()
; #define SCHED __builtin_amdgcn_sched_barrier(0)
; __device__ __forceinline__ void gemm256(const bf16_t* __restrict__ A, long lda, const bf16_t* __restrict__ Bt, long ldb, int K,
;                                         int brow, int bcol, char* smem, f32x4 (&acc)[2][2][4][2]) {
;     ...
;         STAGE(SB(0, 1), Bt, ldb, bcol + 128, t + 2);
;         WAIT_V(6); BAR; MMA(1, 1, At, B1); BAR;
;         LDB(B0, 1, 0); SCHED; LDA(At, 1, 0); STAGE(SA(0, 1), A, lda, brow + 128, t + 2);
;         WAIT_L(8); BAR; WAIT_L(0); MMA(0, 0, At, B0); BAR; SCHED;
;         LDB(B1, 1, 1); STAGE(SB(1, 0), Bt, ldb, bcol, t + 3);
;         BAR; WAIT_L(0); MMA(0, 1, At, B1); BAR;
	v_readfirstlane_b32 s7, v153
	v_lshl_add_u64 v[168:169], v[238:239], 0, s[22:23]
	s_mov_b32 m0, s7
	v_readfirstlane_b32 s7, v154
	global_load_lds_dwordx4 v[168:169], off
	v_lshl_add_u64 v[168:169], v[242:243], 0, s[22:23]
	s_mov_b32 m0, s7
	s_nop 0
	global_load_lds_dwordx4 v[168:169], off
	s_waitcnt vmcnt(6)
	s_barrier
	s_setprio 1
	v_mfma_f32_16x16x32_bf16 v[34:37], v[184:187], v[216:219], v[34:37]
	v_mfma_f32_16x16x32_bf16 v[30:33], v[184:187], v[224:227], v[30:33]
	v_mfma_f32_16x16x32_bf16 v[26:29], v[192:195], v[216:219], v[26:29]
	v_mfma_f32_16x16x32_bf16 v[22:25], v[192:195], v[224:227], v[22:25]
	v_mfma_f32_16x16x32_bf16 v[18:21], v[200:203], v[216:219], v[18:21]
	v_mfma_f32_16x16x32_bf16 v[14:17], v[200:203], v[224:227], v[14:17]
	v_mfma_f32_16x16x32_bf16 v[10:13], v[208:211], v[216:219], v[10:13]
	v_mfma_f32_16x16x32_bf16 v[6:9], v[208:211], v[224:227], v[6:9]
	v_mfma_f32_16x16x32_bf16 v[34:37], v[188:191], v[220:223], v[34:37]
	v_mfma_f32_16x16x32_bf16 v[30:33], v[188:191], v[228:231], v[30:33]
	v_mfma_f32_16x16x32_bf16 v[26:29], v[196:199], v[220:223], v[26:29]
	v_mfma_f32_16x16x32_bf16 v[22:25], v[196:199], v[228:231], v[22:25]
	v_mfma_f32_16x16x32_bf16 v[18:21], v[204:207], v[220:223], v[18:21]
	v_mfma_f32_16x16x32_bf16 v[14:17], v[204:207], v[228:231], v[14:17]
	v_mfma_f32_16x16x32_bf16 v[10:13], v[212:215], v[220:223], v[10:13]
	v_mfma_f32_16x16x32_bf16 v[6:9], v[212:215], v[228:231], v[6:9]
	s_setprio 0
	s_barrier
	s_nop 0
	ds_read_b128 v[168:171], v152
	ds_read_b128 v[172:175], v152 offset:1024
	ds_read_b128 v[176:179], v152 offset:2048
	ds_read_b128 v[180:183], v152 offset:3072
	v_readfirstlane_b32 s7, v155
	v_lshl_add_u64 v[216:217], v[232:233], 0, s[24:25]
	s_mov_b32 m0, s7
	v_readfirstlane_b32 s7, v156
	ds_read_b128 v[184:187], v147 offset:32768
	ds_read_b128 v[188:191], v147 offset:33792
	ds_read_b128 v[192:195], v146 offset:32768
	ds_read_b128 v[196:199], v146 offset:33792
	ds_read_b128 v[200:203], v145 offset:32768
	ds_read_b128 v[204:207], v145 offset:33792
	ds_read_b128 v[208:211], v144 offset:32768
	ds_read_b128 v[212:215], v144 offset:33792
	global_load_lds_dwordx4 v[216:217], off
	v_lshl_add_u64 v[216:217], v[234:235], 0, s[24:25]
	s_mov_b32 m0, s7
	s_nop 0
	global_load_lds_dwordx4 v[216:217], off
	s_waitcnt lgkmcnt(8)
	s_barrier
	s_waitcnt lgkmcnt(0)
	s_setprio 1
	s_waitcnt lgkmcnt(0)
	v_mfma_f32_16x16x32_bf16 v[130:133], v[184:187], v[168:171], v[130:133]
	v_mfma_f32_16x16x32_bf16 v[126:129], v[184:187], v[176:179], v[126:129]
	v_mfma_f32_16x16x32_bf16 v[122:125], v[192:195], v[168:171], v[122:125]
	v_mfma_f32_16x16x32_bf16 v[118:121], v[192:195], v[176:179], v[118:121]
	v_mfma_f32_16x16x32_bf16 v[114:117], v[200:203], v[168:171], v[114:117]
	v_mfma_f32_16x16x32_bf16 v[110:113], v[200:203], v[176:179], v[110:113]
	v_mfma_f32_16x16x32_bf16 v[106:109], v[208:211], v[168:171], v[106:109]
	v_mfma_f32_16x16x32_bf16 v[102:105], v[208:211], v[176:179], v[102:105]
	v_mfma_f32_16x16x32_bf16 v[130:133], v[188:191], v[172:175], v[130:133]
	v_mfma_f32_16x16x32_bf16 v[126:129], v[188:191], v[180:183], v[126:129]
	v_mfma_f32_16x16x32_bf16 v[122:125], v[196:199], v[172:175], v[122:125]
	v_mfma_f32_16x16x32_bf16 v[118:121], v[196:199], v[180:183], v[118:121]
	v_mfma_f32_16x16x32_bf16 v[114:117], v[204:207], v[172:175], v[114:117]
	v_mfma_f32_16x16x32_bf16 v[110:113], v[204:207], v[180:183], v[110:113]
	v_mfma_f32_16x16x32_bf16 v[106:109], v[212:215], v[172:175], v[106:109]
	v_mfma_f32_16x16x32_bf16 v[102:105], v[212:215], v[180:183], v[102:105]
	s_setprio 0
	s_barrier
	v_readfirstlane_b32 s7, v157
	v_lshl_add_u64 v[244:245], v[238:239], 0, s[28:29]
	s_mov_b32 m0, s7
	v_readfirstlane_b32 s7, v158
	s_nop 0
	ds_read_b128 v[216:219], v150
	ds_read_b128 v[220:223], v150 offset:1024
	ds_read_b128 v[224:227], v150 offset:2048
	ds_read_b128 v[228:231], v150 offset:3072
	global_load_lds_dwordx4 v[244:245], off
	v_lshl_add_u64 v[244:245], v[242:243], 0, s[28:29]
	s_mov_b32 m0, s7
	s_nop 0
	global_load_lds_dwordx4 v[244:245], off
	s_barrier
	s_waitcnt lgkmcnt(0)
	s_setprio 1
	s_waitcnt lgkmcnt(0)
	v_mfma_f32_16x16x32_bf16 v[98:101], v[184:187], v[216:219], v[98:101]
	v_mfma_f32_16x16x32_bf16 v[94:97], v[184:187], v[224:227], v[94:97]
	v_mfma_f32_16x16x32_bf16 v[90:93], v[192:195], v[216:219], v[90:93]
	v_mfma_f32_16x16x32_bf16 v[86:89], v[192:195], v[224:227], v[86:89]
	v_mfma_f32_16x16x32_bf16 v[82:85], v[200:203], v[216:219], v[82:85]
	v_mfma_f32_16x16x32_bf16 v[78:81], v[200:203], v[224:227], v[78:81]
	v_mfma_f32_16x16x32_bf16 v[74:77], v[208:211], v[216:219], v[74:77]
	v_mfma_f32_16x16x32_bf16 v[70:73], v[208:211], v[224:227], v[70:73]
	v_mfma_f32_16x16x32_bf16 v[98:101], v[188:191], v[220:223], v[98:101]
	v_mfma_f32_16x16x32_bf16 v[94:97], v[188:191], v[228:231], v[94:97]
	v_mfma_f32_16x16x32_bf16 v[90:93], v[196:199], v[220:223], v[90:93]
	v_mfma_f32_16x16x32_bf16 v[86:89], v[196:199], v[228:231], v[86:89]
	v_mfma_f32_16x16x32_bf16 v[82:85], v[204:207], v[220:223], v[82:85]
	v_mfma_f32_16x16x32_bf16 v[78:81], v[204:207], v[228:231], v[78:81]
	v_mfma_f32_16x16x32_bf16 v[74:77], v[212:215], v[220:223], v[74:77]
	v_mfma_f32_16x16x32_bf16 v[70:73], v[212:215], v[228:231], v[70:73]
	s_setprio 0
	v_readfirstlane_b32 s7, v159
	v_lshl_add_u64 v[232:233], v[232:233], 0, s[34:35]
	s_mov_b32 m0, s7
	v_readfirstlane_b32 s7, v160
	s_barrier
	s_nop 0
	ds_read_b128 v[184:187], v147 offset:49152
	ds_read_b128 v[188:191], v147 offset:50176
	ds_read_b128 v[192:195], v146 offset:49152
	ds_read_b128 v[196:199], v146 offset:50176
	ds_read_b128 v[200:203], v145 offset:49152
	ds_read_b128 v[204:207], v145 offset:50176
	ds_read_b128 v[208:211], v144 offset:49152
	ds_read_b128 v[212:215], v144 offset:50176
	global_load_lds_dwordx4 v[232:233], off
	v_lshl_add_u64 v[232:233], v[234:235], 0, s[34:35]
	s_mov_b32 m0, s7
	s_nop 0
	global_load_lds_dwordx4 v[232:233], off
	s_barrier
; #define STAGE(P, BASE, LD, br, kt) do { const long _g = (long)(br) * (LD) + (long)(kt) * 64; \
;     _Pragma("unroll") for (int _i = 0; _i < 2; ++_i) { const int _b = tid * 16 + _i * 8192; int _r, _c; stage_rc(_b, _r, _c); \
;       __builtin_amdgcn_global_load_lds((const G_AS1 unsigned*)((BASE) + _g + (long)_r * (LD) + _c), \
;         (LAS unsigned*)((char*)(P) + _b), 16, 0, 0); } } while (0)
; #define LDA(dst, b, h) _Pragma("unroll") for (int m = 0; m < 4; ++m) _Pragma("unroll") for (int k = 0; k < 2; ++k) \
;     dst[m][k] = *reinterpret_cast<const bf16x8*>((char*)SA(b, h) + lds_byte(wr * 64 + m * 16 + fr, k * 32 + fq * 8))
; #define LDB(dst, b, h) _Pragma("unroll") for (int n = 0; n < 2; ++n) _Pragma("unroll") for (int k = 0; k < 2; ++k) \
;     dst[n][k] = *reinterpret_cast<const bf16x8*>((char*)SB(b, h) + lds_byte(wc * 32 + n * 16 + fr, k * 32 + fq * 8))
; #define MMA(ai, bj, At_, Bt_) do { __builtin_amdgcn_s_setprio(1); \
;     _Pragma("unroll") for (int m = 0; m < 4; ++m) _Pragma("unroll") for (int n = 0; n < 2; ++n) _Pragma("unroll") for (int k = 0; k < 2; ++k) \
;       acc[ai][bj][m][n] = __builtin_amdgcn_mfma_f32_16x16x32_bf16(At_[m][k], Bt_[n][k], acc[ai][bj][m][n], 0, 0, 0); \
;     __builtin_amdgcn_s_setprio(0); } while (0)
; #define WAIT_V(n) asm volatile("s_waitcnt vmcnt(" #n ")" ::: "memory")
; #define WAIT_L(n) asm volatile("s_waitcnt lgkmcnt(" #n ")" ::: "memory")
; #define BAR __builtin_amdgcn_s_barrier()
; #define SCHED __builtin_amdgcn_sched_barrier(0)
; __device__ __forceinline__ void gemm256(const bf16_t* __restrict__ A, long lda, const bf16_t* __restrict__ Bt, long ldb, int K,
;                                         int brow, int bcol, char* smem, f32x4 (&acc)[2][2][4][2]) {
;     ...
;         LDA(At, 1, 1); STAGE(SA(1, 0), A, lda, brow, t + 3);
;         BAR; WAIT_L(0); MMA(1, 0, At, B0); BAR; SCHED;
;         STAGE(SB(1, 1), Bt, ldb, bcol + 128, t + 3);
;         WAIT_V(6); BAR; MMA(1, 1, At, B1); BAR;
;     }
;     { LDB(B0, 0, 0); LDA(At, 0, 0); STAGE(SA(1, 1), A, lda, brow + 128, nt - 1);
;       BAR; WAIT_L(0); MMA(0, 0, At, B0); BAR;
;       LDB(B1, 0, 1); BAR; WAIT_L(0); MMA(0, 1, At, B1); BAR;
;       LDA(At, 0, 1); WAIT_V(4); BAR; WAIT_L(0); MMA(1, 0, At, B0); MMA(1, 1, At, B1); BAR; }
	s_waitcnt lgkmcnt(0)
	s_setprio 1
	s_waitcnt lgkmcnt(0)
	v_mfma_f32_16x16x32_bf16 v[66:69], v[184:187], v[168:171], v[66:69]
	v_mfma_f32_16x16x32_bf16 v[62:65], v[184:187], v[176:179], v[62:65]
	v_mfma_f32_16x16x32_bf16 v[58:61], v[192:195], v[168:171], v[58:61]
	v_mfma_f32_16x16x32_bf16 v[54:57], v[192:195], v[176:179], v[54:57]
	v_mfma_f32_16x16x32_bf16 v[50:53], v[200:203], v[168:171], v[50:53]
	v_mfma_f32_16x16x32_bf16 v[46:49], v[200:203], v[176:179], v[46:49]
	v_mfma_f32_16x16x32_bf16 v[42:45], v[208:211], v[168:171], v[42:45]
	v_mfma_f32_16x16x32_bf16 v[38:41], v[208:211], v[176:179], v[38:41]
	v_mfma_f32_16x16x32_bf16 v[66:69], v[188:191], v[172:175], v[66:69]
	v_mfma_f32_16x16x32_bf16 v[62:65], v[188:191], v[180:183], v[62:65]
	v_mfma_f32_16x16x32_bf16 v[58:61], v[196:199], v[172:175], v[58:61]
	v_mfma_f32_16x16x32_bf16 v[54:57], v[196:199], v[180:183], v[54:57]
	v_mfma_f32_16x16x32_bf16 v[50:53], v[204:207], v[172:175], v[50:53]
	v_mfma_f32_16x16x32_bf16 v[46:49], v[204:207], v[180:183], v[46:49]
	v_mfma_f32_16x16x32_bf16 v[42:45], v[212:215], v[172:175], v[42:45]
	v_mfma_f32_16x16x32_bf16 v[38:41], v[212:215], v[180:183], v[38:41]
	s_setprio 0
	s_barrier
	v_readfirstlane_b32 s7, v162
	v_lshl_add_u64 v[168:169], v[238:239], 0, s[46:47]
	s_mov_b32 m0, s7
	v_readfirstlane_b32 s7, v163
	global_load_lds_dwordx4 v[168:169], off
	v_lshl_add_u64 v[168:169], v[242:243], 0, s[46:47]
	s_mov_b32 m0, s7
	s_nop 0
	global_load_lds_dwordx4 v[168:169], off
	s_waitcnt vmcnt(6)
	s_barrier
	s_setprio 1
	v_mfma_f32_16x16x32_bf16 v[34:37], v[184:187], v[216:219], v[34:37]
	v_mfma_f32_16x16x32_bf16 v[30:33], v[184:187], v[224:227], v[30:33]
	v_mfma_f32_16x16x32_bf16 v[26:29], v[192:195], v[216:219], v[26:29]
	v_mfma_f32_16x16x32_bf16 v[22:25], v[192:195], v[224:227], v[22:25]
	v_mfma_f32_16x16x32_bf16 v[18:21], v[200:203], v[216:219], v[18:21]
	v_mfma_f32_16x16x32_bf16 v[14:17], v[200:203], v[224:227], v[14:17]
	v_mfma_f32_16x16x32_bf16 v[10:13], v[208:211], v[216:219], v[10:13]
	v_mfma_f32_16x16x32_bf16 v[6:9], v[208:211], v[224:227], v[6:9]
	v_mfma_f32_16x16x32_bf16 v[34:37], v[188:191], v[220:223], v[34:37]
	v_mfma_f32_16x16x32_bf16 v[30:33], v[188:191], v[228:231], v[30:33]
	v_mfma_f32_16x16x32_bf16 v[26:29], v[196:199], v[220:223], v[26:29]
	v_mfma_f32_16x16x32_bf16 v[22:25], v[196:199], v[228:231], v[22:25]
	v_mfma_f32_16x16x32_bf16 v[18:21], v[204:207], v[220:223], v[18:21]
	v_mfma_f32_16x16x32_bf16 v[14:17], v[204:207], v[228:231], v[14:17]
	v_mfma_f32_16x16x32_bf16 v[10:13], v[212:215], v[220:223], v[10:13]
	v_mfma_f32_16x16x32_bf16 v[6:9], v[212:215], v[228:231], v[6:9]
	s_setprio 0
	s_add_i32 s6, s6, 2
	v_lshl_add_u64 v[136:137], v[136:137], 0, s[44:45]
	v_lshl_add_u64 v[138:139], v[138:139], 0, s[44:45]
	v_lshl_add_u64 v[140:141], v[140:141], 0, s[44:45]
	s_cmp_lt_u32 s6, 8
	v_lshl_add_u64 v[142:143], v[142:143], 0, s[44:45]
	s_barrier
	s_cbranch_scc1 .LBB0_1555
	s_mov_b64 s[8:9], 0x580
	v_readfirstlane_b32 s6, v165
	v_lshl_add_u64 v[2:3], v[2:3], 0, s[8:9]
	s_mov_b32 m0, s6
	v_readfirstlane_b32 s6, v166
	s_nop 0
	ds_read_b128 v[136:139], v164
	ds_read_b128 v[140:143], v164 offset:1024
	ds_read_b128 v[154:157], v164 offset:2048
	ds_read_b128 v[168:171], v164 offset:3072
	ds_read_b128 v[172:175], v147
	ds_read_b128 v[176:179], v147 offset:1024
	ds_read_b128 v[180:183], v146
	ds_read_b128 v[184:187], v146 offset:1024
	ds_read_b128 v[188:191], v145
	ds_read_b128 v[192:195], v145 offset:1024
	ds_read_b128 v[196:199], v144
	ds_read_b128 v[200:203], v144 offset:1024
	global_load_lds_dwordx4 v[2:3], off
	v_lshl_add_u64 v[2:3], v[134:135], 0, s[8:9]
	s_mov_b32 m0, s6
	s_nop 0
	global_load_lds_dwordx4 v[2:3], off
	s_barrier
	s_waitcnt lgkmcnt(0)
	s_setprio 1
	s_waitcnt lgkmcnt(0)
	v_mfma_f32_16x16x32_bf16 v[130:133], v[172:175], v[136:139], v[130:133]
	v_mfma_f32_16x16x32_bf16 v[126:129], v[172:175], v[154:157], v[126:129]
	v_mfma_f32_16x16x32_bf16 v[122:125], v[180:183], v[136:139], v[122:125]
	v_mfma_f32_16x16x32_bf16 v[118:121], v[180:183], v[154:157], v[118:121]
	v_mfma_f32_16x16x32_bf16 v[114:117], v[188:191], v[136:139], v[114:117]
	v_mfma_f32_16x16x32_bf16 v[110:113], v[188:191], v[154:157], v[110:113]
	v_mfma_f32_16x16x32_bf16 v[106:109], v[196:199], v[136:139], v[106:109]
	v_mfma_f32_16x16x32_bf16 v[102:105], v[196:199], v[154:157], v[102:105]
	v_mfma_f32_16x16x32_bf16 v[130:133], v[176:179], v[140:143], v[130:133]
	v_mfma_f32_16x16x32_bf16 v[126:129], v[176:179], v[168:171], v[126:129]
	v_mfma_f32_16x16x32_bf16 v[122:125], v[184:187], v[140:143], v[122:125]
	v_mfma_f32_16x16x32_bf16 v[118:121], v[184:187], v[168:171], v[118:121]
	v_mfma_f32_16x16x32_bf16 v[114:117], v[192:195], v[140:143], v[114:117]
	v_mfma_f32_16x16x32_bf16 v[110:113], v[192:195], v[168:171], v[110:113]
	v_mfma_f32_16x16x32_bf16 v[106:109], v[200:203], v[140:143], v[106:109]
	v_mfma_f32_16x16x32_bf16 v[102:105], v[200:203], v[168:171], v[102:105]
	s_setprio 0
	s_barrier
	s_nop 0
	ds_read_b128 v[162:165], v161
	ds_read_b128 v[204:207], v161 offset:1024
	ds_read_b128 v[208:211], v161 offset:2048
	ds_read_b128 v[158:161], v161 offset:3072
	s_barrier
; #define LDA(dst, b, h) _Pragma("unroll") for (int m = 0; m < 4; ++m) _Pragma("unroll") for (int k = 0; k < 2; ++k) \
;     dst[m][k] = *reinterpret_cast<const bf16x8*>((char*)SA(b, h) + lds_byte(wr * 64 + m * 16 + fr, k * 32 + fq * 8))
; #define LDB(dst, b, h) _Pragma("unroll") for (int n = 0; n < 2; ++n) _Pragma("unroll") for (int k = 0; k < 2; ++k) \
;     dst[n][k] = *reinterpret_cast<const bf16x8*>((char*)SB(b, h) + lds_byte(wc * 32 + n * 16 + fr, k * 32 + fq * 8))
; #define MMA(ai, bj, At_, Bt_) do { __builtin_amdgcn_s_setprio(1); \
;     _Pragma("unroll") for (int m = 0; m < 4; ++m) _Pragma("unroll") for (int n = 0; n < 2; ++n) _Pragma("unroll") for (int k = 0; k < 2; ++k) \
;       acc[ai][bj][m][n] = __builtin_amdgcn_mfma_f32_16x16x32_bf16(At_[m][k], Bt_[n][k], acc[ai][bj][m][n], 0, 0, 0); \
;     __builtin_amdgcn_s_setprio(0); } while (0)
; #define WAIT_V(n) asm volatile("s_waitcnt vmcnt(" #n ")" ::: "memory")
; #define WAIT_L(n) asm volatile("s_waitcnt lgkmcnt(" #n ")" ::: "memory")
; #define BAR __builtin_amdgcn_s_barrier()
; __device__ __forceinline__ void gemm256(const bf16_t* __restrict__ A, long lda, const bf16_t* __restrict__ Bt, long ldb, int K,
;                                         int brow, int bcol, char* smem, f32x4 (&acc)[2][2][4][2]) {
;     ...
;       LDB(B1, 0, 1); BAR; WAIT_L(0); MMA(0, 1, At, B1); BAR;
;       LDA(At, 0, 1); WAIT_V(4); BAR; WAIT_L(0); MMA(1, 0, At, B0); MMA(1, 1, At, B1); BAR; }
;     { LDB(B0, 1, 0); LDA(At, 1, 0); WAIT_V(2); BAR; WAIT_L(0); MMA(0, 0, At, B0); BAR;
	s_waitcnt lgkmcnt(0)
	s_setprio 1
	s_waitcnt lgkmcnt(1)
	v_mfma_f32_16x16x32_bf16 v[94:97], v[172:175], v[208:211], v[94:97]
	v_mfma_f32_16x16x32_bf16 v[90:93], v[180:183], v[162:165], v[90:93]
	v_mfma_f32_16x16x32_bf16 v[86:89], v[180:183], v[208:211], v[86:89]
	v_mfma_f32_16x16x32_bf16 v[82:85], v[188:191], v[162:165], v[82:85]
	v_mfma_f32_16x16x32_bf16 v[78:81], v[188:191], v[208:211], v[78:81]
	v_mfma_f32_16x16x32_bf16 v[74:77], v[196:199], v[162:165], v[74:77]
	v_mfma_f32_16x16x32_bf16 v[70:73], v[196:199], v[208:211], v[70:73]
	v_mfma_f32_16x16x32_bf16 v[98:101], v[172:175], v[162:165], v[98:101]
	s_waitcnt lgkmcnt(0)
	v_mfma_f32_16x16x32_bf16 v[94:97], v[176:179], v[158:161], v[94:97]
	v_mfma_f32_16x16x32_bf16 v[90:93], v[184:187], v[204:207], v[90:93]
	v_mfma_f32_16x16x32_bf16 v[86:89], v[184:187], v[158:161], v[86:89]
	v_mfma_f32_16x16x32_bf16 v[82:85], v[192:195], v[204:207], v[82:85]
	v_mfma_f32_16x16x32_bf16 v[78:81], v[192:195], v[158:161], v[78:81]
	v_mfma_f32_16x16x32_bf16 v[74:77], v[200:203], v[204:207], v[74:77]
	v_mfma_f32_16x16x32_bf16 v[70:73], v[200:203], v[158:161], v[70:73]
	v_mfma_f32_16x16x32_bf16 v[212:215], v[176:179], v[204:207], v[98:101]
	s_setprio 0
	s_barrier
	s_nop 0
	ds_read_b128 v[98:101], v147 offset:16384
	ds_read_b128 v[172:175], v147 offset:17408
	ds_read_b128 v[176:179], v146 offset:16384
	ds_read_b128 v[180:183], v146 offset:17408
	ds_read_b128 v[184:187], v145 offset:16384
	ds_read_b128 v[188:191], v145 offset:17408
	ds_read_b128 v[192:195], v144 offset:16384
	ds_read_b128 v[196:199], v144 offset:17408
	s_waitcnt vmcnt(4)
	s_barrier
	s_waitcnt lgkmcnt(0)
	s_setprio 1
	s_waitcnt lgkmcnt(7)
	v_mfma_f32_16x16x32_bf16 v[62:65], v[98:101], v[154:157], v[62:65]
	s_waitcnt lgkmcnt(5)
	v_mfma_f32_16x16x32_bf16 v[58:61], v[176:179], v[136:139], v[58:61]
	v_mfma_f32_16x16x32_bf16 v[54:57], v[176:179], v[154:157], v[54:57]
	s_waitcnt lgkmcnt(3)
	v_mfma_f32_16x16x32_bf16 v[50:53], v[184:187], v[136:139], v[50:53]
	v_mfma_f32_16x16x32_bf16 v[46:49], v[184:187], v[154:157], v[46:49]
	s_waitcnt lgkmcnt(1)
	v_mfma_f32_16x16x32_bf16 v[42:45], v[192:195], v[136:139], v[42:45]
	v_mfma_f32_16x16x32_bf16 v[38:41], v[192:195], v[154:157], v[38:41]
	v_mfma_f32_16x16x32_bf16 v[66:69], v[98:101], v[136:139], v[66:69]
	v_mfma_f32_16x16x32_bf16 v[62:65], v[172:175], v[168:171], v[62:65]
	v_mfma_f32_16x16x32_bf16 v[58:61], v[180:183], v[140:143], v[58:61]
	v_mfma_f32_16x16x32_bf16 v[54:57], v[180:183], v[168:171], v[54:57]
	v_mfma_f32_16x16x32_bf16 v[50:53], v[188:191], v[140:143], v[50:53]
	v_mfma_f32_16x16x32_bf16 v[46:49], v[188:191], v[168:171], v[46:49]
	s_waitcnt lgkmcnt(0)
	v_mfma_f32_16x16x32_bf16 v[42:45], v[196:199], v[140:143], v[42:45]
	v_mfma_f32_16x16x32_bf16 v[38:41], v[196:199], v[168:171], v[38:41]
	v_mfma_f32_16x16x32_bf16 v[200:203], v[172:175], v[140:143], v[66:69]
	s_setprio 0
	s_setprio 1
	v_mfma_f32_16x16x32_bf16 v[34:37], v[98:101], v[162:165], v[34:37]
	v_mfma_f32_16x16x32_bf16 v[30:33], v[98:101], v[208:211], v[30:33]
	v_mfma_f32_16x16x32_bf16 v[26:29], v[176:179], v[162:165], v[26:29]
	v_mfma_f32_16x16x32_bf16 v[22:25], v[176:179], v[208:211], v[22:25]
	v_mfma_f32_16x16x32_bf16 v[18:21], v[184:187], v[162:165], v[18:21]
	v_mfma_f32_16x16x32_bf16 v[14:17], v[184:187], v[208:211], v[14:17]
	v_mfma_f32_16x16x32_bf16 v[10:13], v[192:195], v[162:165], v[10:13]
	v_mfma_f32_16x16x32_bf16 v[6:9], v[192:195], v[208:211], v[6:9]
	v_mfma_f32_16x16x32_bf16 v[34:37], v[172:175], v[204:207], v[34:37]
	v_mfma_f32_16x16x32_bf16 v[30:33], v[172:175], v[158:161], v[30:33]
	v_mfma_f32_16x16x32_bf16 v[26:29], v[180:183], v[204:207], v[26:29]
	v_mfma_f32_16x16x32_bf16 v[22:25], v[180:183], v[158:161], v[22:25]
	v_mfma_f32_16x16x32_bf16 v[18:21], v[188:191], v[204:207], v[18:21]
	v_mfma_f32_16x16x32_bf16 v[14:17], v[188:191], v[158:161], v[14:17]
	v_mfma_f32_16x16x32_bf16 v[10:13], v[196:199], v[204:207], v[10:13]
	v_mfma_f32_16x16x32_bf16 v[6:9], v[196:199], v[158:161], v[6:9]
	s_setprio 0
	s_barrier
	ds_read_b128 v[134:137], v152
	ds_read_b128 v[138:141], v152 offset:1024
	ds_read_b128 v[154:157], v152 offset:2048
	ds_read_b128 v[158:161], v152 offset:3072
	ds_read_b128 v[66:69], v147 offset:32768
	ds_read_b128 v[162:165], v147 offset:33792
	ds_read_b128 v[166:169], v146 offset:32768
	ds_read_b128 v[170:173], v146 offset:33792
	ds_read_b128 v[174:177], v145 offset:32768
	ds_read_b128 v[178:181], v145 offset:33792
	ds_read_b128 v[182:185], v144 offset:32768
	ds_read_b128 v[186:189], v144 offset:33792
	s_waitcnt vmcnt(2)
	s_barrier
; #define LDA(dst, b, h) _Pragma("unroll") for (int m = 0; m < 4; ++m) _Pragma("unroll") for (int k = 0; k < 2; ++k) \
;     dst[m][k] = *reinterpret_cast<const bf16x8*>((char*)SA(b, h) + lds_byte(wr * 64 + m * 16 + fr, k * 32 + fq * 8))
; #define LDB(dst, b, h) _Pragma("unroll") for (int n = 0; n < 2; ++n) _Pragma("unroll") for (int k = 0; k < 2; ++k) \
;     dst[n][k] = *reinterpret_cast<const bf16x8*>((char*)SB(b, h) + lds_byte(wc * 32 + n * 16 + fr, k * 32 + fq * 8))
; #define MMA(ai, bj, At_, Bt_) do { __builtin_amdgcn_s_setprio(1); \
;     _Pragma("unroll") for (int m = 0; m < 4; ++m) _Pragma("unroll") for (int n = 0; n < 2; ++n) _Pragma("unroll") for (int k = 0; k < 2; ++k) \
;       acc[ai][bj][m][n] = __builtin_amdgcn_mfma_f32_16x16x32_bf16(At_[m][k], Bt_[n][k], acc[ai][bj][m][n], 0, 0, 0); \
;     __builtin_amdgcn_s_setprio(0); } while (0)
; #define WAIT_V(n) asm volatile("s_waitcnt vmcnt(" #n ")" ::: "memory")
; #define WAIT_L(n) asm volatile("s_waitcnt lgkmcnt(" #n ")" ::: "memory")
; #define BAR __builtin_amdgcn_s_barrier()
; __device__ __forceinline__ void gemm256(const bf16_t* __restrict__ A, long lda, const bf16_t* __restrict__ Bt, long ldb, int K,
;                                         int brow, int bcol, char* smem, f32x4 (&acc)[2][2][4][2]) {
;     ...
;     { LDB(B0, 1, 0); LDA(At, 1, 0); WAIT_V(2); BAR; WAIT_L(0); MMA(0, 0, At, B0); BAR;
;       LDB(B1, 1, 1); WAIT_V(0); BAR; WAIT_L(0); MMA(0, 1, At, B1); BAR;
;       LDA(At, 1, 1); BAR; WAIT_L(0); MMA(1, 0, At, B0); MMA(1, 1, At, B1); BAR; }
;     if (wr == 0) BAR;
	s_waitcnt lgkmcnt(0)
	s_setprio 1
	s_waitcnt lgkmcnt(7)
	v_mfma_f32_16x16x32_bf16 v[98:101], v[66:69], v[134:137], v[130:133]
	s_waitcnt lgkmcnt(6)
	v_mfma_f32_16x16x32_bf16 v[130:133], v[162:165], v[138:141], v[98:101]
	v_mfma_f32_16x16x32_bf16 v[98:101], v[66:69], v[154:157], v[126:129]
	v_mfma_f32_16x16x32_bf16 v[126:129], v[162:165], v[158:161], v[98:101]
	s_waitcnt lgkmcnt(5)
	v_mfma_f32_16x16x32_bf16 v[98:101], v[166:169], v[134:137], v[122:125]
	s_waitcnt lgkmcnt(4)
	v_mfma_f32_16x16x32_bf16 v[122:125], v[170:173], v[138:141], v[98:101]
	v_mfma_f32_16x16x32_bf16 v[98:101], v[166:169], v[154:157], v[118:121]
	v_mfma_f32_16x16x32_bf16 v[118:121], v[170:173], v[158:161], v[98:101]
	s_waitcnt lgkmcnt(3)
	v_mfma_f32_16x16x32_bf16 v[98:101], v[174:177], v[134:137], v[114:117]
	s_waitcnt lgkmcnt(2)
	v_mfma_f32_16x16x32_bf16 v[114:117], v[178:181], v[138:141], v[98:101]
	v_mfma_f32_16x16x32_bf16 v[98:101], v[174:177], v[154:157], v[110:113]
	v_mfma_f32_16x16x32_bf16 v[110:113], v[178:181], v[158:161], v[98:101]
	s_waitcnt lgkmcnt(1)
	v_mfma_f32_16x16x32_bf16 v[98:101], v[182:185], v[134:137], v[106:109]
	s_waitcnt lgkmcnt(0)
	v_mfma_f32_16x16x32_bf16 v[106:109], v[186:189], v[138:141], v[98:101]
	v_mfma_f32_16x16x32_bf16 v[98:101], v[182:185], v[154:157], v[102:105]
	v_mfma_f32_16x16x32_bf16 v[98:101], v[186:189], v[158:161], v[98:101]
	s_setprio 0
	s_barrier
	ds_read_b128 v[190:193], v150
	ds_read_b128 v[194:197], v150 offset:1024
	ds_read_b128 v[204:207], v150 offset:2048
	ds_read_b128 v[148:151], v150 offset:3072
	s_waitcnt vmcnt(0)
	s_barrier
	s_waitcnt lgkmcnt(0)
	s_setprio 1
	s_waitcnt lgkmcnt(3)
	v_mfma_f32_16x16x32_bf16 v[102:105], v[66:69], v[190:193], v[212:215]
	s_waitcnt lgkmcnt(1)
	v_mfma_f32_16x16x32_bf16 v[66:69], v[66:69], v[204:207], v[94:97]
	s_waitcnt lgkmcnt(0)
	v_mfma_f32_16x16x32_bf16 v[94:97], v[162:165], v[148:151], v[66:69]
	v_mfma_f32_16x16x32_bf16 v[66:69], v[166:169], v[190:193], v[90:93]
	v_mfma_f32_16x16x32_bf16 v[90:93], v[170:173], v[194:197], v[66:69]
	v_mfma_f32_16x16x32_bf16 v[66:69], v[166:169], v[204:207], v[86:89]
	v_mfma_f32_16x16x32_bf16 v[86:89], v[170:173], v[148:151], v[66:69]
	v_mfma_f32_16x16x32_bf16 v[66:69], v[174:177], v[190:193], v[82:85]
	v_mfma_f32_16x16x32_bf16 v[82:85], v[178:181], v[194:197], v[66:69]
	v_mfma_f32_16x16x32_bf16 v[66:69], v[174:177], v[204:207], v[78:81]
	v_mfma_f32_16x16x32_bf16 v[78:81], v[178:181], v[148:151], v[66:69]
	v_mfma_f32_16x16x32_bf16 v[66:69], v[182:185], v[190:193], v[74:77]
	v_mfma_f32_16x16x32_bf16 v[74:77], v[186:189], v[194:197], v[66:69]
	v_mfma_f32_16x16x32_bf16 v[66:69], v[182:185], v[204:207], v[70:73]
	v_mfma_f32_16x16x32_bf16 v[102:105], v[162:165], v[194:197], v[102:105]
	v_mfma_f32_16x16x32_bf16 v[66:69], v[186:189], v[148:151], v[66:69]
	s_setprio 0
	s_barrier
	ds_read_b128 v[162:165], v147 offset:49152
	ds_read_b128 v[166:169], v147 offset:50176
	ds_read_b128 v[170:173], v146 offset:49152
	ds_read_b128 v[174:177], v146 offset:50176
	ds_read_b128 v[178:181], v145 offset:49152
	ds_read_b128 v[182:185], v145 offset:50176
	ds_read_b128 v[186:189], v144 offset:49152
	ds_read_b128 v[142:145], v144 offset:50176
	s_barrier
	s_waitcnt lgkmcnt(0)
	s_setprio 1
	s_waitcnt lgkmcnt(7)
	v_mfma_f32_16x16x32_bf16 v[70:73], v[162:165], v[134:137], v[200:203]
	v_mfma_f32_16x16x32_bf16 v[62:65], v[162:165], v[154:157], v[62:65]
	s_waitcnt lgkmcnt(5)
	v_mfma_f32_16x16x32_bf16 v[58:61], v[170:173], v[134:137], v[58:61]
	v_mfma_f32_16x16x32_bf16 v[54:57], v[170:173], v[154:157], v[54:57]
	s_waitcnt lgkmcnt(3)
	v_mfma_f32_16x16x32_bf16 v[50:53], v[178:181], v[134:137], v[50:53]
	v_mfma_f32_16x16x32_bf16 v[46:49], v[178:181], v[154:157], v[46:49]
	s_waitcnt lgkmcnt(1)
	v_mfma_f32_16x16x32_bf16 v[42:45], v[186:189], v[134:137], v[42:45]
	v_mfma_f32_16x16x32_bf16 v[38:41], v[186:189], v[154:157], v[38:41]
	v_mfma_f32_16x16x32_bf16 v[70:73], v[166:169], v[138:141], v[70:73]
	v_mfma_f32_16x16x32_bf16 v[62:65], v[166:169], v[158:161], v[62:65]
	v_mfma_f32_16x16x32_bf16 v[58:61], v[174:177], v[138:141], v[58:61]
	v_mfma_f32_16x16x32_bf16 v[54:57], v[174:177], v[158:161], v[54:57]
	v_mfma_f32_16x16x32_bf16 v[50:53], v[182:185], v[138:141], v[50:53]
	v_mfma_f32_16x16x32_bf16 v[46:49], v[182:185], v[158:161], v[46:49]
	s_waitcnt lgkmcnt(0)
	v_mfma_f32_16x16x32_bf16 v[42:45], v[142:145], v[138:141], v[42:45]
	v_mfma_f32_16x16x32_bf16 v[38:41], v[142:145], v[158:161], v[38:41]
	s_setprio 0
	s_setprio 1
	v_mfma_f32_16x16x32_bf16 v[34:37], v[162:165], v[190:193], v[34:37]
	v_mfma_f32_16x16x32_bf16 v[30:33], v[162:165], v[204:207], v[30:33]
	v_mfma_f32_16x16x32_bf16 v[26:29], v[170:173], v[190:193], v[26:29]
	v_mfma_f32_16x16x32_bf16 v[22:25], v[170:173], v[204:207], v[22:25]
	v_mfma_f32_16x16x32_bf16 v[18:21], v[178:181], v[190:193], v[18:21]
	v_mfma_f32_16x16x32_bf16 v[14:17], v[178:181], v[204:207], v[14:17]
	v_mfma_f32_16x16x32_bf16 v[10:13], v[186:189], v[190:193], v[10:13]
	v_mfma_f32_16x16x32_bf16 v[6:9], v[186:189], v[204:207], v[6:9]
	v_mfma_f32_16x16x32_bf16 v[34:37], v[166:169], v[194:197], v[34:37]
	v_mfma_f32_16x16x32_bf16 v[30:33], v[166:169], v[148:151], v[30:33]
	v_mfma_f32_16x16x32_bf16 v[26:29], v[174:177], v[194:197], v[26:29]
	v_mfma_f32_16x16x32_bf16 v[22:25], v[174:177], v[148:151], v[22:25]
	v_mfma_f32_16x16x32_bf16 v[18:21], v[182:185], v[194:197], v[18:21]
	v_mfma_f32_16x16x32_bf16 v[14:17], v[182:185], v[148:151], v[14:17]
	v_mfma_f32_16x16x32_bf16 v[10:13], v[142:145], v[194:197], v[10:13]
	v_mfma_f32_16x16x32_bf16 v[6:9], v[142:145], v[148:151], v[6:9]
	s_setprio 0
	v_cmp_gt_u32_e32 vcc, s78, v0
	s_barrier
	s_and_saveexec_b64 s[6:7], vcc
	s_cbranch_execz .LBB0_1558
	s_barrier

; #define STAGE(P, BASE, LD, br, kt) do { const long _g = (long)(br) * (LD) + (long)(kt) * 64; \
;     _Pragma("unroll") for (int _i = 0; _i < 2; ++_i) { const int _b = tid * 16 + _i * 8192; int _r, _c; stage_rc(_b, _r, _c); \
;       __builtin_amdgcn_global_load_lds((const G_AS1 unsigned*)((BASE) + _g + (long)_r * (LD) + _c), \
;         (LAS unsigned*)((char*)(P) + _b), 16, 0, 0); } } while (0)
; #define LDA(dst, b, h) _Pragma("unroll") for (int m = 0; m < 4; ++m) _Pragma("unroll") for (int k = 0; k < 2; ++k) \
;     dst[m][k] = *reinterpret_cast<const bf16x8*>((char*)SA(b, h) + lds_byte(wr * 64 + m * 16 + fr, k * 32 + fq * 8))
; #define LDB(dst, b, h) _Pragma("unroll") for (int n = 0; n < 2; ++n) _Pragma("unroll") for (int k = 0; k < 2; ++k) \
;     dst[n][k] = *reinterpret_cast<const bf16x8*>((char*)SB(b, h) + lds_byte(wc * 32 + n * 16 + fr, k * 32 + fq * 8))
; #define MMA(ai, bj, At_, Bt_) do { __builtin_amdgcn_s_setprio(1); \
;     _Pragma("unroll") for (int m = 0; m < 4; ++m) _Pragma("unroll") for (int n = 0; n < 2; ++n) _Pragma("unroll") for (int k = 0; k < 2; ++k) \
;       acc[ai][bj][m][n] = __builtin_amdgcn_mfma_f32_16x16x32_bf16(At_[m][k], Bt_[n][k], acc[ai][bj][m][n], 0, 0, 0); \
;     __builtin_amdgcn_s_setprio(0); } while (0)
; #define WAIT_V(n) asm volatile("s_waitcnt vmcnt(" #n ")" ::: "memory")
; #define WAIT_L(n) asm volatile("s_waitcnt lgkmcnt(" #n ")" ::: "memory")
; #define BAR __builtin_amdgcn_s_barrier()
; __device__ __forceinline__ void gemm256(const bf16_t* __restrict__ A, long lda, const bf16_t* __restrict__ Bt, long ldb, int K,
;                                         int brow, int bcol, char* smem, f32x4 (&acc)[2][2][4][2]) {
;     ...
;     __syncthreads();
;     STAGE(SB(0, 0), Bt, ldb, bcol, 0); STAGE(SA(0, 0), A, lda, brow, 0);
;     STAGE(SB(0, 1), Bt, ldb, bcol + 128, 0); STAGE(SA(0, 1), A, lda, brow + 128, 0);
;     if (wr == 1) BAR;
;     WAIT_V(4); BAR;
;     STAGE(SB(1, 0), Bt, ldb, bcol, 1); STAGE(SA(1, 0), A, lda, brow, 1); STAGE(SB(1, 1), Bt, ldb, bcol + 128, 1);
;     WAIT_V(6); BAR;
;     for (int t = 0; t < nt - 2; t += 2) {
;         LDB(B0, 0, 0); SCHED; LDA(At, 0, 0); STAGE(SA(1, 1), A, lda, brow + 128, t + 1);
;         WAIT_L(8); BAR; WAIT_L(0); MMA(0, 0, At, B0); BAR; SCHED;
;         LDB(B1, 0, 1); STAGE(SB(0, 0), Bt, ldb, bcol, t + 2);
;         BAR; WAIT_L(0); MMA(0, 1, At, B1); BAR;
.LBB0_1607:
	s_or_b64 exec, exec, s[10:11]
	v_add_u32_e32 v33, 0x18000, v22
	v_lshl_add_u64 v[30:31], v[8:9], 0, s[58:59]
	v_readfirstlane_b32 s18, v33
	v_add_u32_e32 v33, 0x1a000, v22
	s_mov_b32 m0, s18
	v_readfirstlane_b32 s17, v33
	v_add_u32_e32 v33, 0x8000, v22
	s_waitcnt vmcnt(4)
	s_barrier
	global_load_lds_dwordx4 v[30:31], off
	v_lshl_add_u64 v[30:31], v[18:19], 0, s[58:59]
	s_mov_b32 m0, s17
	v_readfirstlane_b32 s16, v33
	v_add_u32_e32 v33, 0xa000, v22
	v_lshlrev_b64 v[14:15], 8, v[14:15]
	global_load_lds_dwordx4 v[30:31], off
	v_lshl_add_u64 v[30:31], v[10:11], 0, s[58:59]
	s_mov_b32 m0, s16
	v_readfirstlane_b32 s15, v33
	s_add_u32 s20, s6, 0x10080
	global_load_lds_dwordx4 v[30:31], off
	v_lshl_add_u64 v[30:31], v[12:13], 0, s[58:59]
	s_mov_b32 m0, s15
	s_addc_u32 s21, s7, 0
	v_lshlrev_b64 v[14:15], 1, v[14:15]
	v_add_u32_e32 v33, 0x1c000, v22
	v_lshlrev_b64 v[16:17], 8, v[16:17]
	global_load_lds_dwordx4 v[30:31], off
	v_lshl_add_u64 v[30:31], s[20:21], 0, v[14:15]
	v_readfirstlane_b32 s11, v33
	v_lshl_add_u64 v[30:31], v[30:31], 0, v[2:3]
	s_mov_b32 m0, s11
	v_lshlrev_b64 v[16:17], 1, v[16:17]
	v_add_u32_e32 v33, 0x1e000, v22
	global_load_lds_dwordx4 v[30:31], off
	v_lshl_add_u64 v[30:31], s[20:21], 0, v[16:17]
	v_readfirstlane_b32 s10, v33
	v_lshl_add_u64 v[30:31], v[30:31], 0, v[6:7]
	s_mov_b32 m0, s10
	v_and_b32_e32 v21, 15, v0
	global_load_lds_dwordx4 v[30:31], off
	v_lshlrev_b32_e32 v33, 2, v0
	v_and_b32_e32 v32, 48, v0
	v_lshlrev_b32_e32 v21, 6, v21
	v_and_b32_e32 v33, 32, v33
	v_lshlrev_b32_e32 v30, 6, v0
	v_or_b32_e32 v31, v21, v32
	v_bitop3_b32 v21, v21, v33, v32 bitop3:0x36
	s_movk_i32 s19, 0x3000
	v_and_or_b32 v34, v30, s19, v21
	s_movk_i32 s19, 0x3c0
	v_or_b32_e32 v222, 0x10000, v34
	v_lshlrev_b32_e32 v20, 13, v20
	v_and_or_b32 v30, v30, s19, v32
	s_waitcnt vmcnt(6)
	s_barrier
	v_or_b32_e32 v223, 0x10400, v34
	v_or_b32_e32 v224, 0x10800, v34
	v_or_b32_e32 v225, 0x10c00, v34
	v_bitop3_b32 v21, v31, v20, v33 bitop3:0xde
	v_bitop3_b32 v20, v20, v30, v33 bitop3:0xf6
	v_or_b32_e32 v226, 0x14000, v34
	v_or_b32_e32 v227, 0x14400, v34
	v_or_b32_e32 v228, 0x14800, v34
	v_or_b32_e32 v229, 0x14c00, v34
	v_or_b32_e32 v230, 0x18000, v34
	v_or_b32_e32 v231, 0x18400, v34
	v_or_b32_e32 v232, 0x18800, v34
	v_or_b32_e32 v233, 0x18c00, v34
	v_or_b32_e32 v234, 0x1c000, v34
	v_or_b32_e32 v235, 0x1c400, v34
	v_or_b32_e32 v238, 0x1c800, v34
	v_or_b32_e32 v239, 0x1cc00, v34
	s_nop 0
	ds_read_b128 v[30:33], v222
	ds_read_b128 v[34:37], v223
	ds_read_b128 v[38:41], v224
	ds_read_b128 v[42:45], v225
	s_add_u32 s22, s8, 0x10080
	s_addc_u32 s23, s9, 0
	v_add_u32_e32 v80, 0xc000, v22
	v_lshl_add_u64 v[78:79], s[22:23], 0, v[14:15]
	v_readfirstlane_b32 s20, v80
	v_lshl_add_u64 v[78:79], v[78:79], 0, v[2:3]
	s_mov_b32 m0, s20
	v_add_u32_e32 v80, 0xe000, v22
	ds_read_b128 v[46:49], v21
	ds_read_b128 v[50:53], v21 offset:1024
	ds_read_b128 v[54:57], v20 offset:2048
	ds_read_b128 v[58:61], v20 offset:3072
	ds_read_b128 v[62:65], v20 offset:4096
	ds_read_b128 v[66:69], v20 offset:5120
	ds_read_b128 v[70:73], v20 offset:6144
	ds_read_b128 v[74:77], v20 offset:7168
	global_load_lds_dwordx4 v[78:79], off
	v_lshl_add_u64 v[78:79], s[22:23], 0, v[16:17]
	v_readfirstlane_b32 s19, v80
	v_lshl_add_u64 v[78:79], v[78:79], 0, v[6:7]
	s_mov_b32 m0, s19
	s_nop 0
	global_load_lds_dwordx4 v[78:79], off
	s_waitcnt lgkmcnt(8)
	s_barrier
	s_waitcnt lgkmcnt(0)
	s_setprio 1
	s_waitcnt lgkmcnt(0)
	v_mfma_f32_16x16x32_bf16 v[78:81], v[46:49], v[30:33], 0
	v_mfma_f32_16x16x32_bf16 v[82:85], v[46:49], v[38:41], 0
	v_mfma_f32_16x16x32_bf16 v[86:89], v[54:57], v[30:33], 0
	v_mfma_f32_16x16x32_bf16 v[90:93], v[54:57], v[38:41], 0
	v_mfma_f32_16x16x32_bf16 v[94:97], v[62:65], v[30:33], 0
	v_mfma_f32_16x16x32_bf16 v[98:101], v[62:65], v[38:41], 0
	v_mfma_f32_16x16x32_bf16 v[102:105], v[70:73], v[30:33], 0
	v_mfma_f32_16x16x32_bf16 v[106:109], v[70:73], v[38:41], 0
	v_mfma_f32_16x16x32_bf16 v[78:81], v[50:53], v[34:37], v[78:81]
	v_mfma_f32_16x16x32_bf16 v[82:85], v[50:53], v[42:45], v[82:85]
	v_mfma_f32_16x16x32_bf16 v[86:89], v[58:61], v[34:37], v[86:89]
	v_mfma_f32_16x16x32_bf16 v[90:93], v[58:61], v[42:45], v[90:93]
	v_mfma_f32_16x16x32_bf16 v[94:97], v[66:69], v[34:37], v[94:97]
	v_mfma_f32_16x16x32_bf16 v[98:101], v[66:69], v[42:45], v[98:101]
	v_mfma_f32_16x16x32_bf16 v[102:105], v[74:77], v[34:37], v[102:105]
	v_mfma_f32_16x16x32_bf16 v[106:109], v[74:77], v[42:45], v[106:109]
	s_setprio 0
	s_barrier
	v_readfirstlane_b32 s21, v28
	v_lshl_add_u64 v[126:127], v[8:9], 0, s[44:45]
	s_mov_b32 m0, s21
	v_readfirstlane_b32 s21, v29
	s_nop 0
	ds_read_b128 v[110:113], v226
	ds_read_b128 v[114:117], v227
	ds_read_b128 v[118:121], v228
	ds_read_b128 v[122:125], v229
	global_load_lds_dwordx4 v[126:127], off
	v_lshl_add_u64 v[126:127], v[18:19], 0, s[44:45]
	s_mov_b32 m0, s21
	s_nop 0
	global_load_lds_dwordx4 v[126:127], off
	s_barrier
	s_waitcnt lgkmcnt(0)
	s_setprio 1
	s_waitcnt lgkmcnt(0)
	v_mfma_f32_16x16x32_bf16 v[126:129], v[46:49], v[110:113], 0
	v_mfma_f32_16x16x32_bf16 v[46:49], v[46:49], v[118:121], 0
	v_mfma_f32_16x16x32_bf16 v[126:129], v[50:53], v[114:117], v[126:129]
	v_mfma_f32_16x16x32_bf16 v[46:49], v[50:53], v[122:125], v[46:49]
	v_mfma_f32_16x16x32_bf16 v[50:53], v[54:57], v[110:113], 0
	v_mfma_f32_16x16x32_bf16 v[54:57], v[54:57], v[118:121], 0
	v_mfma_f32_16x16x32_bf16 v[50:53], v[58:61], v[114:117], v[50:53]
	v_mfma_f32_16x16x32_bf16 v[54:57], v[58:61], v[122:125], v[54:57]
	v_mfma_f32_16x16x32_bf16 v[58:61], v[62:65], v[110:113], 0
	v_mfma_f32_16x16x32_bf16 v[62:65], v[62:65], v[118:121], 0
	v_mfma_f32_16x16x32_bf16 v[58:61], v[66:69], v[114:117], v[58:61]
	v_mfma_f32_16x16x32_bf16 v[62:65], v[66:69], v[122:125], v[62:65]
	v_mfma_f32_16x16x32_bf16 v[66:69], v[70:73], v[110:113], 0
	v_mfma_f32_16x16x32_bf16 v[70:73], v[70:73], v[118:121], 0
	v_mfma_f32_16x16x32_bf16 v[66:69], v[74:77], v[114:117], v[66:69]
	v_mfma_f32_16x16x32_bf16 v[70:73], v[74:77], v[122:125], v[70:73]
	s_setprio 0
	v_readfirstlane_b32 s21, v22
	v_lshl_add_u64 v[28:29], v[10:11], 0, s[44:45]
	s_mov_b32 m0, s21
	v_readfirstlane_b32 s21, v25
	s_barrier
; #define STAGE(P, BASE, LD, br, kt) do { const long _g = (long)(br) * (LD) + (long)(kt) * 64; \
;     _Pragma("unroll") for (int _i = 0; _i < 2; ++_i) { const int _b = tid * 16 + _i * 8192; int _r, _c; stage_rc(_b, _r, _c); \
;       __builtin_amdgcn_global_load_lds((const G_AS1 unsigned*)((BASE) + _g + (long)_r * (LD) + _c), \
;         (LAS unsigned*)((char*)(P) + _b), 16, 0, 0); } } while (0)
; #define LDA(dst, b, h) _Pragma("unroll") for (int m = 0; m < 4; ++m) _Pragma("unroll") for (int k = 0; k < 2; ++k) \
;     dst[m][k] = *reinterpret_cast<const bf16x8*>((char*)SA(b, h) + lds_byte(wr * 64 + m * 16 + fr, k * 32 + fq * 8))
; #define LDB(dst, b, h) _Pragma("unroll") for (int n = 0; n < 2; ++n) _Pragma("unroll") for (int k = 0; k < 2; ++k) \
;     dst[n][k] = *reinterpret_cast<const bf16x8*>((char*)SB(b, h) + lds_byte(wc * 32 + n * 16 + fr, k * 32 + fq * 8))
; #define MMA(ai, bj, At_, Bt_) do { __builtin_amdgcn_s_setprio(1); \
;     _Pragma("unroll") for (int m = 0; m < 4; ++m) _Pragma("unroll") for (int n = 0; n < 2; ++n) _Pragma("unroll") for (int k = 0; k < 2; ++k) \
;       acc[ai][bj][m][n] = __builtin_amdgcn_mfma_f32_16x16x32_bf16(At_[m][k], Bt_[n][k], acc[ai][bj][m][n], 0, 0, 0); \
;     __builtin_amdgcn_s_setprio(0); } while (0)
; #define WAIT_V(n) asm volatile("s_waitcnt vmcnt(" #n ")" ::: "memory")
; #define WAIT_L(n) asm volatile("s_waitcnt lgkmcnt(" #n ")" ::: "memory")
; #define BAR __builtin_amdgcn_s_barrier()
; #define SCHED __builtin_amdgcn_sched_barrier(0)
; __device__ __forceinline__ void gemm256(const bf16_t* __restrict__ A, long lda, const bf16_t* __restrict__ Bt, long ldb, int K,
;                                         int brow, int bcol, char* smem, f32x4 (&acc)[2][2][4][2]) {
;     ...
;         LDA(At, 0, 1); STAGE(SA(0, 0), A, lda, brow, t + 2);
;         BAR; WAIT_L(0); MMA(1, 0, At, B0); BAR; SCHED;
;         STAGE(SB(0, 1), Bt, ldb, bcol + 128, t + 2);
;         WAIT_V(6); BAR; MMA(1, 1, At, B1); BAR;
;         LDB(B0, 1, 0); SCHED; LDA(At, 1, 0); STAGE(SA(0, 1), A, lda, brow + 128, t + 2);
;         WAIT_L(8); BAR; WAIT_L(0); MMA(0, 0, At, B0); BAR; SCHED;
;         LDB(B1, 1, 1); STAGE(SB(1, 0), Bt, ldb, bcol, t + 3);
	s_nop 0
	ds_read_b128 v[74:77], v21 offset:16384
	ds_read_b128 v[130:133], v21 offset:17408
	ds_read_b128 v[134:137], v20 offset:18432
	ds_read_b128 v[138:141], v20 offset:19456
	ds_read_b128 v[142:145], v20 offset:20480
	ds_read_b128 v[146:149], v20 offset:21504
	ds_read_b128 v[150:153], v20 offset:22528
	ds_read_b128 v[154:157], v20 offset:23552
	global_load_lds_dwordx4 v[28:29], off
	v_lshl_add_u64 v[28:29], v[12:13], 0, s[44:45]
	s_mov_b32 m0, s21
	s_nop 0
	global_load_lds_dwordx4 v[28:29], off
	s_barrier
	s_waitcnt lgkmcnt(0)
	s_setprio 1
	s_waitcnt lgkmcnt(0)
	v_mfma_f32_16x16x32_bf16 v[158:161], v[74:77], v[30:33], 0
	v_mfma_f32_16x16x32_bf16 v[166:169], v[134:137], v[30:33], 0
	v_mfma_f32_16x16x32_bf16 v[174:177], v[142:145], v[30:33], 0
	v_mfma_f32_16x16x32_bf16 v[28:31], v[150:153], v[30:33], 0
	v_mfma_f32_16x16x32_bf16 v[158:161], v[130:133], v[34:37], v[158:161]
	v_mfma_f32_16x16x32_bf16 v[166:169], v[138:141], v[34:37], v[166:169]
	v_mfma_f32_16x16x32_bf16 v[174:177], v[146:149], v[34:37], v[174:177]
	v_mfma_f32_16x16x32_bf16 v[28:31], v[154:157], v[34:37], v[28:31]
	v_mfma_f32_16x16x32_bf16 v[32:35], v[150:153], v[38:41], 0
	v_mfma_f32_16x16x32_bf16 v[162:165], v[74:77], v[38:41], 0
	v_mfma_f32_16x16x32_bf16 v[170:173], v[134:137], v[38:41], 0
	v_mfma_f32_16x16x32_bf16 v[178:181], v[142:145], v[38:41], 0
	v_mfma_f32_16x16x32_bf16 v[32:35], v[154:157], v[42:45], v[32:35]
	v_mfma_f32_16x16x32_bf16 v[162:165], v[130:133], v[42:45], v[162:165]
	v_mfma_f32_16x16x32_bf16 v[170:173], v[138:141], v[42:45], v[170:173]
	v_mfma_f32_16x16x32_bf16 v[178:181], v[146:149], v[42:45], v[178:181]
	s_setprio 0
	s_barrier
	s_add_u32 s22, s6, 0x10100
	s_addc_u32 s23, s7, 0
	v_lshl_add_u64 v[36:37], s[22:23], 0, v[14:15]
	v_readfirstlane_b32 s21, v26
	v_lshl_add_u64 v[36:37], v[36:37], 0, v[2:3]
	s_mov_b32 m0, s21
	v_readfirstlane_b32 s21, v27
	global_load_lds_dwordx4 v[36:37], off
	v_lshl_add_u64 v[36:37], s[22:23], 0, v[16:17]
	v_lshl_add_u64 v[36:37], v[36:37], 0, v[6:7]
	s_mov_b32 m0, s21
	s_nop 0
	global_load_lds_dwordx4 v[36:37], off
	s_waitcnt vmcnt(6)
	s_barrier
	s_setprio 1
	v_mfma_f32_16x16x32_bf16 v[36:39], v[74:77], v[110:113], 0
	v_mfma_f32_16x16x32_bf16 v[40:43], v[74:77], v[118:121], 0
	v_mfma_f32_16x16x32_bf16 v[36:39], v[130:133], v[114:117], v[36:39]
	v_mfma_f32_16x16x32_bf16 v[40:43], v[130:133], v[122:125], v[40:43]
	v_mfma_f32_16x16x32_bf16 v[74:77], v[134:137], v[110:113], 0
	v_mfma_f32_16x16x32_bf16 v[130:133], v[134:137], v[118:121], 0
	v_mfma_f32_16x16x32_bf16 v[134:137], v[142:145], v[110:113], 0
	v_mfma_f32_16x16x32_bf16 v[110:113], v[150:153], v[110:113], 0
	v_mfma_f32_16x16x32_bf16 v[74:77], v[138:141], v[114:117], v[74:77]
	v_mfma_f32_16x16x32_bf16 v[134:137], v[146:149], v[114:117], v[134:137]
	v_mfma_f32_16x16x32_bf16 v[110:113], v[154:157], v[114:117], v[110:113]
	v_mfma_f32_16x16x32_bf16 v[114:117], v[150:153], v[118:121], 0
	v_mfma_f32_16x16x32_bf16 v[130:133], v[138:141], v[122:125], v[130:133]
	v_mfma_f32_16x16x32_bf16 v[138:141], v[142:145], v[118:121], 0
	v_mfma_f32_16x16x32_bf16 v[114:117], v[154:157], v[122:125], v[114:117]
	v_mfma_f32_16x16x32_bf16 v[138:141], v[146:149], v[122:125], v[138:141]
	s_setprio 0
	s_barrier
	s_nop 0
	ds_read_b128 v[118:121], v230
	ds_read_b128 v[122:125], v231
	ds_read_b128 v[142:145], v232
	ds_read_b128 v[146:149], v233
	s_add_u32 s22, s8, 0x10100
	s_addc_u32 s23, s9, 0
	v_lshl_add_u64 v[26:27], s[22:23], 0, v[14:15]
	v_readfirstlane_b32 s21, v23
	v_lshl_add_u64 v[26:27], v[26:27], 0, v[2:3]
	s_mov_b32 m0, s21
	v_lshl_add_u64 v[22:23], s[22:23], 0, v[16:17]
	v_readfirstlane_b32 s21, v24
	ds_read_b128 v[150:153], v21 offset:32768
	ds_read_b128 v[154:157], v21 offset:33792
	ds_read_b128 v[182:185], v20 offset:34816
	ds_read_b128 v[190:193], v20 offset:35840
	ds_read_b128 v[194:197], v20 offset:36864
	ds_read_b128 v[198:201], v20 offset:37888
	ds_read_b128 v[202:205], v20 offset:38912
	ds_read_b128 v[206:209], v20 offset:39936
	global_load_lds_dwordx4 v[26:27], off
	v_lshl_add_u64 v[22:23], v[22:23], 0, v[6:7]
	s_mov_b32 m0, s21
	s_nop 0
	global_load_lds_dwordx4 v[22:23], off
	s_waitcnt lgkmcnt(8)
	s_barrier
	s_waitcnt lgkmcnt(0)
	s_setprio 1
	s_waitcnt lgkmcnt(0)
	v_mfma_f32_16x16x32_bf16 v[22:25], v[150:153], v[118:121], v[78:81]
	v_mfma_f32_16x16x32_bf16 v[78:81], v[150:153], v[142:145], v[82:85]
	v_mfma_f32_16x16x32_bf16 v[82:85], v[182:185], v[118:121], v[86:89]
	v_mfma_f32_16x16x32_bf16 v[86:89], v[182:185], v[142:145], v[90:93]
	v_mfma_f32_16x16x32_bf16 v[90:93], v[194:197], v[118:121], v[94:97]
	v_mfma_f32_16x16x32_bf16 v[94:97], v[194:197], v[142:145], v[98:101]
	v_mfma_f32_16x16x32_bf16 v[98:101], v[202:205], v[118:121], v[102:105]
	v_mfma_f32_16x16x32_bf16 v[102:105], v[202:205], v[142:145], v[106:109]
	v_mfma_f32_16x16x32_bf16 v[22:25], v[154:157], v[122:125], v[22:25]
	v_mfma_f32_16x16x32_bf16 v[78:81], v[154:157], v[146:149], v[78:81]
	v_mfma_f32_16x16x32_bf16 v[82:85], v[190:193], v[122:125], v[82:85]
	v_mfma_f32_16x16x32_bf16 v[86:89], v[190:193], v[146:149], v[86:89]
	v_mfma_f32_16x16x32_bf16 v[90:93], v[198:201], v[122:125], v[90:93]
	v_mfma_f32_16x16x32_bf16 v[94:97], v[198:201], v[146:149], v[94:97]
	v_mfma_f32_16x16x32_bf16 v[98:101], v[206:209], v[122:125], v[98:101]
	v_mfma_f32_16x16x32_bf16 v[102:105], v[206:209], v[146:149], v[102:105]
	s_setprio 0
	s_barrier
	s_mov_b64 s[22:23], 0x180
	s_mov_b32 m0, s18
	v_lshl_add_u64 v[8:9], v[8:9], 0, s[22:23]
	s_nop 0
	ds_read_b128 v[106:109], v234
	ds_read_b128 v[210:213], v235
	ds_read_b128 v[214:217], v238
	ds_read_b128 v[218:221], v239
	global_load_lds_dwordx4 v[8:9], off
	v_lshl_add_u64 v[8:9], v[18:19], 0, s[22:23]
	s_mov_b32 m0, s17
	s_nop 0
	global_load_lds_dwordx4 v[8:9], off
	s_barrier
; #define STAGE(P, BASE, LD, br, kt) do { const long _g = (long)(br) * (LD) + (long)(kt) * 64; \
;     _Pragma("unroll") for (int _i = 0; _i < 2; ++_i) { const int _b = tid * 16 + _i * 8192; int _r, _c; stage_rc(_b, _r, _c); \
;       __builtin_amdgcn_global_load_lds((const G_AS1 unsigned*)((BASE) + _g + (long)_r * (LD) + _c), \
;         (LAS unsigned*)((char*)(P) + _b), 16, 0, 0); } } while (0)
; #define LDA(dst, b, h) _Pragma("unroll") for (int m = 0; m < 4; ++m) _Pragma("unroll") for (int k = 0; k < 2; ++k) \
;     dst[m][k] = *reinterpret_cast<const bf16x8*>((char*)SA(b, h) + lds_byte(wr * 64 + m * 16 + fr, k * 32 + fq * 8))
; #define LDB(dst, b, h) _Pragma("unroll") for (int n = 0; n < 2; ++n) _Pragma("unroll") for (int k = 0; k < 2; ++k) \
;     dst[n][k] = *reinterpret_cast<const bf16x8*>((char*)SB(b, h) + lds_byte(wc * 32 + n * 16 + fr, k * 32 + fq * 8))
; #define MMA(ai, bj, At_, Bt_) do { __builtin_amdgcn_s_setprio(1); \
;     _Pragma("unroll") for (int m = 0; m < 4; ++m) _Pragma("unroll") for (int n = 0; n < 2; ++n) _Pragma("unroll") for (int k = 0; k < 2; ++k) \
;       acc[ai][bj][m][n] = __builtin_amdgcn_mfma_f32_16x16x32_bf16(At_[m][k], Bt_[n][k], acc[ai][bj][m][n], 0, 0, 0); \
;     __builtin_amdgcn_s_setprio(0); } while (0)
; #define WAIT_V(n) asm volatile("s_waitcnt vmcnt(" #n ")" ::: "memory")
; #define WAIT_L(n) asm volatile("s_waitcnt lgkmcnt(" #n ")" ::: "memory")
; #define BAR __builtin_amdgcn_s_barrier()
; #define SCHED __builtin_amdgcn_sched_barrier(0)
; __device__ __forceinline__ void gemm256(const bf16_t* __restrict__ A, long lda, const bf16_t* __restrict__ Bt, long ldb, int K,
;                                         int brow, int bcol, char* smem, f32x4 (&acc)[2][2][4][2]) {
;     ...
;         LDB(B1, 1, 1); STAGE(SB(1, 0), Bt, ldb, bcol, t + 3);
;         BAR; WAIT_L(0); MMA(0, 1, At, B1); BAR;
;         LDA(At, 1, 1); STAGE(SA(1, 0), A, lda, brow, t + 3);
;         BAR; WAIT_L(0); MMA(1, 0, At, B0); BAR; SCHED;
;         STAGE(SB(1, 1), Bt, ldb, bcol + 128, t + 3);
;         WAIT_V(6); BAR; MMA(1, 1, At, B1); BAR;
;     }
;     { LDB(B0, 0, 0); LDA(At, 0, 0); STAGE(SA(1, 1), A, lda, brow + 128, nt - 1);
	s_waitcnt lgkmcnt(0)
	s_setprio 1
	s_waitcnt lgkmcnt(0)
	v_mfma_f32_16x16x32_bf16 v[126:129], v[150:153], v[106:109], v[126:129]
	v_mfma_f32_16x16x32_bf16 v[44:47], v[150:153], v[214:217], v[46:49]
	v_mfma_f32_16x16x32_bf16 v[48:51], v[182:185], v[106:109], v[50:53]
	v_mfma_f32_16x16x32_bf16 v[52:55], v[182:185], v[214:217], v[54:57]
	v_mfma_f32_16x16x32_bf16 v[56:59], v[194:197], v[106:109], v[58:61]
	v_mfma_f32_16x16x32_bf16 v[60:63], v[194:197], v[214:217], v[62:65]
	v_mfma_f32_16x16x32_bf16 v[64:67], v[202:205], v[106:109], v[66:69]
	v_mfma_f32_16x16x32_bf16 v[68:71], v[202:205], v[214:217], v[70:73]
	v_mfma_f32_16x16x32_bf16 v[126:129], v[154:157], v[210:213], v[126:129]
	v_mfma_f32_16x16x32_bf16 v[44:47], v[154:157], v[218:221], v[44:47]
	v_mfma_f32_16x16x32_bf16 v[48:51], v[190:193], v[210:213], v[48:51]
	v_mfma_f32_16x16x32_bf16 v[52:55], v[190:193], v[218:221], v[52:55]
	v_mfma_f32_16x16x32_bf16 v[56:59], v[198:201], v[210:213], v[56:59]
	v_mfma_f32_16x16x32_bf16 v[60:63], v[198:201], v[218:221], v[60:63]
	v_mfma_f32_16x16x32_bf16 v[64:67], v[206:209], v[210:213], v[64:67]
	v_mfma_f32_16x16x32_bf16 v[68:71], v[206:209], v[218:221], v[68:71]
	s_setprio 0
	s_mov_b32 m0, s16
	v_lshl_add_u64 v[8:9], v[10:11], 0, s[22:23]
	s_barrier
	s_nop 0
	ds_read_b128 v[150:153], v21 offset:49152
	ds_read_b128 v[154:157], v21 offset:50176
	ds_read_b128 v[182:185], v20 offset:51200
	ds_read_b128 v[190:193], v20 offset:52224
	ds_read_b128 v[194:197], v20 offset:53248
	ds_read_b128 v[198:201], v20 offset:54272
	ds_read_b128 v[202:205], v20 offset:55296
	ds_read_b128 v[206:209], v20 offset:56320
	global_load_lds_dwordx4 v[8:9], off
	v_lshl_add_u64 v[8:9], v[12:13], 0, s[22:23]
	s_mov_b32 m0, s15
	s_nop 0
	global_load_lds_dwordx4 v[8:9], off
	s_barrier
	s_waitcnt lgkmcnt(0)
	s_setprio 1
	s_waitcnt lgkmcnt(0)
	v_mfma_f32_16x16x32_bf16 v[8:11], v[150:153], v[118:121], v[158:161]
	v_mfma_f32_16x16x32_bf16 v[26:29], v[202:205], v[118:121], v[28:31]
	v_mfma_f32_16x16x32_bf16 v[30:33], v[202:205], v[142:145], v[32:35]
	v_mfma_f32_16x16x32_bf16 v[8:11], v[154:157], v[122:125], v[8:11]
	v_mfma_f32_16x16x32_bf16 v[158:161], v[150:153], v[142:145], v[162:165]
	v_mfma_f32_16x16x32_bf16 v[162:165], v[182:185], v[118:121], v[166:169]
	v_mfma_f32_16x16x32_bf16 v[166:169], v[182:185], v[142:145], v[170:173]
	v_mfma_f32_16x16x32_bf16 v[170:173], v[194:197], v[118:121], v[174:177]
	v_mfma_f32_16x16x32_bf16 v[174:177], v[194:197], v[142:145], v[178:181]
	v_mfma_f32_16x16x32_bf16 v[26:29], v[206:209], v[122:125], v[26:29]
	v_mfma_f32_16x16x32_bf16 v[30:33], v[206:209], v[146:149], v[30:33]
	v_mfma_f32_16x16x32_bf16 v[158:161], v[154:157], v[146:149], v[158:161]
	v_mfma_f32_16x16x32_bf16 v[162:165], v[190:193], v[122:125], v[162:165]
	v_mfma_f32_16x16x32_bf16 v[166:169], v[190:193], v[146:149], v[166:169]
	v_mfma_f32_16x16x32_bf16 v[170:173], v[198:201], v[122:125], v[170:173]
	v_mfma_f32_16x16x32_bf16 v[174:177], v[198:201], v[146:149], v[174:177]
	s_setprio 0
	s_barrier
	s_add_u32 s6, s6, 0x10180
	s_addc_u32 s7, s7, 0
	v_lshl_add_u64 v[12:13], s[6:7], 0, v[14:15]
	s_mov_b32 m0, s11
	v_lshl_add_u64 v[12:13], v[12:13], 0, v[2:3]
	global_load_lds_dwordx4 v[12:13], off
	v_lshl_add_u64 v[12:13], s[6:7], 0, v[16:17]
	v_lshl_add_u64 v[12:13], v[12:13], 0, v[6:7]
	s_mov_b32 m0, s10
	s_nop 0
	global_load_lds_dwordx4 v[12:13], off
	s_waitcnt vmcnt(6)
	s_barrier
	s_setprio 1
	v_mfma_f32_16x16x32_bf16 v[34:37], v[150:153], v[106:109], v[36:39]
	v_mfma_f32_16x16x32_bf16 v[38:41], v[150:153], v[214:217], v[40:43]
	v_mfma_f32_16x16x32_bf16 v[72:75], v[182:185], v[106:109], v[74:77]
	v_mfma_f32_16x16x32_bf16 v[118:121], v[182:185], v[214:217], v[130:133]
	v_mfma_f32_16x16x32_bf16 v[122:125], v[194:197], v[106:109], v[134:137]
	v_mfma_f32_16x16x32_bf16 v[130:133], v[194:197], v[214:217], v[138:141]
	v_mfma_f32_16x16x32_bf16 v[106:109], v[202:205], v[106:109], v[110:113]
	v_mfma_f32_16x16x32_bf16 v[110:113], v[202:205], v[214:217], v[114:117]
	v_mfma_f32_16x16x32_bf16 v[34:37], v[154:157], v[210:213], v[34:37]
	v_mfma_f32_16x16x32_bf16 v[38:41], v[154:157], v[218:221], v[38:41]
	v_mfma_f32_16x16x32_bf16 v[72:75], v[190:193], v[210:213], v[72:75]
	v_mfma_f32_16x16x32_bf16 v[118:121], v[190:193], v[218:221], v[118:121]
	v_mfma_f32_16x16x32_bf16 v[122:125], v[198:201], v[210:213], v[122:125]
	v_mfma_f32_16x16x32_bf16 v[130:133], v[198:201], v[218:221], v[130:133]
	v_mfma_f32_16x16x32_bf16 v[106:109], v[206:209], v[210:213], v[106:109]
	v_mfma_f32_16x16x32_bf16 v[110:113], v[206:209], v[218:221], v[110:113]
	s_setprio 0
	s_add_u32 s6, s8, 0x10180
	s_addc_u32 s7, s9, 0
	v_lshl_add_u64 v[12:13], s[6:7], 0, v[14:15]
	s_mov_b32 m0, s20
	v_lshl_add_u64 v[2:3], v[12:13], 0, v[2:3]
	s_barrier
	s_nop 0
	ds_read_b128 v[114:117], v222
	ds_read_b128 v[134:137], v223
	ds_read_b128 v[138:141], v224
	ds_read_b128 v[142:145], v225
	ds_read_b128 v[146:149], v21
	ds_read_b128 v[150:153], v21 offset:1024
	ds_read_b128 v[154:157], v20 offset:2048
	ds_read_b128 v[178:181], v20 offset:3072
	ds_read_b128 v[182:185], v20 offset:4096
	ds_read_b128 v[190:193], v20 offset:5120
	ds_read_b128 v[194:197], v20 offset:6144
	ds_read_b128 v[198:201], v20 offset:7168
	global_load_lds_dwordx4 v[2:3], off
	v_lshl_add_u64 v[2:3], s[6:7], 0, v[16:17]
	v_lshl_add_u64 v[2:3], v[2:3], 0, v[6:7]
	s_mov_b32 m0, s19
	s_nop 0
	global_load_lds_dwordx4 v[2:3], off
	s_barrier
; #define STAGE(P, BASE, LD, br, kt) do { const long _g = (long)(br) * (LD) + (long)(kt) * 64; \
;     _Pragma("unroll") for (int _i = 0; _i < 2; ++_i) { const int _b = tid * 16 + _i * 8192; int _r, _c; stage_rc(_b, _r, _c); \
;       __builtin_amdgcn_global_load_lds((const G_AS1 unsigned*)((BASE) + _g + (long)_r * (LD) + _c), \
;         (LAS unsigned*)((char*)(P) + _b), 16, 0, 0); } } while (0)
; #define LDA(dst, b, h) _Pragma("unroll") for (int m = 0; m < 4; ++m) _Pragma("unroll") for (int k = 0; k < 2; ++k) \
;     dst[m][k] = *reinterpret_cast<const bf16x8*>((char*)SA(b, h) + lds_byte(wr * 64 + m * 16 + fr, k * 32 + fq * 8))
; #define LDB(dst, b, h) _Pragma("unroll") for (int n = 0; n < 2; ++n) _Pragma("unroll") for (int k = 0; k < 2; ++k) \
;     dst[n][k] = *reinterpret_cast<const bf16x8*>((char*)SB(b, h) + lds_byte(wc * 32 + n * 16 + fr, k * 32 + fq * 8))
; #define MMA(ai, bj, At_, Bt_) do { __builtin_amdgcn_s_setprio(1); \
;     _Pragma("unroll") for (int m = 0; m < 4; ++m) _Pragma("unroll") for (int n = 0; n < 2; ++n) _Pragma("unroll") for (int k = 0; k < 2; ++k) \
;       acc[ai][bj][m][n] = __builtin_amdgcn_mfma_f32_16x16x32_bf16(At_[m][k], Bt_[n][k], acc[ai][bj][m][n], 0, 0, 0); \
;     __builtin_amdgcn_s_setprio(0); } while (0)
; #define WAIT_V(n) asm volatile("s_waitcnt vmcnt(" #n ")" ::: "memory")
; #define WAIT_L(n) asm volatile("s_waitcnt lgkmcnt(" #n ")" ::: "memory")
; #define BAR __builtin_amdgcn_s_barrier()
; __device__ __forceinline__ void gemm256(const bf16_t* __restrict__ A, long lda, const bf16_t* __restrict__ Bt, long ldb, int K,
;                                         int brow, int bcol, char* smem, f32x4 (&acc)[2][2][4][2]) {
;     ...
;     { LDB(B0, 0, 0); LDA(At, 0, 0); STAGE(SA(1, 1), A, lda, brow + 128, nt - 1);
;       BAR; WAIT_L(0); MMA(0, 0, At, B0); BAR;
;       LDB(B1, 0, 1); BAR; WAIT_L(0); MMA(0, 1, At, B1); BAR;
;       LDA(At, 0, 1); WAIT_V(4); BAR; WAIT_L(0); MMA(1, 0, At, B0); MMA(1, 1, At, B1); BAR; }
;     { LDB(B0, 1, 0); LDA(At, 1, 0); WAIT_V(2); BAR; WAIT_L(0); MMA(0, 0, At, B0); BAR;
	s_waitcnt lgkmcnt(0)
	s_setprio 1
	s_waitcnt lgkmcnt(0)
	v_mfma_f32_16x16x32_bf16 v[12:15], v[146:149], v[114:117], v[22:25]
	v_mfma_f32_16x16x32_bf16 v[16:19], v[146:149], v[138:141], v[78:81]
	v_mfma_f32_16x16x32_bf16 v[22:25], v[154:157], v[114:117], v[82:85]
	v_mfma_f32_16x16x32_bf16 v[76:79], v[154:157], v[138:141], v[86:89]
	v_mfma_f32_16x16x32_bf16 v[80:83], v[182:185], v[114:117], v[90:93]
	v_mfma_f32_16x16x32_bf16 v[84:87], v[182:185], v[138:141], v[94:97]
	v_mfma_f32_16x16x32_bf16 v[88:91], v[194:197], v[114:117], v[98:101]
	v_mfma_f32_16x16x32_bf16 v[92:95], v[194:197], v[138:141], v[102:105]
	v_mfma_f32_16x16x32_bf16 v[12:15], v[150:153], v[134:137], v[12:15]
	v_mfma_f32_16x16x32_bf16 v[16:19], v[150:153], v[142:145], v[16:19]
	v_mfma_f32_16x16x32_bf16 v[22:25], v[178:181], v[134:137], v[22:25]
	v_mfma_f32_16x16x32_bf16 v[76:79], v[178:181], v[142:145], v[76:79]
	v_mfma_f32_16x16x32_bf16 v[80:83], v[190:193], v[134:137], v[80:83]
	v_mfma_f32_16x16x32_bf16 v[84:87], v[190:193], v[142:145], v[84:87]
	v_mfma_f32_16x16x32_bf16 v[88:91], v[198:201], v[134:137], v[88:91]
	v_mfma_f32_16x16x32_bf16 v[92:95], v[198:201], v[142:145], v[92:95]
	s_setprio 0
	s_barrier
	s_nop 0
	ds_read_b128 v[96:99], v226
	ds_read_b128 v[100:103], v227
	ds_read_b128 v[202:205], v228
	ds_read_b128 v[206:209], v229
	s_barrier
	s_waitcnt lgkmcnt(0)
	s_setprio 1
	s_waitcnt lgkmcnt(1)
	v_mfma_f32_16x16x32_bf16 v[42:45], v[146:149], v[202:205], v[44:47]
	v_mfma_f32_16x16x32_bf16 v[46:49], v[154:157], v[96:99], v[48:51]
	v_mfma_f32_16x16x32_bf16 v[50:53], v[154:157], v[202:205], v[52:55]
	v_mfma_f32_16x16x32_bf16 v[54:57], v[182:185], v[96:99], v[56:59]
	v_mfma_f32_16x16x32_bf16 v[58:61], v[182:185], v[202:205], v[60:63]
	v_mfma_f32_16x16x32_bf16 v[62:65], v[194:197], v[96:99], v[64:67]
	v_mfma_f32_16x16x32_bf16 v[66:69], v[194:197], v[202:205], v[68:71]
	v_mfma_f32_16x16x32_bf16 v[126:129], v[146:149], v[96:99], v[126:129]
	s_waitcnt lgkmcnt(0)
	v_mfma_f32_16x16x32_bf16 v[42:45], v[150:153], v[206:209], v[42:45]
	v_mfma_f32_16x16x32_bf16 v[46:49], v[178:181], v[100:103], v[46:49]
	v_mfma_f32_16x16x32_bf16 v[50:53], v[178:181], v[206:209], v[50:53]
	v_mfma_f32_16x16x32_bf16 v[54:57], v[190:193], v[100:103], v[54:57]
	v_mfma_f32_16x16x32_bf16 v[58:61], v[190:193], v[206:209], v[58:61]
	v_mfma_f32_16x16x32_bf16 v[62:65], v[198:201], v[100:103], v[62:65]
	v_mfma_f32_16x16x32_bf16 v[66:69], v[198:201], v[206:209], v[66:69]
	v_mfma_f32_16x16x32_bf16 v[210:213], v[150:153], v[100:103], v[126:129]
	s_setprio 0
	s_barrier
	s_nop 0
	ds_read_b128 v[126:129], v21 offset:16384
	ds_read_b128 v[146:149], v21 offset:17408
	ds_read_b128 v[150:153], v20 offset:18432
	ds_read_b128 v[154:157], v20 offset:19456
	ds_read_b128 v[178:181], v20 offset:20480
	ds_read_b128 v[182:185], v20 offset:21504
	ds_read_b128 v[190:193], v20 offset:22528
	ds_read_b128 v[194:197], v20 offset:23552
	s_waitcnt vmcnt(4)
	s_barrier
	s_waitcnt lgkmcnt(0)
	s_setprio 1
	s_waitcnt lgkmcnt(7)
	v_mfma_f32_16x16x32_bf16 v[6:9], v[126:129], v[114:117], v[8:11]
	s_waitcnt lgkmcnt(1)
	v_mfma_f32_16x16x32_bf16 v[26:29], v[190:193], v[114:117], v[26:29]
	v_mfma_f32_16x16x32_bf16 v[30:33], v[190:193], v[138:141], v[30:33]
	v_mfma_f32_16x16x32_bf16 v[6:9], v[146:149], v[134:137], v[6:9]
	v_mfma_f32_16x16x32_bf16 v[158:161], v[126:129], v[138:141], v[158:161]
	v_mfma_f32_16x16x32_bf16 v[162:165], v[150:153], v[114:117], v[162:165]
	v_mfma_f32_16x16x32_bf16 v[166:169], v[150:153], v[138:141], v[166:169]
	v_mfma_f32_16x16x32_bf16 v[170:173], v[178:181], v[114:117], v[170:173]
	v_mfma_f32_16x16x32_bf16 v[174:177], v[178:181], v[138:141], v[174:177]
	s_waitcnt lgkmcnt(0)
	v_mfma_f32_16x16x32_bf16 v[26:29], v[194:197], v[134:137], v[26:29]
	v_mfma_f32_16x16x32_bf16 v[30:33], v[194:197], v[142:145], v[30:33]
	v_mfma_f32_16x16x32_bf16 v[158:161], v[146:149], v[142:145], v[158:161]
	v_mfma_f32_16x16x32_bf16 v[162:165], v[154:157], v[134:137], v[162:165]
	v_mfma_f32_16x16x32_bf16 v[166:169], v[154:157], v[142:145], v[166:169]
	v_mfma_f32_16x16x32_bf16 v[170:173], v[182:185], v[134:137], v[170:173]
	v_mfma_f32_16x16x32_bf16 v[174:177], v[182:185], v[142:145], v[174:177]
	s_setprio 0
	s_setprio 1
	v_mfma_f32_16x16x32_bf16 v[38:41], v[126:129], v[202:205], v[38:41]
	v_mfma_f32_16x16x32_bf16 v[134:137], v[146:149], v[206:209], v[38:41]
	v_mfma_f32_16x16x32_bf16 v[38:41], v[150:153], v[96:99], v[72:75]
	v_mfma_f32_16x16x32_bf16 v[138:141], v[154:157], v[100:103], v[38:41]
	v_mfma_f32_16x16x32_bf16 v[38:41], v[150:153], v[202:205], v[118:121]
	v_mfma_f32_16x16x32_bf16 v[34:37], v[126:129], v[96:99], v[34:37]
	v_mfma_f32_16x16x32_bf16 v[142:145], v[154:157], v[206:209], v[38:41]
	v_mfma_f32_16x16x32_bf16 v[38:41], v[178:181], v[96:99], v[122:125]
	v_mfma_f32_16x16x32_bf16 v[34:37], v[146:149], v[100:103], v[34:37]
	v_mfma_f32_16x16x32_bf16 v[146:149], v[182:185], v[100:103], v[38:41]
	v_mfma_f32_16x16x32_bf16 v[38:41], v[178:181], v[202:205], v[130:133]
	v_mfma_f32_16x16x32_bf16 v[150:153], v[182:185], v[206:209], v[38:41]
	v_mfma_f32_16x16x32_bf16 v[38:41], v[190:193], v[96:99], v[106:109]
	v_mfma_f32_16x16x32_bf16 v[154:157], v[194:197], v[100:103], v[38:41]
	v_mfma_f32_16x16x32_bf16 v[38:41], v[190:193], v[202:205], v[110:113]
	v_mfma_f32_16x16x32_bf16 v[178:181], v[194:197], v[206:209], v[38:41]
	s_setprio 0
	s_barrier
	s_nop 4
	ds_read_b128 v[38:41], v230
	ds_read_b128 v[182:185], v231
	ds_read_b128 v[190:193], v232
	ds_read_b128 v[194:197], v233
	ds_read_b128 v[70:73], v21 offset:32768
	ds_read_b128 v[198:201], v21 offset:33792
	ds_read_b128 v[202:205], v20 offset:34816
	ds_read_b128 v[206:209], v20 offset:35840
	ds_read_b128 v[214:217], v20 offset:36864
	ds_read_b128 v[218:221], v20 offset:37888
	ds_read_b128 v[222:225], v20 offset:38912
	ds_read_b128 v[226:229], v20 offset:39936
	s_waitcnt vmcnt(2)
	s_barrier
; #define LDA(dst, b, h) _Pragma("unroll") for (int m = 0; m < 4; ++m) _Pragma("unroll") for (int k = 0; k < 2; ++k) \
;     dst[m][k] = *reinterpret_cast<const bf16x8*>((char*)SA(b, h) + lds_byte(wr * 64 + m * 16 + fr, k * 32 + fq * 8))
; #define LDB(dst, b, h) _Pragma("unroll") for (int n = 0; n < 2; ++n) _Pragma("unroll") for (int k = 0; k < 2; ++k) \
;     dst[n][k] = *reinterpret_cast<const bf16x8*>((char*)SB(b, h) + lds_byte(wc * 32 + n * 16 + fr, k * 32 + fq * 8))
; #define MMA(ai, bj, At_, Bt_) do { __builtin_amdgcn_s_setprio(1); \
;     _Pragma("unroll") for (int m = 0; m < 4; ++m) _Pragma("unroll") for (int n = 0; n < 2; ++n) _Pragma("unroll") for (int k = 0; k < 2; ++k) \
;       acc[ai][bj][m][n] = __builtin_amdgcn_mfma_f32_16x16x32_bf16(At_[m][k], Bt_[n][k], acc[ai][bj][m][n], 0, 0, 0); \
;     __builtin_amdgcn_s_setprio(0); } while (0)
; #define WAIT_V(n) asm volatile("s_waitcnt vmcnt(" #n ")" ::: "memory")
; #define WAIT_L(n) asm volatile("s_waitcnt lgkmcnt(" #n ")" ::: "memory")
; #define BAR __builtin_amdgcn_s_barrier()
; __device__ __forceinline__ void gemm256(const bf16_t* __restrict__ A, long lda, const bf16_t* __restrict__ Bt, long ldb, int K,
;                                         int brow, int bcol, char* smem, f32x4 (&acc)[2][2][4][2]) {
;     ...
;     { LDB(B0, 1, 0); LDA(At, 1, 0); WAIT_V(2); BAR; WAIT_L(0); MMA(0, 0, At, B0); BAR;
;       LDB(B1, 1, 1); WAIT_V(0); BAR; WAIT_L(0); MMA(0, 1, At, B1); BAR;
;       LDA(At, 1, 1); BAR; WAIT_L(0); MMA(1, 0, At, B0); MMA(1, 1, At, B1); BAR; }
;     if (wr == 0) BAR;
	s_waitcnt lgkmcnt(0)
	s_setprio 1
	s_waitcnt lgkmcnt(7)
	v_mfma_f32_16x16x32_bf16 v[10:13], v[70:73], v[38:41], v[12:15]
	s_waitcnt lgkmcnt(6)
	v_mfma_f32_16x16x32_bf16 v[130:133], v[198:201], v[182:185], v[10:13]
	v_mfma_f32_16x16x32_bf16 v[10:13], v[70:73], v[190:193], v[16:19]
	v_mfma_f32_16x16x32_bf16 v[126:129], v[198:201], v[194:197], v[10:13]
	s_waitcnt lgkmcnt(5)
	v_mfma_f32_16x16x32_bf16 v[10:13], v[202:205], v[38:41], v[22:25]
	s_waitcnt lgkmcnt(4)
	v_mfma_f32_16x16x32_bf16 v[122:125], v[206:209], v[182:185], v[10:13]
	v_mfma_f32_16x16x32_bf16 v[10:13], v[202:205], v[190:193], v[76:79]
	v_mfma_f32_16x16x32_bf16 v[118:121], v[206:209], v[194:197], v[10:13]
	s_waitcnt lgkmcnt(3)
	v_mfma_f32_16x16x32_bf16 v[10:13], v[214:217], v[38:41], v[80:83]
	s_waitcnt lgkmcnt(2)
	v_mfma_f32_16x16x32_bf16 v[114:117], v[218:221], v[182:185], v[10:13]
	v_mfma_f32_16x16x32_bf16 v[10:13], v[214:217], v[190:193], v[84:87]
	v_mfma_f32_16x16x32_bf16 v[110:113], v[218:221], v[194:197], v[10:13]
	s_waitcnt lgkmcnt(1)
	v_mfma_f32_16x16x32_bf16 v[10:13], v[222:225], v[38:41], v[88:91]
	s_waitcnt lgkmcnt(0)
	v_mfma_f32_16x16x32_bf16 v[106:109], v[226:229], v[182:185], v[10:13]
	v_mfma_f32_16x16x32_bf16 v[10:13], v[222:225], v[190:193], v[92:95]
	v_mfma_f32_16x16x32_bf16 v[98:101], v[226:229], v[194:197], v[10:13]
	s_setprio 0
	s_barrier
	s_nop 4
	ds_read_b128 v[10:13], v234
	ds_read_b128 v[230:233], v235
	ds_read_b128 v[250:253], v238
	ds_read_b128 v[242:245], v239
	s_waitcnt vmcnt(0)
	s_barrier
	s_waitcnt lgkmcnt(0)
	s_setprio 1
	s_waitcnt lgkmcnt(3)
	v_mfma_f32_16x16x32_bf16 v[14:17], v[70:73], v[10:13], v[210:213]
	s_waitcnt lgkmcnt(2)
	v_mfma_f32_16x16x32_bf16 v[102:105], v[198:201], v[230:233], v[14:17]
	s_waitcnt lgkmcnt(1)
	v_mfma_f32_16x16x32_bf16 v[14:17], v[70:73], v[250:253], v[42:45]
	s_waitcnt lgkmcnt(0)
	v_mfma_f32_16x16x32_bf16 v[94:97], v[198:201], v[242:245], v[14:17]
	v_mfma_f32_16x16x32_bf16 v[14:17], v[202:205], v[10:13], v[46:49]
	v_mfma_f32_16x16x32_bf16 v[90:93], v[206:209], v[230:233], v[14:17]
	v_mfma_f32_16x16x32_bf16 v[14:17], v[202:205], v[250:253], v[50:53]
	v_mfma_f32_16x16x32_bf16 v[86:89], v[206:209], v[242:245], v[14:17]
	v_mfma_f32_16x16x32_bf16 v[14:17], v[214:217], v[10:13], v[54:57]
	v_mfma_f32_16x16x32_bf16 v[82:85], v[218:221], v[230:233], v[14:17]
	v_mfma_f32_16x16x32_bf16 v[14:17], v[214:217], v[250:253], v[58:61]
	v_mfma_f32_16x16x32_bf16 v[78:81], v[218:221], v[242:245], v[14:17]
	v_mfma_f32_16x16x32_bf16 v[14:17], v[222:225], v[10:13], v[62:65]
	v_mfma_f32_16x16x32_bf16 v[74:77], v[226:229], v[230:233], v[14:17]
	v_mfma_f32_16x16x32_bf16 v[14:17], v[222:225], v[250:253], v[66:69]
	v_mfma_f32_16x16x32_bf16 v[70:73], v[226:229], v[242:245], v[14:17]
	s_setprio 0
	s_barrier
	s_nop 4
	ds_read_b128 v[14:17], v21 offset:49152
	ds_read_b128 v[22:25], v21 offset:50176
	ds_read_b128 v[198:201], v20 offset:51200
	ds_read_b128 v[202:205], v20 offset:52224
	ds_read_b128 v[206:209], v20 offset:53248
	ds_read_b128 v[210:213], v20 offset:54272
	ds_read_b128 v[214:217], v20 offset:55296
	ds_read_b128 v[218:221], v20 offset:56320
	s_barrier
	s_waitcnt lgkmcnt(0)
	s_setprio 1
	s_waitcnt lgkmcnt(7)
	v_mfma_f32_16x16x32_bf16 v[6:9], v[14:17], v[38:41], v[6:9]
	s_waitcnt lgkmcnt(6)
	v_mfma_f32_16x16x32_bf16 v[66:69], v[22:25], v[182:185], v[6:9]
	v_mfma_f32_16x16x32_bf16 v[6:9], v[14:17], v[190:193], v[158:161]
	v_mfma_f32_16x16x32_bf16 v[62:65], v[22:25], v[194:197], v[6:9]
	s_waitcnt lgkmcnt(5)
	v_mfma_f32_16x16x32_bf16 v[6:9], v[198:201], v[38:41], v[162:165]
	s_waitcnt lgkmcnt(4)
	v_mfma_f32_16x16x32_bf16 v[58:61], v[202:205], v[182:185], v[6:9]
	v_mfma_f32_16x16x32_bf16 v[6:9], v[198:201], v[190:193], v[166:169]
	v_mfma_f32_16x16x32_bf16 v[54:57], v[202:205], v[194:197], v[6:9]
	s_waitcnt lgkmcnt(3)
	v_mfma_f32_16x16x32_bf16 v[6:9], v[206:209], v[38:41], v[170:173]
	s_waitcnt lgkmcnt(2)
	v_mfma_f32_16x16x32_bf16 v[50:53], v[210:213], v[182:185], v[6:9]
	v_mfma_f32_16x16x32_bf16 v[6:9], v[206:209], v[190:193], v[174:177]
	v_mfma_f32_16x16x32_bf16 v[46:49], v[210:213], v[194:197], v[6:9]
	s_waitcnt lgkmcnt(1)
	v_mfma_f32_16x16x32_bf16 v[6:9], v[214:217], v[38:41], v[26:29]
	s_waitcnt lgkmcnt(0)
	v_mfma_f32_16x16x32_bf16 v[42:45], v[218:221], v[182:185], v[6:9]
	v_mfma_f32_16x16x32_bf16 v[6:9], v[214:217], v[190:193], v[30:33]
	v_mfma_f32_16x16x32_bf16 v[38:41], v[218:221], v[194:197], v[6:9]
	s_setprio 0
	s_setprio 1
	v_mfma_f32_16x16x32_bf16 v[6:9], v[14:17], v[10:13], v[34:37]
	v_mfma_f32_16x16x32_bf16 v[34:37], v[22:25], v[230:233], v[6:9]
	v_mfma_f32_16x16x32_bf16 v[6:9], v[14:17], v[250:253], v[134:137]
	v_mfma_f32_16x16x32_bf16 v[30:33], v[22:25], v[242:245], v[6:9]
	v_mfma_f32_16x16x32_bf16 v[6:9], v[198:201], v[10:13], v[138:141]
	v_mfma_f32_16x16x32_bf16 v[26:29], v[202:205], v[230:233], v[6:9]
	v_mfma_f32_16x16x32_bf16 v[6:9], v[198:201], v[250:253], v[142:145]
	v_mfma_f32_16x16x32_bf16 v[22:25], v[202:205], v[242:245], v[6:9]
	v_mfma_f32_16x16x32_bf16 v[6:9], v[206:209], v[10:13], v[146:149]
	v_mfma_f32_16x16x32_bf16 v[18:21], v[210:213], v[230:233], v[6:9]
	v_mfma_f32_16x16x32_bf16 v[6:9], v[206:209], v[250:253], v[150:153]
	v_mfma_f32_16x16x32_bf16 v[14:17], v[210:213], v[242:245], v[6:9]
	v_mfma_f32_16x16x32_bf16 v[6:9], v[214:217], v[10:13], v[154:157]
	v_mfma_f32_16x16x32_bf16 v[10:13], v[218:221], v[230:233], v[6:9]
	v_mfma_f32_16x16x32_bf16 v[6:9], v[214:217], v[250:253], v[178:181]
	v_mfma_f32_16x16x32_bf16 v[6:9], v[218:221], v[242:245], v[6:9]
	s_setprio 0
	v_cmp_gt_u32_e32 vcc, s78, v0
	s_barrier
	s_and_saveexec_b64 s[6:7], vcc
	s_cbranch_execz .LBB0_1609
	s_barrier
